# postbar2
# baseline (speedup 1.0000x reference)
; #define STAGE(P, BASE, LD, br, kt) do { const char* _g = (const char*)((BASE) + (size_t)(br) * (LD) + (size_t)(kt) * 64); \
;     for (int _i = 0; _i < 2; ++_i) { int _b = tidx * 16 + _i * 8192; int _r, _c; stage_rc(_b, _r, _c); \
;       __builtin_amdgcn_global_load_lds((const unsigned*)(_g + (unsigned)((_r * (LD) + _c) * 2)), (unsigned*)((char*)(P) + _b), 16, 0, 0); } } while (0)
; #define LDA(dst, b, h) for (int m = 0; m < 4; ++m) for (int k = 0; k < 2; ++k) \
;     dst[m][k] = *reinterpret_cast<const bf16x8*>((char*)SA(b, h) + lds_byte(wr * 64 + m * 16 + fr, k * 32 + fq * 8))
; #define LDB(dst, b, h) for (int n = 0; n < 2; ++n) for (int k = 0; k < 2; ++k) \
;     dst[n][k] = *reinterpret_cast<const bf16x8*>((char*)SB(b, h) + lds_byte(wc * 32 + n * 16 + fr, k * 32 + fq * 8))
; #define MMA(ai, bj, At_, Bt_) do { __builtin_amdgcn_s_setprio(1); \
;     for (int k = 0; k < 2; ++k) for (int m = 0; m < 4; ++m) for (int n = 0; n < 2; ++n) \
;       acc[ai][bj][m][n] = __builtin_amdgcn_mfma_f32_16x16x32_bf16(At_[m][k], Bt_[n][k], acc[ai][bj][m][n], 0, 0, 0); \
;     __builtin_amdgcn_s_setprio(0); } while (0)
; #define WAIT_L(n) asm volatile("s_waitcnt lgkmcnt(" #n ")" ::: "memory")
; #define BAR __builtin_amdgcn_s_barrier()
; #define SCHED __builtin_amdgcn_sched_barrier(0)
; template <int EPI, int lda, int ldb, int N, int K>
; __device__ __forceinline__ void gemm_phase(const u16* __restrict__ A, const u16* __restrict__ Bt, const GemmEpi ep, int wv) {
;     ...
;     for (int t = 0; t < nt - 2; t += 2) {
;       LDB(B0, 0, 0); SCHED; LDA(At, 0, 0); STAGE(SA(1, 1), Ab, lda, brow + HALF, t + 1);
;       WAIT_L(8); BAR; WAIT_L(0); MMA(0, 0, At, B0); BAR; SCHED;
;       LDB(B1, 0, 1); STAGE(SB(0, 0), Bt, ldb, bcol, t + 2);
;       BAR; WAIT_L(0); MMA(0, 1, At, B1); BAR;
;       LDA(At, 0, 1); STAGE(SA(0, 0), Ab, lda, brow, t + 2);
;       BAR; WAIT_L(0); MMA(1, 0, At, B0); BAR; SCHED;
.LBB0_53:
	ds_read_b128 v[172:175], v161
	ds_read_b128 v[176:179], v161 offset:1024
	ds_read_b128 v[180:183], v161 offset:2048
	ds_read_b128 v[184:187], v161 offset:3072
	v_add_u32_e32 v169, 0xc000, v148
	v_lshl_add_u64 v[236:237], v[136:137], 0, s[42:43]
	v_readfirstlane_b32 s45, v169
	v_add_u32_e32 v170, 0xe000, v148
	v_lshl_add_u64 v[162:163], v[236:237], 0, s[14:15]
	s_mov_b32 m0, s45
	v_lshl_add_u64 v[238:239], v[134:135], 0, s[42:43]
	v_readfirstlane_b32 s45, v170
	ds_read_b128 v[164:167], v152
	ds_read_b128 v[188:191], v152 offset:1024
	ds_read_b128 v[192:195], v151
	ds_read_b128 v[196:199], v151 offset:1024
	ds_read_b128 v[200:203], v150
	ds_read_b128 v[204:207], v150 offset:1024
	ds_read_b128 v[208:211], v149
	ds_read_b128 v[212:215], v149 offset:1024
	global_load_lds_dwordx4 v[162:163], off
	v_lshl_add_u64 v[162:163], v[238:239], 0, s[14:15]
	s_mov_b32 m0, s45
	s_nop 0
	global_load_lds_dwordx4 v[162:163], off
	s_waitcnt lgkmcnt(8)
	s_barrier
	s_waitcnt lgkmcnt(0)
	s_waitcnt lgkmcnt(0)
	v_mfma_f32_16x16x32_bf16 v[124:127], v[172:175], v[164:167], v[124:127]
	v_mfma_f32_16x16x32_bf16 v[120:123], v[180:183], v[164:167], v[120:123]
	v_mfma_f32_16x16x32_bf16 v[116:119], v[172:175], v[192:195], v[116:119]
	v_mfma_f32_16x16x32_bf16 v[112:115], v[180:183], v[192:195], v[112:115]
	v_mfma_f32_16x16x32_bf16 v[108:111], v[172:175], v[200:203], v[108:111]
	v_mfma_f32_16x16x32_bf16 v[104:107], v[180:183], v[200:203], v[104:107]
	v_mfma_f32_16x16x32_bf16 v[100:103], v[172:175], v[208:211], v[100:103]
	v_mfma_f32_16x16x32_bf16 v[96:99], v[180:183], v[208:211], v[96:99]
	v_mfma_f32_16x16x32_bf16 v[124:127], v[176:179], v[188:191], v[124:127]
	v_mfma_f32_16x16x32_bf16 v[120:123], v[184:187], v[188:191], v[120:123]
	v_mfma_f32_16x16x32_bf16 v[116:119], v[176:179], v[196:199], v[116:119]
	v_mfma_f32_16x16x32_bf16 v[112:115], v[184:187], v[196:199], v[112:115]
	v_mfma_f32_16x16x32_bf16 v[108:111], v[176:179], v[204:207], v[108:111]
	v_mfma_f32_16x16x32_bf16 v[104:107], v[184:187], v[204:207], v[104:107]
	v_mfma_f32_16x16x32_bf16 v[100:103], v[176:179], v[212:215], v[100:103]
	v_mfma_f32_16x16x32_bf16 v[96:99], v[184:187], v[212:215], v[96:99]
	s_barrier
	v_add_u32_e32 v162, s54, v153
	v_lshl_add_u64 v[240:241], v[140:141], 0, s[42:43]
	v_readfirstlane_b32 s45, v162
	v_add_u32_e32 v163, 0x2000, v162
	v_lshl_add_u64 v[232:233], v[240:241], 0, s[16:17]
	s_mov_b32 m0, s45
	v_lshl_add_u64 v[242:243], v[138:139], 0, s[42:43]
	v_readfirstlane_b32 s45, v163
	ds_read_b128 v[216:219], v160
	ds_read_b128 v[220:223], v160 offset:1024
	ds_read_b128 v[224:227], v160 offset:2048
	ds_read_b128 v[228:231], v160 offset:3072
	global_load_lds_dwordx4 v[232:233], off
	v_lshl_add_u64 v[232:233], v[242:243], 0, s[16:17]
	s_mov_b32 m0, s45
	s_nop 0
	global_load_lds_dwordx4 v[232:233], off
	s_barrier
	s_waitcnt lgkmcnt(0)
	s_waitcnt lgkmcnt(0)
	v_mfma_f32_16x16x32_bf16 v[92:95], v[216:219], v[164:167], v[92:95]
	v_mfma_f32_16x16x32_bf16 v[88:91], v[224:227], v[164:167], v[88:91]
	v_mfma_f32_16x16x32_bf16 v[84:87], v[216:219], v[192:195], v[84:87]
	v_mfma_f32_16x16x32_bf16 v[80:83], v[224:227], v[192:195], v[80:83]
	v_mfma_f32_16x16x32_bf16 v[76:79], v[216:219], v[200:203], v[76:79]
	v_mfma_f32_16x16x32_bf16 v[72:75], v[224:227], v[200:203], v[72:75]
	v_mfma_f32_16x16x32_bf16 v[68:71], v[216:219], v[208:211], v[68:71]
	v_mfma_f32_16x16x32_bf16 v[64:67], v[224:227], v[208:211], v[64:67]
	v_mfma_f32_16x16x32_bf16 v[92:95], v[220:223], v[188:191], v[92:95]
	v_mfma_f32_16x16x32_bf16 v[88:91], v[228:231], v[188:191], v[88:91]
	v_mfma_f32_16x16x32_bf16 v[84:87], v[220:223], v[196:199], v[84:87]
	v_mfma_f32_16x16x32_bf16 v[80:83], v[228:231], v[196:199], v[80:83]
	v_mfma_f32_16x16x32_bf16 v[76:79], v[220:223], v[204:207], v[76:79]
	v_mfma_f32_16x16x32_bf16 v[72:75], v[228:231], v[204:207], v[72:75]
	v_mfma_f32_16x16x32_bf16 v[68:71], v[220:223], v[212:215], v[68:71]
	v_mfma_f32_16x16x32_bf16 v[64:67], v[228:231], v[212:215], v[64:67]
	s_barrier
	v_readfirstlane_b32 s45, v148
	v_lshl_add_u64 v[164:165], v[236:237], 0, s[18:19]
	s_mov_b32 m0, s45
	ds_read_b128 v[188:191], v152 offset:16384
	ds_read_b128 v[192:195], v152 offset:17408
	ds_read_b128 v[196:199], v151 offset:16384
	ds_read_b128 v[200:203], v151 offset:17408
	ds_read_b128 v[204:207], v150 offset:16384
	ds_read_b128 v[208:211], v150 offset:17408
	ds_read_b128 v[212:215], v149 offset:16384
	ds_read_b128 v[232:235], v149 offset:17408
	global_load_lds_dwordx4 v[164:165], off
	v_add_u32_e32 v164, 0x2000, v148
	v_lshl_add_u64 v[166:167], v[238:239], 0, s[18:19]
	v_readfirstlane_b32 s45, v164
	s_mov_b32 m0, s45
	s_nop 0
	global_load_lds_dwordx4 v[166:167], off
	s_barrier
	s_waitcnt lgkmcnt(0)
	s_waitcnt lgkmcnt(0)
	v_mfma_f32_16x16x32_bf16 v[60:63], v[172:175], v[188:191], v[60:63]
	v_mfma_f32_16x16x32_bf16 v[56:59], v[180:183], v[188:191], v[56:59]
	v_mfma_f32_16x16x32_bf16 v[52:55], v[172:175], v[196:199], v[52:55]
	v_mfma_f32_16x16x32_bf16 v[48:51], v[180:183], v[196:199], v[48:51]
	v_mfma_f32_16x16x32_bf16 v[44:47], v[172:175], v[204:207], v[44:47]
	v_mfma_f32_16x16x32_bf16 v[40:43], v[180:183], v[204:207], v[40:43]
	v_mfma_f32_16x16x32_bf16 v[36:39], v[172:175], v[212:215], v[36:39]
	v_mfma_f32_16x16x32_bf16 v[32:35], v[180:183], v[212:215], v[32:35]
	v_mfma_f32_16x16x32_bf16 v[60:63], v[176:179], v[192:195], v[60:63]
	v_mfma_f32_16x16x32_bf16 v[56:59], v[184:187], v[192:195], v[56:59]
	v_mfma_f32_16x16x32_bf16 v[52:55], v[176:179], v[200:203], v[52:55]
	v_mfma_f32_16x16x32_bf16 v[48:51], v[184:187], v[200:203], v[48:51]
	v_mfma_f32_16x16x32_bf16 v[44:47], v[176:179], v[208:211], v[44:47]
	v_mfma_f32_16x16x32_bf16 v[40:43], v[184:187], v[208:211], v[40:43]
	v_mfma_f32_16x16x32_bf16 v[36:39], v[176:179], v[232:235], v[36:39]
	v_mfma_f32_16x16x32_bf16 v[32:35], v[184:187], v[232:235], v[32:35]
	s_barrier
; #define STAGE(P, BASE, LD, br, kt) do { const char* _g = (const char*)((BASE) + (size_t)(br) * (LD) + (size_t)(kt) * 64); \
;     for (int _i = 0; _i < 2; ++_i) { int _b = tidx * 16 + _i * 8192; int _r, _c; stage_rc(_b, _r, _c); \
;       __builtin_amdgcn_global_load_lds((const unsigned*)(_g + (unsigned)((_r * (LD) + _c) * 2)), (unsigned*)((char*)(P) + _b), 16, 0, 0); } } while (0)
; #define LDA(dst, b, h) for (int m = 0; m < 4; ++m) for (int k = 0; k < 2; ++k) \
;     dst[m][k] = *reinterpret_cast<const bf16x8*>((char*)SA(b, h) + lds_byte(wr * 64 + m * 16 + fr, k * 32 + fq * 8))
; #define LDB(dst, b, h) for (int n = 0; n < 2; ++n) for (int k = 0; k < 2; ++k) \
;     dst[n][k] = *reinterpret_cast<const bf16x8*>((char*)SB(b, h) + lds_byte(wc * 32 + n * 16 + fr, k * 32 + fq * 8))
; #define MMA(ai, bj, At_, Bt_) do { __builtin_amdgcn_s_setprio(1); \
;     for (int k = 0; k < 2; ++k) for (int m = 0; m < 4; ++m) for (int n = 0; n < 2; ++n) \
;       acc[ai][bj][m][n] = __builtin_amdgcn_mfma_f32_16x16x32_bf16(At_[m][k], Bt_[n][k], acc[ai][bj][m][n], 0, 0, 0); \
;     __builtin_amdgcn_s_setprio(0); } while (0)
; #define WAIT_V(n) asm volatile("s_waitcnt vmcnt(" #n ")" ::: "memory")
; #define WAIT_L(n) asm volatile("s_waitcnt lgkmcnt(" #n ")" ::: "memory")
; #define BAR __builtin_amdgcn_s_barrier()
; #define SCHED __builtin_amdgcn_sched_barrier(0)
; template <int EPI, int lda, int ldb, int N, int K>
; __device__ __forceinline__ void gemm_phase(const u16* __restrict__ A, const u16* __restrict__ Bt, const GemmEpi ep, int wv) {
;     ...
;       STAGE(SB(0, 1), Bt, ldb, bcol + HALF, t + 2);
;       WAIT_V(6); BAR; MMA(1, 1, At, B1); BAR;
;       LDB(B0, 1, 0); SCHED; LDA(At, 1, 0); STAGE(SA(0, 1), Ab, lda, brow + HALF, t + 2);
;       WAIT_L(8); BAR; WAIT_L(0); MMA(0, 0, At, B0); BAR; SCHED;
;       LDB(B1, 1, 1); STAGE(SB(1, 0), Bt, ldb, bcol, t + 3);
;       BAR; WAIT_L(0); MMA(0, 1, At, B1); BAR;
;       LDA(At, 1, 1); STAGE(SA(1, 0), Ab, lda, brow, t + 3);
	v_add_u32_e32 v165, s55, v153
	v_lshl_add_u64 v[166:167], v[240:241], 0, s[20:21]
	v_readfirstlane_b32 s45, v165
	s_mov_b32 m0, s45
	v_lshl_add_u64 v[172:173], v[242:243], 0, s[20:21]
	global_load_lds_dwordx4 v[166:167], off
	v_add_u32_e32 v166, 0x2000, v165
	s_nop 0
	v_readfirstlane_b32 s45, v166
	s_mov_b32 m0, s45
	s_nop 0
	global_load_lds_dwordx4 v[172:173], off
	s_waitcnt vmcnt(6)
	s_barrier
	v_mfma_f32_16x16x32_bf16 v[28:31], v[216:219], v[188:191], v[28:31]
	v_mfma_f32_16x16x32_bf16 v[24:27], v[224:227], v[188:191], v[24:27]
	v_mfma_f32_16x16x32_bf16 v[20:23], v[216:219], v[196:199], v[20:23]
	v_mfma_f32_16x16x32_bf16 v[16:19], v[224:227], v[196:199], v[16:19]
	v_mfma_f32_16x16x32_bf16 v[12:15], v[216:219], v[204:207], v[12:15]
	v_mfma_f32_16x16x32_bf16 v[8:11], v[224:227], v[204:207], v[8:11]
	v_mfma_f32_16x16x32_bf16 v[4:7], v[216:219], v[212:215], v[4:7]
	v_mfma_f32_16x16x32_bf16 v[0:3], v[224:227], v[212:215], v[0:3]
	v_mfma_f32_16x16x32_bf16 v[28:31], v[220:223], v[192:195], v[28:31]
	v_mfma_f32_16x16x32_bf16 v[24:27], v[228:231], v[192:195], v[24:27]
	v_mfma_f32_16x16x32_bf16 v[20:23], v[220:223], v[200:203], v[20:23]
	v_mfma_f32_16x16x32_bf16 v[16:19], v[228:231], v[200:203], v[16:19]
	v_mfma_f32_16x16x32_bf16 v[12:15], v[220:223], v[208:211], v[12:15]
	v_mfma_f32_16x16x32_bf16 v[8:11], v[228:231], v[208:211], v[8:11]
	v_mfma_f32_16x16x32_bf16 v[4:7], v[220:223], v[232:235], v[4:7]
	v_mfma_f32_16x16x32_bf16 v[0:3], v[228:231], v[232:235], v[0:3]
	s_barrier
	ds_read_b128 v[172:175], v156
	ds_read_b128 v[176:179], v156 offset:1024
	ds_read_b128 v[180:183], v156 offset:2048
	ds_read_b128 v[184:187], v156 offset:3072
	v_add_u32_e32 v167, 0x4000, v148
	v_add_u32_e32 v168, 0x6000, v148
	v_readfirstlane_b32 s45, v167
	v_lshl_add_u64 v[220:221], v[236:237], 0, s[22:23]
	s_mov_b32 m0, s45
	v_readfirstlane_b32 s45, v168
	ds_read_b128 v[188:191], v152 offset:32768
	ds_read_b128 v[192:195], v152 offset:33792
	ds_read_b128 v[196:199], v151 offset:32768
	ds_read_b128 v[200:203], v151 offset:33792
	ds_read_b128 v[204:207], v150 offset:32768
	ds_read_b128 v[208:211], v150 offset:33792
	ds_read_b128 v[212:215], v149 offset:32768
	ds_read_b128 v[216:219], v149 offset:33792
	global_load_lds_dwordx4 v[220:221], off
	v_lshl_add_u64 v[220:221], v[238:239], 0, s[22:23]
	s_mov_b32 m0, s45
	s_nop 0
	global_load_lds_dwordx4 v[220:221], off
	s_waitcnt lgkmcnt(8)
	s_barrier
	s_waitcnt lgkmcnt(0)
	s_waitcnt lgkmcnt(0)
	v_mfma_f32_16x16x32_bf16 v[124:127], v[172:175], v[188:191], v[124:127]
	v_mfma_f32_16x16x32_bf16 v[120:123], v[180:183], v[188:191], v[120:123]
	v_mfma_f32_16x16x32_bf16 v[116:119], v[172:175], v[196:199], v[116:119]
	v_mfma_f32_16x16x32_bf16 v[112:115], v[180:183], v[196:199], v[112:115]
	v_mfma_f32_16x16x32_bf16 v[108:111], v[172:175], v[204:207], v[108:111]
	v_mfma_f32_16x16x32_bf16 v[104:107], v[180:183], v[204:207], v[104:107]
	v_mfma_f32_16x16x32_bf16 v[100:103], v[172:175], v[212:215], v[100:103]
	v_mfma_f32_16x16x32_bf16 v[96:99], v[180:183], v[212:215], v[96:99]
	v_mfma_f32_16x16x32_bf16 v[124:127], v[176:179], v[192:195], v[124:127]
	v_mfma_f32_16x16x32_bf16 v[120:123], v[184:187], v[192:195], v[120:123]
	v_mfma_f32_16x16x32_bf16 v[116:119], v[176:179], v[200:203], v[116:119]
	v_mfma_f32_16x16x32_bf16 v[112:115], v[184:187], v[200:203], v[112:115]
	v_mfma_f32_16x16x32_bf16 v[108:111], v[176:179], v[208:211], v[108:111]
	v_mfma_f32_16x16x32_bf16 v[104:107], v[184:187], v[208:211], v[104:107]
	v_mfma_f32_16x16x32_bf16 v[100:103], v[176:179], v[216:219], v[100:103]
	v_mfma_f32_16x16x32_bf16 v[96:99], v[184:187], v[216:219], v[96:99]
	s_barrier
	v_readfirstlane_b32 s45, v155
	v_add_u32_e32 v171, 0x2000, v155
	v_lshl_add_u64 v[244:245], v[240:241], 0, s[24:25]
	s_mov_b32 m0, s45
	v_readfirstlane_b32 s45, v171
	ds_read_b128 v[220:223], v154
	ds_read_b128 v[224:227], v154 offset:1024
	ds_read_b128 v[228:231], v154 offset:2048
	ds_read_b128 v[232:235], v154 offset:3072
	global_load_lds_dwordx4 v[244:245], off
	v_lshl_add_u64 v[244:245], v[242:243], 0, s[24:25]
	s_mov_b32 m0, s45
	s_nop 0
	global_load_lds_dwordx4 v[244:245], off
	s_barrier
	s_waitcnt lgkmcnt(0)
	s_waitcnt lgkmcnt(0)
	v_mfma_f32_16x16x32_bf16 v[92:95], v[220:223], v[188:191], v[92:95]
	v_mfma_f32_16x16x32_bf16 v[88:91], v[228:231], v[188:191], v[88:91]
	v_mfma_f32_16x16x32_bf16 v[84:87], v[220:223], v[196:199], v[84:87]
	v_mfma_f32_16x16x32_bf16 v[80:83], v[228:231], v[196:199], v[80:83]
	v_mfma_f32_16x16x32_bf16 v[76:79], v[220:223], v[204:207], v[76:79]
	v_mfma_f32_16x16x32_bf16 v[72:75], v[228:231], v[204:207], v[72:75]
	v_mfma_f32_16x16x32_bf16 v[68:71], v[220:223], v[212:215], v[68:71]
	v_mfma_f32_16x16x32_bf16 v[64:67], v[228:231], v[212:215], v[64:67]
	v_mfma_f32_16x16x32_bf16 v[92:95], v[224:227], v[192:195], v[92:95]
	v_mfma_f32_16x16x32_bf16 v[88:91], v[232:235], v[192:195], v[88:91]
	v_mfma_f32_16x16x32_bf16 v[84:87], v[224:227], v[200:203], v[84:87]
	v_mfma_f32_16x16x32_bf16 v[80:83], v[232:235], v[200:203], v[80:83]
	v_mfma_f32_16x16x32_bf16 v[76:79], v[224:227], v[208:211], v[76:79]
	v_mfma_f32_16x16x32_bf16 v[72:75], v[232:235], v[208:211], v[72:75]
	v_mfma_f32_16x16x32_bf16 v[68:71], v[224:227], v[216:219], v[68:71]
	v_mfma_f32_16x16x32_bf16 v[64:67], v[232:235], v[216:219], v[64:67]
	s_barrier
	v_readfirstlane_b32 s45, v157
	v_lshl_add_u64 v[236:237], v[236:237], 0, s[26:27]
	s_mov_b32 m0, s45
	v_readfirstlane_b32 s45, v158
	ds_read_b128 v[188:191], v152 offset:49152
	ds_read_b128 v[192:195], v152 offset:50176
	ds_read_b128 v[196:199], v151 offset:49152
	ds_read_b128 v[200:203], v151 offset:50176
	ds_read_b128 v[204:207], v150 offset:49152
	ds_read_b128 v[208:211], v150 offset:50176
	ds_read_b128 v[212:215], v149 offset:49152
	ds_read_b128 v[216:219], v149 offset:50176
	global_load_lds_dwordx4 v[236:237], off
	v_lshl_add_u64 v[236:237], v[238:239], 0, s[26:27]
	s_mov_b32 m0, s45
	s_nop 0
	global_load_lds_dwordx4 v[236:237], off
	s_barrier
; #define STAGE(P, BASE, LD, br, kt) do { const char* _g = (const char*)((BASE) + (size_t)(br) * (LD) + (size_t)(kt) * 64); \
;     for (int _i = 0; _i < 2; ++_i) { int _b = tidx * 16 + _i * 8192; int _r, _c; stage_rc(_b, _r, _c); \
;       __builtin_amdgcn_global_load_lds((const unsigned*)(_g + (unsigned)((_r * (LD) + _c) * 2)), (unsigned*)((char*)(P) + _b), 16, 0, 0); } } while (0)
; #define LDA(dst, b, h) for (int m = 0; m < 4; ++m) for (int k = 0; k < 2; ++k) \
;     dst[m][k] = *reinterpret_cast<const bf16x8*>((char*)SA(b, h) + lds_byte(wr * 64 + m * 16 + fr, k * 32 + fq * 8))
; #define LDB(dst, b, h) for (int n = 0; n < 2; ++n) for (int k = 0; k < 2; ++k) \
;     dst[n][k] = *reinterpret_cast<const bf16x8*>((char*)SB(b, h) + lds_byte(wc * 32 + n * 16 + fr, k * 32 + fq * 8))
; #define MMA(ai, bj, At_, Bt_) do { __builtin_amdgcn_s_setprio(1); \
;     for (int k = 0; k < 2; ++k) for (int m = 0; m < 4; ++m) for (int n = 0; n < 2; ++n) \
;       acc[ai][bj][m][n] = __builtin_amdgcn_mfma_f32_16x16x32_bf16(At_[m][k], Bt_[n][k], acc[ai][bj][m][n], 0, 0, 0); \
;     __builtin_amdgcn_s_setprio(0); } while (0)
; #define WAIT_V(n) asm volatile("s_waitcnt vmcnt(" #n ")" ::: "memory")
; #define WAIT_L(n) asm volatile("s_waitcnt lgkmcnt(" #n ")" ::: "memory")
; #define BAR __builtin_amdgcn_s_barrier()
; #define SCHED __builtin_amdgcn_sched_barrier(0)
; template <int EPI, int lda, int ldb, int N, int K>
; __device__ __forceinline__ void gemm_phase(const u16* __restrict__ A, const u16* __restrict__ Bt, const GemmEpi ep, int wv) {
;     ...
;       BAR; WAIT_L(0); MMA(1, 0, At, B0); BAR; SCHED;
;       STAGE(SB(1, 1), Bt, ldb, bcol + HALF, t + 3);
;       WAIT_V(6); BAR; MMA(1, 1, At, B1); BAR;
;     }
;     { LDB(B0, 0, 0); LDA(At, 0, 0); STAGE(SA(1, 1), Ab, lda, brow + HALF, nt - 1);
;       BAR; WAIT_L(0); MMA(0, 0, At, B0); BAR;
;       LDB(B1, 0, 1); BAR; WAIT_L(0); MMA(0, 1, At, B1); BAR;
	s_waitcnt lgkmcnt(0)
	s_waitcnt lgkmcnt(0)
	v_mfma_f32_16x16x32_bf16 v[60:63], v[172:175], v[188:191], v[60:63]
	v_mfma_f32_16x16x32_bf16 v[56:59], v[180:183], v[188:191], v[56:59]
	v_mfma_f32_16x16x32_bf16 v[52:55], v[172:175], v[196:199], v[52:55]
	v_mfma_f32_16x16x32_bf16 v[48:51], v[180:183], v[196:199], v[48:51]
	v_mfma_f32_16x16x32_bf16 v[44:47], v[172:175], v[204:207], v[44:47]
	v_mfma_f32_16x16x32_bf16 v[40:43], v[180:183], v[204:207], v[40:43]
	v_mfma_f32_16x16x32_bf16 v[36:39], v[172:175], v[212:215], v[36:39]
	v_mfma_f32_16x16x32_bf16 v[32:35], v[180:183], v[212:215], v[32:35]
	v_mfma_f32_16x16x32_bf16 v[60:63], v[176:179], v[192:195], v[60:63]
	v_mfma_f32_16x16x32_bf16 v[56:59], v[184:187], v[192:195], v[56:59]
	v_mfma_f32_16x16x32_bf16 v[52:55], v[176:179], v[200:203], v[52:55]
	v_mfma_f32_16x16x32_bf16 v[48:51], v[184:187], v[200:203], v[48:51]
	v_mfma_f32_16x16x32_bf16 v[44:47], v[176:179], v[208:211], v[44:47]
	v_mfma_f32_16x16x32_bf16 v[40:43], v[184:187], v[208:211], v[40:43]
	v_mfma_f32_16x16x32_bf16 v[36:39], v[176:179], v[216:219], v[36:39]
	v_mfma_f32_16x16x32_bf16 v[32:35], v[184:187], v[216:219], v[32:35]
	s_barrier
	v_readfirstlane_b32 s45, v159
	v_add_u32_e32 v171, 0x2000, v159
	v_lshl_add_u64 v[172:173], v[240:241], 0, s[34:35]
	s_mov_b32 m0, s45
	v_readfirstlane_b32 s45, v171
	global_load_lds_dwordx4 v[172:173], off
	v_lshl_add_u64 v[172:173], v[242:243], 0, s[34:35]
	s_mov_b32 m0, s45
	s_nop 0
	global_load_lds_dwordx4 v[172:173], off
	s_waitcnt vmcnt(6)
	s_barrier
	v_mfma_f32_16x16x32_bf16 v[28:31], v[220:223], v[188:191], v[28:31]
	v_mfma_f32_16x16x32_bf16 v[24:27], v[228:231], v[188:191], v[24:27]
	v_mfma_f32_16x16x32_bf16 v[20:23], v[220:223], v[196:199], v[20:23]
	v_mfma_f32_16x16x32_bf16 v[16:19], v[228:231], v[196:199], v[16:19]
	v_mfma_f32_16x16x32_bf16 v[12:15], v[220:223], v[204:207], v[12:15]
	v_mfma_f32_16x16x32_bf16 v[8:11], v[228:231], v[204:207], v[8:11]
	v_mfma_f32_16x16x32_bf16 v[4:7], v[220:223], v[212:215], v[4:7]
	v_mfma_f32_16x16x32_bf16 v[0:3], v[228:231], v[212:215], v[0:3]
	v_mfma_f32_16x16x32_bf16 v[28:31], v[224:227], v[192:195], v[28:31]
	v_mfma_f32_16x16x32_bf16 v[24:27], v[232:235], v[192:195], v[24:27]
	v_mfma_f32_16x16x32_bf16 v[20:23], v[224:227], v[200:203], v[20:23]
	v_mfma_f32_16x16x32_bf16 v[16:19], v[232:235], v[200:203], v[16:19]
	v_mfma_f32_16x16x32_bf16 v[12:15], v[224:227], v[208:211], v[12:15]
	v_mfma_f32_16x16x32_bf16 v[8:11], v[232:235], v[208:211], v[8:11]
	v_mfma_f32_16x16x32_bf16 v[4:7], v[224:227], v[216:219], v[4:7]
	v_mfma_f32_16x16x32_bf16 v[0:3], v[232:235], v[216:219], v[0:3]
	s_barrier
	s_add_i32 s44, s44, 2
	s_add_u32 s42, s42, 0x100
	s_addc_u32 s43, s43, 0
	s_cmp_gt_u32 s44, 27
	s_cbranch_scc0 .LBB0_53
	s_add_i32 s42, s38, 0x80
	s_mul_hi_i32 s43, s42, 0x1080
	s_mulk_i32 s42, 0x1080
	s_add_u32 s42, s51, s42
	s_addc_u32 s43, s52, s43
	v_lshl_add_u64 v[158:159], s[42:43], 0, v[128:129]
	v_readfirstlane_b32 s44, v169
	v_lshl_add_u64 v[158:159], v[158:159], 0, s[36:37]
	s_mov_b32 m0, s44
	ds_read_b128 v[134:137], v161
	ds_read_b128 v[138:141], v161 offset:1024
	ds_read_b128 v[172:175], v161 offset:2048
	ds_read_b128 v[176:179], v161 offset:3072
	ds_read_b128 v[180:183], v152
	ds_read_b128 v[184:187], v152 offset:1024
	ds_read_b128 v[188:191], v151
	ds_read_b128 v[192:195], v151 offset:1024
	ds_read_b128 v[196:199], v150
	ds_read_b128 v[200:203], v150 offset:1024
	ds_read_b128 v[204:207], v149
	ds_read_b128 v[208:211], v149 offset:1024
	global_load_lds_dwordx4 v[158:159], off
	v_lshl_add_u64 v[158:159], s[42:43], 0, v[132:133]
	v_readfirstlane_b32 s42, v170
	v_lshl_add_u64 v[158:159], v[158:159], 0, s[36:37]
	s_mov_b32 m0, s42
	s_nop 0
	global_load_lds_dwordx4 v[158:159], off
	s_barrier
	s_waitcnt lgkmcnt(0)
	s_waitcnt lgkmcnt(0)
	v_mfma_f32_16x16x32_bf16 v[124:127], v[134:137], v[180:183], v[124:127]
	v_mfma_f32_16x16x32_bf16 v[120:123], v[172:175], v[180:183], v[120:123]
	v_mfma_f32_16x16x32_bf16 v[116:119], v[134:137], v[188:191], v[116:119]
	v_mfma_f32_16x16x32_bf16 v[112:115], v[172:175], v[188:191], v[112:115]
	v_mfma_f32_16x16x32_bf16 v[108:111], v[134:137], v[196:199], v[108:111]
	v_mfma_f32_16x16x32_bf16 v[104:107], v[172:175], v[196:199], v[104:107]
	v_mfma_f32_16x16x32_bf16 v[100:103], v[134:137], v[204:207], v[100:103]
	v_mfma_f32_16x16x32_bf16 v[96:99], v[172:175], v[204:207], v[96:99]
	v_mfma_f32_16x16x32_bf16 v[124:127], v[138:141], v[184:187], v[124:127]
	v_mfma_f32_16x16x32_bf16 v[120:123], v[176:179], v[184:187], v[120:123]
	v_mfma_f32_16x16x32_bf16 v[116:119], v[138:141], v[192:195], v[116:119]
	v_mfma_f32_16x16x32_bf16 v[112:115], v[176:179], v[192:195], v[112:115]
	v_mfma_f32_16x16x32_bf16 v[108:111], v[138:141], v[200:203], v[108:111]
	v_mfma_f32_16x16x32_bf16 v[104:107], v[176:179], v[200:203], v[104:107]
	v_mfma_f32_16x16x32_bf16 v[100:103], v[138:141], v[208:211], v[100:103]
	v_mfma_f32_16x16x32_bf16 v[96:99], v[176:179], v[208:211], v[96:99]
	s_barrier
	ds_read_b128 v[212:215], v160
	ds_read_b128 v[216:219], v160 offset:1024
	ds_read_b128 v[220:223], v160 offset:2048
	ds_read_b128 v[158:161], v160 offset:3072
	s_barrier
; #define LDA(dst, b, h) for (int m = 0; m < 4; ++m) for (int k = 0; k < 2; ++k) \
;     dst[m][k] = *reinterpret_cast<const bf16x8*>((char*)SA(b, h) + lds_byte(wr * 64 + m * 16 + fr, k * 32 + fq * 8))
; #define LDB(dst, b, h) for (int n = 0; n < 2; ++n) for (int k = 0; k < 2; ++k) \
;     dst[n][k] = *reinterpret_cast<const bf16x8*>((char*)SB(b, h) + lds_byte(wc * 32 + n * 16 + fr, k * 32 + fq * 8))
; #define MMA(ai, bj, At_, Bt_) do { __builtin_amdgcn_s_setprio(1); \
;     for (int k = 0; k < 2; ++k) for (int m = 0; m < 4; ++m) for (int n = 0; n < 2; ++n) \
;       acc[ai][bj][m][n] = __builtin_amdgcn_mfma_f32_16x16x32_bf16(At_[m][k], Bt_[n][k], acc[ai][bj][m][n], 0, 0, 0); \
;     __builtin_amdgcn_s_setprio(0); } while (0)
; #define WAIT_V(n) asm volatile("s_waitcnt vmcnt(" #n ")" ::: "memory")
; #define WAIT_L(n) asm volatile("s_waitcnt lgkmcnt(" #n ")" ::: "memory")
; #define BAR __builtin_amdgcn_s_barrier()
; template <int EPI, int lda, int ldb, int N, int K>
; __device__ __forceinline__ void gemm_phase(const u16* __restrict__ A, const u16* __restrict__ Bt, const GemmEpi ep, int wv) {
;     ...
;       LDB(B1, 0, 1); BAR; WAIT_L(0); MMA(0, 1, At, B1); BAR;
;       LDA(At, 0, 1); WAIT_V(4); BAR; WAIT_L(0); MMA(1, 0, At, B0); MMA(1, 1, At, B1); BAR; }
;     { LDB(B0, 1, 0); LDA(At, 1, 0); WAIT_V(2); BAR; WAIT_L(0); MMA(0, 0, At, B0); BAR;
	s_waitcnt lgkmcnt(0)
	s_waitcnt lgkmcnt(0)
	v_mfma_f32_16x16x32_bf16 v[92:95], v[212:215], v[180:183], v[92:95]
	v_mfma_f32_16x16x32_bf16 v[88:91], v[220:223], v[180:183], v[88:91]
	v_mfma_f32_16x16x32_bf16 v[76:79], v[212:215], v[196:199], v[76:79]
	v_mfma_f32_16x16x32_bf16 v[72:75], v[220:223], v[196:199], v[72:75]
	v_mfma_f32_16x16x32_bf16 v[84:87], v[212:215], v[188:191], v[84:87]
	v_mfma_f32_16x16x32_bf16 v[80:83], v[220:223], v[188:191], v[80:83]
	v_mfma_f32_16x16x32_bf16 v[68:71], v[212:215], v[204:207], v[68:71]
	v_mfma_f32_16x16x32_bf16 v[64:67], v[220:223], v[204:207], v[64:67]
	v_mfma_f32_16x16x32_bf16 v[92:95], v[216:219], v[184:187], v[92:95]
	v_mfma_f32_16x16x32_bf16 v[88:91], v[158:161], v[184:187], v[88:91]
	v_mfma_f32_16x16x32_bf16 v[76:79], v[216:219], v[200:203], v[76:79]
	v_mfma_f32_16x16x32_bf16 v[72:75], v[158:161], v[200:203], v[72:75]
	v_mfma_f32_16x16x32_bf16 v[180:183], v[216:219], v[192:195], v[84:87]
	v_mfma_f32_16x16x32_bf16 v[184:187], v[158:161], v[192:195], v[80:83]
	v_mfma_f32_16x16x32_bf16 v[188:191], v[216:219], v[208:211], v[68:71]
	v_mfma_f32_16x16x32_bf16 v[192:195], v[158:161], v[208:211], v[64:67]
	s_barrier
	s_nop 0
	ds_read_b128 v[64:67], v152 offset:16384
	ds_read_b128 v[68:71], v152 offset:17408
	ds_read_b128 v[80:83], v151 offset:16384
	ds_read_b128 v[84:87], v151 offset:17408
	ds_read_b128 v[196:199], v150 offset:16384
	ds_read_b128 v[200:203], v150 offset:17408
	ds_read_b128 v[204:207], v149 offset:16384
	ds_read_b128 v[208:211], v149 offset:17408
	s_waitcnt vmcnt(4)
	s_barrier
	s_waitcnt lgkmcnt(0)
	s_waitcnt lgkmcnt(0)
	v_mfma_f32_16x16x32_bf16 v[60:63], v[134:137], v[64:67], v[60:63]
	v_mfma_f32_16x16x32_bf16 v[56:59], v[172:175], v[64:67], v[56:59]
	v_mfma_f32_16x16x32_bf16 v[52:55], v[134:137], v[80:83], v[52:55]
	v_mfma_f32_16x16x32_bf16 v[48:51], v[172:175], v[80:83], v[48:51]
	v_mfma_f32_16x16x32_bf16 v[44:47], v[134:137], v[196:199], v[44:47]
	v_mfma_f32_16x16x32_bf16 v[40:43], v[172:175], v[196:199], v[40:43]
	v_mfma_f32_16x16x32_bf16 v[36:39], v[134:137], v[204:207], v[36:39]
	v_mfma_f32_16x16x32_bf16 v[32:35], v[172:175], v[204:207], v[32:35]
	v_mfma_f32_16x16x32_bf16 v[60:63], v[138:141], v[68:71], v[60:63]
	v_mfma_f32_16x16x32_bf16 v[56:59], v[176:179], v[68:71], v[56:59]
	v_mfma_f32_16x16x32_bf16 v[52:55], v[138:141], v[84:87], v[52:55]
	v_mfma_f32_16x16x32_bf16 v[48:51], v[176:179], v[84:87], v[48:51]
	v_mfma_f32_16x16x32_bf16 v[44:47], v[138:141], v[200:203], v[44:47]
	v_mfma_f32_16x16x32_bf16 v[40:43], v[176:179], v[200:203], v[40:43]
	v_mfma_f32_16x16x32_bf16 v[36:39], v[138:141], v[208:211], v[36:39]
	v_mfma_f32_16x16x32_bf16 v[32:35], v[176:179], v[208:211], v[32:35]
	v_mfma_f32_16x16x32_bf16 v[28:31], v[212:215], v[64:67], v[28:31]
	v_mfma_f32_16x16x32_bf16 v[24:27], v[220:223], v[64:67], v[24:27]
	v_mfma_f32_16x16x32_bf16 v[12:15], v[212:215], v[196:199], v[12:15]
	v_mfma_f32_16x16x32_bf16 v[8:11], v[220:223], v[196:199], v[8:11]
	v_mfma_f32_16x16x32_bf16 v[20:23], v[212:215], v[80:83], v[20:23]
	v_mfma_f32_16x16x32_bf16 v[16:19], v[220:223], v[80:83], v[16:19]
	v_mfma_f32_16x16x32_bf16 v[4:7], v[212:215], v[204:207], v[4:7]
	v_mfma_f32_16x16x32_bf16 v[0:3], v[220:223], v[204:207], v[0:3]
	v_mfma_f32_16x16x32_bf16 v[28:31], v[216:219], v[68:71], v[28:31]
	v_mfma_f32_16x16x32_bf16 v[24:27], v[158:161], v[68:71], v[24:27]
	v_mfma_f32_16x16x32_bf16 v[12:15], v[216:219], v[200:203], v[12:15]
	v_mfma_f32_16x16x32_bf16 v[8:11], v[158:161], v[200:203], v[8:11]
	v_mfma_f32_16x16x32_bf16 v[134:137], v[216:219], v[84:87], v[20:23]
	v_mfma_f32_16x16x32_bf16 v[138:141], v[158:161], v[84:87], v[16:19]
	v_mfma_f32_16x16x32_bf16 v[170:173], v[216:219], v[208:211], v[4:7]
	v_mfma_f32_16x16x32_bf16 v[158:161], v[158:161], v[208:211], v[0:3]
	s_barrier
	s_nop 0
	ds_read_b128 v[0:3], v156
	ds_read_b128 v[4:7], v156 offset:1024
	ds_read_b128 v[16:19], v156 offset:2048
	ds_read_b128 v[174:177], v156 offset:3072
	ds_read_b128 v[20:23], v152 offset:32768
	ds_read_b128 v[196:199], v152 offset:33792
	ds_read_b128 v[200:203], v151 offset:32768
	ds_read_b128 v[204:207], v151 offset:33792
	ds_read_b128 v[208:211], v150 offset:32768
	ds_read_b128 v[212:215], v150 offset:33792
	ds_read_b128 v[216:219], v149 offset:32768
	ds_read_b128 v[220:223], v149 offset:33792
	s_waitcnt vmcnt(2)
	s_barrier
; #define LDA(dst, b, h) for (int m = 0; m < 4; ++m) for (int k = 0; k < 2; ++k) \
;     dst[m][k] = *reinterpret_cast<const bf16x8*>((char*)SA(b, h) + lds_byte(wr * 64 + m * 16 + fr, k * 32 + fq * 8))
; #define LDB(dst, b, h) for (int n = 0; n < 2; ++n) for (int k = 0; k < 2; ++k) \
;     dst[n][k] = *reinterpret_cast<const bf16x8*>((char*)SB(b, h) + lds_byte(wc * 32 + n * 16 + fr, k * 32 + fq * 8))
; #define MMA(ai, bj, At_, Bt_) do { __builtin_amdgcn_s_setprio(1); \
;     for (int k = 0; k < 2; ++k) for (int m = 0; m < 4; ++m) for (int n = 0; n < 2; ++n) \
;       acc[ai][bj][m][n] = __builtin_amdgcn_mfma_f32_16x16x32_bf16(At_[m][k], Bt_[n][k], acc[ai][bj][m][n], 0, 0, 0); \
;     __builtin_amdgcn_s_setprio(0); } while (0)
; #define WAIT_V(n) asm volatile("s_waitcnt vmcnt(" #n ")" ::: "memory")
; #define WAIT_L(n) asm volatile("s_waitcnt lgkmcnt(" #n ")" ::: "memory")
; #define BAR __builtin_amdgcn_s_barrier()
; template <int EPI, int lda, int ldb, int N, int K>
; __device__ __forceinline__ void gemm_phase(const u16* __restrict__ A, const u16* __restrict__ Bt, const GemmEpi ep, int wv) {
;     ...
;     { LDB(B0, 1, 0); LDA(At, 1, 0); WAIT_V(2); BAR; WAIT_L(0); MMA(0, 0, At, B0); BAR;
;       LDB(B1, 1, 1); WAIT_V(0); BAR; WAIT_L(0); MMA(0, 1, At, B1); BAR;
;       LDA(At, 1, 1); BAR; WAIT_L(0); MMA(1, 0, At, B0); MMA(1, 1, At, B1); BAR; }
;     if (wr == 0) BAR;
	s_waitcnt lgkmcnt(0)
	s_waitcnt lgkmcnt(0)
	v_mfma_f32_16x16x32_bf16 v[64:67], v[0:3], v[20:23], v[124:127]
	v_mfma_f32_16x16x32_bf16 v[68:71], v[16:19], v[20:23], v[120:123]
	v_mfma_f32_16x16x32_bf16 v[80:83], v[0:3], v[200:203], v[116:119]
	v_mfma_f32_16x16x32_bf16 v[84:87], v[16:19], v[200:203], v[112:115]
	v_mfma_f32_16x16x32_bf16 v[108:111], v[0:3], v[208:211], v[108:111]
	v_mfma_f32_16x16x32_bf16 v[104:107], v[16:19], v[208:211], v[104:107]
	v_mfma_f32_16x16x32_bf16 v[120:123], v[0:3], v[216:219], v[100:103]
	v_mfma_f32_16x16x32_bf16 v[124:127], v[16:19], v[216:219], v[96:99]
	v_mfma_f32_16x16x32_bf16 v[116:119], v[4:7], v[196:199], v[64:67]
	v_mfma_f32_16x16x32_bf16 v[112:115], v[174:177], v[196:199], v[68:71]
	v_mfma_f32_16x16x32_bf16 v[100:103], v[4:7], v[204:207], v[80:83]
	v_mfma_f32_16x16x32_bf16 v[96:99], v[174:177], v[204:207], v[84:87]
	v_mfma_f32_16x16x32_bf16 v[84:87], v[4:7], v[212:215], v[108:111]
	v_mfma_f32_16x16x32_bf16 v[80:83], v[174:177], v[212:215], v[104:107]
	v_mfma_f32_16x16x32_bf16 v[68:71], v[4:7], v[220:223], v[120:123]
	v_mfma_f32_16x16x32_bf16 v[64:67], v[174:177], v[220:223], v[124:127]
	s_barrier
	ds_read_b128 v[224:227], v154
	ds_read_b128 v[228:231], v154 offset:1024
	ds_read_b128 v[232:235], v154 offset:2048
	ds_read_b128 v[154:157], v154 offset:3072
	s_waitcnt vmcnt(0)
	s_barrier
	s_waitcnt lgkmcnt(0)
	s_waitcnt lgkmcnt(0)
	v_mfma_f32_16x16x32_bf16 v[92:95], v[224:227], v[20:23], v[92:95]
	v_mfma_f32_16x16x32_bf16 v[20:23], v[232:235], v[20:23], v[88:91]
	v_mfma_f32_16x16x32_bf16 v[88:91], v[224:227], v[200:203], v[180:183]
	v_mfma_f32_16x16x32_bf16 v[104:107], v[232:235], v[200:203], v[184:187]
	v_mfma_f32_16x16x32_bf16 v[76:79], v[224:227], v[208:211], v[76:79]
	v_mfma_f32_16x16x32_bf16 v[72:75], v[232:235], v[208:211], v[72:75]
	v_mfma_f32_16x16x32_bf16 v[178:181], v[224:227], v[216:219], v[188:191]
	v_mfma_f32_16x16x32_bf16 v[182:185], v[232:235], v[216:219], v[192:195]
	v_mfma_f32_16x16x32_bf16 v[124:127], v[228:231], v[196:199], v[92:95]
	v_mfma_f32_16x16x32_bf16 v[120:123], v[154:157], v[196:199], v[20:23]
	v_mfma_f32_16x16x32_bf16 v[108:111], v[228:231], v[204:207], v[88:91]
	v_mfma_f32_16x16x32_bf16 v[104:107], v[154:157], v[204:207], v[104:107]
	v_mfma_f32_16x16x32_bf16 v[92:95], v[228:231], v[212:215], v[76:79]
	v_mfma_f32_16x16x32_bf16 v[88:91], v[154:157], v[212:215], v[72:75]
	v_mfma_f32_16x16x32_bf16 v[76:79], v[228:231], v[220:223], v[178:181]
	v_mfma_f32_16x16x32_bf16 v[72:75], v[154:157], v[220:223], v[182:185]
	s_barrier
	ds_read_b128 v[178:181], v152 offset:49152
	ds_read_b128 v[182:185], v152 offset:50176
	ds_read_b128 v[186:189], v151 offset:49152
	ds_read_b128 v[190:193], v151 offset:50176
	ds_read_b128 v[194:197], v150 offset:49152
	ds_read_b128 v[150:153], v150 offset:50176
	ds_read_b128 v[198:201], v149 offset:49152
	ds_read_b128 v[202:205], v149 offset:50176
	s_barrier
	s_waitcnt lgkmcnt(0)
	s_waitcnt lgkmcnt(0)
	v_mfma_f32_16x16x32_bf16 v[20:23], v[0:3], v[178:181], v[60:63]
	v_mfma_f32_16x16x32_bf16 v[56:59], v[16:19], v[178:181], v[56:59]
	v_mfma_f32_16x16x32_bf16 v[60:63], v[0:3], v[186:189], v[52:55]
	v_mfma_f32_16x16x32_bf16 v[206:209], v[16:19], v[186:189], v[48:51]
	v_mfma_f32_16x16x32_bf16 v[44:47], v[0:3], v[194:197], v[44:47]
	v_mfma_f32_16x16x32_bf16 v[40:43], v[16:19], v[194:197], v[40:43]
	v_mfma_f32_16x16x32_bf16 v[0:3], v[0:3], v[198:201], v[36:39]
	v_mfma_f32_16x16x32_bf16 v[210:213], v[16:19], v[198:201], v[32:35]
	v_mfma_f32_16x16x32_bf16 v[52:55], v[4:7], v[182:185], v[20:23]
	v_mfma_f32_16x16x32_bf16 v[48:51], v[174:177], v[182:185], v[56:59]
	v_mfma_f32_16x16x32_bf16 v[36:39], v[4:7], v[190:193], v[60:63]
	v_mfma_f32_16x16x32_bf16 v[32:35], v[174:177], v[190:193], v[206:209]
	v_mfma_f32_16x16x32_bf16 v[20:23], v[4:7], v[150:153], v[44:47]
	v_mfma_f32_16x16x32_bf16 v[16:19], v[174:177], v[150:153], v[40:43]
	v_mfma_f32_16x16x32_bf16 v[4:7], v[4:7], v[202:205], v[0:3]
	v_mfma_f32_16x16x32_bf16 v[0:3], v[174:177], v[202:205], v[210:213]
	v_mfma_f32_16x16x32_bf16 v[28:31], v[224:227], v[178:181], v[28:31]
	v_mfma_f32_16x16x32_bf16 v[24:27], v[232:235], v[178:181], v[24:27]
	v_mfma_f32_16x16x32_bf16 v[40:43], v[224:227], v[186:189], v[134:137]
	v_mfma_f32_16x16x32_bf16 v[134:137], v[232:235], v[186:189], v[138:141]
	v_mfma_f32_16x16x32_bf16 v[12:15], v[224:227], v[194:197], v[12:15]
	v_mfma_f32_16x16x32_bf16 v[8:11], v[232:235], v[194:197], v[8:11]
	v_mfma_f32_16x16x32_bf16 v[138:141], v[224:227], v[198:201], v[170:173]
	v_mfma_f32_16x16x32_bf16 v[158:161], v[232:235], v[198:201], v[158:161]
	v_mfma_f32_16x16x32_bf16 v[60:63], v[228:231], v[182:185], v[28:31]
	v_mfma_f32_16x16x32_bf16 v[56:59], v[154:157], v[182:185], v[24:27]
	v_mfma_f32_16x16x32_bf16 v[44:47], v[228:231], v[190:193], v[40:43]
	v_mfma_f32_16x16x32_bf16 v[40:43], v[154:157], v[190:193], v[134:137]
	v_mfma_f32_16x16x32_bf16 v[28:31], v[228:231], v[150:153], v[12:15]
	v_mfma_f32_16x16x32_bf16 v[24:27], v[154:157], v[150:153], v[8:11]
	v_mfma_f32_16x16x32_bf16 v[12:15], v[228:231], v[202:205], v[138:141]
	v_mfma_f32_16x16x32_bf16 v[8:11], v[154:157], v[202:205], v[158:161]
	v_cmp_gt_u32_e32 vcc, s56, v130
	s_barrier
	s_and_saveexec_b64 s[42:43], vcc
	s_cbranch_execz .LBB0_56
	s_barrier

; #define STAGE(P, BASE, LD, br, kt) do { const char* _g = (const char*)((BASE) + (size_t)(br) * (LD) + (size_t)(kt) * 64); \
;     for (int _i = 0; _i < 2; ++_i) { int _b = tidx * 16 + _i * 8192; int _r, _c; stage_rc(_b, _r, _c); \
;       __builtin_amdgcn_global_load_lds((const unsigned*)(_g + (unsigned)((_r * (LD) + _c) * 2)), (unsigned*)((char*)(P) + _b), 16, 0, 0); } } while (0)
; #define LDA(dst, b, h) for (int m = 0; m < 4; ++m) for (int k = 0; k < 2; ++k) \
;     dst[m][k] = *reinterpret_cast<const bf16x8*>((char*)SA(b, h) + lds_byte(wr * 64 + m * 16 + fr, k * 32 + fq * 8))
; #define LDB(dst, b, h) for (int n = 0; n < 2; ++n) for (int k = 0; k < 2; ++k) \
;     dst[n][k] = *reinterpret_cast<const bf16x8*>((char*)SB(b, h) + lds_byte(wc * 32 + n * 16 + fr, k * 32 + fq * 8))
; #define MMA(ai, bj, At_, Bt_) do { __builtin_amdgcn_s_setprio(1); \
;     for (int k = 0; k < 2; ++k) for (int m = 0; m < 4; ++m) for (int n = 0; n < 2; ++n) \
;       acc[ai][bj][m][n] = __builtin_amdgcn_mfma_f32_16x16x32_bf16(At_[m][k], Bt_[n][k], acc[ai][bj][m][n], 0, 0, 0); \
;     __builtin_amdgcn_s_setprio(0); } while (0)
; #define WAIT_L(n) asm volatile("s_waitcnt lgkmcnt(" #n ")" ::: "memory")
; #define BAR __builtin_amdgcn_s_barrier()
; #define SCHED __builtin_amdgcn_sched_barrier(0)
; template <int EPI, int lda, int ldb, int N, int K>
; __device__ __forceinline__ void gemm_phase(const u16* __restrict__ A, const u16* __restrict__ Bt, const GemmEpi ep, int wv) {
;     ...
;     for (int t = 0; t < nt - 2; t += 2) {
;       LDB(B0, 0, 0); SCHED; LDA(At, 0, 0); STAGE(SA(1, 1), Ab, lda, brow + HALF, t + 1);
;       WAIT_L(8); BAR; WAIT_L(0); MMA(0, 0, At, B0); BAR; SCHED;
;       LDB(B1, 0, 1); STAGE(SB(0, 0), Bt, ldb, bcol, t + 2);
;       BAR; WAIT_L(0); MMA(0, 1, At, B1); BAR;
;       LDA(At, 0, 1); STAGE(SA(0, 0), Ab, lda, brow, t + 2);
;       BAR; WAIT_L(0); MMA(1, 0, At, B0); BAR; SCHED;
.LBB0_224:
	ds_read_b128 v[168:171], v164
	ds_read_b128 v[174:177], v164 offset:1024
	ds_read_b128 v[178:181], v164 offset:2048
	ds_read_b128 v[182:185], v164 offset:3072
	v_add_u32_e32 v172, 0xc000, v147
	v_lshl_add_u64 v[238:239], v[136:137], 0, s[44:45]
	v_readfirstlane_b32 s66, v172
	v_add_u32_e32 v173, 0xe000, v147
	v_lshl_add_u64 v[166:167], v[238:239], 0, s[18:19]
	s_mov_b32 m0, s66
	v_lshl_add_u64 v[240:241], v[134:135], 0, s[44:45]
	v_readfirstlane_b32 s66, v173
	ds_read_b128 v[186:189], v155
	ds_read_b128 v[190:193], v155 offset:1024
	ds_read_b128 v[194:197], v154
	ds_read_b128 v[198:201], v154 offset:1024
	ds_read_b128 v[202:205], v153
	ds_read_b128 v[206:209], v153 offset:1024
	ds_read_b128 v[210:213], v152
	ds_read_b128 v[214:217], v152 offset:1024
	global_load_lds_dwordx4 v[166:167], off
	v_lshl_add_u64 v[166:167], v[240:241], 0, s[18:19]
	s_mov_b32 m0, s66
	s_nop 0
	global_load_lds_dwordx4 v[166:167], off
	s_waitcnt lgkmcnt(8)
	s_barrier
	s_waitcnt lgkmcnt(0)
	s_waitcnt lgkmcnt(0)
	v_mfma_f32_16x16x32_bf16 v[124:127], v[168:171], v[186:189], v[124:127]
	v_mfma_f32_16x16x32_bf16 v[120:123], v[178:181], v[186:189], v[120:123]
	v_mfma_f32_16x16x32_bf16 v[116:119], v[168:171], v[194:197], v[116:119]
	v_mfma_f32_16x16x32_bf16 v[112:115], v[178:181], v[194:197], v[112:115]
	v_mfma_f32_16x16x32_bf16 v[108:111], v[168:171], v[202:205], v[108:111]
	v_mfma_f32_16x16x32_bf16 v[104:107], v[178:181], v[202:205], v[104:107]
	v_mfma_f32_16x16x32_bf16 v[100:103], v[168:171], v[210:213], v[100:103]
	v_mfma_f32_16x16x32_bf16 v[96:99], v[178:181], v[210:213], v[96:99]
	v_mfma_f32_16x16x32_bf16 v[124:127], v[174:177], v[190:193], v[124:127]
	v_mfma_f32_16x16x32_bf16 v[120:123], v[182:185], v[190:193], v[120:123]
	v_mfma_f32_16x16x32_bf16 v[116:119], v[174:177], v[198:201], v[116:119]
	v_mfma_f32_16x16x32_bf16 v[112:115], v[182:185], v[198:201], v[112:115]
	v_mfma_f32_16x16x32_bf16 v[108:111], v[174:177], v[206:209], v[108:111]
	v_mfma_f32_16x16x32_bf16 v[104:107], v[182:185], v[206:209], v[104:107]
	v_mfma_f32_16x16x32_bf16 v[100:103], v[174:177], v[214:217], v[100:103]
	v_mfma_f32_16x16x32_bf16 v[96:99], v[182:185], v[214:217], v[96:99]
	s_barrier
	v_add_u32_e32 v165, s55, v156
	v_lshl_add_u64 v[242:243], v[144:145], 0, s[44:45]
	v_readfirstlane_b32 s66, v165
	v_lshl_add_u64 v[166:167], v[242:243], 0, s[20:21]
	s_mov_b32 m0, s66
	ds_read_b128 v[218:221], v163
	ds_read_b128 v[222:225], v163 offset:1024
	ds_read_b128 v[226:229], v163 offset:2048
	ds_read_b128 v[230:233], v163 offset:3072
	global_load_lds_dwordx4 v[166:167], off
	v_add_u32_e32 v166, 0x2000, v165
	v_lshl_add_u64 v[244:245], v[142:143], 0, s[44:45]
	v_readfirstlane_b32 s66, v166
	v_lshl_add_u64 v[234:235], v[244:245], 0, s[20:21]
	s_mov_b32 m0, s66
	s_nop 0
	global_load_lds_dwordx4 v[234:235], off
	s_barrier
	s_waitcnt lgkmcnt(0)
	s_waitcnt lgkmcnt(0)
	v_mfma_f32_16x16x32_bf16 v[92:95], v[218:221], v[186:189], v[92:95]
	v_mfma_f32_16x16x32_bf16 v[88:91], v[226:229], v[186:189], v[88:91]
	v_mfma_f32_16x16x32_bf16 v[84:87], v[218:221], v[194:197], v[84:87]
	v_mfma_f32_16x16x32_bf16 v[80:83], v[226:229], v[194:197], v[80:83]
	v_mfma_f32_16x16x32_bf16 v[76:79], v[218:221], v[202:205], v[76:79]
	v_mfma_f32_16x16x32_bf16 v[72:75], v[226:229], v[202:205], v[72:75]
	v_mfma_f32_16x16x32_bf16 v[68:71], v[218:221], v[210:213], v[68:71]
	v_mfma_f32_16x16x32_bf16 v[64:67], v[226:229], v[210:213], v[64:67]
	v_mfma_f32_16x16x32_bf16 v[92:95], v[222:225], v[190:193], v[92:95]
	v_mfma_f32_16x16x32_bf16 v[88:91], v[230:233], v[190:193], v[88:91]
	v_mfma_f32_16x16x32_bf16 v[84:87], v[222:225], v[198:201], v[84:87]
	v_mfma_f32_16x16x32_bf16 v[80:83], v[230:233], v[198:201], v[80:83]
	v_mfma_f32_16x16x32_bf16 v[76:79], v[222:225], v[206:209], v[76:79]
	v_mfma_f32_16x16x32_bf16 v[72:75], v[230:233], v[206:209], v[72:75]
	v_mfma_f32_16x16x32_bf16 v[68:71], v[222:225], v[214:217], v[68:71]
	v_mfma_f32_16x16x32_bf16 v[64:67], v[230:233], v[214:217], v[64:67]
	s_barrier
	v_readfirstlane_b32 s66, v147
	v_add_u32_e32 v167, 0x2000, v147
	v_lshl_add_u64 v[234:235], v[238:239], 0, s[22:23]
	s_mov_b32 m0, s66
	v_readfirstlane_b32 s66, v167
	ds_read_b128 v[186:189], v155 offset:16384
	ds_read_b128 v[190:193], v155 offset:17408
	ds_read_b128 v[194:197], v154 offset:16384
	ds_read_b128 v[198:201], v154 offset:17408
	ds_read_b128 v[202:205], v153 offset:16384
	ds_read_b128 v[206:209], v153 offset:17408
	ds_read_b128 v[210:213], v152 offset:16384
	ds_read_b128 v[214:217], v152 offset:17408
	global_load_lds_dwordx4 v[234:235], off
	v_lshl_add_u64 v[234:235], v[240:241], 0, s[22:23]
	s_mov_b32 m0, s66
	s_nop 0
	global_load_lds_dwordx4 v[234:235], off
	s_barrier
	s_waitcnt lgkmcnt(0)
	s_waitcnt lgkmcnt(0)
	v_mfma_f32_16x16x32_bf16 v[60:63], v[168:171], v[186:189], v[60:63]
	v_mfma_f32_16x16x32_bf16 v[56:59], v[178:181], v[186:189], v[56:59]
	v_mfma_f32_16x16x32_bf16 v[52:55], v[168:171], v[194:197], v[52:55]
	v_mfma_f32_16x16x32_bf16 v[48:51], v[178:181], v[194:197], v[48:51]
	v_mfma_f32_16x16x32_bf16 v[44:47], v[168:171], v[202:205], v[44:47]
	v_mfma_f32_16x16x32_bf16 v[40:43], v[178:181], v[202:205], v[40:43]
	v_mfma_f32_16x16x32_bf16 v[36:39], v[168:171], v[210:213], v[36:39]
	v_mfma_f32_16x16x32_bf16 v[32:35], v[178:181], v[210:213], v[32:35]
	v_mfma_f32_16x16x32_bf16 v[60:63], v[174:177], v[190:193], v[60:63]
	v_mfma_f32_16x16x32_bf16 v[56:59], v[182:185], v[190:193], v[56:59]
	v_mfma_f32_16x16x32_bf16 v[52:55], v[174:177], v[198:201], v[52:55]
	v_mfma_f32_16x16x32_bf16 v[48:51], v[182:185], v[198:201], v[48:51]
	v_mfma_f32_16x16x32_bf16 v[44:47], v[174:177], v[206:209], v[44:47]
	v_mfma_f32_16x16x32_bf16 v[40:43], v[182:185], v[206:209], v[40:43]
	v_mfma_f32_16x16x32_bf16 v[36:39], v[174:177], v[214:217], v[36:39]
	v_mfma_f32_16x16x32_bf16 v[32:35], v[182:185], v[214:217], v[32:35]
	s_barrier
; #define STAGE(P, BASE, LD, br, kt) do { const char* _g = (const char*)((BASE) + (size_t)(br) * (LD) + (size_t)(kt) * 64); \
;     for (int _i = 0; _i < 2; ++_i) { int _b = tidx * 16 + _i * 8192; int _r, _c; stage_rc(_b, _r, _c); \
;       __builtin_amdgcn_global_load_lds((const unsigned*)(_g + (unsigned)((_r * (LD) + _c) * 2)), (unsigned*)((char*)(P) + _b), 16, 0, 0); } } while (0)
; #define LDA(dst, b, h) for (int m = 0; m < 4; ++m) for (int k = 0; k < 2; ++k) \
;     dst[m][k] = *reinterpret_cast<const bf16x8*>((char*)SA(b, h) + lds_byte(wr * 64 + m * 16 + fr, k * 32 + fq * 8))
; #define LDB(dst, b, h) for (int n = 0; n < 2; ++n) for (int k = 0; k < 2; ++k) \
;     dst[n][k] = *reinterpret_cast<const bf16x8*>((char*)SB(b, h) + lds_byte(wc * 32 + n * 16 + fr, k * 32 + fq * 8))
; #define MMA(ai, bj, At_, Bt_) do { __builtin_amdgcn_s_setprio(1); \
;     for (int k = 0; k < 2; ++k) for (int m = 0; m < 4; ++m) for (int n = 0; n < 2; ++n) \
;       acc[ai][bj][m][n] = __builtin_amdgcn_mfma_f32_16x16x32_bf16(At_[m][k], Bt_[n][k], acc[ai][bj][m][n], 0, 0, 0); \
;     __builtin_amdgcn_s_setprio(0); } while (0)
; #define WAIT_V(n) asm volatile("s_waitcnt vmcnt(" #n ")" ::: "memory")
; #define WAIT_L(n) asm volatile("s_waitcnt lgkmcnt(" #n ")" ::: "memory")
; #define BAR __builtin_amdgcn_s_barrier()
; #define SCHED __builtin_amdgcn_sched_barrier(0)
; template <int EPI, int lda, int ldb, int N, int K>
; __device__ __forceinline__ void gemm_phase(const u16* __restrict__ A, const u16* __restrict__ Bt, const GemmEpi ep, int wv) {
;     ...
;       STAGE(SB(0, 1), Bt, ldb, bcol + HALF, t + 2);
;       WAIT_V(6); BAR; MMA(1, 1, At, B1); BAR;
;       LDB(B0, 1, 0); SCHED; LDA(At, 1, 0); STAGE(SA(0, 1), Ab, lda, brow + HALF, t + 2);
;       WAIT_L(8); BAR; WAIT_L(0); MMA(0, 0, At, B0); BAR; SCHED;
;       LDB(B1, 1, 1); STAGE(SB(1, 0), Bt, ldb, bcol, t + 3);
;       BAR; WAIT_L(0); MMA(0, 1, At, B1); BAR;
;       LDA(At, 1, 1); STAGE(SA(1, 0), Ab, lda, brow, t + 3);
	v_add_u32_e32 v168, s56, v156
	v_lshl_add_u64 v[246:247], v[140:141], 0, s[44:45]
	v_readfirstlane_b32 s66, v168
	v_add_u32_e32 v169, 0x2000, v168
	v_lshl_add_u64 v[170:171], v[246:247], 0, s[24:25]
	s_mov_b32 m0, s66
	v_lshl_add_u64 v[248:249], v[138:139], 0, s[44:45]
	v_readfirstlane_b32 s66, v169
	global_load_lds_dwordx4 v[170:171], off
	v_lshl_add_u64 v[170:171], v[248:249], 0, s[24:25]
	s_mov_b32 m0, s66
	s_nop 0
	global_load_lds_dwordx4 v[170:171], off
	s_waitcnt vmcnt(6)
	s_barrier
	v_mfma_f32_16x16x32_bf16 v[28:31], v[218:221], v[186:189], v[28:31]
	v_mfma_f32_16x16x32_bf16 v[24:27], v[226:229], v[186:189], v[24:27]
	v_mfma_f32_16x16x32_bf16 v[20:23], v[218:221], v[194:197], v[20:23]
	v_mfma_f32_16x16x32_bf16 v[16:19], v[226:229], v[194:197], v[16:19]
	v_mfma_f32_16x16x32_bf16 v[12:15], v[218:221], v[202:205], v[12:15]
	v_mfma_f32_16x16x32_bf16 v[8:11], v[226:229], v[202:205], v[8:11]
	v_mfma_f32_16x16x32_bf16 v[4:7], v[218:221], v[210:213], v[4:7]
	v_mfma_f32_16x16x32_bf16 v[0:3], v[226:229], v[210:213], v[0:3]
	v_mfma_f32_16x16x32_bf16 v[28:31], v[222:225], v[190:193], v[28:31]
	v_mfma_f32_16x16x32_bf16 v[24:27], v[230:233], v[190:193], v[24:27]
	v_mfma_f32_16x16x32_bf16 v[20:23], v[222:225], v[198:201], v[20:23]
	v_mfma_f32_16x16x32_bf16 v[16:19], v[230:233], v[198:201], v[16:19]
	v_mfma_f32_16x16x32_bf16 v[12:15], v[222:225], v[206:209], v[12:15]
	v_mfma_f32_16x16x32_bf16 v[8:11], v[230:233], v[206:209], v[8:11]
	v_mfma_f32_16x16x32_bf16 v[4:7], v[222:225], v[214:217], v[4:7]
	v_mfma_f32_16x16x32_bf16 v[0:3], v[230:233], v[214:217], v[0:3]
	s_barrier
	ds_read_b128 v[174:177], v159
	ds_read_b128 v[178:181], v159 offset:1024
	ds_read_b128 v[182:185], v159 offset:2048
	ds_read_b128 v[186:189], v159 offset:3072
	v_add_u32_e32 v170, 0x4000, v147
	v_add_u32_e32 v171, 0x6000, v147
	v_readfirstlane_b32 s66, v170
	v_lshl_add_u64 v[222:223], v[238:239], 0, s[26:27]
	s_mov_b32 m0, s66
	v_readfirstlane_b32 s66, v171
	ds_read_b128 v[190:193], v155 offset:32768
	ds_read_b128 v[194:197], v155 offset:33792
	ds_read_b128 v[198:201], v154 offset:32768
	ds_read_b128 v[202:205], v154 offset:33792
	ds_read_b128 v[206:209], v153 offset:32768
	ds_read_b128 v[210:213], v153 offset:33792
	ds_read_b128 v[214:217], v152 offset:32768
	ds_read_b128 v[218:221], v152 offset:33792
	global_load_lds_dwordx4 v[222:223], off
	v_lshl_add_u64 v[222:223], v[240:241], 0, s[26:27]
	s_mov_b32 m0, s66
	s_nop 0
	global_load_lds_dwordx4 v[222:223], off
	s_waitcnt lgkmcnt(8)
	s_barrier
	s_waitcnt lgkmcnt(0)
	s_waitcnt lgkmcnt(0)
	v_mfma_f32_16x16x32_bf16 v[124:127], v[174:177], v[190:193], v[124:127]
	v_mfma_f32_16x16x32_bf16 v[120:123], v[182:185], v[190:193], v[120:123]
	v_mfma_f32_16x16x32_bf16 v[116:119], v[174:177], v[198:201], v[116:119]
	v_mfma_f32_16x16x32_bf16 v[112:115], v[182:185], v[198:201], v[112:115]
	v_mfma_f32_16x16x32_bf16 v[108:111], v[174:177], v[206:209], v[108:111]
	v_mfma_f32_16x16x32_bf16 v[104:107], v[182:185], v[206:209], v[104:107]
	v_mfma_f32_16x16x32_bf16 v[100:103], v[174:177], v[214:217], v[100:103]
	v_mfma_f32_16x16x32_bf16 v[96:99], v[182:185], v[214:217], v[96:99]
	v_mfma_f32_16x16x32_bf16 v[124:127], v[178:181], v[194:197], v[124:127]
	v_mfma_f32_16x16x32_bf16 v[120:123], v[186:189], v[194:197], v[120:123]
	v_mfma_f32_16x16x32_bf16 v[116:119], v[178:181], v[202:205], v[116:119]
	v_mfma_f32_16x16x32_bf16 v[112:115], v[186:189], v[202:205], v[112:115]
	v_mfma_f32_16x16x32_bf16 v[108:111], v[178:181], v[210:213], v[108:111]
	v_mfma_f32_16x16x32_bf16 v[104:107], v[186:189], v[210:213], v[104:107]
	v_mfma_f32_16x16x32_bf16 v[100:103], v[178:181], v[218:221], v[100:103]
	v_mfma_f32_16x16x32_bf16 v[96:99], v[186:189], v[218:221], v[96:99]
	s_barrier
	v_readfirstlane_b32 s66, v158
	v_lshl_add_u64 v[242:243], v[242:243], 0, s[36:37]
	s_mov_b32 m0, s66
	ds_read_b128 v[222:225], v157
	ds_read_b128 v[226:229], v157 offset:1024
	ds_read_b128 v[230:233], v157 offset:2048
	ds_read_b128 v[234:237], v157 offset:3072
	global_load_lds_dwordx4 v[242:243], off
	v_lshl_add_u64 v[242:243], v[244:245], 0, s[36:37]
	v_add_u32_e32 v244, 0x2000, v158
	s_nop 0
	v_readfirstlane_b32 s66, v244
	s_mov_b32 m0, s66
	s_nop 0
	global_load_lds_dwordx4 v[242:243], off
	s_barrier
	s_waitcnt lgkmcnt(0)
	s_waitcnt lgkmcnt(0)
	v_mfma_f32_16x16x32_bf16 v[92:95], v[222:225], v[190:193], v[92:95]
	v_mfma_f32_16x16x32_bf16 v[88:91], v[230:233], v[190:193], v[88:91]
	v_mfma_f32_16x16x32_bf16 v[84:87], v[222:225], v[198:201], v[84:87]
	v_mfma_f32_16x16x32_bf16 v[80:83], v[230:233], v[198:201], v[80:83]
	v_mfma_f32_16x16x32_bf16 v[76:79], v[222:225], v[206:209], v[76:79]
	v_mfma_f32_16x16x32_bf16 v[72:75], v[230:233], v[206:209], v[72:75]
	v_mfma_f32_16x16x32_bf16 v[68:71], v[222:225], v[214:217], v[68:71]
	v_mfma_f32_16x16x32_bf16 v[64:67], v[230:233], v[214:217], v[64:67]
	v_mfma_f32_16x16x32_bf16 v[92:95], v[226:229], v[194:197], v[92:95]
	v_mfma_f32_16x16x32_bf16 v[88:91], v[234:237], v[194:197], v[88:91]
	v_mfma_f32_16x16x32_bf16 v[84:87], v[226:229], v[202:205], v[84:87]
	v_mfma_f32_16x16x32_bf16 v[80:83], v[234:237], v[202:205], v[80:83]
	v_mfma_f32_16x16x32_bf16 v[76:79], v[226:229], v[210:213], v[76:79]
	v_mfma_f32_16x16x32_bf16 v[72:75], v[234:237], v[210:213], v[72:75]
	v_mfma_f32_16x16x32_bf16 v[68:71], v[226:229], v[218:221], v[68:71]
	v_mfma_f32_16x16x32_bf16 v[64:67], v[234:237], v[218:221], v[64:67]
	s_barrier
; #define STAGE(P, BASE, LD, br, kt) do { const char* _g = (const char*)((BASE) + (size_t)(br) * (LD) + (size_t)(kt) * 64); \
;     for (int _i = 0; _i < 2; ++_i) { int _b = tidx * 16 + _i * 8192; int _r, _c; stage_rc(_b, _r, _c); \
;       __builtin_amdgcn_global_load_lds((const unsigned*)(_g + (unsigned)((_r * (LD) + _c) * 2)), (unsigned*)((char*)(P) + _b), 16, 0, 0); } } while (0)
; #define LDA(dst, b, h) for (int m = 0; m < 4; ++m) for (int k = 0; k < 2; ++k) \
;     dst[m][k] = *reinterpret_cast<const bf16x8*>((char*)SA(b, h) + lds_byte(wr * 64 + m * 16 + fr, k * 32 + fq * 8))
; #define LDB(dst, b, h) for (int n = 0; n < 2; ++n) for (int k = 0; k < 2; ++k) \
;     dst[n][k] = *reinterpret_cast<const bf16x8*>((char*)SB(b, h) + lds_byte(wc * 32 + n * 16 + fr, k * 32 + fq * 8))
; #define MMA(ai, bj, At_, Bt_) do { __builtin_amdgcn_s_setprio(1); \
;     for (int k = 0; k < 2; ++k) for (int m = 0; m < 4; ++m) for (int n = 0; n < 2; ++n) \
;       acc[ai][bj][m][n] = __builtin_amdgcn_mfma_f32_16x16x32_bf16(At_[m][k], Bt_[n][k], acc[ai][bj][m][n], 0, 0, 0); \
;     __builtin_amdgcn_s_setprio(0); } while (0)
; #define WAIT_V(n) asm volatile("s_waitcnt vmcnt(" #n ")" ::: "memory")
; #define WAIT_L(n) asm volatile("s_waitcnt lgkmcnt(" #n ")" ::: "memory")
; #define BAR __builtin_amdgcn_s_barrier()
; #define SCHED __builtin_amdgcn_sched_barrier(0)
; template <int EPI, int lda, int ldb, int N, int K>
; __device__ __forceinline__ void gemm_phase(const u16* __restrict__ A, const u16* __restrict__ Bt, const GemmEpi ep, int wv) {
;     ...
;       LDA(At, 1, 1); STAGE(SA(1, 0), Ab, lda, brow, t + 3);
;       BAR; WAIT_L(0); MMA(1, 0, At, B0); BAR; SCHED;
;       STAGE(SB(1, 1), Bt, ldb, bcol + HALF, t + 3);
;       WAIT_V(6); BAR; MMA(1, 1, At, B1); BAR;
;     }
;     { LDB(B0, 0, 0); LDA(At, 0, 0); STAGE(SA(1, 1), Ab, lda, brow + HALF, nt - 1);
;       BAR; WAIT_L(0); MMA(0, 0, At, B0); BAR;
;       LDB(B1, 0, 1); BAR; WAIT_L(0); MMA(0, 1, At, B1); BAR;
	v_readfirstlane_b32 s66, v160
	v_lshl_add_u64 v[238:239], v[238:239], 0, s[38:39]
	s_mov_b32 m0, s66
	v_readfirstlane_b32 s66, v161
	ds_read_b128 v[190:193], v155 offset:49152
	ds_read_b128 v[194:197], v155 offset:50176
	ds_read_b128 v[198:201], v154 offset:49152
	ds_read_b128 v[202:205], v154 offset:50176
	ds_read_b128 v[206:209], v153 offset:49152
	ds_read_b128 v[210:213], v153 offset:50176
	ds_read_b128 v[214:217], v152 offset:49152
	ds_read_b128 v[218:221], v152 offset:50176
	global_load_lds_dwordx4 v[238:239], off
	v_lshl_add_u64 v[238:239], v[240:241], 0, s[38:39]
	s_mov_b32 m0, s66
	s_nop 0
	global_load_lds_dwordx4 v[238:239], off
	s_barrier
	s_waitcnt lgkmcnt(0)
	s_waitcnt lgkmcnt(0)
	v_mfma_f32_16x16x32_bf16 v[60:63], v[174:177], v[190:193], v[60:63]
	v_mfma_f32_16x16x32_bf16 v[56:59], v[182:185], v[190:193], v[56:59]
	v_mfma_f32_16x16x32_bf16 v[52:55], v[174:177], v[198:201], v[52:55]
	v_mfma_f32_16x16x32_bf16 v[48:51], v[182:185], v[198:201], v[48:51]
	v_mfma_f32_16x16x32_bf16 v[44:47], v[174:177], v[206:209], v[44:47]
	v_mfma_f32_16x16x32_bf16 v[40:43], v[182:185], v[206:209], v[40:43]
	v_mfma_f32_16x16x32_bf16 v[36:39], v[174:177], v[214:217], v[36:39]
	v_mfma_f32_16x16x32_bf16 v[32:35], v[182:185], v[214:217], v[32:35]
	v_mfma_f32_16x16x32_bf16 v[60:63], v[178:181], v[194:197], v[60:63]
	v_mfma_f32_16x16x32_bf16 v[56:59], v[186:189], v[194:197], v[56:59]
	v_mfma_f32_16x16x32_bf16 v[52:55], v[178:181], v[202:205], v[52:55]
	v_mfma_f32_16x16x32_bf16 v[48:51], v[186:189], v[202:205], v[48:51]
	v_mfma_f32_16x16x32_bf16 v[44:47], v[178:181], v[210:213], v[44:47]
	v_mfma_f32_16x16x32_bf16 v[40:43], v[186:189], v[210:213], v[40:43]
	v_mfma_f32_16x16x32_bf16 v[36:39], v[178:181], v[218:221], v[36:39]
	v_mfma_f32_16x16x32_bf16 v[32:35], v[186:189], v[218:221], v[32:35]
	s_barrier
	v_readfirstlane_b32 s66, v162
	v_add_u32_e32 v176, 0x2000, v162
	v_lshl_add_u64 v[174:175], v[246:247], 0, s[42:43]
	s_mov_b32 m0, s66
	v_readfirstlane_b32 s66, v176
	global_load_lds_dwordx4 v[174:175], off
	v_lshl_add_u64 v[174:175], v[248:249], 0, s[42:43]
	s_mov_b32 m0, s66
	s_nop 0
	global_load_lds_dwordx4 v[174:175], off
	s_waitcnt vmcnt(6)
	s_barrier
	v_mfma_f32_16x16x32_bf16 v[28:31], v[222:225], v[190:193], v[28:31]
	v_mfma_f32_16x16x32_bf16 v[24:27], v[230:233], v[190:193], v[24:27]
	v_mfma_f32_16x16x32_bf16 v[20:23], v[222:225], v[198:201], v[20:23]
	v_mfma_f32_16x16x32_bf16 v[16:19], v[230:233], v[198:201], v[16:19]
	v_mfma_f32_16x16x32_bf16 v[12:15], v[222:225], v[206:209], v[12:15]
	v_mfma_f32_16x16x32_bf16 v[8:11], v[230:233], v[206:209], v[8:11]
	v_mfma_f32_16x16x32_bf16 v[4:7], v[222:225], v[214:217], v[4:7]
	v_mfma_f32_16x16x32_bf16 v[0:3], v[230:233], v[214:217], v[0:3]
	v_mfma_f32_16x16x32_bf16 v[28:31], v[226:229], v[194:197], v[28:31]
	v_mfma_f32_16x16x32_bf16 v[24:27], v[234:237], v[194:197], v[24:27]
	v_mfma_f32_16x16x32_bf16 v[20:23], v[226:229], v[202:205], v[20:23]
	v_mfma_f32_16x16x32_bf16 v[16:19], v[234:237], v[202:205], v[16:19]
	v_mfma_f32_16x16x32_bf16 v[12:15], v[226:229], v[210:213], v[12:15]
	v_mfma_f32_16x16x32_bf16 v[8:11], v[234:237], v[210:213], v[8:11]
	v_mfma_f32_16x16x32_bf16 v[4:7], v[226:229], v[218:221], v[4:7]
	v_mfma_f32_16x16x32_bf16 v[0:3], v[234:237], v[218:221], v[0:3]
	s_barrier
	s_add_i32 s65, s65, 2
	s_add_u32 s44, s44, 0x100
	s_addc_u32 s45, s45, 0
	s_cmpk_gt_u32 s65, 0x51
	s_cbranch_scc0 .LBB0_224
	s_add_i32 s44, s14, 0x80
	s_mul_hi_i32 s45, s44, 0x2b00
	s_mulk_i32 s44, 0x2b00
	s_add_u32 s44, s48, s44
	s_addc_u32 s45, s49, s45
	s_add_u32 s44, s44, 0x2a80
	s_addc_u32 s45, s45, 0
	v_readfirstlane_b32 s65, v172
	v_lshl_add_u64 v[160:161], s[44:45], 0, v[128:129]
	s_mov_b32 m0, s65
	ds_read_b128 v[134:137], v164
	ds_read_b128 v[138:141], v164 offset:1024
	ds_read_b128 v[142:145], v164 offset:2048
	ds_read_b128 v[174:177], v164 offset:3072
	ds_read_b128 v[178:181], v155
	ds_read_b128 v[182:185], v155 offset:1024
	ds_read_b128 v[186:189], v154
	ds_read_b128 v[190:193], v154 offset:1024
	ds_read_b128 v[194:197], v153
	ds_read_b128 v[198:201], v153 offset:1024
	ds_read_b128 v[202:205], v152
	ds_read_b128 v[206:209], v152 offset:1024
	global_load_lds_dwordx4 v[160:161], off
	v_lshl_add_u64 v[160:161], s[44:45], 0, v[132:133]
	v_readfirstlane_b32 s44, v173
	s_mov_b32 m0, s44
	s_nop 0
	global_load_lds_dwordx4 v[160:161], off
	s_barrier
	s_waitcnt lgkmcnt(0)
	s_waitcnt lgkmcnt(0)
	v_mfma_f32_16x16x32_bf16 v[124:127], v[134:137], v[178:181], v[124:127]
	v_mfma_f32_16x16x32_bf16 v[120:123], v[142:145], v[178:181], v[120:123]
	v_mfma_f32_16x16x32_bf16 v[116:119], v[134:137], v[186:189], v[116:119]
	v_mfma_f32_16x16x32_bf16 v[112:115], v[142:145], v[186:189], v[112:115]
	v_mfma_f32_16x16x32_bf16 v[108:111], v[134:137], v[194:197], v[108:111]
	v_mfma_f32_16x16x32_bf16 v[104:107], v[142:145], v[194:197], v[104:107]
	v_mfma_f32_16x16x32_bf16 v[100:103], v[134:137], v[202:205], v[100:103]
	v_mfma_f32_16x16x32_bf16 v[96:99], v[142:145], v[202:205], v[96:99]
	v_mfma_f32_16x16x32_bf16 v[124:127], v[138:141], v[182:185], v[124:127]
	v_mfma_f32_16x16x32_bf16 v[120:123], v[174:177], v[182:185], v[120:123]
	v_mfma_f32_16x16x32_bf16 v[116:119], v[138:141], v[190:193], v[116:119]
	v_mfma_f32_16x16x32_bf16 v[112:115], v[174:177], v[190:193], v[112:115]
	v_mfma_f32_16x16x32_bf16 v[108:111], v[138:141], v[198:201], v[108:111]
	v_mfma_f32_16x16x32_bf16 v[104:107], v[174:177], v[198:201], v[104:107]
	v_mfma_f32_16x16x32_bf16 v[100:103], v[138:141], v[206:209], v[100:103]
	v_mfma_f32_16x16x32_bf16 v[96:99], v[174:177], v[206:209], v[96:99]
	s_barrier
; #define LDA(dst, b, h) for (int m = 0; m < 4; ++m) for (int k = 0; k < 2; ++k) \
;     dst[m][k] = *reinterpret_cast<const bf16x8*>((char*)SA(b, h) + lds_byte(wr * 64 + m * 16 + fr, k * 32 + fq * 8))
; #define LDB(dst, b, h) for (int n = 0; n < 2; ++n) for (int k = 0; k < 2; ++k) \
;     dst[n][k] = *reinterpret_cast<const bf16x8*>((char*)SB(b, h) + lds_byte(wc * 32 + n * 16 + fr, k * 32 + fq * 8))
; #define MMA(ai, bj, At_, Bt_) do { __builtin_amdgcn_s_setprio(1); \
;     for (int k = 0; k < 2; ++k) for (int m = 0; m < 4; ++m) for (int n = 0; n < 2; ++n) \
;       acc[ai][bj][m][n] = __builtin_amdgcn_mfma_f32_16x16x32_bf16(At_[m][k], Bt_[n][k], acc[ai][bj][m][n], 0, 0, 0); \
;     __builtin_amdgcn_s_setprio(0); } while (0)
; #define WAIT_V(n) asm volatile("s_waitcnt vmcnt(" #n ")" ::: "memory")
; #define WAIT_L(n) asm volatile("s_waitcnt lgkmcnt(" #n ")" ::: "memory")
; #define BAR __builtin_amdgcn_s_barrier()
; template <int EPI, int lda, int ldb, int N, int K>
; __device__ __forceinline__ void gemm_phase(const u16* __restrict__ A, const u16* __restrict__ Bt, const GemmEpi ep, int wv) {
;     ...
;       LDB(B1, 0, 1); BAR; WAIT_L(0); MMA(0, 1, At, B1); BAR;
;       LDA(At, 0, 1); WAIT_V(4); BAR; WAIT_L(0); MMA(1, 0, At, B0); MMA(1, 1, At, B1); BAR; }
;     { LDB(B0, 1, 0); LDA(At, 1, 0); WAIT_V(2); BAR; WAIT_L(0); MMA(0, 0, At, B0); BAR;
	ds_read_b128 v[210:213], v163
	ds_read_b128 v[214:217], v163 offset:1024
	ds_read_b128 v[218:221], v163 offset:2048
	ds_read_b128 v[160:163], v163 offset:3072
	s_barrier
	s_waitcnt lgkmcnt(0)
	s_waitcnt lgkmcnt(0)
	v_mfma_f32_16x16x32_bf16 v[92:95], v[210:213], v[178:181], v[92:95]
	v_mfma_f32_16x16x32_bf16 v[88:91], v[218:221], v[178:181], v[88:91]
	v_mfma_f32_16x16x32_bf16 v[76:79], v[210:213], v[194:197], v[76:79]
	v_mfma_f32_16x16x32_bf16 v[72:75], v[218:221], v[194:197], v[72:75]
	v_mfma_f32_16x16x32_bf16 v[84:87], v[210:213], v[186:189], v[84:87]
	v_mfma_f32_16x16x32_bf16 v[80:83], v[218:221], v[186:189], v[80:83]
	v_mfma_f32_16x16x32_bf16 v[68:71], v[210:213], v[202:205], v[68:71]
	v_mfma_f32_16x16x32_bf16 v[64:67], v[218:221], v[202:205], v[64:67]
	v_mfma_f32_16x16x32_bf16 v[92:95], v[214:217], v[182:185], v[92:95]
	v_mfma_f32_16x16x32_bf16 v[88:91], v[160:163], v[182:185], v[88:91]
	v_mfma_f32_16x16x32_bf16 v[76:79], v[214:217], v[198:201], v[76:79]
	v_mfma_f32_16x16x32_bf16 v[72:75], v[160:163], v[198:201], v[72:75]
	v_mfma_f32_16x16x32_bf16 v[178:181], v[214:217], v[190:193], v[84:87]
	v_mfma_f32_16x16x32_bf16 v[182:185], v[160:163], v[190:193], v[80:83]
	v_mfma_f32_16x16x32_bf16 v[186:189], v[214:217], v[206:209], v[68:71]
	v_mfma_f32_16x16x32_bf16 v[190:193], v[160:163], v[206:209], v[64:67]
	s_barrier
	s_nop 0
	ds_read_b128 v[64:67], v155 offset:16384
	ds_read_b128 v[68:71], v155 offset:17408
	ds_read_b128 v[80:83], v154 offset:16384
	ds_read_b128 v[84:87], v154 offset:17408
	ds_read_b128 v[194:197], v153 offset:16384
	ds_read_b128 v[198:201], v153 offset:17408
	ds_read_b128 v[202:205], v152 offset:16384
	ds_read_b128 v[206:209], v152 offset:17408
	s_waitcnt vmcnt(4)
	s_barrier
	s_waitcnt lgkmcnt(0)
	s_waitcnt lgkmcnt(0)
	v_mfma_f32_16x16x32_bf16 v[60:63], v[134:137], v[64:67], v[60:63]
	v_mfma_f32_16x16x32_bf16 v[56:59], v[142:145], v[64:67], v[56:59]
	v_mfma_f32_16x16x32_bf16 v[52:55], v[134:137], v[80:83], v[52:55]
	v_mfma_f32_16x16x32_bf16 v[48:51], v[142:145], v[80:83], v[48:51]
	v_mfma_f32_16x16x32_bf16 v[44:47], v[134:137], v[194:197], v[44:47]
	v_mfma_f32_16x16x32_bf16 v[40:43], v[142:145], v[194:197], v[40:43]
	v_mfma_f32_16x16x32_bf16 v[36:39], v[134:137], v[202:205], v[36:39]
	v_mfma_f32_16x16x32_bf16 v[32:35], v[142:145], v[202:205], v[32:35]
	v_mfma_f32_16x16x32_bf16 v[60:63], v[138:141], v[68:71], v[60:63]
	v_mfma_f32_16x16x32_bf16 v[56:59], v[174:177], v[68:71], v[56:59]
	v_mfma_f32_16x16x32_bf16 v[52:55], v[138:141], v[84:87], v[52:55]
	v_mfma_f32_16x16x32_bf16 v[48:51], v[174:177], v[84:87], v[48:51]
	v_mfma_f32_16x16x32_bf16 v[44:47], v[138:141], v[198:201], v[44:47]
	v_mfma_f32_16x16x32_bf16 v[40:43], v[174:177], v[198:201], v[40:43]
	v_mfma_f32_16x16x32_bf16 v[36:39], v[138:141], v[206:209], v[36:39]
	v_mfma_f32_16x16x32_bf16 v[32:35], v[174:177], v[206:209], v[32:35]
	v_mfma_f32_16x16x32_bf16 v[28:31], v[210:213], v[64:67], v[28:31]
	v_mfma_f32_16x16x32_bf16 v[16:19], v[218:221], v[80:83], v[16:19]
	v_mfma_f32_16x16x32_bf16 v[12:15], v[210:213], v[194:197], v[12:15]
	v_mfma_f32_16x16x32_bf16 v[0:3], v[218:221], v[202:205], v[0:3]
	v_mfma_f32_16x16x32_bf16 v[24:27], v[218:221], v[64:67], v[24:27]
	v_mfma_f32_16x16x32_bf16 v[20:23], v[210:213], v[80:83], v[20:23]
	v_mfma_f32_16x16x32_bf16 v[8:11], v[218:221], v[194:197], v[8:11]
	v_mfma_f32_16x16x32_bf16 v[4:7], v[210:213], v[202:205], v[4:7]
	v_mfma_f32_16x16x32_bf16 v[28:31], v[214:217], v[68:71], v[28:31]
	v_mfma_f32_16x16x32_bf16 v[16:19], v[160:163], v[84:87], v[16:19]
	v_mfma_f32_16x16x32_bf16 v[12:15], v[214:217], v[198:201], v[12:15]
	v_mfma_f32_16x16x32_bf16 v[0:3], v[160:163], v[206:209], v[0:3]
	v_mfma_f32_16x16x32_bf16 v[134:137], v[160:163], v[68:71], v[24:27]
	v_mfma_f32_16x16x32_bf16 v[138:141], v[214:217], v[84:87], v[20:23]
	v_mfma_f32_16x16x32_bf16 v[142:145], v[160:163], v[198:201], v[8:11]
	v_mfma_f32_16x16x32_bf16 v[172:175], v[214:217], v[206:209], v[4:7]
	s_barrier
	s_nop 0
	ds_read_b128 v[4:7], v159
	ds_read_b128 v[8:11], v159 offset:1024
	ds_read_b128 v[20:23], v159 offset:2048
	ds_read_b128 v[158:161], v159 offset:3072
	ds_read_b128 v[24:27], v155 offset:32768
	ds_read_b128 v[194:197], v155 offset:33792
	ds_read_b128 v[198:201], v154 offset:32768
	ds_read_b128 v[202:205], v154 offset:33792
	ds_read_b128 v[206:209], v153 offset:32768
	ds_read_b128 v[210:213], v153 offset:33792
	ds_read_b128 v[214:217], v152 offset:32768
	ds_read_b128 v[218:221], v152 offset:33792
	s_waitcnt vmcnt(2)
	s_barrier
; #define LDA(dst, b, h) for (int m = 0; m < 4; ++m) for (int k = 0; k < 2; ++k) \
;     dst[m][k] = *reinterpret_cast<const bf16x8*>((char*)SA(b, h) + lds_byte(wr * 64 + m * 16 + fr, k * 32 + fq * 8))
; #define LDB(dst, b, h) for (int n = 0; n < 2; ++n) for (int k = 0; k < 2; ++k) \
;     dst[n][k] = *reinterpret_cast<const bf16x8*>((char*)SB(b, h) + lds_byte(wc * 32 + n * 16 + fr, k * 32 + fq * 8))
; #define MMA(ai, bj, At_, Bt_) do { __builtin_amdgcn_s_setprio(1); \
;     for (int k = 0; k < 2; ++k) for (int m = 0; m < 4; ++m) for (int n = 0; n < 2; ++n) \
;       acc[ai][bj][m][n] = __builtin_amdgcn_mfma_f32_16x16x32_bf16(At_[m][k], Bt_[n][k], acc[ai][bj][m][n], 0, 0, 0); \
;     __builtin_amdgcn_s_setprio(0); } while (0)
; #define WAIT_V(n) asm volatile("s_waitcnt vmcnt(" #n ")" ::: "memory")
; #define WAIT_L(n) asm volatile("s_waitcnt lgkmcnt(" #n ")" ::: "memory")
; #define BAR __builtin_amdgcn_s_barrier()
; template <int EPI, int lda, int ldb, int N, int K>
; __device__ __forceinline__ void gemm_phase(const u16* __restrict__ A, const u16* __restrict__ Bt, const GemmEpi ep, int wv) {
;     ...
;     { LDB(B0, 1, 0); LDA(At, 1, 0); WAIT_V(2); BAR; WAIT_L(0); MMA(0, 0, At, B0); BAR;
;       LDB(B1, 1, 1); WAIT_V(0); BAR; WAIT_L(0); MMA(0, 1, At, B1); BAR;
;       LDA(At, 1, 1); BAR; WAIT_L(0); MMA(1, 0, At, B0); MMA(1, 1, At, B1); BAR; }
;     if (wr == 0) BAR;
	s_waitcnt lgkmcnt(0)
	s_waitcnt lgkmcnt(0)
	v_mfma_f32_16x16x32_bf16 v[64:67], v[4:7], v[24:27], v[124:127]
	v_mfma_f32_16x16x32_bf16 v[68:71], v[20:23], v[24:27], v[120:123]
	v_mfma_f32_16x16x32_bf16 v[80:83], v[4:7], v[198:201], v[116:119]
	v_mfma_f32_16x16x32_bf16 v[84:87], v[20:23], v[198:201], v[112:115]
	v_mfma_f32_16x16x32_bf16 v[108:111], v[4:7], v[206:209], v[108:111]
	v_mfma_f32_16x16x32_bf16 v[104:107], v[20:23], v[206:209], v[104:107]
	v_mfma_f32_16x16x32_bf16 v[120:123], v[4:7], v[214:217], v[100:103]
	v_mfma_f32_16x16x32_bf16 v[124:127], v[20:23], v[214:217], v[96:99]
	v_mfma_f32_16x16x32_bf16 v[116:119], v[8:11], v[194:197], v[64:67]
	v_mfma_f32_16x16x32_bf16 v[112:115], v[158:161], v[194:197], v[68:71]
	v_mfma_f32_16x16x32_bf16 v[100:103], v[8:11], v[202:205], v[80:83]
	v_mfma_f32_16x16x32_bf16 v[96:99], v[158:161], v[202:205], v[84:87]
	v_mfma_f32_16x16x32_bf16 v[84:87], v[8:11], v[210:213], v[108:111]
	v_mfma_f32_16x16x32_bf16 v[80:83], v[158:161], v[210:213], v[104:107]
	v_mfma_f32_16x16x32_bf16 v[68:71], v[8:11], v[218:221], v[120:123]
	v_mfma_f32_16x16x32_bf16 v[64:67], v[158:161], v[218:221], v[124:127]
	s_barrier
	ds_read_b128 v[222:225], v157
	ds_read_b128 v[226:229], v157 offset:1024
	ds_read_b128 v[230:233], v157 offset:2048
	ds_read_b128 v[234:237], v157 offset:3072
	s_waitcnt vmcnt(0)
	s_barrier
	s_waitcnt lgkmcnt(0)
	s_waitcnt lgkmcnt(0)
	v_mfma_f32_16x16x32_bf16 v[92:95], v[222:225], v[24:27], v[92:95]
	v_mfma_f32_16x16x32_bf16 v[24:27], v[230:233], v[24:27], v[88:91]
	v_mfma_f32_16x16x32_bf16 v[88:91], v[222:225], v[198:201], v[178:181]
	v_mfma_f32_16x16x32_bf16 v[104:107], v[230:233], v[198:201], v[182:185]
	v_mfma_f32_16x16x32_bf16 v[76:79], v[222:225], v[206:209], v[76:79]
	v_mfma_f32_16x16x32_bf16 v[72:75], v[230:233], v[206:209], v[72:75]
	v_mfma_f32_16x16x32_bf16 v[176:179], v[222:225], v[214:217], v[186:189]
	v_mfma_f32_16x16x32_bf16 v[180:183], v[230:233], v[214:217], v[190:193]
	v_mfma_f32_16x16x32_bf16 v[124:127], v[226:229], v[194:197], v[92:95]
	v_mfma_f32_16x16x32_bf16 v[120:123], v[234:237], v[194:197], v[24:27]
	v_mfma_f32_16x16x32_bf16 v[108:111], v[226:229], v[202:205], v[88:91]
	v_mfma_f32_16x16x32_bf16 v[104:107], v[234:237], v[202:205], v[104:107]
	v_mfma_f32_16x16x32_bf16 v[92:95], v[226:229], v[210:213], v[76:79]
	v_mfma_f32_16x16x32_bf16 v[88:91], v[234:237], v[210:213], v[72:75]
	v_mfma_f32_16x16x32_bf16 v[76:79], v[226:229], v[218:221], v[176:179]
	v_mfma_f32_16x16x32_bf16 v[72:75], v[234:237], v[218:221], v[180:183]
	s_barrier
	ds_read_b128 v[176:179], v155 offset:49152
	ds_read_b128 v[180:183], v155 offset:50176
	ds_read_b128 v[184:187], v154 offset:49152
	ds_read_b128 v[154:157], v154 offset:50176
	ds_read_b128 v[188:191], v153 offset:49152
	ds_read_b128 v[192:195], v153 offset:50176
	ds_read_b128 v[196:199], v152 offset:49152
	ds_read_b128 v[200:203], v152 offset:50176
	s_barrier
	s_waitcnt lgkmcnt(0)
	s_waitcnt lgkmcnt(0)
	v_mfma_f32_16x16x32_bf16 v[24:27], v[4:7], v[176:179], v[60:63]
	v_mfma_f32_16x16x32_bf16 v[60:63], v[20:23], v[176:179], v[56:59]
	v_mfma_f32_16x16x32_bf16 v[204:207], v[4:7], v[184:187], v[52:55]
	v_mfma_f32_16x16x32_bf16 v[48:51], v[20:23], v[184:187], v[48:51]
	v_mfma_f32_16x16x32_bf16 v[44:47], v[4:7], v[188:191], v[44:47]
	v_mfma_f32_16x16x32_bf16 v[208:211], v[20:23], v[188:191], v[40:43]
	v_mfma_f32_16x16x32_bf16 v[4:7], v[4:7], v[196:199], v[36:39]
	v_mfma_f32_16x16x32_bf16 v[32:35], v[20:23], v[196:199], v[32:35]
	v_mfma_f32_16x16x32_bf16 v[56:59], v[8:11], v[180:183], v[24:27]
	v_mfma_f32_16x16x32_bf16 v[52:55], v[158:161], v[180:183], v[60:63]
	v_mfma_f32_16x16x32_bf16 v[40:43], v[8:11], v[154:157], v[204:207]
	v_mfma_f32_16x16x32_bf16 v[36:39], v[158:161], v[154:157], v[48:51]
	v_mfma_f32_16x16x32_bf16 v[24:27], v[8:11], v[192:195], v[44:47]
	v_mfma_f32_16x16x32_bf16 v[20:23], v[158:161], v[192:195], v[208:211]
	v_mfma_f32_16x16x32_bf16 v[8:11], v[8:11], v[200:203], v[4:7]
	v_mfma_f32_16x16x32_bf16 v[4:7], v[158:161], v[200:203], v[32:35]
	v_mfma_f32_16x16x32_bf16 v[28:31], v[222:225], v[176:179], v[28:31]
	v_mfma_f32_16x16x32_bf16 v[32:35], v[230:233], v[176:179], v[134:137]
	v_mfma_f32_16x16x32_bf16 v[44:47], v[222:225], v[184:187], v[138:141]
	v_mfma_f32_16x16x32_bf16 v[16:19], v[230:233], v[184:187], v[16:19]
	v_mfma_f32_16x16x32_bf16 v[12:15], v[222:225], v[188:191], v[12:15]
	v_mfma_f32_16x16x32_bf16 v[134:137], v[230:233], v[188:191], v[142:145]
	v_mfma_f32_16x16x32_bf16 v[138:141], v[222:225], v[196:199], v[172:175]
	v_mfma_f32_16x16x32_bf16 v[0:3], v[230:233], v[196:199], v[0:3]
	v_mfma_f32_16x16x32_bf16 v[60:63], v[226:229], v[180:183], v[28:31]
	v_mfma_f32_16x16x32_bf16 v[48:51], v[234:237], v[180:183], v[32:35]
	v_mfma_f32_16x16x32_bf16 v[44:47], v[226:229], v[154:157], v[44:47]
	v_mfma_f32_16x16x32_bf16 v[32:35], v[234:237], v[154:157], v[16:19]
	v_mfma_f32_16x16x32_bf16 v[28:31], v[226:229], v[192:195], v[12:15]
	v_mfma_f32_16x16x32_bf16 v[16:19], v[234:237], v[192:195], v[134:137]
	v_mfma_f32_16x16x32_bf16 v[12:15], v[226:229], v[200:203], v[138:141]
	v_mfma_f32_16x16x32_bf16 v[0:3], v[234:237], v[200:203], v[0:3]
	v_cmp_gt_u32_e32 vcc, s62, v130
	s_barrier
	s_and_saveexec_b64 s[44:45], vcc
	s_cbranch_execz .LBB0_227
	s_barrier

; #define STAGE(P, BASE, LD, br, kt) do { const char* _g = (const char*)((BASE) + (size_t)(br) * (LD) + (size_t)(kt) * 64); \
;     for (int _i = 0; _i < 2; ++_i) { int _b = tidx * 16 + _i * 8192; int _r, _c; stage_rc(_b, _r, _c); \
;       __builtin_amdgcn_global_load_lds((const unsigned*)(_g + (unsigned)((_r * (LD) + _c) * 2)), (unsigned*)((char*)(P) + _b), 16, 0, 0); } } while (0)
; #define LDA(dst, b, h) for (int m = 0; m < 4; ++m) for (int k = 0; k < 2; ++k) \
;     dst[m][k] = *reinterpret_cast<const bf16x8*>((char*)SA(b, h) + lds_byte(wr * 64 + m * 16 + fr, k * 32 + fq * 8))
; #define LDB(dst, b, h) for (int n = 0; n < 2; ++n) for (int k = 0; k < 2; ++k) \
;     dst[n][k] = *reinterpret_cast<const bf16x8*>((char*)SB(b, h) + lds_byte(wc * 32 + n * 16 + fr, k * 32 + fq * 8))
; #define MMA(ai, bj, At_, Bt_) do { __builtin_amdgcn_s_setprio(1); \
;     for (int k = 0; k < 2; ++k) for (int m = 0; m < 4; ++m) for (int n = 0; n < 2; ++n) \
;       acc[ai][bj][m][n] = __builtin_amdgcn_mfma_f32_16x16x32_bf16(At_[m][k], Bt_[n][k], acc[ai][bj][m][n], 0, 0, 0); \
;     __builtin_amdgcn_s_setprio(0); } while (0)
; #define WAIT_L(n) asm volatile("s_waitcnt lgkmcnt(" #n ")" ::: "memory")
; #define BAR __builtin_amdgcn_s_barrier()
; #define SCHED __builtin_amdgcn_sched_barrier(0)
; template <int EPI, int lda, int ldb, int N, int K>
; __device__ __forceinline__ void gemm_phase(const u16* __restrict__ A, const u16* __restrict__ Bt, const GemmEpi ep, int wv) {
;     ...
;     for (int t = 0; t < nt - 2; t += 2) {
;       LDB(B0, 0, 0); SCHED; LDA(At, 0, 0); STAGE(SA(1, 1), Ab, lda, brow + HALF, t + 1);
;       WAIT_L(8); BAR; WAIT_L(0); MMA(0, 0, At, B0); BAR; SCHED;
;       LDB(B1, 0, 1); STAGE(SB(0, 0), Bt, ldb, bcol, t + 2);
;       BAR; WAIT_L(0); MMA(0, 1, At, B1); BAR;
;       LDA(At, 0, 1); STAGE(SA(0, 0), Ab, lda, brow, t + 2);
;       BAR; WAIT_L(0); MMA(1, 0, At, B0); BAR; SCHED;
.LBB0_340:
	ds_read_b128 v[166:169], v162
	ds_read_b128 v[172:175], v162 offset:1024
	ds_read_b128 v[176:179], v162 offset:2048
	ds_read_b128 v[180:183], v162 offset:3072
	v_add_u32_e32 v170, 0xc000, v149
	v_lshl_add_u64 v[236:237], v[138:139], 0, s[48:49]
	v_readfirstlane_b32 s51, v170
	v_add_u32_e32 v171, 0xe000, v149
	v_lshl_add_u64 v[164:165], v[236:237], 0, s[18:19]
	s_mov_b32 m0, s51
	v_lshl_add_u64 v[238:239], v[140:141], 0, s[48:49]
	v_readfirstlane_b32 s51, v171
	ds_read_b128 v[184:187], v153
	ds_read_b128 v[188:191], v153 offset:1024
	ds_read_b128 v[192:195], v152
	ds_read_b128 v[196:199], v152 offset:1024
	ds_read_b128 v[200:203], v151
	ds_read_b128 v[204:207], v151 offset:1024
	ds_read_b128 v[208:211], v150
	ds_read_b128 v[212:215], v150 offset:1024
	global_load_lds_dwordx4 v[164:165], off
	v_lshl_add_u64 v[164:165], v[238:239], 0, s[18:19]
	s_mov_b32 m0, s51
	s_nop 0
	global_load_lds_dwordx4 v[164:165], off
	s_waitcnt lgkmcnt(8)
	s_barrier
	s_waitcnt lgkmcnt(0)
	s_waitcnt lgkmcnt(0)
	v_mfma_f32_16x16x32_bf16 v[124:127], v[184:187], v[166:169], v[124:127]
	v_mfma_f32_16x16x32_bf16 v[120:123], v[184:187], v[176:179], v[120:123]
	v_mfma_f32_16x16x32_bf16 v[116:119], v[192:195], v[166:169], v[116:119]
	v_mfma_f32_16x16x32_bf16 v[112:115], v[192:195], v[176:179], v[112:115]
	v_mfma_f32_16x16x32_bf16 v[108:111], v[200:203], v[166:169], v[108:111]
	v_mfma_f32_16x16x32_bf16 v[104:107], v[200:203], v[176:179], v[104:107]
	v_mfma_f32_16x16x32_bf16 v[100:103], v[208:211], v[166:169], v[100:103]
	v_mfma_f32_16x16x32_bf16 v[96:99], v[208:211], v[176:179], v[96:99]
	v_mfma_f32_16x16x32_bf16 v[124:127], v[188:191], v[172:175], v[124:127]
	v_mfma_f32_16x16x32_bf16 v[120:123], v[188:191], v[180:183], v[120:123]
	v_mfma_f32_16x16x32_bf16 v[116:119], v[196:199], v[172:175], v[116:119]
	v_mfma_f32_16x16x32_bf16 v[112:115], v[196:199], v[180:183], v[112:115]
	v_mfma_f32_16x16x32_bf16 v[108:111], v[204:207], v[172:175], v[108:111]
	v_mfma_f32_16x16x32_bf16 v[104:107], v[204:207], v[180:183], v[104:107]
	v_mfma_f32_16x16x32_bf16 v[100:103], v[212:215], v[172:175], v[100:103]
	v_mfma_f32_16x16x32_bf16 v[96:99], v[212:215], v[180:183], v[96:99]
	s_barrier
	v_add_u32_e32 v163, s62, v155
	v_lshl_add_u64 v[240:241], v[134:135], 0, s[48:49]
	v_readfirstlane_b32 s51, v163
	v_lshl_add_u64 v[164:165], v[240:241], 0, s[20:21]
	s_mov_b32 m0, s51
	ds_read_b128 v[216:219], v161
	ds_read_b128 v[220:223], v161 offset:1024
	ds_read_b128 v[224:227], v161 offset:2048
	ds_read_b128 v[228:231], v161 offset:3072
	global_load_lds_dwordx4 v[164:165], off
	v_add_u32_e32 v164, 0x2000, v163
	v_lshl_add_u64 v[242:243], v[136:137], 0, s[48:49]
	v_readfirstlane_b32 s51, v164
	v_lshl_add_u64 v[232:233], v[242:243], 0, s[20:21]
	s_mov_b32 m0, s51
	s_nop 0
	global_load_lds_dwordx4 v[232:233], off
	s_barrier
	s_waitcnt lgkmcnt(0)
	s_waitcnt lgkmcnt(0)
	v_mfma_f32_16x16x32_bf16 v[92:95], v[184:187], v[216:219], v[92:95]
	v_mfma_f32_16x16x32_bf16 v[88:91], v[184:187], v[224:227], v[88:91]
	v_mfma_f32_16x16x32_bf16 v[84:87], v[192:195], v[216:219], v[84:87]
	v_mfma_f32_16x16x32_bf16 v[80:83], v[192:195], v[224:227], v[80:83]
	v_mfma_f32_16x16x32_bf16 v[76:79], v[200:203], v[216:219], v[76:79]
	v_mfma_f32_16x16x32_bf16 v[72:75], v[200:203], v[224:227], v[72:75]
	v_mfma_f32_16x16x32_bf16 v[68:71], v[208:211], v[216:219], v[68:71]
	v_mfma_f32_16x16x32_bf16 v[64:67], v[208:211], v[224:227], v[64:67]
	v_mfma_f32_16x16x32_bf16 v[92:95], v[188:191], v[220:223], v[92:95]
	v_mfma_f32_16x16x32_bf16 v[88:91], v[188:191], v[228:231], v[88:91]
	v_mfma_f32_16x16x32_bf16 v[84:87], v[196:199], v[220:223], v[84:87]
	v_mfma_f32_16x16x32_bf16 v[80:83], v[196:199], v[228:231], v[80:83]
	v_mfma_f32_16x16x32_bf16 v[76:79], v[204:207], v[220:223], v[76:79]
	v_mfma_f32_16x16x32_bf16 v[72:75], v[204:207], v[228:231], v[72:75]
	v_mfma_f32_16x16x32_bf16 v[68:71], v[212:215], v[220:223], v[68:71]
	v_mfma_f32_16x16x32_bf16 v[64:67], v[212:215], v[228:231], v[64:67]
	s_barrier
	v_readfirstlane_b32 s51, v149
	v_add_u32_e32 v165, 0x2000, v149
	v_lshl_add_u64 v[232:233], v[236:237], 0, s[22:23]
	s_mov_b32 m0, s51
	v_readfirstlane_b32 s51, v165
	ds_read_b128 v[184:187], v153 offset:16384
	ds_read_b128 v[188:191], v153 offset:17408
	ds_read_b128 v[192:195], v152 offset:16384
	ds_read_b128 v[196:199], v152 offset:17408
	ds_read_b128 v[200:203], v151 offset:16384
	ds_read_b128 v[204:207], v151 offset:17408
	ds_read_b128 v[208:211], v150 offset:16384
	ds_read_b128 v[212:215], v150 offset:17408
	global_load_lds_dwordx4 v[232:233], off
	v_lshl_add_u64 v[232:233], v[238:239], 0, s[22:23]
	s_mov_b32 m0, s51
	s_nop 0
	global_load_lds_dwordx4 v[232:233], off
	s_barrier
	s_waitcnt lgkmcnt(0)
	s_waitcnt lgkmcnt(0)
	v_mfma_f32_16x16x32_bf16 v[60:63], v[184:187], v[166:169], v[60:63]
	v_mfma_f32_16x16x32_bf16 v[56:59], v[184:187], v[176:179], v[56:59]
	v_mfma_f32_16x16x32_bf16 v[52:55], v[192:195], v[166:169], v[52:55]
	v_mfma_f32_16x16x32_bf16 v[48:51], v[192:195], v[176:179], v[48:51]
	v_mfma_f32_16x16x32_bf16 v[44:47], v[200:203], v[166:169], v[44:47]
	v_mfma_f32_16x16x32_bf16 v[40:43], v[200:203], v[176:179], v[40:43]
	v_mfma_f32_16x16x32_bf16 v[36:39], v[208:211], v[166:169], v[36:39]
	v_mfma_f32_16x16x32_bf16 v[32:35], v[208:211], v[176:179], v[32:35]
	v_mfma_f32_16x16x32_bf16 v[60:63], v[188:191], v[172:175], v[60:63]
	v_mfma_f32_16x16x32_bf16 v[56:59], v[188:191], v[180:183], v[56:59]
	v_mfma_f32_16x16x32_bf16 v[52:55], v[196:199], v[172:175], v[52:55]
	v_mfma_f32_16x16x32_bf16 v[48:51], v[196:199], v[180:183], v[48:51]
	v_mfma_f32_16x16x32_bf16 v[44:47], v[204:207], v[172:175], v[44:47]
	v_mfma_f32_16x16x32_bf16 v[40:43], v[204:207], v[180:183], v[40:43]
	v_mfma_f32_16x16x32_bf16 v[36:39], v[212:215], v[172:175], v[36:39]
	v_mfma_f32_16x16x32_bf16 v[32:35], v[212:215], v[180:183], v[32:35]
	s_barrier
; #define STAGE(P, BASE, LD, br, kt) do { const char* _g = (const char*)((BASE) + (size_t)(br) * (LD) + (size_t)(kt) * 64); \
;     for (int _i = 0; _i < 2; ++_i) { int _b = tidx * 16 + _i * 8192; int _r, _c; stage_rc(_b, _r, _c); \
;       __builtin_amdgcn_global_load_lds((const unsigned*)(_g + (unsigned)((_r * (LD) + _c) * 2)), (unsigned*)((char*)(P) + _b), 16, 0, 0); } } while (0)
; #define LDA(dst, b, h) for (int m = 0; m < 4; ++m) for (int k = 0; k < 2; ++k) \
;     dst[m][k] = *reinterpret_cast<const bf16x8*>((char*)SA(b, h) + lds_byte(wr * 64 + m * 16 + fr, k * 32 + fq * 8))
; #define LDB(dst, b, h) for (int n = 0; n < 2; ++n) for (int k = 0; k < 2; ++k) \
;     dst[n][k] = *reinterpret_cast<const bf16x8*>((char*)SB(b, h) + lds_byte(wc * 32 + n * 16 + fr, k * 32 + fq * 8))
; #define MMA(ai, bj, At_, Bt_) do { __builtin_amdgcn_s_setprio(1); \
;     for (int k = 0; k < 2; ++k) for (int m = 0; m < 4; ++m) for (int n = 0; n < 2; ++n) \
;       acc[ai][bj][m][n] = __builtin_amdgcn_mfma_f32_16x16x32_bf16(At_[m][k], Bt_[n][k], acc[ai][bj][m][n], 0, 0, 0); \
;     __builtin_amdgcn_s_setprio(0); } while (0)
; #define WAIT_V(n) asm volatile("s_waitcnt vmcnt(" #n ")" ::: "memory")
; #define WAIT_L(n) asm volatile("s_waitcnt lgkmcnt(" #n ")" ::: "memory")
; #define BAR __builtin_amdgcn_s_barrier()
; #define SCHED __builtin_amdgcn_sched_barrier(0)
; template <int EPI, int lda, int ldb, int N, int K>
; __device__ __forceinline__ void gemm_phase(const u16* __restrict__ A, const u16* __restrict__ Bt, const GemmEpi ep, int wv) {
;     ...
;       STAGE(SB(0, 1), Bt, ldb, bcol + HALF, t + 2);
;       WAIT_V(6); BAR; MMA(1, 1, At, B1); BAR;
;       LDB(B0, 1, 0); SCHED; LDA(At, 1, 0); STAGE(SA(0, 1), Ab, lda, brow + HALF, t + 2);
;       WAIT_L(8); BAR; WAIT_L(0); MMA(0, 0, At, B0); BAR; SCHED;
;       LDB(B1, 1, 1); STAGE(SB(1, 0), Bt, ldb, bcol, t + 3);
;       BAR; WAIT_L(0); MMA(0, 1, At, B1); BAR;
;       LDA(At, 1, 1); STAGE(SA(1, 0), Ab, lda, brow, t + 3);
	v_add_u32_e32 v166, s63, v155
	v_add_u32_e32 v167, 0x2000, v166
	v_readfirstlane_b32 s51, v166
	v_lshl_add_u64 v[168:169], v[240:241], 0, s[24:25]
	s_mov_b32 m0, s51
	v_readfirstlane_b32 s51, v167
	global_load_lds_dwordx4 v[168:169], off
	v_lshl_add_u64 v[168:169], v[242:243], 0, s[24:25]
	s_mov_b32 m0, s51
	s_nop 0
	global_load_lds_dwordx4 v[168:169], off
	s_waitcnt vmcnt(6)
	s_barrier
	v_mfma_f32_16x16x32_bf16 v[28:31], v[184:187], v[216:219], v[28:31]
	v_mfma_f32_16x16x32_bf16 v[24:27], v[184:187], v[224:227], v[24:27]
	v_mfma_f32_16x16x32_bf16 v[20:23], v[192:195], v[216:219], v[20:23]
	v_mfma_f32_16x16x32_bf16 v[16:19], v[192:195], v[224:227], v[16:19]
	v_mfma_f32_16x16x32_bf16 v[12:15], v[200:203], v[216:219], v[12:15]
	v_mfma_f32_16x16x32_bf16 v[8:11], v[200:203], v[224:227], v[8:11]
	v_mfma_f32_16x16x32_bf16 v[4:7], v[208:211], v[216:219], v[4:7]
	v_mfma_f32_16x16x32_bf16 v[0:3], v[208:211], v[224:227], v[0:3]
	v_mfma_f32_16x16x32_bf16 v[28:31], v[188:191], v[220:223], v[28:31]
	v_mfma_f32_16x16x32_bf16 v[24:27], v[188:191], v[228:231], v[24:27]
	v_mfma_f32_16x16x32_bf16 v[20:23], v[196:199], v[220:223], v[20:23]
	v_mfma_f32_16x16x32_bf16 v[16:19], v[196:199], v[228:231], v[16:19]
	v_mfma_f32_16x16x32_bf16 v[12:15], v[204:207], v[220:223], v[12:15]
	v_mfma_f32_16x16x32_bf16 v[8:11], v[204:207], v[228:231], v[8:11]
	v_mfma_f32_16x16x32_bf16 v[4:7], v[212:215], v[220:223], v[4:7]
	v_mfma_f32_16x16x32_bf16 v[0:3], v[212:215], v[228:231], v[0:3]
	s_barrier
	ds_read_b128 v[172:175], v156
	ds_read_b128 v[176:179], v156 offset:1024
	ds_read_b128 v[180:183], v156 offset:2048
	ds_read_b128 v[184:187], v156 offset:3072
	v_add_u32_e32 v168, 0x4000, v149
	v_add_u32_e32 v169, 0x6000, v149
	v_readfirstlane_b32 s51, v168
	v_lshl_add_u64 v[220:221], v[236:237], 0, s[26:27]
	s_mov_b32 m0, s51
	v_readfirstlane_b32 s51, v169
	ds_read_b128 v[188:191], v153 offset:32768
	ds_read_b128 v[192:195], v153 offset:33792
	ds_read_b128 v[196:199], v152 offset:32768
	ds_read_b128 v[200:203], v152 offset:33792
	ds_read_b128 v[204:207], v151 offset:32768
	ds_read_b128 v[208:211], v151 offset:33792
	ds_read_b128 v[212:215], v150 offset:32768
	ds_read_b128 v[216:219], v150 offset:33792
	global_load_lds_dwordx4 v[220:221], off
	v_lshl_add_u64 v[220:221], v[238:239], 0, s[26:27]
	s_mov_b32 m0, s51
	s_nop 0
	global_load_lds_dwordx4 v[220:221], off
	s_waitcnt lgkmcnt(8)
	s_barrier
	s_waitcnt lgkmcnt(0)
	s_waitcnt lgkmcnt(0)
	v_mfma_f32_16x16x32_bf16 v[124:127], v[188:191], v[172:175], v[124:127]
	v_mfma_f32_16x16x32_bf16 v[120:123], v[188:191], v[180:183], v[120:123]
	v_mfma_f32_16x16x32_bf16 v[116:119], v[196:199], v[172:175], v[116:119]
	v_mfma_f32_16x16x32_bf16 v[112:115], v[196:199], v[180:183], v[112:115]
	v_mfma_f32_16x16x32_bf16 v[108:111], v[204:207], v[172:175], v[108:111]
	v_mfma_f32_16x16x32_bf16 v[104:107], v[204:207], v[180:183], v[104:107]
	v_mfma_f32_16x16x32_bf16 v[100:103], v[212:215], v[172:175], v[100:103]
	v_mfma_f32_16x16x32_bf16 v[96:99], v[212:215], v[180:183], v[96:99]
	v_mfma_f32_16x16x32_bf16 v[124:127], v[192:195], v[176:179], v[124:127]
	v_mfma_f32_16x16x32_bf16 v[120:123], v[192:195], v[184:187], v[120:123]
	v_mfma_f32_16x16x32_bf16 v[116:119], v[200:203], v[176:179], v[116:119]
	v_mfma_f32_16x16x32_bf16 v[112:115], v[200:203], v[184:187], v[112:115]
	v_mfma_f32_16x16x32_bf16 v[108:111], v[208:211], v[176:179], v[108:111]
	v_mfma_f32_16x16x32_bf16 v[104:107], v[208:211], v[184:187], v[104:107]
	v_mfma_f32_16x16x32_bf16 v[100:103], v[216:219], v[176:179], v[100:103]
	v_mfma_f32_16x16x32_bf16 v[96:99], v[216:219], v[184:187], v[96:99]
	s_barrier
	v_readfirstlane_b32 s51, v157
	v_add_u32_e32 v246, 0x2000, v157
	v_lshl_add_u64 v[244:245], v[240:241], 0, s[36:37]
	s_mov_b32 m0, s51
	v_readfirstlane_b32 s51, v246
	ds_read_b128 v[220:223], v154
	ds_read_b128 v[224:227], v154 offset:1024
	ds_read_b128 v[228:231], v154 offset:2048
	ds_read_b128 v[232:235], v154 offset:3072
	global_load_lds_dwordx4 v[244:245], off
	v_lshl_add_u64 v[244:245], v[242:243], 0, s[36:37]
	s_mov_b32 m0, s51
	s_nop 0
	global_load_lds_dwordx4 v[244:245], off
	s_barrier
	s_waitcnt lgkmcnt(0)
	s_waitcnt lgkmcnt(0)
	v_mfma_f32_16x16x32_bf16 v[92:95], v[188:191], v[220:223], v[92:95]
	v_mfma_f32_16x16x32_bf16 v[88:91], v[188:191], v[228:231], v[88:91]
	v_mfma_f32_16x16x32_bf16 v[84:87], v[196:199], v[220:223], v[84:87]
	v_mfma_f32_16x16x32_bf16 v[80:83], v[196:199], v[228:231], v[80:83]
	v_mfma_f32_16x16x32_bf16 v[76:79], v[204:207], v[220:223], v[76:79]
	v_mfma_f32_16x16x32_bf16 v[72:75], v[204:207], v[228:231], v[72:75]
	v_mfma_f32_16x16x32_bf16 v[68:71], v[212:215], v[220:223], v[68:71]
	v_mfma_f32_16x16x32_bf16 v[64:67], v[212:215], v[228:231], v[64:67]
	v_mfma_f32_16x16x32_bf16 v[92:95], v[192:195], v[224:227], v[92:95]
	v_mfma_f32_16x16x32_bf16 v[88:91], v[192:195], v[232:235], v[88:91]
	v_mfma_f32_16x16x32_bf16 v[84:87], v[200:203], v[224:227], v[84:87]
	v_mfma_f32_16x16x32_bf16 v[80:83], v[200:203], v[232:235], v[80:83]
	v_mfma_f32_16x16x32_bf16 v[76:79], v[208:211], v[224:227], v[76:79]
	v_mfma_f32_16x16x32_bf16 v[72:75], v[208:211], v[232:235], v[72:75]
	v_mfma_f32_16x16x32_bf16 v[68:71], v[216:219], v[224:227], v[68:71]
	v_mfma_f32_16x16x32_bf16 v[64:67], v[216:219], v[232:235], v[64:67]
	s_barrier
	v_readfirstlane_b32 s51, v158
	v_lshl_add_u64 v[236:237], v[236:237], 0, s[38:39]
	s_mov_b32 m0, s51
	v_readfirstlane_b32 s51, v159
	ds_read_b128 v[188:191], v153 offset:49152
	ds_read_b128 v[192:195], v153 offset:50176
	ds_read_b128 v[196:199], v152 offset:49152
	ds_read_b128 v[200:203], v152 offset:50176
	ds_read_b128 v[204:207], v151 offset:49152
	ds_read_b128 v[208:211], v151 offset:50176
	ds_read_b128 v[212:215], v150 offset:49152
	ds_read_b128 v[216:219], v150 offset:50176
	global_load_lds_dwordx4 v[236:237], off
	v_lshl_add_u64 v[236:237], v[238:239], 0, s[38:39]
	s_mov_b32 m0, s51
	s_nop 0
	global_load_lds_dwordx4 v[236:237], off
	s_barrier
; #define STAGE(P, BASE, LD, br, kt) do { const char* _g = (const char*)((BASE) + (size_t)(br) * (LD) + (size_t)(kt) * 64); \
;     for (int _i = 0; _i < 2; ++_i) { int _b = tidx * 16 + _i * 8192; int _r, _c; stage_rc(_b, _r, _c); \
;       __builtin_amdgcn_global_load_lds((const unsigned*)(_g + (unsigned)((_r * (LD) + _c) * 2)), (unsigned*)((char*)(P) + _b), 16, 0, 0); } } while (0)
; #define LDA(dst, b, h) for (int m = 0; m < 4; ++m) for (int k = 0; k < 2; ++k) \
;     dst[m][k] = *reinterpret_cast<const bf16x8*>((char*)SA(b, h) + lds_byte(wr * 64 + m * 16 + fr, k * 32 + fq * 8))
; #define LDB(dst, b, h) for (int n = 0; n < 2; ++n) for (int k = 0; k < 2; ++k) \
;     dst[n][k] = *reinterpret_cast<const bf16x8*>((char*)SB(b, h) + lds_byte(wc * 32 + n * 16 + fr, k * 32 + fq * 8))
; #define MMA(ai, bj, At_, Bt_) do { __builtin_amdgcn_s_setprio(1); \
;     for (int k = 0; k < 2; ++k) for (int m = 0; m < 4; ++m) for (int n = 0; n < 2; ++n) \
;       acc[ai][bj][m][n] = __builtin_amdgcn_mfma_f32_16x16x32_bf16(At_[m][k], Bt_[n][k], acc[ai][bj][m][n], 0, 0, 0); \
;     __builtin_amdgcn_s_setprio(0); } while (0)
; #define WAIT_V(n) asm volatile("s_waitcnt vmcnt(" #n ")" ::: "memory")
; #define WAIT_L(n) asm volatile("s_waitcnt lgkmcnt(" #n ")" ::: "memory")
; #define BAR __builtin_amdgcn_s_barrier()
; #define SCHED __builtin_amdgcn_sched_barrier(0)
; template <int EPI, int lda, int ldb, int N, int K>
; __device__ __forceinline__ void gemm_phase(const u16* __restrict__ A, const u16* __restrict__ Bt, const GemmEpi ep, int wv) {
;     ...
;       BAR; WAIT_L(0); MMA(1, 0, At, B0); BAR; SCHED;
;       STAGE(SB(1, 1), Bt, ldb, bcol + HALF, t + 3);
;       WAIT_V(6); BAR; MMA(1, 1, At, B1); BAR;
;     }
;     { LDB(B0, 0, 0); LDA(At, 0, 0); STAGE(SA(1, 1), Ab, lda, brow + HALF, nt - 1);
;       BAR; WAIT_L(0); MMA(0, 0, At, B0); BAR;
;       LDB(B1, 0, 1); BAR; WAIT_L(0); MMA(0, 1, At, B1); BAR;
	s_waitcnt lgkmcnt(0)
	s_waitcnt lgkmcnt(0)
	v_mfma_f32_16x16x32_bf16 v[60:63], v[188:191], v[172:175], v[60:63]
	v_mfma_f32_16x16x32_bf16 v[56:59], v[188:191], v[180:183], v[56:59]
	v_mfma_f32_16x16x32_bf16 v[52:55], v[196:199], v[172:175], v[52:55]
	v_mfma_f32_16x16x32_bf16 v[48:51], v[196:199], v[180:183], v[48:51]
	v_mfma_f32_16x16x32_bf16 v[44:47], v[204:207], v[172:175], v[44:47]
	v_mfma_f32_16x16x32_bf16 v[40:43], v[204:207], v[180:183], v[40:43]
	v_mfma_f32_16x16x32_bf16 v[36:39], v[212:215], v[172:175], v[36:39]
	v_mfma_f32_16x16x32_bf16 v[32:35], v[212:215], v[180:183], v[32:35]
	v_mfma_f32_16x16x32_bf16 v[60:63], v[192:195], v[176:179], v[60:63]
	v_mfma_f32_16x16x32_bf16 v[56:59], v[192:195], v[184:187], v[56:59]
	v_mfma_f32_16x16x32_bf16 v[52:55], v[200:203], v[176:179], v[52:55]
	v_mfma_f32_16x16x32_bf16 v[48:51], v[200:203], v[184:187], v[48:51]
	v_mfma_f32_16x16x32_bf16 v[44:47], v[208:211], v[176:179], v[44:47]
	v_mfma_f32_16x16x32_bf16 v[40:43], v[208:211], v[184:187], v[40:43]
	v_mfma_f32_16x16x32_bf16 v[36:39], v[216:219], v[176:179], v[36:39]
	v_mfma_f32_16x16x32_bf16 v[32:35], v[216:219], v[184:187], v[32:35]
	s_barrier
	v_readfirstlane_b32 s51, v160
	v_add_u32_e32 v174, 0x2000, v160
	v_lshl_add_u64 v[172:173], v[240:241], 0, s[42:43]
	s_mov_b32 m0, s51
	v_readfirstlane_b32 s51, v174
	global_load_lds_dwordx4 v[172:173], off
	v_lshl_add_u64 v[172:173], v[242:243], 0, s[42:43]
	s_mov_b32 m0, s51
	s_nop 0
	global_load_lds_dwordx4 v[172:173], off
	s_waitcnt vmcnt(6)
	s_barrier
	v_mfma_f32_16x16x32_bf16 v[28:31], v[188:191], v[220:223], v[28:31]
	v_mfma_f32_16x16x32_bf16 v[24:27], v[188:191], v[228:231], v[24:27]
	v_mfma_f32_16x16x32_bf16 v[20:23], v[196:199], v[220:223], v[20:23]
	v_mfma_f32_16x16x32_bf16 v[16:19], v[196:199], v[228:231], v[16:19]
	v_mfma_f32_16x16x32_bf16 v[12:15], v[204:207], v[220:223], v[12:15]
	v_mfma_f32_16x16x32_bf16 v[8:11], v[204:207], v[228:231], v[8:11]
	v_mfma_f32_16x16x32_bf16 v[4:7], v[212:215], v[220:223], v[4:7]
	v_mfma_f32_16x16x32_bf16 v[0:3], v[212:215], v[228:231], v[0:3]
	v_mfma_f32_16x16x32_bf16 v[28:31], v[192:195], v[224:227], v[28:31]
	v_mfma_f32_16x16x32_bf16 v[24:27], v[192:195], v[232:235], v[24:27]
	v_mfma_f32_16x16x32_bf16 v[20:23], v[200:203], v[224:227], v[20:23]
	v_mfma_f32_16x16x32_bf16 v[16:19], v[200:203], v[232:235], v[16:19]
	v_mfma_f32_16x16x32_bf16 v[12:15], v[208:211], v[224:227], v[12:15]
	v_mfma_f32_16x16x32_bf16 v[8:11], v[208:211], v[232:235], v[8:11]
	v_mfma_f32_16x16x32_bf16 v[4:7], v[216:219], v[224:227], v[4:7]
	v_mfma_f32_16x16x32_bf16 v[0:3], v[216:219], v[232:235], v[0:3]
	s_barrier
	s_add_i32 s50, s50, 2
	s_add_u32 s48, s48, 0x100
	s_addc_u32 s49, s49, 0
	s_cmp_gt_u32 s50, 27
	s_cbranch_scc0 .LBB0_340
	s_add_i32 s48, s46, 0x80
	s_mul_hi_i32 s49, s48, 0x1080
	s_mulk_i32 s48, 0x1080
	s_add_u32 s48, s31, s48
	s_addc_u32 s49, s56, s49
	v_lshl_add_u64 v[158:159], s[48:49], 0, v[128:129]
	v_readfirstlane_b32 s50, v170
	v_lshl_add_u64 v[158:159], v[158:159], 0, s[44:45]
	s_mov_b32 m0, s50
	ds_read_b128 v[134:137], v162
	ds_read_b128 v[138:141], v162 offset:1024
	ds_read_b128 v[172:175], v162 offset:2048
	ds_read_b128 v[176:179], v162 offset:3072
	ds_read_b128 v[180:183], v153
	ds_read_b128 v[184:187], v153 offset:1024
	ds_read_b128 v[188:191], v152
	ds_read_b128 v[192:195], v152 offset:1024
	ds_read_b128 v[196:199], v151
	ds_read_b128 v[200:203], v151 offset:1024
	ds_read_b128 v[204:207], v150
	ds_read_b128 v[208:211], v150 offset:1024
	global_load_lds_dwordx4 v[158:159], off
	v_lshl_add_u64 v[158:159], s[48:49], 0, v[132:133]
	v_readfirstlane_b32 s48, v171
	v_lshl_add_u64 v[158:159], v[158:159], 0, s[44:45]
	s_mov_b32 m0, s48
	s_nop 0
	global_load_lds_dwordx4 v[158:159], off
	s_barrier
	s_waitcnt lgkmcnt(0)
	s_waitcnt lgkmcnt(0)
	v_mfma_f32_16x16x32_bf16 v[124:127], v[180:183], v[134:137], v[124:127]
	v_mfma_f32_16x16x32_bf16 v[120:123], v[180:183], v[172:175], v[120:123]
	v_mfma_f32_16x16x32_bf16 v[116:119], v[188:191], v[134:137], v[116:119]
	v_mfma_f32_16x16x32_bf16 v[112:115], v[188:191], v[172:175], v[112:115]
	v_mfma_f32_16x16x32_bf16 v[108:111], v[196:199], v[134:137], v[108:111]
	v_mfma_f32_16x16x32_bf16 v[104:107], v[196:199], v[172:175], v[104:107]
	v_mfma_f32_16x16x32_bf16 v[100:103], v[204:207], v[134:137], v[100:103]
	v_mfma_f32_16x16x32_bf16 v[96:99], v[204:207], v[172:175], v[96:99]
	v_mfma_f32_16x16x32_bf16 v[124:127], v[184:187], v[138:141], v[124:127]
	v_mfma_f32_16x16x32_bf16 v[120:123], v[184:187], v[176:179], v[120:123]
	v_mfma_f32_16x16x32_bf16 v[116:119], v[192:195], v[138:141], v[116:119]
	v_mfma_f32_16x16x32_bf16 v[112:115], v[192:195], v[176:179], v[112:115]
	v_mfma_f32_16x16x32_bf16 v[108:111], v[200:203], v[138:141], v[108:111]
	v_mfma_f32_16x16x32_bf16 v[104:107], v[200:203], v[176:179], v[104:107]
	v_mfma_f32_16x16x32_bf16 v[100:103], v[208:211], v[138:141], v[100:103]
	v_mfma_f32_16x16x32_bf16 v[96:99], v[208:211], v[176:179], v[96:99]
	s_barrier
	ds_read_b128 v[212:215], v161
	ds_read_b128 v[216:219], v161 offset:1024
	ds_read_b128 v[220:223], v161 offset:2048
	ds_read_b128 v[158:161], v161 offset:3072
	s_barrier
; #define LDA(dst, b, h) for (int m = 0; m < 4; ++m) for (int k = 0; k < 2; ++k) \
;     dst[m][k] = *reinterpret_cast<const bf16x8*>((char*)SA(b, h) + lds_byte(wr * 64 + m * 16 + fr, k * 32 + fq * 8))
; #define LDB(dst, b, h) for (int n = 0; n < 2; ++n) for (int k = 0; k < 2; ++k) \
;     dst[n][k] = *reinterpret_cast<const bf16x8*>((char*)SB(b, h) + lds_byte(wc * 32 + n * 16 + fr, k * 32 + fq * 8))
; #define MMA(ai, bj, At_, Bt_) do { __builtin_amdgcn_s_setprio(1); \
;     for (int k = 0; k < 2; ++k) for (int m = 0; m < 4; ++m) for (int n = 0; n < 2; ++n) \
;       acc[ai][bj][m][n] = __builtin_amdgcn_mfma_f32_16x16x32_bf16(At_[m][k], Bt_[n][k], acc[ai][bj][m][n], 0, 0, 0); \
;     __builtin_amdgcn_s_setprio(0); } while (0)
; #define WAIT_V(n) asm volatile("s_waitcnt vmcnt(" #n ")" ::: "memory")
; #define WAIT_L(n) asm volatile("s_waitcnt lgkmcnt(" #n ")" ::: "memory")
; #define BAR __builtin_amdgcn_s_barrier()
; template <int EPI, int lda, int ldb, int N, int K>
; __device__ __forceinline__ void gemm_phase(const u16* __restrict__ A, const u16* __restrict__ Bt, const GemmEpi ep, int wv) {
;     ...
;       LDB(B1, 0, 1); BAR; WAIT_L(0); MMA(0, 1, At, B1); BAR;
;       LDA(At, 0, 1); WAIT_V(4); BAR; WAIT_L(0); MMA(1, 0, At, B0); MMA(1, 1, At, B1); BAR; }
;     { LDB(B0, 1, 0); LDA(At, 1, 0); WAIT_V(2); BAR; WAIT_L(0); MMA(0, 0, At, B0); BAR;
	s_waitcnt lgkmcnt(0)
	s_waitcnt lgkmcnt(0)
	v_mfma_f32_16x16x32_bf16 v[92:95], v[180:183], v[212:215], v[92:95]
	v_mfma_f32_16x16x32_bf16 v[88:91], v[180:183], v[220:223], v[88:91]
	v_mfma_f32_16x16x32_bf16 v[76:79], v[196:199], v[212:215], v[76:79]
	v_mfma_f32_16x16x32_bf16 v[72:75], v[196:199], v[220:223], v[72:75]
	v_mfma_f32_16x16x32_bf16 v[68:71], v[204:207], v[212:215], v[68:71]
	v_mfma_f32_16x16x32_bf16 v[64:67], v[204:207], v[220:223], v[64:67]
	v_mfma_f32_16x16x32_bf16 v[84:87], v[188:191], v[212:215], v[84:87]
	v_mfma_f32_16x16x32_bf16 v[80:83], v[188:191], v[220:223], v[80:83]
	v_mfma_f32_16x16x32_bf16 v[92:95], v[184:187], v[216:219], v[92:95]
	v_mfma_f32_16x16x32_bf16 v[88:91], v[184:187], v[158:161], v[88:91]
	v_mfma_f32_16x16x32_bf16 v[76:79], v[200:203], v[216:219], v[76:79]
	v_mfma_f32_16x16x32_bf16 v[72:75], v[200:203], v[158:161], v[72:75]
	v_mfma_f32_16x16x32_bf16 v[68:71], v[208:211], v[216:219], v[68:71]
	v_mfma_f32_16x16x32_bf16 v[64:67], v[208:211], v[158:161], v[64:67]
	v_mfma_f32_16x16x32_bf16 v[180:183], v[192:195], v[216:219], v[84:87]
	v_mfma_f32_16x16x32_bf16 v[184:187], v[192:195], v[158:161], v[80:83]
	s_barrier
	s_nop 0
	ds_read_b128 v[80:83], v153 offset:16384
	ds_read_b128 v[84:87], v153 offset:17408
	ds_read_b128 v[188:191], v152 offset:16384
	ds_read_b128 v[192:195], v152 offset:17408
	ds_read_b128 v[196:199], v151 offset:16384
	ds_read_b128 v[200:203], v151 offset:17408
	ds_read_b128 v[204:207], v150 offset:16384
	ds_read_b128 v[208:211], v150 offset:17408
	s_waitcnt vmcnt(4)
	s_barrier
	s_waitcnt lgkmcnt(0)
	s_waitcnt lgkmcnt(0)
	v_mfma_f32_16x16x32_bf16 v[60:63], v[80:83], v[134:137], v[60:63]
	v_mfma_f32_16x16x32_bf16 v[44:47], v[196:199], v[134:137], v[44:47]
	v_mfma_f32_16x16x32_bf16 v[40:43], v[196:199], v[172:175], v[40:43]
	v_mfma_f32_16x16x32_bf16 v[36:39], v[204:207], v[134:137], v[36:39]
	v_mfma_f32_16x16x32_bf16 v[32:35], v[204:207], v[172:175], v[32:35]
	v_mfma_f32_16x16x32_bf16 v[56:59], v[80:83], v[172:175], v[56:59]
	v_mfma_f32_16x16x32_bf16 v[52:55], v[188:191], v[134:137], v[52:55]
	v_mfma_f32_16x16x32_bf16 v[48:51], v[188:191], v[172:175], v[48:51]
	v_mfma_f32_16x16x32_bf16 v[60:63], v[84:87], v[138:141], v[60:63]
	v_mfma_f32_16x16x32_bf16 v[44:47], v[200:203], v[138:141], v[44:47]
	v_mfma_f32_16x16x32_bf16 v[40:43], v[200:203], v[176:179], v[40:43]
	v_mfma_f32_16x16x32_bf16 v[36:39], v[208:211], v[138:141], v[36:39]
	v_mfma_f32_16x16x32_bf16 v[32:35], v[208:211], v[176:179], v[32:35]
	v_mfma_f32_16x16x32_bf16 v[134:137], v[84:87], v[176:179], v[56:59]
	v_mfma_f32_16x16x32_bf16 v[170:173], v[192:195], v[138:141], v[52:55]
	v_mfma_f32_16x16x32_bf16 v[224:227], v[192:195], v[176:179], v[48:51]
	v_mfma_f32_16x16x32_bf16 v[28:31], v[80:83], v[212:215], v[28:31]
	v_mfma_f32_16x16x32_bf16 v[20:23], v[188:191], v[212:215], v[20:23]
	v_mfma_f32_16x16x32_bf16 v[12:15], v[196:199], v[212:215], v[12:15]
	v_mfma_f32_16x16x32_bf16 v[4:7], v[204:207], v[212:215], v[4:7]
	v_mfma_f32_16x16x32_bf16 v[24:27], v[80:83], v[220:223], v[24:27]
	v_mfma_f32_16x16x32_bf16 v[16:19], v[188:191], v[220:223], v[16:19]
	v_mfma_f32_16x16x32_bf16 v[8:11], v[196:199], v[220:223], v[8:11]
	v_mfma_f32_16x16x32_bf16 v[0:3], v[204:207], v[220:223], v[0:3]
	v_mfma_f32_16x16x32_bf16 v[28:31], v[84:87], v[216:219], v[28:31]
	v_mfma_f32_16x16x32_bf16 v[20:23], v[192:195], v[216:219], v[20:23]
	v_mfma_f32_16x16x32_bf16 v[12:15], v[200:203], v[216:219], v[12:15]
	v_mfma_f32_16x16x32_bf16 v[4:7], v[208:211], v[216:219], v[4:7]
	v_mfma_f32_16x16x32_bf16 v[138:141], v[84:87], v[158:161], v[24:27]
	v_mfma_f32_16x16x32_bf16 v[174:177], v[192:195], v[158:161], v[16:19]
	v_mfma_f32_16x16x32_bf16 v[188:191], v[200:203], v[158:161], v[8:11]
	v_mfma_f32_16x16x32_bf16 v[158:161], v[208:211], v[158:161], v[0:3]
	s_barrier
	s_nop 0
	ds_read_b128 v[0:3], v156
	ds_read_b128 v[8:11], v156 offset:1024
	ds_read_b128 v[16:19], v156 offset:2048
	ds_read_b128 v[192:195], v156 offset:3072
	ds_read_b128 v[24:27], v153 offset:32768
	ds_read_b128 v[56:59], v153 offset:33792
	ds_read_b128 v[196:199], v152 offset:32768
	ds_read_b128 v[200:203], v152 offset:33792
	ds_read_b128 v[204:207], v151 offset:32768
	ds_read_b128 v[208:211], v151 offset:33792
	ds_read_b128 v[212:215], v150 offset:32768
	ds_read_b128 v[216:219], v150 offset:33792
	s_waitcnt vmcnt(2)
	s_barrier
; #define LDA(dst, b, h) for (int m = 0; m < 4; ++m) for (int k = 0; k < 2; ++k) \
;     dst[m][k] = *reinterpret_cast<const bf16x8*>((char*)SA(b, h) + lds_byte(wr * 64 + m * 16 + fr, k * 32 + fq * 8))
; #define LDB(dst, b, h) for (int n = 0; n < 2; ++n) for (int k = 0; k < 2; ++k) \
;     dst[n][k] = *reinterpret_cast<const bf16x8*>((char*)SB(b, h) + lds_byte(wc * 32 + n * 16 + fr, k * 32 + fq * 8))
; #define MMA(ai, bj, At_, Bt_) do { __builtin_amdgcn_s_setprio(1); \
;     for (int k = 0; k < 2; ++k) for (int m = 0; m < 4; ++m) for (int n = 0; n < 2; ++n) \
;       acc[ai][bj][m][n] = __builtin_amdgcn_mfma_f32_16x16x32_bf16(At_[m][k], Bt_[n][k], acc[ai][bj][m][n], 0, 0, 0); \
;     __builtin_amdgcn_s_setprio(0); } while (0)
; #define WAIT_V(n) asm volatile("s_waitcnt vmcnt(" #n ")" ::: "memory")
; #define WAIT_L(n) asm volatile("s_waitcnt lgkmcnt(" #n ")" ::: "memory")
; #define BAR __builtin_amdgcn_s_barrier()
; template <int EPI, int lda, int ldb, int N, int K>
; __device__ __forceinline__ void gemm_phase(const u16* __restrict__ A, const u16* __restrict__ Bt, const GemmEpi ep, int wv) {
;     ...
;     { LDB(B0, 1, 0); LDA(At, 1, 0); WAIT_V(2); BAR; WAIT_L(0); MMA(0, 0, At, B0); BAR;
;       LDB(B1, 1, 1); WAIT_V(0); BAR; WAIT_L(0); MMA(0, 1, At, B1); BAR;
;       LDA(At, 1, 1); BAR; WAIT_L(0); MMA(1, 0, At, B0); MMA(1, 1, At, B1); BAR; }
;     if (wr == 0) BAR;
	s_waitcnt lgkmcnt(0)
	s_waitcnt lgkmcnt(0)
	v_mfma_f32_16x16x32_bf16 v[48:51], v[24:27], v[0:3], v[124:127]
	v_mfma_f32_16x16x32_bf16 v[52:55], v[24:27], v[16:19], v[120:123]
	v_mfma_f32_16x16x32_bf16 v[80:83], v[196:199], v[0:3], v[116:119]
	v_mfma_f32_16x16x32_bf16 v[84:87], v[196:199], v[16:19], v[112:115]
	v_mfma_f32_16x16x32_bf16 v[108:111], v[204:207], v[0:3], v[108:111]
	v_mfma_f32_16x16x32_bf16 v[104:107], v[204:207], v[16:19], v[104:107]
	v_mfma_f32_16x16x32_bf16 v[112:115], v[212:215], v[0:3], v[100:103]
	v_mfma_f32_16x16x32_bf16 v[120:123], v[212:215], v[16:19], v[96:99]
	v_mfma_f32_16x16x32_bf16 v[124:127], v[56:59], v[8:11], v[48:51]
	v_mfma_f32_16x16x32_bf16 v[116:119], v[56:59], v[192:195], v[52:55]
	v_mfma_f32_16x16x32_bf16 v[100:103], v[200:203], v[8:11], v[80:83]
	v_mfma_f32_16x16x32_bf16 v[96:99], v[200:203], v[192:195], v[84:87]
	v_mfma_f32_16x16x32_bf16 v[84:87], v[208:211], v[8:11], v[108:111]
	v_mfma_f32_16x16x32_bf16 v[80:83], v[208:211], v[192:195], v[104:107]
	v_mfma_f32_16x16x32_bf16 v[52:55], v[216:219], v[8:11], v[112:115]
	v_mfma_f32_16x16x32_bf16 v[48:51], v[216:219], v[192:195], v[120:123]
	s_barrier
	ds_read_b128 v[220:223], v154
	ds_read_b128 v[228:231], v154 offset:1024
	ds_read_b128 v[232:235], v154 offset:2048
	ds_read_b128 v[154:157], v154 offset:3072
	s_waitcnt vmcnt(0)
	s_barrier
	s_waitcnt lgkmcnt(0)
	s_waitcnt lgkmcnt(0)
	v_mfma_f32_16x16x32_bf16 v[92:95], v[24:27], v[220:223], v[92:95]
	v_mfma_f32_16x16x32_bf16 v[24:27], v[24:27], v[232:235], v[88:91]
	v_mfma_f32_16x16x32_bf16 v[88:91], v[196:199], v[220:223], v[180:183]
	v_mfma_f32_16x16x32_bf16 v[104:107], v[196:199], v[232:235], v[184:187]
	v_mfma_f32_16x16x32_bf16 v[76:79], v[204:207], v[220:223], v[76:79]
	v_mfma_f32_16x16x32_bf16 v[72:75], v[204:207], v[232:235], v[72:75]
	v_mfma_f32_16x16x32_bf16 v[68:71], v[212:215], v[220:223], v[68:71]
	v_mfma_f32_16x16x32_bf16 v[64:67], v[212:215], v[232:235], v[64:67]
	v_mfma_f32_16x16x32_bf16 v[120:123], v[56:59], v[228:231], v[92:95]
	v_mfma_f32_16x16x32_bf16 v[112:115], v[56:59], v[154:157], v[24:27]
	v_mfma_f32_16x16x32_bf16 v[108:111], v[200:203], v[228:231], v[88:91]
	v_mfma_f32_16x16x32_bf16 v[104:107], v[200:203], v[154:157], v[104:107]
	v_mfma_f32_16x16x32_bf16 v[92:95], v[208:211], v[228:231], v[76:79]
	v_mfma_f32_16x16x32_bf16 v[88:91], v[208:211], v[154:157], v[72:75]
	v_mfma_f32_16x16x32_bf16 v[68:71], v[216:219], v[228:231], v[68:71]
	v_mfma_f32_16x16x32_bf16 v[56:59], v[216:219], v[154:157], v[64:67]
	s_barrier
	s_nop 0
	ds_read_b128 v[64:67], v153 offset:49152
	ds_read_b128 v[178:181], v153 offset:50176
	ds_read_b128 v[76:79], v152 offset:49152
	ds_read_b128 v[182:185], v152 offset:50176
	ds_read_b128 v[196:199], v151 offset:49152
	ds_read_b128 v[200:203], v151 offset:50176
	ds_read_b128 v[204:207], v150 offset:49152
	ds_read_b128 v[150:153], v150 offset:50176
	s_barrier
	s_waitcnt lgkmcnt(0)
	s_waitcnt lgkmcnt(0)
	v_mfma_f32_16x16x32_bf16 v[24:27], v[64:67], v[0:3], v[60:63]
	v_mfma_f32_16x16x32_bf16 v[60:63], v[64:67], v[16:19], v[134:137]
	v_mfma_f32_16x16x32_bf16 v[134:137], v[76:79], v[0:3], v[170:173]
	v_mfma_f32_16x16x32_bf16 v[170:173], v[76:79], v[16:19], v[224:227]
	v_mfma_f32_16x16x32_bf16 v[44:47], v[196:199], v[0:3], v[44:47]
	v_mfma_f32_16x16x32_bf16 v[208:211], v[196:199], v[16:19], v[40:43]
	v_mfma_f32_16x16x32_bf16 v[0:3], v[204:207], v[0:3], v[36:39]
	v_mfma_f32_16x16x32_bf16 v[36:39], v[204:207], v[16:19], v[32:35]
	v_mfma_f32_16x16x32_bf16 v[72:75], v[178:181], v[8:11], v[24:27]
	v_mfma_f32_16x16x32_bf16 v[60:63], v[178:181], v[192:195], v[60:63]
	v_mfma_f32_16x16x32_bf16 v[40:43], v[182:185], v[8:11], v[134:137]
	v_mfma_f32_16x16x32_bf16 v[32:35], v[182:185], v[192:195], v[170:173]
	v_mfma_f32_16x16x32_bf16 v[24:27], v[200:203], v[8:11], v[44:47]
	v_mfma_f32_16x16x32_bf16 v[16:19], v[200:203], v[192:195], v[208:211]
	v_mfma_f32_16x16x32_bf16 v[8:11], v[150:153], v[8:11], v[0:3]
	v_mfma_f32_16x16x32_bf16 v[0:3], v[150:153], v[192:195], v[36:39]
	v_mfma_f32_16x16x32_bf16 v[28:31], v[64:67], v[220:223], v[28:31]
	v_mfma_f32_16x16x32_bf16 v[36:39], v[64:67], v[232:235], v[138:141]
	v_mfma_f32_16x16x32_bf16 v[20:23], v[76:79], v[220:223], v[20:23]
	v_mfma_f32_16x16x32_bf16 v[134:137], v[76:79], v[232:235], v[174:177]
	v_mfma_f32_16x16x32_bf16 v[12:15], v[196:199], v[220:223], v[12:15]
	v_mfma_f32_16x16x32_bf16 v[138:141], v[196:199], v[232:235], v[188:191]
	v_mfma_f32_16x16x32_bf16 v[4:7], v[204:207], v[220:223], v[4:7]
	v_mfma_f32_16x16x32_bf16 v[158:161], v[204:207], v[232:235], v[158:161]
	v_mfma_f32_16x16x32_bf16 v[76:79], v[178:181], v[228:231], v[28:31]
	v_mfma_f32_16x16x32_bf16 v[64:67], v[178:181], v[154:157], v[36:39]
	v_mfma_f32_16x16x32_bf16 v[44:47], v[182:185], v[228:231], v[20:23]
	v_mfma_f32_16x16x32_bf16 v[36:39], v[182:185], v[154:157], v[134:137]
	v_mfma_f32_16x16x32_bf16 v[28:31], v[200:203], v[228:231], v[12:15]
	v_mfma_f32_16x16x32_bf16 v[20:23], v[200:203], v[154:157], v[138:141]
	v_mfma_f32_16x16x32_bf16 v[12:15], v[150:153], v[228:231], v[4:7]
	v_mfma_f32_16x16x32_bf16 v[4:7], v[150:153], v[154:157], v[158:161]
	v_cmp_gt_u32_e32 vcc, s64, v130
	s_barrier
	s_and_saveexec_b64 s[48:49], vcc
	s_cbranch_execz .LBB0_343
	s_barrier

; #define STAGE(P, BASE, LD, br, kt) do { const char* _g = (const char*)((BASE) + (size_t)(br) * (LD) + (size_t)(kt) * 64); \
;     for (int _i = 0; _i < 2; ++_i) { int _b = tidx * 16 + _i * 8192; int _r, _c; stage_rc(_b, _r, _c); \
;       __builtin_amdgcn_global_load_lds((const unsigned*)(_g + (unsigned)((_r * (LD) + _c) * 2)), (unsigned*)((char*)(P) + _b), 16, 0, 0); } } while (0)
; #define LDA(dst, b, h) for (int m = 0; m < 4; ++m) for (int k = 0; k < 2; ++k) \
;     dst[m][k] = *reinterpret_cast<const bf16x8*>((char*)SA(b, h) + lds_byte(wr * 64 + m * 16 + fr, k * 32 + fq * 8))
; #define LDB(dst, b, h) for (int n = 0; n < 2; ++n) for (int k = 0; k < 2; ++k) \
;     dst[n][k] = *reinterpret_cast<const bf16x8*>((char*)SB(b, h) + lds_byte(wc * 32 + n * 16 + fr, k * 32 + fq * 8))
; #define MMA(ai, bj, At_, Bt_) do { __builtin_amdgcn_s_setprio(1); \
;     for (int k = 0; k < 2; ++k) for (int m = 0; m < 4; ++m) for (int n = 0; n < 2; ++n) \
;       acc[ai][bj][m][n] = __builtin_amdgcn_mfma_f32_16x16x32_bf16(At_[m][k], Bt_[n][k], acc[ai][bj][m][n], 0, 0, 0); \
;     __builtin_amdgcn_s_setprio(0); } while (0)
; #define WAIT_L(n) asm volatile("s_waitcnt lgkmcnt(" #n ")" ::: "memory")
; #define BAR __builtin_amdgcn_s_barrier()
; #define SCHED __builtin_amdgcn_sched_barrier(0)
; template <int EPI, int lda, int ldb, int N, int K>
; __device__ __forceinline__ void gemm_phase(const u16* __restrict__ A, const u16* __restrict__ Bt, const GemmEpi ep, int wv) {
;     ...
;     for (int t = 0; t < nt - 2; t += 2) {
;       LDB(B0, 0, 0); SCHED; LDA(At, 0, 0); STAGE(SA(1, 1), Ab, lda, brow + HALF, t + 1);
;       WAIT_L(8); BAR; WAIT_L(0); MMA(0, 0, At, B0); BAR; SCHED;
;       LDB(B1, 0, 1); STAGE(SB(0, 0), Bt, ldb, bcol, t + 2);
;       BAR; WAIT_L(0); MMA(0, 1, At, B1); BAR;
;       LDA(At, 0, 1); STAGE(SA(0, 0), Ab, lda, brow, t + 2);
;       BAR; WAIT_L(0); MMA(1, 0, At, B0); BAR; SCHED;
.LBB0_654:
	ds_read_b128 v[164:167], v160
	ds_read_b128 v[170:173], v160 offset:1024
	ds_read_b128 v[174:177], v160 offset:2048
	ds_read_b128 v[178:181], v160 offset:3072
	v_add_u32_e32 v168, 0xc000, v143
	v_lshl_add_u64 v[234:235], v[138:139], 0, s[52:53]
	v_readfirstlane_b32 s55, v168
	v_add_u32_e32 v169, 0xe000, v143
	v_lshl_add_u64 v[162:163], v[234:235], 0, s[20:21]
	s_mov_b32 m0, s55
	v_lshl_add_u64 v[236:237], v[140:141], 0, s[52:53]
	v_readfirstlane_b32 s55, v169
	ds_read_b128 v[182:185], v151
	ds_read_b128 v[186:189], v151 offset:1024
	ds_read_b128 v[190:193], v150
	ds_read_b128 v[194:197], v150 offset:1024
	ds_read_b128 v[198:201], v149
	ds_read_b128 v[202:205], v149 offset:1024
	ds_read_b128 v[206:209], v148
	ds_read_b128 v[210:213], v148 offset:1024
	global_load_lds_dwordx4 v[162:163], off
	v_lshl_add_u64 v[162:163], v[236:237], 0, s[20:21]
	s_mov_b32 m0, s55
	s_nop 0
	global_load_lds_dwordx4 v[162:163], off
	s_waitcnt lgkmcnt(8)
	s_barrier
	s_waitcnt lgkmcnt(0)
	s_waitcnt lgkmcnt(0)
	v_mfma_f32_16x16x32_bf16 v[124:127], v[164:167], v[182:185], v[124:127]
	v_mfma_f32_16x16x32_bf16 v[120:123], v[174:177], v[182:185], v[120:123]
	v_mfma_f32_16x16x32_bf16 v[116:119], v[164:167], v[190:193], v[116:119]
	v_mfma_f32_16x16x32_bf16 v[112:115], v[174:177], v[190:193], v[112:115]
	v_mfma_f32_16x16x32_bf16 v[108:111], v[164:167], v[198:201], v[108:111]
	v_mfma_f32_16x16x32_bf16 v[104:107], v[174:177], v[198:201], v[104:107]
	v_mfma_f32_16x16x32_bf16 v[100:103], v[164:167], v[206:209], v[100:103]
	v_mfma_f32_16x16x32_bf16 v[96:99], v[174:177], v[206:209], v[96:99]
	v_mfma_f32_16x16x32_bf16 v[124:127], v[170:173], v[186:189], v[124:127]
	v_mfma_f32_16x16x32_bf16 v[120:123], v[178:181], v[186:189], v[120:123]
	v_mfma_f32_16x16x32_bf16 v[116:119], v[170:173], v[194:197], v[116:119]
	v_mfma_f32_16x16x32_bf16 v[112:115], v[178:181], v[194:197], v[112:115]
	v_mfma_f32_16x16x32_bf16 v[108:111], v[170:173], v[202:205], v[108:111]
	v_mfma_f32_16x16x32_bf16 v[104:107], v[178:181], v[202:205], v[104:107]
	v_mfma_f32_16x16x32_bf16 v[100:103], v[170:173], v[210:213], v[100:103]
	v_mfma_f32_16x16x32_bf16 v[96:99], v[178:181], v[210:213], v[96:99]
	s_barrier
	v_add_u32_e32 v161, s65, v153
	v_lshl_add_u64 v[238:239], v[134:135], 0, s[52:53]
	v_readfirstlane_b32 s55, v161
	v_lshl_add_u64 v[162:163], v[238:239], 0, s[22:23]
	s_mov_b32 m0, s55
	ds_read_b128 v[214:217], v159
	ds_read_b128 v[218:221], v159 offset:1024
	ds_read_b128 v[222:225], v159 offset:2048
	ds_read_b128 v[226:229], v159 offset:3072
	global_load_lds_dwordx4 v[162:163], off
	v_add_u32_e32 v162, 0x2000, v161
	v_lshl_add_u64 v[240:241], v[136:137], 0, s[52:53]
	v_readfirstlane_b32 s55, v162
	v_lshl_add_u64 v[230:231], v[240:241], 0, s[22:23]
	s_mov_b32 m0, s55
	s_nop 0
	global_load_lds_dwordx4 v[230:231], off
	s_barrier
	s_waitcnt lgkmcnt(0)
	s_waitcnt lgkmcnt(0)
	v_mfma_f32_16x16x32_bf16 v[92:95], v[214:217], v[182:185], v[92:95]
	v_mfma_f32_16x16x32_bf16 v[88:91], v[222:225], v[182:185], v[88:91]
	v_mfma_f32_16x16x32_bf16 v[84:87], v[214:217], v[190:193], v[84:87]
	v_mfma_f32_16x16x32_bf16 v[80:83], v[222:225], v[190:193], v[80:83]
	v_mfma_f32_16x16x32_bf16 v[76:79], v[214:217], v[198:201], v[76:79]
	v_mfma_f32_16x16x32_bf16 v[72:75], v[222:225], v[198:201], v[72:75]
	v_mfma_f32_16x16x32_bf16 v[68:71], v[214:217], v[206:209], v[68:71]
	v_mfma_f32_16x16x32_bf16 v[64:67], v[222:225], v[206:209], v[64:67]
	v_mfma_f32_16x16x32_bf16 v[92:95], v[218:221], v[186:189], v[92:95]
	v_mfma_f32_16x16x32_bf16 v[88:91], v[226:229], v[186:189], v[88:91]
	v_mfma_f32_16x16x32_bf16 v[84:87], v[218:221], v[194:197], v[84:87]
	v_mfma_f32_16x16x32_bf16 v[80:83], v[226:229], v[194:197], v[80:83]
	v_mfma_f32_16x16x32_bf16 v[76:79], v[218:221], v[202:205], v[76:79]
	v_mfma_f32_16x16x32_bf16 v[72:75], v[226:229], v[202:205], v[72:75]
	v_mfma_f32_16x16x32_bf16 v[68:71], v[218:221], v[210:213], v[68:71]
	v_mfma_f32_16x16x32_bf16 v[64:67], v[226:229], v[210:213], v[64:67]
	s_barrier
	v_readfirstlane_b32 s55, v143
	v_add_u32_e32 v163, 0x2000, v143
	v_lshl_add_u64 v[230:231], v[234:235], 0, s[24:25]
	s_mov_b32 m0, s55
	v_readfirstlane_b32 s55, v163
	ds_read_b128 v[182:185], v151 offset:16384
	ds_read_b128 v[186:189], v151 offset:17408
	ds_read_b128 v[190:193], v150 offset:16384
	ds_read_b128 v[194:197], v150 offset:17408
	ds_read_b128 v[198:201], v149 offset:16384
	ds_read_b128 v[202:205], v149 offset:17408
	ds_read_b128 v[206:209], v148 offset:16384
	ds_read_b128 v[210:213], v148 offset:17408
	global_load_lds_dwordx4 v[230:231], off
	v_lshl_add_u64 v[230:231], v[236:237], 0, s[24:25]
	s_mov_b32 m0, s55
	s_nop 0
	global_load_lds_dwordx4 v[230:231], off
	s_barrier
	s_waitcnt lgkmcnt(0)
	s_waitcnt lgkmcnt(0)
	v_mfma_f32_16x16x32_bf16 v[60:63], v[164:167], v[182:185], v[60:63]
	v_mfma_f32_16x16x32_bf16 v[56:59], v[174:177], v[182:185], v[56:59]
	v_mfma_f32_16x16x32_bf16 v[52:55], v[164:167], v[190:193], v[52:55]
	v_mfma_f32_16x16x32_bf16 v[48:51], v[174:177], v[190:193], v[48:51]
	v_mfma_f32_16x16x32_bf16 v[44:47], v[164:167], v[198:201], v[44:47]
	v_mfma_f32_16x16x32_bf16 v[40:43], v[174:177], v[198:201], v[40:43]
	v_mfma_f32_16x16x32_bf16 v[36:39], v[164:167], v[206:209], v[36:39]
	v_mfma_f32_16x16x32_bf16 v[32:35], v[174:177], v[206:209], v[32:35]
	v_mfma_f32_16x16x32_bf16 v[60:63], v[170:173], v[186:189], v[60:63]
	v_mfma_f32_16x16x32_bf16 v[56:59], v[178:181], v[186:189], v[56:59]
	v_mfma_f32_16x16x32_bf16 v[52:55], v[170:173], v[194:197], v[52:55]
	v_mfma_f32_16x16x32_bf16 v[48:51], v[178:181], v[194:197], v[48:51]
	v_mfma_f32_16x16x32_bf16 v[44:47], v[170:173], v[202:205], v[44:47]
	v_mfma_f32_16x16x32_bf16 v[40:43], v[178:181], v[202:205], v[40:43]
	v_mfma_f32_16x16x32_bf16 v[36:39], v[170:173], v[210:213], v[36:39]
	v_mfma_f32_16x16x32_bf16 v[32:35], v[178:181], v[210:213], v[32:35]
	s_barrier
; #define STAGE(P, BASE, LD, br, kt) do { const char* _g = (const char*)((BASE) + (size_t)(br) * (LD) + (size_t)(kt) * 64); \
;     for (int _i = 0; _i < 2; ++_i) { int _b = tidx * 16 + _i * 8192; int _r, _c; stage_rc(_b, _r, _c); \
;       __builtin_amdgcn_global_load_lds((const unsigned*)(_g + (unsigned)((_r * (LD) + _c) * 2)), (unsigned*)((char*)(P) + _b), 16, 0, 0); } } while (0)
; #define LDA(dst, b, h) for (int m = 0; m < 4; ++m) for (int k = 0; k < 2; ++k) \
;     dst[m][k] = *reinterpret_cast<const bf16x8*>((char*)SA(b, h) + lds_byte(wr * 64 + m * 16 + fr, k * 32 + fq * 8))
; #define LDB(dst, b, h) for (int n = 0; n < 2; ++n) for (int k = 0; k < 2; ++k) \
;     dst[n][k] = *reinterpret_cast<const bf16x8*>((char*)SB(b, h) + lds_byte(wc * 32 + n * 16 + fr, k * 32 + fq * 8))
; #define MMA(ai, bj, At_, Bt_) do { __builtin_amdgcn_s_setprio(1); \
;     for (int k = 0; k < 2; ++k) for (int m = 0; m < 4; ++m) for (int n = 0; n < 2; ++n) \
;       acc[ai][bj][m][n] = __builtin_amdgcn_mfma_f32_16x16x32_bf16(At_[m][k], Bt_[n][k], acc[ai][bj][m][n], 0, 0, 0); \
;     __builtin_amdgcn_s_setprio(0); } while (0)
; #define WAIT_V(n) asm volatile("s_waitcnt vmcnt(" #n ")" ::: "memory")
; #define WAIT_L(n) asm volatile("s_waitcnt lgkmcnt(" #n ")" ::: "memory")
; #define BAR __builtin_amdgcn_s_barrier()
; #define SCHED __builtin_amdgcn_sched_barrier(0)
; template <int EPI, int lda, int ldb, int N, int K>
; __device__ __forceinline__ void gemm_phase(const u16* __restrict__ A, const u16* __restrict__ Bt, const GemmEpi ep, int wv) {
;     ...
;       STAGE(SB(0, 1), Bt, ldb, bcol + HALF, t + 2);
;       WAIT_V(6); BAR; MMA(1, 1, At, B1); BAR;
;       LDB(B0, 1, 0); SCHED; LDA(At, 1, 0); STAGE(SA(0, 1), Ab, lda, brow + HALF, t + 2);
;       WAIT_L(8); BAR; WAIT_L(0); MMA(0, 0, At, B0); BAR; SCHED;
;       LDB(B1, 1, 1); STAGE(SB(1, 0), Bt, ldb, bcol, t + 3);
;       BAR; WAIT_L(0); MMA(0, 1, At, B1); BAR;
;       LDA(At, 1, 1); STAGE(SA(1, 0), Ab, lda, brow, t + 3);
	v_add_u32_e32 v164, s66, v153
	v_add_u32_e32 v165, 0x2000, v164
	v_readfirstlane_b32 s55, v164
	v_lshl_add_u64 v[166:167], v[238:239], 0, s[26:27]
	s_mov_b32 m0, s55
	v_readfirstlane_b32 s55, v165
	global_load_lds_dwordx4 v[166:167], off
	v_lshl_add_u64 v[166:167], v[240:241], 0, s[26:27]
	s_mov_b32 m0, s55
	s_nop 0
	global_load_lds_dwordx4 v[166:167], off
	s_waitcnt vmcnt(6)
	s_barrier
	v_mfma_f32_16x16x32_bf16 v[28:31], v[214:217], v[182:185], v[28:31]
	v_mfma_f32_16x16x32_bf16 v[24:27], v[222:225], v[182:185], v[24:27]
	v_mfma_f32_16x16x32_bf16 v[20:23], v[214:217], v[190:193], v[20:23]
	v_mfma_f32_16x16x32_bf16 v[16:19], v[222:225], v[190:193], v[16:19]
	v_mfma_f32_16x16x32_bf16 v[12:15], v[214:217], v[198:201], v[12:15]
	v_mfma_f32_16x16x32_bf16 v[8:11], v[222:225], v[198:201], v[8:11]
	v_mfma_f32_16x16x32_bf16 v[4:7], v[214:217], v[206:209], v[4:7]
	v_mfma_f32_16x16x32_bf16 v[0:3], v[222:225], v[206:209], v[0:3]
	v_mfma_f32_16x16x32_bf16 v[28:31], v[218:221], v[186:189], v[28:31]
	v_mfma_f32_16x16x32_bf16 v[24:27], v[226:229], v[186:189], v[24:27]
	v_mfma_f32_16x16x32_bf16 v[20:23], v[218:221], v[194:197], v[20:23]
	v_mfma_f32_16x16x32_bf16 v[16:19], v[226:229], v[194:197], v[16:19]
	v_mfma_f32_16x16x32_bf16 v[12:15], v[218:221], v[202:205], v[12:15]
	v_mfma_f32_16x16x32_bf16 v[8:11], v[226:229], v[202:205], v[8:11]
	v_mfma_f32_16x16x32_bf16 v[4:7], v[218:221], v[210:213], v[4:7]
	v_mfma_f32_16x16x32_bf16 v[0:3], v[226:229], v[210:213], v[0:3]
	s_barrier
	ds_read_b128 v[170:173], v154
	ds_read_b128 v[174:177], v154 offset:1024
	ds_read_b128 v[178:181], v154 offset:2048
	ds_read_b128 v[182:185], v154 offset:3072
	v_add_u32_e32 v166, 0x4000, v143
	v_add_u32_e32 v167, 0x6000, v143
	v_readfirstlane_b32 s55, v166
	v_lshl_add_u64 v[218:219], v[234:235], 0, s[42:43]
	s_mov_b32 m0, s55
	v_readfirstlane_b32 s55, v167
	ds_read_b128 v[186:189], v151 offset:32768
	ds_read_b128 v[190:193], v151 offset:33792
	ds_read_b128 v[194:197], v150 offset:32768
	ds_read_b128 v[198:201], v150 offset:33792
	ds_read_b128 v[202:205], v149 offset:32768
	ds_read_b128 v[206:209], v149 offset:33792
	ds_read_b128 v[210:213], v148 offset:32768
	ds_read_b128 v[214:217], v148 offset:33792
	global_load_lds_dwordx4 v[218:219], off
	v_lshl_add_u64 v[218:219], v[236:237], 0, s[42:43]
	s_mov_b32 m0, s55
	s_nop 0
	global_load_lds_dwordx4 v[218:219], off
	s_waitcnt lgkmcnt(8)
	s_barrier
	s_waitcnt lgkmcnt(0)
	s_waitcnt lgkmcnt(0)
	v_mfma_f32_16x16x32_bf16 v[124:127], v[170:173], v[186:189], v[124:127]
	v_mfma_f32_16x16x32_bf16 v[120:123], v[178:181], v[186:189], v[120:123]
	v_mfma_f32_16x16x32_bf16 v[116:119], v[170:173], v[194:197], v[116:119]
	v_mfma_f32_16x16x32_bf16 v[112:115], v[178:181], v[194:197], v[112:115]
	v_mfma_f32_16x16x32_bf16 v[108:111], v[170:173], v[202:205], v[108:111]
	v_mfma_f32_16x16x32_bf16 v[104:107], v[178:181], v[202:205], v[104:107]
	v_mfma_f32_16x16x32_bf16 v[100:103], v[170:173], v[210:213], v[100:103]
	v_mfma_f32_16x16x32_bf16 v[96:99], v[178:181], v[210:213], v[96:99]
	v_mfma_f32_16x16x32_bf16 v[124:127], v[174:177], v[190:193], v[124:127]
	v_mfma_f32_16x16x32_bf16 v[120:123], v[182:185], v[190:193], v[120:123]
	v_mfma_f32_16x16x32_bf16 v[116:119], v[174:177], v[198:201], v[116:119]
	v_mfma_f32_16x16x32_bf16 v[112:115], v[182:185], v[198:201], v[112:115]
	v_mfma_f32_16x16x32_bf16 v[108:111], v[174:177], v[206:209], v[108:111]
	v_mfma_f32_16x16x32_bf16 v[104:107], v[182:185], v[206:209], v[104:107]
	v_mfma_f32_16x16x32_bf16 v[100:103], v[174:177], v[214:217], v[100:103]
	v_mfma_f32_16x16x32_bf16 v[96:99], v[182:185], v[214:217], v[96:99]
	s_barrier
	v_readfirstlane_b32 s55, v155
	v_add_u32_e32 v244, 0x2000, v155
	v_lshl_add_u64 v[242:243], v[238:239], 0, s[44:45]
	s_mov_b32 m0, s55
	v_readfirstlane_b32 s55, v244
	ds_read_b128 v[218:221], v152
	ds_read_b128 v[222:225], v152 offset:1024
	ds_read_b128 v[226:229], v152 offset:2048
	ds_read_b128 v[230:233], v152 offset:3072
	global_load_lds_dwordx4 v[242:243], off
	v_lshl_add_u64 v[242:243], v[240:241], 0, s[44:45]
	s_mov_b32 m0, s55
	s_nop 0
	global_load_lds_dwordx4 v[242:243], off
	s_barrier
	s_waitcnt lgkmcnt(0)
	s_waitcnt lgkmcnt(0)
	v_mfma_f32_16x16x32_bf16 v[92:95], v[218:221], v[186:189], v[92:95]
	v_mfma_f32_16x16x32_bf16 v[88:91], v[226:229], v[186:189], v[88:91]
	v_mfma_f32_16x16x32_bf16 v[84:87], v[218:221], v[194:197], v[84:87]
	v_mfma_f32_16x16x32_bf16 v[80:83], v[226:229], v[194:197], v[80:83]
	v_mfma_f32_16x16x32_bf16 v[76:79], v[218:221], v[202:205], v[76:79]
	v_mfma_f32_16x16x32_bf16 v[72:75], v[226:229], v[202:205], v[72:75]
	v_mfma_f32_16x16x32_bf16 v[68:71], v[218:221], v[210:213], v[68:71]
	v_mfma_f32_16x16x32_bf16 v[64:67], v[226:229], v[210:213], v[64:67]
	v_mfma_f32_16x16x32_bf16 v[92:95], v[222:225], v[190:193], v[92:95]
	v_mfma_f32_16x16x32_bf16 v[88:91], v[230:233], v[190:193], v[88:91]
	v_mfma_f32_16x16x32_bf16 v[84:87], v[222:225], v[198:201], v[84:87]
	v_mfma_f32_16x16x32_bf16 v[80:83], v[230:233], v[198:201], v[80:83]
	v_mfma_f32_16x16x32_bf16 v[76:79], v[222:225], v[206:209], v[76:79]
	v_mfma_f32_16x16x32_bf16 v[72:75], v[230:233], v[206:209], v[72:75]
	v_mfma_f32_16x16x32_bf16 v[68:71], v[222:225], v[214:217], v[68:71]
	v_mfma_f32_16x16x32_bf16 v[64:67], v[230:233], v[214:217], v[64:67]
	s_barrier
	v_readfirstlane_b32 s55, v156
	v_lshl_add_u64 v[234:235], v[234:235], 0, s[46:47]
	s_mov_b32 m0, s55
	v_readfirstlane_b32 s55, v157
	ds_read_b128 v[186:189], v151 offset:49152
	ds_read_b128 v[190:193], v151 offset:50176
	ds_read_b128 v[194:197], v150 offset:49152
	ds_read_b128 v[198:201], v150 offset:50176
	ds_read_b128 v[202:205], v149 offset:49152
	ds_read_b128 v[206:209], v149 offset:50176
	ds_read_b128 v[210:213], v148 offset:49152
	ds_read_b128 v[214:217], v148 offset:50176
	global_load_lds_dwordx4 v[234:235], off
	v_lshl_add_u64 v[234:235], v[236:237], 0, s[46:47]
	s_mov_b32 m0, s55
	s_nop 0
	global_load_lds_dwordx4 v[234:235], off
	s_barrier
; #define STAGE(P, BASE, LD, br, kt) do { const char* _g = (const char*)((BASE) + (size_t)(br) * (LD) + (size_t)(kt) * 64); \
;     for (int _i = 0; _i < 2; ++_i) { int _b = tidx * 16 + _i * 8192; int _r, _c; stage_rc(_b, _r, _c); \
;       __builtin_amdgcn_global_load_lds((const unsigned*)(_g + (unsigned)((_r * (LD) + _c) * 2)), (unsigned*)((char*)(P) + _b), 16, 0, 0); } } while (0)
; #define LDA(dst, b, h) for (int m = 0; m < 4; ++m) for (int k = 0; k < 2; ++k) \
;     dst[m][k] = *reinterpret_cast<const bf16x8*>((char*)SA(b, h) + lds_byte(wr * 64 + m * 16 + fr, k * 32 + fq * 8))
; #define LDB(dst, b, h) for (int n = 0; n < 2; ++n) for (int k = 0; k < 2; ++k) \
;     dst[n][k] = *reinterpret_cast<const bf16x8*>((char*)SB(b, h) + lds_byte(wc * 32 + n * 16 + fr, k * 32 + fq * 8))
; #define MMA(ai, bj, At_, Bt_) do { __builtin_amdgcn_s_setprio(1); \
;     for (int k = 0; k < 2; ++k) for (int m = 0; m < 4; ++m) for (int n = 0; n < 2; ++n) \
;       acc[ai][bj][m][n] = __builtin_amdgcn_mfma_f32_16x16x32_bf16(At_[m][k], Bt_[n][k], acc[ai][bj][m][n], 0, 0, 0); \
;     __builtin_amdgcn_s_setprio(0); } while (0)
; #define WAIT_V(n) asm volatile("s_waitcnt vmcnt(" #n ")" ::: "memory")
; #define WAIT_L(n) asm volatile("s_waitcnt lgkmcnt(" #n ")" ::: "memory")
; #define BAR __builtin_amdgcn_s_barrier()
; #define SCHED __builtin_amdgcn_sched_barrier(0)
; template <int EPI, int lda, int ldb, int N, int K>
; __device__ __forceinline__ void gemm_phase(const u16* __restrict__ A, const u16* __restrict__ Bt, const GemmEpi ep, int wv) {
;     ...
;       BAR; WAIT_L(0); MMA(1, 0, At, B0); BAR; SCHED;
;       STAGE(SB(1, 1), Bt, ldb, bcol + HALF, t + 3);
;       WAIT_V(6); BAR; MMA(1, 1, At, B1); BAR;
;     }
;     { LDB(B0, 0, 0); LDA(At, 0, 0); STAGE(SA(1, 1), Ab, lda, brow + HALF, nt - 1);
;       BAR; WAIT_L(0); MMA(0, 0, At, B0); BAR;
;       LDB(B1, 0, 1); BAR; WAIT_L(0); MMA(0, 1, At, B1); BAR;
	s_waitcnt lgkmcnt(0)
	s_waitcnt lgkmcnt(0)
	v_mfma_f32_16x16x32_bf16 v[60:63], v[170:173], v[186:189], v[60:63]
	v_mfma_f32_16x16x32_bf16 v[56:59], v[178:181], v[186:189], v[56:59]
	v_mfma_f32_16x16x32_bf16 v[52:55], v[170:173], v[194:197], v[52:55]
	v_mfma_f32_16x16x32_bf16 v[48:51], v[178:181], v[194:197], v[48:51]
	v_mfma_f32_16x16x32_bf16 v[44:47], v[170:173], v[202:205], v[44:47]
	v_mfma_f32_16x16x32_bf16 v[40:43], v[178:181], v[202:205], v[40:43]
	v_mfma_f32_16x16x32_bf16 v[36:39], v[170:173], v[210:213], v[36:39]
	v_mfma_f32_16x16x32_bf16 v[32:35], v[178:181], v[210:213], v[32:35]
	v_mfma_f32_16x16x32_bf16 v[60:63], v[174:177], v[190:193], v[60:63]
	v_mfma_f32_16x16x32_bf16 v[56:59], v[182:185], v[190:193], v[56:59]
	v_mfma_f32_16x16x32_bf16 v[52:55], v[174:177], v[198:201], v[52:55]
	v_mfma_f32_16x16x32_bf16 v[48:51], v[182:185], v[198:201], v[48:51]
	v_mfma_f32_16x16x32_bf16 v[44:47], v[174:177], v[206:209], v[44:47]
	v_mfma_f32_16x16x32_bf16 v[40:43], v[182:185], v[206:209], v[40:43]
	v_mfma_f32_16x16x32_bf16 v[36:39], v[174:177], v[214:217], v[36:39]
	v_mfma_f32_16x16x32_bf16 v[32:35], v[182:185], v[214:217], v[32:35]
	s_barrier
	v_readfirstlane_b32 s55, v158
	v_add_u32_e32 v172, 0x2000, v158
	v_lshl_add_u64 v[170:171], v[238:239], 0, s[48:49]
	s_mov_b32 m0, s55
	v_readfirstlane_b32 s55, v172
	global_load_lds_dwordx4 v[170:171], off
	v_lshl_add_u64 v[170:171], v[240:241], 0, s[48:49]
	s_mov_b32 m0, s55
	s_nop 0
	global_load_lds_dwordx4 v[170:171], off
	s_waitcnt vmcnt(6)
	s_barrier
	v_mfma_f32_16x16x32_bf16 v[28:31], v[218:221], v[186:189], v[28:31]
	v_mfma_f32_16x16x32_bf16 v[24:27], v[226:229], v[186:189], v[24:27]
	v_mfma_f32_16x16x32_bf16 v[20:23], v[218:221], v[194:197], v[20:23]
	v_mfma_f32_16x16x32_bf16 v[16:19], v[226:229], v[194:197], v[16:19]
	v_mfma_f32_16x16x32_bf16 v[12:15], v[218:221], v[202:205], v[12:15]
	v_mfma_f32_16x16x32_bf16 v[8:11], v[226:229], v[202:205], v[8:11]
	v_mfma_f32_16x16x32_bf16 v[4:7], v[218:221], v[210:213], v[4:7]
	v_mfma_f32_16x16x32_bf16 v[0:3], v[226:229], v[210:213], v[0:3]
	v_mfma_f32_16x16x32_bf16 v[28:31], v[222:225], v[190:193], v[28:31]
	v_mfma_f32_16x16x32_bf16 v[24:27], v[230:233], v[190:193], v[24:27]
	v_mfma_f32_16x16x32_bf16 v[20:23], v[222:225], v[198:201], v[20:23]
	v_mfma_f32_16x16x32_bf16 v[16:19], v[230:233], v[198:201], v[16:19]
	v_mfma_f32_16x16x32_bf16 v[12:15], v[222:225], v[206:209], v[12:15]
	v_mfma_f32_16x16x32_bf16 v[8:11], v[230:233], v[206:209], v[8:11]
	v_mfma_f32_16x16x32_bf16 v[4:7], v[222:225], v[214:217], v[4:7]
	v_mfma_f32_16x16x32_bf16 v[0:3], v[230:233], v[214:217], v[0:3]
	s_barrier
	s_add_i32 s54, s54, 2
	s_add_u32 s52, s52, 0x100
	s_addc_u32 s53, s53, 0
	s_cmp_gt_u32 s54, 27
	s_cbranch_scc0 .LBB0_654
	s_lshl_b64 s[52:53], s[16:17], 12
	s_add_u32 s52, s14, s52
	s_addc_u32 s53, s15, s53
	s_add_u32 s52, s52, 0x80000
	s_addc_u32 s53, s53, 0
	v_lshl_add_u64 v[156:157], s[52:53], 0, v[128:129]
	v_readfirstlane_b32 s54, v168
	v_lshl_add_u64 v[156:157], v[156:157], 0, s[50:51]
	s_mov_b32 m0, s54
	ds_read_b128 v[134:137], v160
	ds_read_b128 v[138:141], v160 offset:1024
	ds_read_b128 v[170:173], v160 offset:2048
	ds_read_b128 v[174:177], v160 offset:3072
	ds_read_b128 v[178:181], v151
	ds_read_b128 v[182:185], v151 offset:1024
	ds_read_b128 v[186:189], v150
	ds_read_b128 v[190:193], v150 offset:1024
	ds_read_b128 v[194:197], v149
	ds_read_b128 v[198:201], v149 offset:1024
	ds_read_b128 v[202:205], v148
	ds_read_b128 v[206:209], v148 offset:1024
	global_load_lds_dwordx4 v[156:157], off
	v_lshl_add_u64 v[156:157], s[52:53], 0, v[132:133]
	v_readfirstlane_b32 s52, v169
	v_lshl_add_u64 v[156:157], v[156:157], 0, s[50:51]
	s_mov_b32 m0, s52
	s_nop 0
	global_load_lds_dwordx4 v[156:157], off
	s_barrier
	s_waitcnt lgkmcnt(0)
	s_waitcnt lgkmcnt(0)
	v_mfma_f32_16x16x32_bf16 v[124:127], v[134:137], v[178:181], v[124:127]
	v_mfma_f32_16x16x32_bf16 v[120:123], v[170:173], v[178:181], v[120:123]
	v_mfma_f32_16x16x32_bf16 v[116:119], v[134:137], v[186:189], v[116:119]
	v_mfma_f32_16x16x32_bf16 v[112:115], v[170:173], v[186:189], v[112:115]
	v_mfma_f32_16x16x32_bf16 v[108:111], v[134:137], v[194:197], v[108:111]
	v_mfma_f32_16x16x32_bf16 v[104:107], v[170:173], v[194:197], v[104:107]
	v_mfma_f32_16x16x32_bf16 v[100:103], v[134:137], v[202:205], v[100:103]
	v_mfma_f32_16x16x32_bf16 v[96:99], v[170:173], v[202:205], v[96:99]
	v_mfma_f32_16x16x32_bf16 v[124:127], v[138:141], v[182:185], v[124:127]
	v_mfma_f32_16x16x32_bf16 v[120:123], v[174:177], v[182:185], v[120:123]
	v_mfma_f32_16x16x32_bf16 v[116:119], v[138:141], v[190:193], v[116:119]
	v_mfma_f32_16x16x32_bf16 v[112:115], v[174:177], v[190:193], v[112:115]
	v_mfma_f32_16x16x32_bf16 v[108:111], v[138:141], v[198:201], v[108:111]
	v_mfma_f32_16x16x32_bf16 v[104:107], v[174:177], v[198:201], v[104:107]
	v_mfma_f32_16x16x32_bf16 v[100:103], v[138:141], v[206:209], v[100:103]
	v_mfma_f32_16x16x32_bf16 v[96:99], v[174:177], v[206:209], v[96:99]
	s_barrier
	ds_read_b128 v[210:213], v159
	ds_read_b128 v[214:217], v159 offset:1024
	ds_read_b128 v[218:221], v159 offset:2048
	ds_read_b128 v[156:159], v159 offset:3072
	s_barrier
; #define LDA(dst, b, h) for (int m = 0; m < 4; ++m) for (int k = 0; k < 2; ++k) \
;     dst[m][k] = *reinterpret_cast<const bf16x8*>((char*)SA(b, h) + lds_byte(wr * 64 + m * 16 + fr, k * 32 + fq * 8))
; #define LDB(dst, b, h) for (int n = 0; n < 2; ++n) for (int k = 0; k < 2; ++k) \
;     dst[n][k] = *reinterpret_cast<const bf16x8*>((char*)SB(b, h) + lds_byte(wc * 32 + n * 16 + fr, k * 32 + fq * 8))
; #define MMA(ai, bj, At_, Bt_) do { __builtin_amdgcn_s_setprio(1); \
;     for (int k = 0; k < 2; ++k) for (int m = 0; m < 4; ++m) for (int n = 0; n < 2; ++n) \
;       acc[ai][bj][m][n] = __builtin_amdgcn_mfma_f32_16x16x32_bf16(At_[m][k], Bt_[n][k], acc[ai][bj][m][n], 0, 0, 0); \
;     __builtin_amdgcn_s_setprio(0); } while (0)
; #define WAIT_V(n) asm volatile("s_waitcnt vmcnt(" #n ")" ::: "memory")
; #define WAIT_L(n) asm volatile("s_waitcnt lgkmcnt(" #n ")" ::: "memory")
; #define BAR __builtin_amdgcn_s_barrier()
; template <int EPI, int lda, int ldb, int N, int K>
; __device__ __forceinline__ void gemm_phase(const u16* __restrict__ A, const u16* __restrict__ Bt, const GemmEpi ep, int wv) {
;     ...
;       LDB(B1, 0, 1); BAR; WAIT_L(0); MMA(0, 1, At, B1); BAR;
;       LDA(At, 0, 1); WAIT_V(4); BAR; WAIT_L(0); MMA(1, 0, At, B0); MMA(1, 1, At, B1); BAR; }
;     { LDB(B0, 1, 0); LDA(At, 1, 0); WAIT_V(2); BAR; WAIT_L(0); MMA(0, 0, At, B0); BAR;
	s_waitcnt lgkmcnt(0)
	s_waitcnt lgkmcnt(0)
	v_mfma_f32_16x16x32_bf16 v[92:95], v[210:213], v[178:181], v[92:95]
	v_mfma_f32_16x16x32_bf16 v[88:91], v[218:221], v[178:181], v[88:91]
	v_mfma_f32_16x16x32_bf16 v[76:79], v[210:213], v[194:197], v[76:79]
	v_mfma_f32_16x16x32_bf16 v[72:75], v[218:221], v[194:197], v[72:75]
	v_mfma_f32_16x16x32_bf16 v[84:87], v[210:213], v[186:189], v[84:87]
	v_mfma_f32_16x16x32_bf16 v[80:83], v[218:221], v[186:189], v[80:83]
	v_mfma_f32_16x16x32_bf16 v[68:71], v[210:213], v[202:205], v[68:71]
	v_mfma_f32_16x16x32_bf16 v[64:67], v[218:221], v[202:205], v[64:67]
	v_mfma_f32_16x16x32_bf16 v[92:95], v[214:217], v[182:185], v[92:95]
	v_mfma_f32_16x16x32_bf16 v[88:91], v[156:159], v[182:185], v[88:91]
	v_mfma_f32_16x16x32_bf16 v[76:79], v[214:217], v[198:201], v[76:79]
	v_mfma_f32_16x16x32_bf16 v[72:75], v[156:159], v[198:201], v[72:75]
	v_mfma_f32_16x16x32_bf16 v[178:181], v[214:217], v[190:193], v[84:87]
	v_mfma_f32_16x16x32_bf16 v[182:185], v[156:159], v[190:193], v[80:83]
	v_mfma_f32_16x16x32_bf16 v[186:189], v[214:217], v[206:209], v[68:71]
	v_mfma_f32_16x16x32_bf16 v[190:193], v[156:159], v[206:209], v[64:67]
	s_barrier
	s_nop 0
	ds_read_b128 v[64:67], v151 offset:16384
	ds_read_b128 v[68:71], v151 offset:17408
	ds_read_b128 v[80:83], v150 offset:16384
	ds_read_b128 v[84:87], v150 offset:17408
	ds_read_b128 v[194:197], v149 offset:16384
	ds_read_b128 v[198:201], v149 offset:17408
	ds_read_b128 v[202:205], v148 offset:16384
	ds_read_b128 v[206:209], v148 offset:17408
	s_waitcnt vmcnt(4)
	s_barrier
	s_waitcnt lgkmcnt(0)
	s_waitcnt lgkmcnt(0)
	v_mfma_f32_16x16x32_bf16 v[60:63], v[134:137], v[64:67], v[60:63]
	v_mfma_f32_16x16x32_bf16 v[56:59], v[170:173], v[64:67], v[56:59]
	v_mfma_f32_16x16x32_bf16 v[52:55], v[134:137], v[80:83], v[52:55]
	v_mfma_f32_16x16x32_bf16 v[48:51], v[170:173], v[80:83], v[48:51]
	v_mfma_f32_16x16x32_bf16 v[44:47], v[134:137], v[194:197], v[44:47]
	v_mfma_f32_16x16x32_bf16 v[40:43], v[170:173], v[194:197], v[40:43]
	v_mfma_f32_16x16x32_bf16 v[36:39], v[134:137], v[202:205], v[36:39]
	v_mfma_f32_16x16x32_bf16 v[32:35], v[170:173], v[202:205], v[32:35]
	v_mfma_f32_16x16x32_bf16 v[60:63], v[138:141], v[68:71], v[60:63]
	v_mfma_f32_16x16x32_bf16 v[56:59], v[174:177], v[68:71], v[56:59]
	v_mfma_f32_16x16x32_bf16 v[52:55], v[138:141], v[84:87], v[52:55]
	v_mfma_f32_16x16x32_bf16 v[48:51], v[174:177], v[84:87], v[48:51]
	v_mfma_f32_16x16x32_bf16 v[44:47], v[138:141], v[198:201], v[44:47]
	v_mfma_f32_16x16x32_bf16 v[40:43], v[174:177], v[198:201], v[40:43]
	v_mfma_f32_16x16x32_bf16 v[36:39], v[138:141], v[206:209], v[36:39]
	v_mfma_f32_16x16x32_bf16 v[32:35], v[174:177], v[206:209], v[32:35]
	v_mfma_f32_16x16x32_bf16 v[28:31], v[210:213], v[64:67], v[28:31]
	v_mfma_f32_16x16x32_bf16 v[20:23], v[210:213], v[80:83], v[20:23]
	v_mfma_f32_16x16x32_bf16 v[12:15], v[210:213], v[194:197], v[12:15]
	v_mfma_f32_16x16x32_bf16 v[4:7], v[210:213], v[202:205], v[4:7]
	v_mfma_f32_16x16x32_bf16 v[24:27], v[218:221], v[64:67], v[24:27]
	v_mfma_f32_16x16x32_bf16 v[16:19], v[218:221], v[80:83], v[16:19]
	v_mfma_f32_16x16x32_bf16 v[8:11], v[218:221], v[194:197], v[8:11]
	v_mfma_f32_16x16x32_bf16 v[0:3], v[218:221], v[202:205], v[0:3]
	v_mfma_f32_16x16x32_bf16 v[28:31], v[214:217], v[68:71], v[28:31]
	v_mfma_f32_16x16x32_bf16 v[20:23], v[214:217], v[84:87], v[20:23]
	v_mfma_f32_16x16x32_bf16 v[12:15], v[214:217], v[198:201], v[12:15]
	v_mfma_f32_16x16x32_bf16 v[4:7], v[214:217], v[206:209], v[4:7]
	v_mfma_f32_16x16x32_bf16 v[134:137], v[156:159], v[68:71], v[24:27]
	v_mfma_f32_16x16x32_bf16 v[138:141], v[156:159], v[84:87], v[16:19]
	v_mfma_f32_16x16x32_bf16 v[168:171], v[156:159], v[198:201], v[8:11]
	v_mfma_f32_16x16x32_bf16 v[156:159], v[156:159], v[206:209], v[0:3]
	s_barrier
	s_nop 0
	ds_read_b128 v[0:3], v154
	ds_read_b128 v[8:11], v154 offset:1024
	ds_read_b128 v[16:19], v154 offset:2048
	ds_read_b128 v[172:175], v154 offset:3072
	ds_read_b128 v[24:27], v151 offset:32768
	ds_read_b128 v[194:197], v151 offset:33792
	ds_read_b128 v[198:201], v150 offset:32768
	ds_read_b128 v[202:205], v150 offset:33792
	ds_read_b128 v[206:209], v149 offset:32768
	ds_read_b128 v[210:213], v149 offset:33792
	ds_read_b128 v[214:217], v148 offset:32768
	ds_read_b128 v[218:221], v148 offset:33792
	s_waitcnt vmcnt(2)
	s_barrier
; #define LDA(dst, b, h) for (int m = 0; m < 4; ++m) for (int k = 0; k < 2; ++k) \
;     dst[m][k] = *reinterpret_cast<const bf16x8*>((char*)SA(b, h) + lds_byte(wr * 64 + m * 16 + fr, k * 32 + fq * 8))
; #define LDB(dst, b, h) for (int n = 0; n < 2; ++n) for (int k = 0; k < 2; ++k) \
;     dst[n][k] = *reinterpret_cast<const bf16x8*>((char*)SB(b, h) + lds_byte(wc * 32 + n * 16 + fr, k * 32 + fq * 8))
; #define MMA(ai, bj, At_, Bt_) do { __builtin_amdgcn_s_setprio(1); \
;     for (int k = 0; k < 2; ++k) for (int m = 0; m < 4; ++m) for (int n = 0; n < 2; ++n) \
;       acc[ai][bj][m][n] = __builtin_amdgcn_mfma_f32_16x16x32_bf16(At_[m][k], Bt_[n][k], acc[ai][bj][m][n], 0, 0, 0); \
;     __builtin_amdgcn_s_setprio(0); } while (0)
; #define WAIT_V(n) asm volatile("s_waitcnt vmcnt(" #n ")" ::: "memory")
; #define WAIT_L(n) asm volatile("s_waitcnt lgkmcnt(" #n ")" ::: "memory")
; #define BAR __builtin_amdgcn_s_barrier()
; template <int EPI, int lda, int ldb, int N, int K>
; __device__ __forceinline__ void gemm_phase(const u16* __restrict__ A, const u16* __restrict__ Bt, const GemmEpi ep, int wv) {
;     ...
;     { LDB(B0, 1, 0); LDA(At, 1, 0); WAIT_V(2); BAR; WAIT_L(0); MMA(0, 0, At, B0); BAR;
;       LDB(B1, 1, 1); WAIT_V(0); BAR; WAIT_L(0); MMA(0, 1, At, B1); BAR;
;       LDA(At, 1, 1); BAR; WAIT_L(0); MMA(1, 0, At, B0); MMA(1, 1, At, B1); BAR; }
;     if (wr == 0) BAR;
	s_waitcnt lgkmcnt(0)
	s_waitcnt lgkmcnt(0)
	v_mfma_f32_16x16x32_bf16 v[64:67], v[0:3], v[24:27], v[124:127]
	v_mfma_f32_16x16x32_bf16 v[68:71], v[16:19], v[24:27], v[120:123]
	v_mfma_f32_16x16x32_bf16 v[80:83], v[0:3], v[198:201], v[116:119]
	v_mfma_f32_16x16x32_bf16 v[84:87], v[16:19], v[198:201], v[112:115]
	v_mfma_f32_16x16x32_bf16 v[108:111], v[0:3], v[206:209], v[108:111]
	v_mfma_f32_16x16x32_bf16 v[104:107], v[16:19], v[206:209], v[104:107]
	v_mfma_f32_16x16x32_bf16 v[120:123], v[0:3], v[214:217], v[100:103]
	v_mfma_f32_16x16x32_bf16 v[124:127], v[16:19], v[214:217], v[96:99]
	v_mfma_f32_16x16x32_bf16 v[116:119], v[8:11], v[194:197], v[64:67]
	v_mfma_f32_16x16x32_bf16 v[112:115], v[172:175], v[194:197], v[68:71]
	v_mfma_f32_16x16x32_bf16 v[100:103], v[8:11], v[202:205], v[80:83]
	v_mfma_f32_16x16x32_bf16 v[96:99], v[172:175], v[202:205], v[84:87]
	v_mfma_f32_16x16x32_bf16 v[84:87], v[8:11], v[210:213], v[108:111]
	v_mfma_f32_16x16x32_bf16 v[80:83], v[172:175], v[210:213], v[104:107]
	v_mfma_f32_16x16x32_bf16 v[68:71], v[8:11], v[218:221], v[120:123]
	v_mfma_f32_16x16x32_bf16 v[64:67], v[172:175], v[218:221], v[124:127]
	s_barrier
	ds_read_b128 v[222:225], v152
	ds_read_b128 v[226:229], v152 offset:1024
	ds_read_b128 v[230:233], v152 offset:2048
	ds_read_b128 v[152:155], v152 offset:3072
	s_waitcnt vmcnt(0)
	s_barrier
	s_waitcnt lgkmcnt(0)
	s_waitcnt lgkmcnt(0)
	v_mfma_f32_16x16x32_bf16 v[92:95], v[222:225], v[24:27], v[92:95]
	v_mfma_f32_16x16x32_bf16 v[24:27], v[230:233], v[24:27], v[88:91]
	v_mfma_f32_16x16x32_bf16 v[88:91], v[222:225], v[198:201], v[178:181]
	v_mfma_f32_16x16x32_bf16 v[104:107], v[230:233], v[198:201], v[182:185]
	v_mfma_f32_16x16x32_bf16 v[76:79], v[222:225], v[206:209], v[76:79]
	v_mfma_f32_16x16x32_bf16 v[72:75], v[230:233], v[206:209], v[72:75]
	v_mfma_f32_16x16x32_bf16 v[176:179], v[222:225], v[214:217], v[186:189]
	v_mfma_f32_16x16x32_bf16 v[180:183], v[230:233], v[214:217], v[190:193]
	v_mfma_f32_16x16x32_bf16 v[124:127], v[226:229], v[194:197], v[92:95]
	v_mfma_f32_16x16x32_bf16 v[120:123], v[152:155], v[194:197], v[24:27]
	v_mfma_f32_16x16x32_bf16 v[108:111], v[226:229], v[202:205], v[88:91]
	v_mfma_f32_16x16x32_bf16 v[104:107], v[152:155], v[202:205], v[104:107]
	v_mfma_f32_16x16x32_bf16 v[92:95], v[226:229], v[210:213], v[76:79]
	v_mfma_f32_16x16x32_bf16 v[88:91], v[152:155], v[210:213], v[72:75]
	v_mfma_f32_16x16x32_bf16 v[76:79], v[226:229], v[218:221], v[176:179]
	v_mfma_f32_16x16x32_bf16 v[72:75], v[152:155], v[218:221], v[180:183]
	s_barrier
	ds_read_b128 v[176:179], v151 offset:49152
	ds_read_b128 v[180:183], v151 offset:50176
	ds_read_b128 v[184:187], v150 offset:49152
	ds_read_b128 v[188:191], v150 offset:50176
	ds_read_b128 v[192:195], v149 offset:49152
	ds_read_b128 v[196:199], v149 offset:50176
	ds_read_b128 v[200:203], v148 offset:49152
	ds_read_b128 v[148:151], v148 offset:50176
	s_barrier
	s_waitcnt lgkmcnt(0)
	s_waitcnt lgkmcnt(0)
	v_mfma_f32_16x16x32_bf16 v[24:27], v[0:3], v[176:179], v[60:63]
	v_mfma_f32_16x16x32_bf16 v[60:63], v[16:19], v[176:179], v[56:59]
	v_mfma_f32_16x16x32_bf16 v[52:55], v[0:3], v[184:187], v[52:55]
	v_mfma_f32_16x16x32_bf16 v[204:207], v[16:19], v[184:187], v[48:51]
	v_mfma_f32_16x16x32_bf16 v[44:47], v[0:3], v[192:195], v[44:47]
	v_mfma_f32_16x16x32_bf16 v[208:211], v[16:19], v[192:195], v[40:43]
	v_mfma_f32_16x16x32_bf16 v[0:3], v[0:3], v[200:203], v[36:39]
	v_mfma_f32_16x16x32_bf16 v[36:39], v[16:19], v[200:203], v[32:35]
	v_mfma_f32_16x16x32_bf16 v[56:59], v[8:11], v[180:183], v[24:27]
	v_mfma_f32_16x16x32_bf16 v[48:51], v[172:175], v[180:183], v[60:63]
	v_mfma_f32_16x16x32_bf16 v[40:43], v[8:11], v[188:191], v[52:55]
	v_mfma_f32_16x16x32_bf16 v[32:35], v[172:175], v[188:191], v[204:207]
	v_mfma_f32_16x16x32_bf16 v[24:27], v[8:11], v[196:199], v[44:47]
	v_mfma_f32_16x16x32_bf16 v[16:19], v[172:175], v[196:199], v[208:211]
	v_mfma_f32_16x16x32_bf16 v[8:11], v[8:11], v[148:151], v[0:3]
	v_mfma_f32_16x16x32_bf16 v[0:3], v[172:175], v[148:151], v[36:39]
	v_mfma_f32_16x16x32_bf16 v[28:31], v[222:225], v[176:179], v[28:31]
	v_mfma_f32_16x16x32_bf16 v[36:39], v[230:233], v[176:179], v[134:137]
	v_mfma_f32_16x16x32_bf16 v[20:23], v[222:225], v[184:187], v[20:23]
	v_mfma_f32_16x16x32_bf16 v[134:137], v[230:233], v[184:187], v[138:141]
	v_mfma_f32_16x16x32_bf16 v[12:15], v[222:225], v[192:195], v[12:15]
	v_mfma_f32_16x16x32_bf16 v[138:141], v[230:233], v[192:195], v[168:171]
	v_mfma_f32_16x16x32_bf16 v[4:7], v[222:225], v[200:203], v[4:7]
	v_mfma_f32_16x16x32_bf16 v[156:159], v[230:233], v[200:203], v[156:159]
	v_mfma_f32_16x16x32_bf16 v[60:63], v[226:229], v[180:183], v[28:31]
	v_mfma_f32_16x16x32_bf16 v[52:55], v[152:155], v[180:183], v[36:39]
	v_mfma_f32_16x16x32_bf16 v[44:47], v[226:229], v[188:191], v[20:23]
	v_mfma_f32_16x16x32_bf16 v[36:39], v[152:155], v[188:191], v[134:137]
	v_mfma_f32_16x16x32_bf16 v[28:31], v[226:229], v[196:199], v[12:15]
	v_mfma_f32_16x16x32_bf16 v[20:23], v[152:155], v[196:199], v[138:141]
	v_mfma_f32_16x16x32_bf16 v[12:15], v[226:229], v[148:151], v[4:7]
	v_mfma_f32_16x16x32_bf16 v[4:7], v[152:155], v[148:151], v[156:159]
	v_cmp_gt_u32_e32 vcc, s70, v130
	s_barrier
	s_and_saveexec_b64 s[52:53], vcc
	s_cbranch_execz .LBB0_657
	s_barrier

; #define STAGE(P, BASE, LD, br, kt) do { const char* _g = (const char*)((BASE) + (size_t)(br) * (LD) + (size_t)(kt) * 64); \
;     for (int _i = 0; _i < 2; ++_i) { int _b = tidx * 16 + _i * 8192; int _r, _c; stage_rc(_b, _r, _c); \
;       __builtin_amdgcn_global_load_lds((const unsigned*)(_g + (unsigned)((_r * (LD) + _c) * 2)), (unsigned*)((char*)(P) + _b), 16, 0, 0); } } while (0)
; #define LDA(dst, b, h) for (int m = 0; m < 4; ++m) for (int k = 0; k < 2; ++k) \
;     dst[m][k] = *reinterpret_cast<const bf16x8*>((char*)SA(b, h) + lds_byte(wr * 64 + m * 16 + fr, k * 32 + fq * 8))
; #define LDB(dst, b, h) for (int n = 0; n < 2; ++n) for (int k = 0; k < 2; ++k) \
;     dst[n][k] = *reinterpret_cast<const bf16x8*>((char*)SB(b, h) + lds_byte(wc * 32 + n * 16 + fr, k * 32 + fq * 8))
; #define MMA(ai, bj, At_, Bt_) do { __builtin_amdgcn_s_setprio(1); \
;     for (int k = 0; k < 2; ++k) for (int m = 0; m < 4; ++m) for (int n = 0; n < 2; ++n) \
;       acc[ai][bj][m][n] = __builtin_amdgcn_mfma_f32_16x16x32_bf16(At_[m][k], Bt_[n][k], acc[ai][bj][m][n], 0, 0, 0); \
;     __builtin_amdgcn_s_setprio(0); } while (0)
; #define WAIT_L(n) asm volatile("s_waitcnt lgkmcnt(" #n ")" ::: "memory")
; #define BAR __builtin_amdgcn_s_barrier()
; #define SCHED __builtin_amdgcn_sched_barrier(0)
; template <int EPI, int lda, int ldb, int N, int K>
; __device__ __forceinline__ void gemm_phase(const u16* __restrict__ A, const u16* __restrict__ Bt, const GemmEpi ep, int wv) {
;     ...
;     for (int t = 0; t < nt - 2; t += 2) {
;       LDB(B0, 0, 0); SCHED; LDA(At, 0, 0); STAGE(SA(1, 1), Ab, lda, brow + HALF, t + 1);
;       WAIT_L(8); BAR; WAIT_L(0); MMA(0, 0, At, B0); BAR; SCHED;
;       LDB(B1, 0, 1); STAGE(SB(0, 0), Bt, ldb, bcol, t + 2);
;       BAR; WAIT_L(0); MMA(0, 1, At, B1); BAR;
;       LDA(At, 0, 1); STAGE(SA(0, 0), Ab, lda, brow, t + 2);
;       BAR; WAIT_L(0); MMA(1, 0, At, B0); BAR; SCHED;
.LBB0_770:
	ds_read_b128 v[172:175], v161
	ds_read_b128 v[176:179], v161 offset:1024
	ds_read_b128 v[180:183], v161 offset:2048
	ds_read_b128 v[184:187], v161 offset:3072
	v_add_u32_e32 v169, 0xc000, v148
	v_lshl_add_u64 v[236:237], v[136:137], 0, s[50:51]
	v_readfirstlane_b32 s53, v169
	v_add_u32_e32 v170, 0xe000, v148
	v_lshl_add_u64 v[162:163], v[236:237], 0, s[18:19]
	s_mov_b32 m0, s53
	v_lshl_add_u64 v[238:239], v[134:135], 0, s[50:51]
	v_readfirstlane_b32 s53, v170
	ds_read_b128 v[164:167], v152
	ds_read_b128 v[188:191], v152 offset:1024
	ds_read_b128 v[192:195], v151
	ds_read_b128 v[196:199], v151 offset:1024
	ds_read_b128 v[200:203], v150
	ds_read_b128 v[204:207], v150 offset:1024
	ds_read_b128 v[208:211], v149
	ds_read_b128 v[212:215], v149 offset:1024
	global_load_lds_dwordx4 v[162:163], off
	v_lshl_add_u64 v[162:163], v[238:239], 0, s[18:19]
	s_mov_b32 m0, s53
	s_nop 0
	global_load_lds_dwordx4 v[162:163], off
	s_waitcnt lgkmcnt(8)
	s_barrier
	s_waitcnt lgkmcnt(0)
	s_waitcnt lgkmcnt(0)
	v_mfma_f32_16x16x32_bf16 v[124:127], v[172:175], v[164:167], v[124:127]
	v_mfma_f32_16x16x32_bf16 v[120:123], v[180:183], v[164:167], v[120:123]
	v_mfma_f32_16x16x32_bf16 v[116:119], v[172:175], v[192:195], v[116:119]
	v_mfma_f32_16x16x32_bf16 v[112:115], v[180:183], v[192:195], v[112:115]
	v_mfma_f32_16x16x32_bf16 v[108:111], v[172:175], v[200:203], v[108:111]
	v_mfma_f32_16x16x32_bf16 v[104:107], v[180:183], v[200:203], v[104:107]
	v_mfma_f32_16x16x32_bf16 v[100:103], v[172:175], v[208:211], v[100:103]
	v_mfma_f32_16x16x32_bf16 v[96:99], v[180:183], v[208:211], v[96:99]
	v_mfma_f32_16x16x32_bf16 v[124:127], v[176:179], v[188:191], v[124:127]
	v_mfma_f32_16x16x32_bf16 v[120:123], v[184:187], v[188:191], v[120:123]
	v_mfma_f32_16x16x32_bf16 v[116:119], v[176:179], v[196:199], v[116:119]
	v_mfma_f32_16x16x32_bf16 v[112:115], v[184:187], v[196:199], v[112:115]
	v_mfma_f32_16x16x32_bf16 v[108:111], v[176:179], v[204:207], v[108:111]
	v_mfma_f32_16x16x32_bf16 v[104:107], v[184:187], v[204:207], v[104:107]
	v_mfma_f32_16x16x32_bf16 v[100:103], v[176:179], v[212:215], v[100:103]
	v_mfma_f32_16x16x32_bf16 v[96:99], v[184:187], v[212:215], v[96:99]
	s_barrier
	v_add_u32_e32 v162, s64, v153
	v_lshl_add_u64 v[240:241], v[140:141], 0, s[50:51]
	v_readfirstlane_b32 s53, v162
	v_add_u32_e32 v163, 0x2000, v162
	v_lshl_add_u64 v[232:233], v[240:241], 0, s[20:21]
	s_mov_b32 m0, s53
	v_lshl_add_u64 v[242:243], v[138:139], 0, s[50:51]
	v_readfirstlane_b32 s53, v163
	ds_read_b128 v[216:219], v160
	ds_read_b128 v[220:223], v160 offset:1024
	ds_read_b128 v[224:227], v160 offset:2048
	ds_read_b128 v[228:231], v160 offset:3072
	global_load_lds_dwordx4 v[232:233], off
	v_lshl_add_u64 v[232:233], v[242:243], 0, s[20:21]
	s_mov_b32 m0, s53
	s_nop 0
	global_load_lds_dwordx4 v[232:233], off
	s_barrier
	s_waitcnt lgkmcnt(0)
	s_waitcnt lgkmcnt(0)
	v_mfma_f32_16x16x32_bf16 v[92:95], v[216:219], v[164:167], v[92:95]
	v_mfma_f32_16x16x32_bf16 v[88:91], v[224:227], v[164:167], v[88:91]
	v_mfma_f32_16x16x32_bf16 v[84:87], v[216:219], v[192:195], v[84:87]
	v_mfma_f32_16x16x32_bf16 v[80:83], v[224:227], v[192:195], v[80:83]
	v_mfma_f32_16x16x32_bf16 v[76:79], v[216:219], v[200:203], v[76:79]
	v_mfma_f32_16x16x32_bf16 v[72:75], v[224:227], v[200:203], v[72:75]
	v_mfma_f32_16x16x32_bf16 v[68:71], v[216:219], v[208:211], v[68:71]
	v_mfma_f32_16x16x32_bf16 v[64:67], v[224:227], v[208:211], v[64:67]
	v_mfma_f32_16x16x32_bf16 v[92:95], v[220:223], v[188:191], v[92:95]
	v_mfma_f32_16x16x32_bf16 v[88:91], v[228:231], v[188:191], v[88:91]
	v_mfma_f32_16x16x32_bf16 v[84:87], v[220:223], v[196:199], v[84:87]
	v_mfma_f32_16x16x32_bf16 v[80:83], v[228:231], v[196:199], v[80:83]
	v_mfma_f32_16x16x32_bf16 v[76:79], v[220:223], v[204:207], v[76:79]
	v_mfma_f32_16x16x32_bf16 v[72:75], v[228:231], v[204:207], v[72:75]
	v_mfma_f32_16x16x32_bf16 v[68:71], v[220:223], v[212:215], v[68:71]
	v_mfma_f32_16x16x32_bf16 v[64:67], v[228:231], v[212:215], v[64:67]
	s_barrier
	v_readfirstlane_b32 s53, v148
	v_lshl_add_u64 v[164:165], v[236:237], 0, s[22:23]
	s_mov_b32 m0, s53
	ds_read_b128 v[188:191], v152 offset:16384
	ds_read_b128 v[192:195], v152 offset:17408
	ds_read_b128 v[196:199], v151 offset:16384
	ds_read_b128 v[200:203], v151 offset:17408
	ds_read_b128 v[204:207], v150 offset:16384
	ds_read_b128 v[208:211], v150 offset:17408
	ds_read_b128 v[212:215], v149 offset:16384
	ds_read_b128 v[232:235], v149 offset:17408
	global_load_lds_dwordx4 v[164:165], off
	v_add_u32_e32 v164, 0x2000, v148
	v_lshl_add_u64 v[166:167], v[238:239], 0, s[22:23]
	v_readfirstlane_b32 s53, v164
	s_mov_b32 m0, s53
	s_nop 0
	global_load_lds_dwordx4 v[166:167], off
	s_barrier
	s_waitcnt lgkmcnt(0)
	s_waitcnt lgkmcnt(0)
	v_mfma_f32_16x16x32_bf16 v[60:63], v[172:175], v[188:191], v[60:63]
	v_mfma_f32_16x16x32_bf16 v[56:59], v[180:183], v[188:191], v[56:59]
	v_mfma_f32_16x16x32_bf16 v[52:55], v[172:175], v[196:199], v[52:55]
	v_mfma_f32_16x16x32_bf16 v[48:51], v[180:183], v[196:199], v[48:51]
	v_mfma_f32_16x16x32_bf16 v[44:47], v[172:175], v[204:207], v[44:47]
	v_mfma_f32_16x16x32_bf16 v[40:43], v[180:183], v[204:207], v[40:43]
	v_mfma_f32_16x16x32_bf16 v[36:39], v[172:175], v[212:215], v[36:39]
	v_mfma_f32_16x16x32_bf16 v[32:35], v[180:183], v[212:215], v[32:35]
	v_mfma_f32_16x16x32_bf16 v[60:63], v[176:179], v[192:195], v[60:63]
	v_mfma_f32_16x16x32_bf16 v[56:59], v[184:187], v[192:195], v[56:59]
	v_mfma_f32_16x16x32_bf16 v[52:55], v[176:179], v[200:203], v[52:55]
	v_mfma_f32_16x16x32_bf16 v[48:51], v[184:187], v[200:203], v[48:51]
	v_mfma_f32_16x16x32_bf16 v[44:47], v[176:179], v[208:211], v[44:47]
	v_mfma_f32_16x16x32_bf16 v[40:43], v[184:187], v[208:211], v[40:43]
	v_mfma_f32_16x16x32_bf16 v[36:39], v[176:179], v[232:235], v[36:39]
	v_mfma_f32_16x16x32_bf16 v[32:35], v[184:187], v[232:235], v[32:35]
	s_barrier
; #define STAGE(P, BASE, LD, br, kt) do { const char* _g = (const char*)((BASE) + (size_t)(br) * (LD) + (size_t)(kt) * 64); \
;     for (int _i = 0; _i < 2; ++_i) { int _b = tidx * 16 + _i * 8192; int _r, _c; stage_rc(_b, _r, _c); \
;       __builtin_amdgcn_global_load_lds((const unsigned*)(_g + (unsigned)((_r * (LD) + _c) * 2)), (unsigned*)((char*)(P) + _b), 16, 0, 0); } } while (0)
; #define LDA(dst, b, h) for (int m = 0; m < 4; ++m) for (int k = 0; k < 2; ++k) \
;     dst[m][k] = *reinterpret_cast<const bf16x8*>((char*)SA(b, h) + lds_byte(wr * 64 + m * 16 + fr, k * 32 + fq * 8))
; #define LDB(dst, b, h) for (int n = 0; n < 2; ++n) for (int k = 0; k < 2; ++k) \
;     dst[n][k] = *reinterpret_cast<const bf16x8*>((char*)SB(b, h) + lds_byte(wc * 32 + n * 16 + fr, k * 32 + fq * 8))
; #define MMA(ai, bj, At_, Bt_) do { __builtin_amdgcn_s_setprio(1); \
;     for (int k = 0; k < 2; ++k) for (int m = 0; m < 4; ++m) for (int n = 0; n < 2; ++n) \
;       acc[ai][bj][m][n] = __builtin_amdgcn_mfma_f32_16x16x32_bf16(At_[m][k], Bt_[n][k], acc[ai][bj][m][n], 0, 0, 0); \
;     __builtin_amdgcn_s_setprio(0); } while (0)
; #define WAIT_V(n) asm volatile("s_waitcnt vmcnt(" #n ")" ::: "memory")
; #define WAIT_L(n) asm volatile("s_waitcnt lgkmcnt(" #n ")" ::: "memory")
; #define BAR __builtin_amdgcn_s_barrier()
; #define SCHED __builtin_amdgcn_sched_barrier(0)
; template <int EPI, int lda, int ldb, int N, int K>
; __device__ __forceinline__ void gemm_phase(const u16* __restrict__ A, const u16* __restrict__ Bt, const GemmEpi ep, int wv) {
;     ...
;       STAGE(SB(0, 1), Bt, ldb, bcol + HALF, t + 2);
;       WAIT_V(6); BAR; MMA(1, 1, At, B1); BAR;
;       LDB(B0, 1, 0); SCHED; LDA(At, 1, 0); STAGE(SA(0, 1), Ab, lda, brow + HALF, t + 2);
;       WAIT_L(8); BAR; WAIT_L(0); MMA(0, 0, At, B0); BAR; SCHED;
;       LDB(B1, 1, 1); STAGE(SB(1, 0), Bt, ldb, bcol, t + 3);
;       BAR; WAIT_L(0); MMA(0, 1, At, B1); BAR;
;       LDA(At, 1, 1); STAGE(SA(1, 0), Ab, lda, brow, t + 3);
	v_add_u32_e32 v165, s65, v153
	v_lshl_add_u64 v[166:167], v[240:241], 0, s[24:25]
	v_readfirstlane_b32 s53, v165
	s_mov_b32 m0, s53
	v_lshl_add_u64 v[172:173], v[242:243], 0, s[24:25]
	global_load_lds_dwordx4 v[166:167], off
	v_add_u32_e32 v166, 0x2000, v165
	s_nop 0
	v_readfirstlane_b32 s53, v166
	s_mov_b32 m0, s53
	s_nop 0
	global_load_lds_dwordx4 v[172:173], off
	s_waitcnt vmcnt(6)
	s_barrier
	v_mfma_f32_16x16x32_bf16 v[28:31], v[216:219], v[188:191], v[28:31]
	v_mfma_f32_16x16x32_bf16 v[24:27], v[224:227], v[188:191], v[24:27]
	v_mfma_f32_16x16x32_bf16 v[20:23], v[216:219], v[196:199], v[20:23]
	v_mfma_f32_16x16x32_bf16 v[16:19], v[224:227], v[196:199], v[16:19]
	v_mfma_f32_16x16x32_bf16 v[12:15], v[216:219], v[204:207], v[12:15]
	v_mfma_f32_16x16x32_bf16 v[8:11], v[224:227], v[204:207], v[8:11]
	v_mfma_f32_16x16x32_bf16 v[4:7], v[216:219], v[212:215], v[4:7]
	v_mfma_f32_16x16x32_bf16 v[0:3], v[224:227], v[212:215], v[0:3]
	v_mfma_f32_16x16x32_bf16 v[28:31], v[220:223], v[192:195], v[28:31]
	v_mfma_f32_16x16x32_bf16 v[24:27], v[228:231], v[192:195], v[24:27]
	v_mfma_f32_16x16x32_bf16 v[20:23], v[220:223], v[200:203], v[20:23]
	v_mfma_f32_16x16x32_bf16 v[16:19], v[228:231], v[200:203], v[16:19]
	v_mfma_f32_16x16x32_bf16 v[12:15], v[220:223], v[208:211], v[12:15]
	v_mfma_f32_16x16x32_bf16 v[8:11], v[228:231], v[208:211], v[8:11]
	v_mfma_f32_16x16x32_bf16 v[4:7], v[220:223], v[232:235], v[4:7]
	v_mfma_f32_16x16x32_bf16 v[0:3], v[228:231], v[232:235], v[0:3]
	s_barrier
	ds_read_b128 v[172:175], v156
	ds_read_b128 v[176:179], v156 offset:1024
	ds_read_b128 v[180:183], v156 offset:2048
	ds_read_b128 v[184:187], v156 offset:3072
	v_add_u32_e32 v167, 0x4000, v148
	v_add_u32_e32 v168, 0x6000, v148
	v_readfirstlane_b32 s53, v167
	v_lshl_add_u64 v[220:221], v[236:237], 0, s[26:27]
	s_mov_b32 m0, s53
	v_readfirstlane_b32 s53, v168
	ds_read_b128 v[188:191], v152 offset:32768
	ds_read_b128 v[192:195], v152 offset:33792
	ds_read_b128 v[196:199], v151 offset:32768
	ds_read_b128 v[200:203], v151 offset:33792
	ds_read_b128 v[204:207], v150 offset:32768
	ds_read_b128 v[208:211], v150 offset:33792
	ds_read_b128 v[212:215], v149 offset:32768
	ds_read_b128 v[216:219], v149 offset:33792
	global_load_lds_dwordx4 v[220:221], off
	v_lshl_add_u64 v[220:221], v[238:239], 0, s[26:27]
	s_mov_b32 m0, s53
	s_nop 0
	global_load_lds_dwordx4 v[220:221], off
	s_waitcnt lgkmcnt(8)
	s_barrier
	s_waitcnt lgkmcnt(0)
	s_waitcnt lgkmcnt(0)
	v_mfma_f32_16x16x32_bf16 v[124:127], v[172:175], v[188:191], v[124:127]
	v_mfma_f32_16x16x32_bf16 v[120:123], v[180:183], v[188:191], v[120:123]
	v_mfma_f32_16x16x32_bf16 v[116:119], v[172:175], v[196:199], v[116:119]
	v_mfma_f32_16x16x32_bf16 v[112:115], v[180:183], v[196:199], v[112:115]
	v_mfma_f32_16x16x32_bf16 v[108:111], v[172:175], v[204:207], v[108:111]
	v_mfma_f32_16x16x32_bf16 v[104:107], v[180:183], v[204:207], v[104:107]
	v_mfma_f32_16x16x32_bf16 v[100:103], v[172:175], v[212:215], v[100:103]
	v_mfma_f32_16x16x32_bf16 v[96:99], v[180:183], v[212:215], v[96:99]
	v_mfma_f32_16x16x32_bf16 v[124:127], v[176:179], v[192:195], v[124:127]
	v_mfma_f32_16x16x32_bf16 v[120:123], v[184:187], v[192:195], v[120:123]
	v_mfma_f32_16x16x32_bf16 v[116:119], v[176:179], v[200:203], v[116:119]
	v_mfma_f32_16x16x32_bf16 v[112:115], v[184:187], v[200:203], v[112:115]
	v_mfma_f32_16x16x32_bf16 v[108:111], v[176:179], v[208:211], v[108:111]
	v_mfma_f32_16x16x32_bf16 v[104:107], v[184:187], v[208:211], v[104:107]
	v_mfma_f32_16x16x32_bf16 v[100:103], v[176:179], v[216:219], v[100:103]
	v_mfma_f32_16x16x32_bf16 v[96:99], v[184:187], v[216:219], v[96:99]
	s_barrier
	v_readfirstlane_b32 s53, v155
	v_add_u32_e32 v171, 0x2000, v155
	v_lshl_add_u64 v[244:245], v[240:241], 0, s[40:41]
	s_mov_b32 m0, s53
	v_readfirstlane_b32 s53, v171
	ds_read_b128 v[220:223], v154
	ds_read_b128 v[224:227], v154 offset:1024
	ds_read_b128 v[228:231], v154 offset:2048
	ds_read_b128 v[232:235], v154 offset:3072
	global_load_lds_dwordx4 v[244:245], off
	v_lshl_add_u64 v[244:245], v[242:243], 0, s[40:41]
	s_mov_b32 m0, s53
	s_nop 0
	global_load_lds_dwordx4 v[244:245], off
	s_barrier
	s_waitcnt lgkmcnt(0)
	s_waitcnt lgkmcnt(0)
	v_mfma_f32_16x16x32_bf16 v[92:95], v[220:223], v[188:191], v[92:95]
	v_mfma_f32_16x16x32_bf16 v[88:91], v[228:231], v[188:191], v[88:91]
	v_mfma_f32_16x16x32_bf16 v[84:87], v[220:223], v[196:199], v[84:87]
	v_mfma_f32_16x16x32_bf16 v[80:83], v[228:231], v[196:199], v[80:83]
	v_mfma_f32_16x16x32_bf16 v[76:79], v[220:223], v[204:207], v[76:79]
	v_mfma_f32_16x16x32_bf16 v[72:75], v[228:231], v[204:207], v[72:75]
	v_mfma_f32_16x16x32_bf16 v[68:71], v[220:223], v[212:215], v[68:71]
	v_mfma_f32_16x16x32_bf16 v[64:67], v[228:231], v[212:215], v[64:67]
	v_mfma_f32_16x16x32_bf16 v[92:95], v[224:227], v[192:195], v[92:95]
	v_mfma_f32_16x16x32_bf16 v[88:91], v[232:235], v[192:195], v[88:91]
	v_mfma_f32_16x16x32_bf16 v[84:87], v[224:227], v[200:203], v[84:87]
	v_mfma_f32_16x16x32_bf16 v[80:83], v[232:235], v[200:203], v[80:83]
	v_mfma_f32_16x16x32_bf16 v[76:79], v[224:227], v[208:211], v[76:79]
	v_mfma_f32_16x16x32_bf16 v[72:75], v[232:235], v[208:211], v[72:75]
	v_mfma_f32_16x16x32_bf16 v[68:71], v[224:227], v[216:219], v[68:71]
	v_mfma_f32_16x16x32_bf16 v[64:67], v[232:235], v[216:219], v[64:67]
	s_barrier
	v_readfirstlane_b32 s53, v157
	v_lshl_add_u64 v[236:237], v[236:237], 0, s[42:43]
	s_mov_b32 m0, s53
	v_readfirstlane_b32 s53, v158
	ds_read_b128 v[188:191], v152 offset:49152
	ds_read_b128 v[192:195], v152 offset:50176
	ds_read_b128 v[196:199], v151 offset:49152
	ds_read_b128 v[200:203], v151 offset:50176
	ds_read_b128 v[204:207], v150 offset:49152
	ds_read_b128 v[208:211], v150 offset:50176
	ds_read_b128 v[212:215], v149 offset:49152
	ds_read_b128 v[216:219], v149 offset:50176
	global_load_lds_dwordx4 v[236:237], off
	v_lshl_add_u64 v[236:237], v[238:239], 0, s[42:43]
	s_mov_b32 m0, s53
	s_nop 0
	global_load_lds_dwordx4 v[236:237], off
	s_barrier
; #define STAGE(P, BASE, LD, br, kt) do { const char* _g = (const char*)((BASE) + (size_t)(br) * (LD) + (size_t)(kt) * 64); \
;     for (int _i = 0; _i < 2; ++_i) { int _b = tidx * 16 + _i * 8192; int _r, _c; stage_rc(_b, _r, _c); \
;       __builtin_amdgcn_global_load_lds((const unsigned*)(_g + (unsigned)((_r * (LD) + _c) * 2)), (unsigned*)((char*)(P) + _b), 16, 0, 0); } } while (0)
; #define LDA(dst, b, h) for (int m = 0; m < 4; ++m) for (int k = 0; k < 2; ++k) \
;     dst[m][k] = *reinterpret_cast<const bf16x8*>((char*)SA(b, h) + lds_byte(wr * 64 + m * 16 + fr, k * 32 + fq * 8))
; #define LDB(dst, b, h) for (int n = 0; n < 2; ++n) for (int k = 0; k < 2; ++k) \
;     dst[n][k] = *reinterpret_cast<const bf16x8*>((char*)SB(b, h) + lds_byte(wc * 32 + n * 16 + fr, k * 32 + fq * 8))
; #define MMA(ai, bj, At_, Bt_) do { __builtin_amdgcn_s_setprio(1); \
;     for (int k = 0; k < 2; ++k) for (int m = 0; m < 4; ++m) for (int n = 0; n < 2; ++n) \
;       acc[ai][bj][m][n] = __builtin_amdgcn_mfma_f32_16x16x32_bf16(At_[m][k], Bt_[n][k], acc[ai][bj][m][n], 0, 0, 0); \
;     __builtin_amdgcn_s_setprio(0); } while (0)
; #define WAIT_V(n) asm volatile("s_waitcnt vmcnt(" #n ")" ::: "memory")
; #define WAIT_L(n) asm volatile("s_waitcnt lgkmcnt(" #n ")" ::: "memory")
; #define BAR __builtin_amdgcn_s_barrier()
; #define SCHED __builtin_amdgcn_sched_barrier(0)
; template <int EPI, int lda, int ldb, int N, int K>
; __device__ __forceinline__ void gemm_phase(const u16* __restrict__ A, const u16* __restrict__ Bt, const GemmEpi ep, int wv) {
;     ...
;       BAR; WAIT_L(0); MMA(1, 0, At, B0); BAR; SCHED;
;       STAGE(SB(1, 1), Bt, ldb, bcol + HALF, t + 3);
;       WAIT_V(6); BAR; MMA(1, 1, At, B1); BAR;
;     }
;     { LDB(B0, 0, 0); LDA(At, 0, 0); STAGE(SA(1, 1), Ab, lda, brow + HALF, nt - 1);
;       BAR; WAIT_L(0); MMA(0, 0, At, B0); BAR;
;       LDB(B1, 0, 1); BAR; WAIT_L(0); MMA(0, 1, At, B1); BAR;
	s_waitcnt lgkmcnt(0)
	s_waitcnt lgkmcnt(0)
	v_mfma_f32_16x16x32_bf16 v[60:63], v[172:175], v[188:191], v[60:63]
	v_mfma_f32_16x16x32_bf16 v[56:59], v[180:183], v[188:191], v[56:59]
	v_mfma_f32_16x16x32_bf16 v[52:55], v[172:175], v[196:199], v[52:55]
	v_mfma_f32_16x16x32_bf16 v[48:51], v[180:183], v[196:199], v[48:51]
	v_mfma_f32_16x16x32_bf16 v[44:47], v[172:175], v[204:207], v[44:47]
	v_mfma_f32_16x16x32_bf16 v[40:43], v[180:183], v[204:207], v[40:43]
	v_mfma_f32_16x16x32_bf16 v[36:39], v[172:175], v[212:215], v[36:39]
	v_mfma_f32_16x16x32_bf16 v[32:35], v[180:183], v[212:215], v[32:35]
	v_mfma_f32_16x16x32_bf16 v[60:63], v[176:179], v[192:195], v[60:63]
	v_mfma_f32_16x16x32_bf16 v[56:59], v[184:187], v[192:195], v[56:59]
	v_mfma_f32_16x16x32_bf16 v[52:55], v[176:179], v[200:203], v[52:55]
	v_mfma_f32_16x16x32_bf16 v[48:51], v[184:187], v[200:203], v[48:51]
	v_mfma_f32_16x16x32_bf16 v[44:47], v[176:179], v[208:211], v[44:47]
	v_mfma_f32_16x16x32_bf16 v[40:43], v[184:187], v[208:211], v[40:43]
	v_mfma_f32_16x16x32_bf16 v[36:39], v[176:179], v[216:219], v[36:39]
	v_mfma_f32_16x16x32_bf16 v[32:35], v[184:187], v[216:219], v[32:35]
	s_barrier
	v_readfirstlane_b32 s53, v159
	v_add_u32_e32 v171, 0x2000, v159
	v_lshl_add_u64 v[172:173], v[240:241], 0, s[44:45]
	s_mov_b32 m0, s53
	v_readfirstlane_b32 s53, v171
	global_load_lds_dwordx4 v[172:173], off
	v_lshl_add_u64 v[172:173], v[242:243], 0, s[44:45]
	s_mov_b32 m0, s53
	s_nop 0
	global_load_lds_dwordx4 v[172:173], off
	s_waitcnt vmcnt(6)
	s_barrier
	v_mfma_f32_16x16x32_bf16 v[28:31], v[220:223], v[188:191], v[28:31]
	v_mfma_f32_16x16x32_bf16 v[24:27], v[228:231], v[188:191], v[24:27]
	v_mfma_f32_16x16x32_bf16 v[20:23], v[220:223], v[196:199], v[20:23]
	v_mfma_f32_16x16x32_bf16 v[16:19], v[228:231], v[196:199], v[16:19]
	v_mfma_f32_16x16x32_bf16 v[12:15], v[220:223], v[204:207], v[12:15]
	v_mfma_f32_16x16x32_bf16 v[8:11], v[228:231], v[204:207], v[8:11]
	v_mfma_f32_16x16x32_bf16 v[4:7], v[220:223], v[212:215], v[4:7]
	v_mfma_f32_16x16x32_bf16 v[0:3], v[228:231], v[212:215], v[0:3]
	v_mfma_f32_16x16x32_bf16 v[28:31], v[224:227], v[192:195], v[28:31]
	v_mfma_f32_16x16x32_bf16 v[24:27], v[232:235], v[192:195], v[24:27]
	v_mfma_f32_16x16x32_bf16 v[20:23], v[224:227], v[200:203], v[20:23]
	v_mfma_f32_16x16x32_bf16 v[16:19], v[232:235], v[200:203], v[16:19]
	v_mfma_f32_16x16x32_bf16 v[12:15], v[224:227], v[208:211], v[12:15]
	v_mfma_f32_16x16x32_bf16 v[8:11], v[232:235], v[208:211], v[8:11]
	v_mfma_f32_16x16x32_bf16 v[4:7], v[224:227], v[216:219], v[4:7]
	v_mfma_f32_16x16x32_bf16 v[0:3], v[232:235], v[216:219], v[0:3]
	s_barrier
	s_add_i32 s52, s52, 2
	s_add_u32 s50, s50, 0x100
	s_addc_u32 s51, s51, 0
	s_cmp_gt_u32 s52, 27
	s_cbranch_scc0 .LBB0_770
	s_add_i32 s50, s48, 0x80
	s_mul_hi_i32 s51, s50, 0x1080
	s_mulk_i32 s50, 0x1080
	s_add_u32 s50, s61, s50
	s_addc_u32 s51, s62, s51
	v_lshl_add_u64 v[158:159], s[50:51], 0, v[128:129]
	v_readfirstlane_b32 s52, v169
	v_lshl_add_u64 v[158:159], v[158:159], 0, s[46:47]
	s_mov_b32 m0, s52
	ds_read_b128 v[134:137], v161
	ds_read_b128 v[138:141], v161 offset:1024
	ds_read_b128 v[172:175], v161 offset:2048
	ds_read_b128 v[176:179], v161 offset:3072
	ds_read_b128 v[180:183], v152
	ds_read_b128 v[184:187], v152 offset:1024
	ds_read_b128 v[188:191], v151
	ds_read_b128 v[192:195], v151 offset:1024
	ds_read_b128 v[196:199], v150
	ds_read_b128 v[200:203], v150 offset:1024
	ds_read_b128 v[204:207], v149
	ds_read_b128 v[208:211], v149 offset:1024
	global_load_lds_dwordx4 v[158:159], off
	v_lshl_add_u64 v[158:159], s[50:51], 0, v[132:133]
	v_readfirstlane_b32 s50, v170
	v_lshl_add_u64 v[158:159], v[158:159], 0, s[46:47]
	s_mov_b32 m0, s50
	s_nop 0
	global_load_lds_dwordx4 v[158:159], off
	s_barrier
	s_waitcnt lgkmcnt(0)
	s_waitcnt lgkmcnt(0)
	v_mfma_f32_16x16x32_bf16 v[124:127], v[134:137], v[180:183], v[124:127]
	v_mfma_f32_16x16x32_bf16 v[120:123], v[172:175], v[180:183], v[120:123]
	v_mfma_f32_16x16x32_bf16 v[116:119], v[134:137], v[188:191], v[116:119]
	v_mfma_f32_16x16x32_bf16 v[112:115], v[172:175], v[188:191], v[112:115]
	v_mfma_f32_16x16x32_bf16 v[108:111], v[134:137], v[196:199], v[108:111]
	v_mfma_f32_16x16x32_bf16 v[104:107], v[172:175], v[196:199], v[104:107]
	v_mfma_f32_16x16x32_bf16 v[100:103], v[134:137], v[204:207], v[100:103]
	v_mfma_f32_16x16x32_bf16 v[96:99], v[172:175], v[204:207], v[96:99]
	v_mfma_f32_16x16x32_bf16 v[124:127], v[138:141], v[184:187], v[124:127]
	v_mfma_f32_16x16x32_bf16 v[120:123], v[176:179], v[184:187], v[120:123]
	v_mfma_f32_16x16x32_bf16 v[116:119], v[138:141], v[192:195], v[116:119]
	v_mfma_f32_16x16x32_bf16 v[112:115], v[176:179], v[192:195], v[112:115]
	v_mfma_f32_16x16x32_bf16 v[108:111], v[138:141], v[200:203], v[108:111]
	v_mfma_f32_16x16x32_bf16 v[104:107], v[176:179], v[200:203], v[104:107]
	v_mfma_f32_16x16x32_bf16 v[100:103], v[138:141], v[208:211], v[100:103]
	v_mfma_f32_16x16x32_bf16 v[96:99], v[176:179], v[208:211], v[96:99]
	s_barrier
	ds_read_b128 v[212:215], v160
	ds_read_b128 v[216:219], v160 offset:1024
	ds_read_b128 v[220:223], v160 offset:2048
	ds_read_b128 v[158:161], v160 offset:3072
	s_barrier
; #define LDA(dst, b, h) for (int m = 0; m < 4; ++m) for (int k = 0; k < 2; ++k) \
;     dst[m][k] = *reinterpret_cast<const bf16x8*>((char*)SA(b, h) + lds_byte(wr * 64 + m * 16 + fr, k * 32 + fq * 8))
; #define LDB(dst, b, h) for (int n = 0; n < 2; ++n) for (int k = 0; k < 2; ++k) \
;     dst[n][k] = *reinterpret_cast<const bf16x8*>((char*)SB(b, h) + lds_byte(wc * 32 + n * 16 + fr, k * 32 + fq * 8))
; #define MMA(ai, bj, At_, Bt_) do { __builtin_amdgcn_s_setprio(1); \
;     for (int k = 0; k < 2; ++k) for (int m = 0; m < 4; ++m) for (int n = 0; n < 2; ++n) \
;       acc[ai][bj][m][n] = __builtin_amdgcn_mfma_f32_16x16x32_bf16(At_[m][k], Bt_[n][k], acc[ai][bj][m][n], 0, 0, 0); \
;     __builtin_amdgcn_s_setprio(0); } while (0)
; #define WAIT_V(n) asm volatile("s_waitcnt vmcnt(" #n ")" ::: "memory")
; #define WAIT_L(n) asm volatile("s_waitcnt lgkmcnt(" #n ")" ::: "memory")
; #define BAR __builtin_amdgcn_s_barrier()
; template <int EPI, int lda, int ldb, int N, int K>
; __device__ __forceinline__ void gemm_phase(const u16* __restrict__ A, const u16* __restrict__ Bt, const GemmEpi ep, int wv) {
;     ...
;       LDB(B1, 0, 1); BAR; WAIT_L(0); MMA(0, 1, At, B1); BAR;
;       LDA(At, 0, 1); WAIT_V(4); BAR; WAIT_L(0); MMA(1, 0, At, B0); MMA(1, 1, At, B1); BAR; }
;     { LDB(B0, 1, 0); LDA(At, 1, 0); WAIT_V(2); BAR; WAIT_L(0); MMA(0, 0, At, B0); BAR;
	s_waitcnt lgkmcnt(0)
	s_waitcnt lgkmcnt(0)
	v_mfma_f32_16x16x32_bf16 v[92:95], v[212:215], v[180:183], v[92:95]
	v_mfma_f32_16x16x32_bf16 v[88:91], v[220:223], v[180:183], v[88:91]
	v_mfma_f32_16x16x32_bf16 v[76:79], v[212:215], v[196:199], v[76:79]
	v_mfma_f32_16x16x32_bf16 v[72:75], v[220:223], v[196:199], v[72:75]
	v_mfma_f32_16x16x32_bf16 v[84:87], v[212:215], v[188:191], v[84:87]
	v_mfma_f32_16x16x32_bf16 v[80:83], v[220:223], v[188:191], v[80:83]
	v_mfma_f32_16x16x32_bf16 v[68:71], v[212:215], v[204:207], v[68:71]
	v_mfma_f32_16x16x32_bf16 v[64:67], v[220:223], v[204:207], v[64:67]
	v_mfma_f32_16x16x32_bf16 v[92:95], v[216:219], v[184:187], v[92:95]
	v_mfma_f32_16x16x32_bf16 v[88:91], v[158:161], v[184:187], v[88:91]
	v_mfma_f32_16x16x32_bf16 v[76:79], v[216:219], v[200:203], v[76:79]
	v_mfma_f32_16x16x32_bf16 v[72:75], v[158:161], v[200:203], v[72:75]
	v_mfma_f32_16x16x32_bf16 v[180:183], v[216:219], v[192:195], v[84:87]
	v_mfma_f32_16x16x32_bf16 v[184:187], v[158:161], v[192:195], v[80:83]
	v_mfma_f32_16x16x32_bf16 v[188:191], v[216:219], v[208:211], v[68:71]
	v_mfma_f32_16x16x32_bf16 v[192:195], v[158:161], v[208:211], v[64:67]
	s_barrier
	s_nop 0
	ds_read_b128 v[64:67], v152 offset:16384
	ds_read_b128 v[68:71], v152 offset:17408
	ds_read_b128 v[80:83], v151 offset:16384
	ds_read_b128 v[84:87], v151 offset:17408
	ds_read_b128 v[196:199], v150 offset:16384
	ds_read_b128 v[200:203], v150 offset:17408
	ds_read_b128 v[204:207], v149 offset:16384
	ds_read_b128 v[208:211], v149 offset:17408
	s_waitcnt vmcnt(4)
	s_barrier
	s_waitcnt lgkmcnt(0)
	s_waitcnt lgkmcnt(0)
	v_mfma_f32_16x16x32_bf16 v[60:63], v[134:137], v[64:67], v[60:63]
	v_mfma_f32_16x16x32_bf16 v[56:59], v[172:175], v[64:67], v[56:59]
	v_mfma_f32_16x16x32_bf16 v[52:55], v[134:137], v[80:83], v[52:55]
	v_mfma_f32_16x16x32_bf16 v[48:51], v[172:175], v[80:83], v[48:51]
	v_mfma_f32_16x16x32_bf16 v[44:47], v[134:137], v[196:199], v[44:47]
	v_mfma_f32_16x16x32_bf16 v[40:43], v[172:175], v[196:199], v[40:43]
	v_mfma_f32_16x16x32_bf16 v[36:39], v[134:137], v[204:207], v[36:39]
	v_mfma_f32_16x16x32_bf16 v[32:35], v[172:175], v[204:207], v[32:35]
	v_mfma_f32_16x16x32_bf16 v[60:63], v[138:141], v[68:71], v[60:63]
	v_mfma_f32_16x16x32_bf16 v[56:59], v[176:179], v[68:71], v[56:59]
	v_mfma_f32_16x16x32_bf16 v[52:55], v[138:141], v[84:87], v[52:55]
	v_mfma_f32_16x16x32_bf16 v[48:51], v[176:179], v[84:87], v[48:51]
	v_mfma_f32_16x16x32_bf16 v[44:47], v[138:141], v[200:203], v[44:47]
	v_mfma_f32_16x16x32_bf16 v[40:43], v[176:179], v[200:203], v[40:43]
	v_mfma_f32_16x16x32_bf16 v[36:39], v[138:141], v[208:211], v[36:39]
	v_mfma_f32_16x16x32_bf16 v[32:35], v[176:179], v[208:211], v[32:35]
	v_mfma_f32_16x16x32_bf16 v[28:31], v[212:215], v[64:67], v[28:31]
	v_mfma_f32_16x16x32_bf16 v[24:27], v[220:223], v[64:67], v[24:27]
	v_mfma_f32_16x16x32_bf16 v[12:15], v[212:215], v[196:199], v[12:15]
	v_mfma_f32_16x16x32_bf16 v[8:11], v[220:223], v[196:199], v[8:11]
	v_mfma_f32_16x16x32_bf16 v[20:23], v[212:215], v[80:83], v[20:23]
	v_mfma_f32_16x16x32_bf16 v[16:19], v[220:223], v[80:83], v[16:19]
	v_mfma_f32_16x16x32_bf16 v[4:7], v[212:215], v[204:207], v[4:7]
	v_mfma_f32_16x16x32_bf16 v[0:3], v[220:223], v[204:207], v[0:3]
	v_mfma_f32_16x16x32_bf16 v[28:31], v[216:219], v[68:71], v[28:31]
	v_mfma_f32_16x16x32_bf16 v[24:27], v[158:161], v[68:71], v[24:27]
	v_mfma_f32_16x16x32_bf16 v[12:15], v[216:219], v[200:203], v[12:15]
	v_mfma_f32_16x16x32_bf16 v[8:11], v[158:161], v[200:203], v[8:11]
	v_mfma_f32_16x16x32_bf16 v[134:137], v[216:219], v[84:87], v[20:23]
	v_mfma_f32_16x16x32_bf16 v[138:141], v[158:161], v[84:87], v[16:19]
	v_mfma_f32_16x16x32_bf16 v[170:173], v[216:219], v[208:211], v[4:7]
	v_mfma_f32_16x16x32_bf16 v[158:161], v[158:161], v[208:211], v[0:3]
	s_barrier
	s_nop 0
	ds_read_b128 v[0:3], v156
	ds_read_b128 v[4:7], v156 offset:1024
	ds_read_b128 v[16:19], v156 offset:2048
	ds_read_b128 v[174:177], v156 offset:3072
	ds_read_b128 v[20:23], v152 offset:32768
	ds_read_b128 v[196:199], v152 offset:33792
	ds_read_b128 v[200:203], v151 offset:32768
	ds_read_b128 v[204:207], v151 offset:33792
	ds_read_b128 v[208:211], v150 offset:32768
	ds_read_b128 v[212:215], v150 offset:33792
	ds_read_b128 v[216:219], v149 offset:32768
	ds_read_b128 v[220:223], v149 offset:33792
	s_waitcnt vmcnt(2)
	s_barrier
; #define LDA(dst, b, h) for (int m = 0; m < 4; ++m) for (int k = 0; k < 2; ++k) \
;     dst[m][k] = *reinterpret_cast<const bf16x8*>((char*)SA(b, h) + lds_byte(wr * 64 + m * 16 + fr, k * 32 + fq * 8))
; #define LDB(dst, b, h) for (int n = 0; n < 2; ++n) for (int k = 0; k < 2; ++k) \
;     dst[n][k] = *reinterpret_cast<const bf16x8*>((char*)SB(b, h) + lds_byte(wc * 32 + n * 16 + fr, k * 32 + fq * 8))
; #define MMA(ai, bj, At_, Bt_) do { __builtin_amdgcn_s_setprio(1); \
;     for (int k = 0; k < 2; ++k) for (int m = 0; m < 4; ++m) for (int n = 0; n < 2; ++n) \
;       acc[ai][bj][m][n] = __builtin_amdgcn_mfma_f32_16x16x32_bf16(At_[m][k], Bt_[n][k], acc[ai][bj][m][n], 0, 0, 0); \
;     __builtin_amdgcn_s_setprio(0); } while (0)
; #define WAIT_V(n) asm volatile("s_waitcnt vmcnt(" #n ")" ::: "memory")
; #define WAIT_L(n) asm volatile("s_waitcnt lgkmcnt(" #n ")" ::: "memory")
; #define BAR __builtin_amdgcn_s_barrier()
; template <int EPI, int lda, int ldb, int N, int K>
; __device__ __forceinline__ void gemm_phase(const u16* __restrict__ A, const u16* __restrict__ Bt, const GemmEpi ep, int wv) {
;     ...
;     { LDB(B0, 1, 0); LDA(At, 1, 0); WAIT_V(2); BAR; WAIT_L(0); MMA(0, 0, At, B0); BAR;
;       LDB(B1, 1, 1); WAIT_V(0); BAR; WAIT_L(0); MMA(0, 1, At, B1); BAR;
;       LDA(At, 1, 1); BAR; WAIT_L(0); MMA(1, 0, At, B0); MMA(1, 1, At, B1); BAR; }
;     if (wr == 0) BAR;
	s_waitcnt lgkmcnt(0)
	s_waitcnt lgkmcnt(0)
	v_mfma_f32_16x16x32_bf16 v[64:67], v[0:3], v[20:23], v[124:127]
	v_mfma_f32_16x16x32_bf16 v[68:71], v[16:19], v[20:23], v[120:123]
	v_mfma_f32_16x16x32_bf16 v[80:83], v[0:3], v[200:203], v[116:119]
	v_mfma_f32_16x16x32_bf16 v[84:87], v[16:19], v[200:203], v[112:115]
	v_mfma_f32_16x16x32_bf16 v[108:111], v[0:3], v[208:211], v[108:111]
	v_mfma_f32_16x16x32_bf16 v[104:107], v[16:19], v[208:211], v[104:107]
	v_mfma_f32_16x16x32_bf16 v[120:123], v[0:3], v[216:219], v[100:103]
	v_mfma_f32_16x16x32_bf16 v[124:127], v[16:19], v[216:219], v[96:99]
	v_mfma_f32_16x16x32_bf16 v[116:119], v[4:7], v[196:199], v[64:67]
	v_mfma_f32_16x16x32_bf16 v[112:115], v[174:177], v[196:199], v[68:71]
	v_mfma_f32_16x16x32_bf16 v[100:103], v[4:7], v[204:207], v[80:83]
	v_mfma_f32_16x16x32_bf16 v[96:99], v[174:177], v[204:207], v[84:87]
	v_mfma_f32_16x16x32_bf16 v[84:87], v[4:7], v[212:215], v[108:111]
	v_mfma_f32_16x16x32_bf16 v[80:83], v[174:177], v[212:215], v[104:107]
	v_mfma_f32_16x16x32_bf16 v[68:71], v[4:7], v[220:223], v[120:123]
	v_mfma_f32_16x16x32_bf16 v[64:67], v[174:177], v[220:223], v[124:127]
	s_barrier
	ds_read_b128 v[224:227], v154
	ds_read_b128 v[228:231], v154 offset:1024
	ds_read_b128 v[232:235], v154 offset:2048
	ds_read_b128 v[154:157], v154 offset:3072
	s_waitcnt vmcnt(0)
	s_barrier
	s_waitcnt lgkmcnt(0)
	s_waitcnt lgkmcnt(0)
	v_mfma_f32_16x16x32_bf16 v[92:95], v[224:227], v[20:23], v[92:95]
	v_mfma_f32_16x16x32_bf16 v[20:23], v[232:235], v[20:23], v[88:91]
	v_mfma_f32_16x16x32_bf16 v[88:91], v[224:227], v[200:203], v[180:183]
	v_mfma_f32_16x16x32_bf16 v[104:107], v[232:235], v[200:203], v[184:187]
	v_mfma_f32_16x16x32_bf16 v[76:79], v[224:227], v[208:211], v[76:79]
	v_mfma_f32_16x16x32_bf16 v[72:75], v[232:235], v[208:211], v[72:75]
	v_mfma_f32_16x16x32_bf16 v[178:181], v[224:227], v[216:219], v[188:191]
	v_mfma_f32_16x16x32_bf16 v[182:185], v[232:235], v[216:219], v[192:195]
	v_mfma_f32_16x16x32_bf16 v[124:127], v[228:231], v[196:199], v[92:95]
	v_mfma_f32_16x16x32_bf16 v[120:123], v[154:157], v[196:199], v[20:23]
	v_mfma_f32_16x16x32_bf16 v[108:111], v[228:231], v[204:207], v[88:91]
	v_mfma_f32_16x16x32_bf16 v[104:107], v[154:157], v[204:207], v[104:107]
	v_mfma_f32_16x16x32_bf16 v[92:95], v[228:231], v[212:215], v[76:79]
	v_mfma_f32_16x16x32_bf16 v[88:91], v[154:157], v[212:215], v[72:75]
	v_mfma_f32_16x16x32_bf16 v[76:79], v[228:231], v[220:223], v[178:181]
	v_mfma_f32_16x16x32_bf16 v[72:75], v[154:157], v[220:223], v[182:185]
	s_barrier
	ds_read_b128 v[178:181], v152 offset:49152
	ds_read_b128 v[182:185], v152 offset:50176
	ds_read_b128 v[186:189], v151 offset:49152
	ds_read_b128 v[190:193], v151 offset:50176
	ds_read_b128 v[194:197], v150 offset:49152
	ds_read_b128 v[150:153], v150 offset:50176
	ds_read_b128 v[198:201], v149 offset:49152
	ds_read_b128 v[202:205], v149 offset:50176
	s_barrier
	s_waitcnt lgkmcnt(0)
	s_waitcnt lgkmcnt(0)
	v_mfma_f32_16x16x32_bf16 v[20:23], v[0:3], v[178:181], v[60:63]
	v_mfma_f32_16x16x32_bf16 v[56:59], v[16:19], v[178:181], v[56:59]
	v_mfma_f32_16x16x32_bf16 v[60:63], v[0:3], v[186:189], v[52:55]
	v_mfma_f32_16x16x32_bf16 v[206:209], v[16:19], v[186:189], v[48:51]
	v_mfma_f32_16x16x32_bf16 v[44:47], v[0:3], v[194:197], v[44:47]
	v_mfma_f32_16x16x32_bf16 v[40:43], v[16:19], v[194:197], v[40:43]
	v_mfma_f32_16x16x32_bf16 v[0:3], v[0:3], v[198:201], v[36:39]
	v_mfma_f32_16x16x32_bf16 v[210:213], v[16:19], v[198:201], v[32:35]
	v_mfma_f32_16x16x32_bf16 v[52:55], v[4:7], v[182:185], v[20:23]
	v_mfma_f32_16x16x32_bf16 v[48:51], v[174:177], v[182:185], v[56:59]
	v_mfma_f32_16x16x32_bf16 v[36:39], v[4:7], v[190:193], v[60:63]
	v_mfma_f32_16x16x32_bf16 v[32:35], v[174:177], v[190:193], v[206:209]
	v_mfma_f32_16x16x32_bf16 v[20:23], v[4:7], v[150:153], v[44:47]
	v_mfma_f32_16x16x32_bf16 v[16:19], v[174:177], v[150:153], v[40:43]
	v_mfma_f32_16x16x32_bf16 v[4:7], v[4:7], v[202:205], v[0:3]
	v_mfma_f32_16x16x32_bf16 v[0:3], v[174:177], v[202:205], v[210:213]
	v_mfma_f32_16x16x32_bf16 v[28:31], v[224:227], v[178:181], v[28:31]
	v_mfma_f32_16x16x32_bf16 v[24:27], v[232:235], v[178:181], v[24:27]
	v_mfma_f32_16x16x32_bf16 v[40:43], v[224:227], v[186:189], v[134:137]
	v_mfma_f32_16x16x32_bf16 v[134:137], v[232:235], v[186:189], v[138:141]
	v_mfma_f32_16x16x32_bf16 v[12:15], v[224:227], v[194:197], v[12:15]
	v_mfma_f32_16x16x32_bf16 v[8:11], v[232:235], v[194:197], v[8:11]
	v_mfma_f32_16x16x32_bf16 v[138:141], v[224:227], v[198:201], v[170:173]
	v_mfma_f32_16x16x32_bf16 v[158:161], v[232:235], v[198:201], v[158:161]
	v_mfma_f32_16x16x32_bf16 v[60:63], v[228:231], v[182:185], v[28:31]
	v_mfma_f32_16x16x32_bf16 v[56:59], v[154:157], v[182:185], v[24:27]
	v_mfma_f32_16x16x32_bf16 v[44:47], v[228:231], v[190:193], v[40:43]
	v_mfma_f32_16x16x32_bf16 v[40:43], v[154:157], v[190:193], v[134:137]
	v_mfma_f32_16x16x32_bf16 v[28:31], v[228:231], v[150:153], v[12:15]
	v_mfma_f32_16x16x32_bf16 v[24:27], v[154:157], v[150:153], v[8:11]
	v_mfma_f32_16x16x32_bf16 v[12:15], v[228:231], v[202:205], v[138:141]
	v_mfma_f32_16x16x32_bf16 v[8:11], v[154:157], v[202:205], v[158:161]
	v_cmp_gt_u32_e32 vcc, s66, v130
	s_barrier
	s_and_saveexec_b64 s[50:51], vcc
	s_cbranch_execz .LBB0_773
	s_barrier

; #define STAGE(P, BASE, LD, br, kt) do { const char* _g = (const char*)((BASE) + (size_t)(br) * (LD) + (size_t)(kt) * 64); \
;     for (int _i = 0; _i < 2; ++_i) { int _b = tidx * 16 + _i * 8192; int _r, _c; stage_rc(_b, _r, _c); \
;       __builtin_amdgcn_global_load_lds((const unsigned*)(_g + (unsigned)((_r * (LD) + _c) * 2)), (unsigned*)((char*)(P) + _b), 16, 0, 0); } } while (0)
; #define LDA(dst, b, h) for (int m = 0; m < 4; ++m) for (int k = 0; k < 2; ++k) \
;     dst[m][k] = *reinterpret_cast<const bf16x8*>((char*)SA(b, h) + lds_byte(wr * 64 + m * 16 + fr, k * 32 + fq * 8))
; #define LDB(dst, b, h) for (int n = 0; n < 2; ++n) for (int k = 0; k < 2; ++k) \
;     dst[n][k] = *reinterpret_cast<const bf16x8*>((char*)SB(b, h) + lds_byte(wc * 32 + n * 16 + fr, k * 32 + fq * 8))
; #define MMA(ai, bj, At_, Bt_) do { __builtin_amdgcn_s_setprio(1); \
;     for (int k = 0; k < 2; ++k) for (int m = 0; m < 4; ++m) for (int n = 0; n < 2; ++n) \
;       acc[ai][bj][m][n] = __builtin_amdgcn_mfma_f32_16x16x32_bf16(At_[m][k], Bt_[n][k], acc[ai][bj][m][n], 0, 0, 0); \
;     __builtin_amdgcn_s_setprio(0); } while (0)
; #define WAIT_L(n) asm volatile("s_waitcnt lgkmcnt(" #n ")" ::: "memory")
; #define BAR __builtin_amdgcn_s_barrier()
; #define SCHED __builtin_amdgcn_sched_barrier(0)
; template <int EPI, int lda, int ldb, int N, int K>
; __device__ __forceinline__ void gemm_phase(const u16* __restrict__ A, const u16* __restrict__ Bt, const GemmEpi ep, int wv) {
;     ...
;       LDB(B0, 0, 0); SCHED; LDA(At, 0, 0); STAGE(SA(1, 1), Ab, lda, brow + HALF, t + 1);
;       WAIT_L(8); BAR; WAIT_L(0); MMA(0, 0, At, B0); BAR; SCHED;
;       LDB(B1, 0, 1); STAGE(SB(0, 0), Bt, ldb, bcol, t + 2);
;       BAR; WAIT_L(0); MMA(0, 1, At, B1); BAR;
;       LDA(At, 0, 1); STAGE(SA(0, 0), Ab, lda, brow, t + 2);
;       BAR; WAIT_L(0); MMA(1, 0, At, B0); BAR; SCHED;
.LBB0_838:
	ds_read_b128 v[168:171], v164
	ds_read_b128 v[174:177], v164 offset:1024
	ds_read_b128 v[178:181], v164 offset:2048
	ds_read_b128 v[182:185], v164 offset:3072
	v_add_u32_e32 v172, 0xc000, v147
	v_lshl_add_u64 v[238:239], v[136:137], 0, s[50:51]
	v_readfirstlane_b32 s73, v172
	v_add_u32_e32 v173, 0xe000, v147
	v_lshl_add_u64 v[166:167], v[238:239], 0, s[22:23]
	s_mov_b32 m0, s73
	v_lshl_add_u64 v[240:241], v[134:135], 0, s[50:51]
	v_readfirstlane_b32 s73, v173
	ds_read_b128 v[186:189], v155
	ds_read_b128 v[190:193], v155 offset:1024
	ds_read_b128 v[194:197], v154
	ds_read_b128 v[198:201], v154 offset:1024
	ds_read_b128 v[202:205], v153
	ds_read_b128 v[206:209], v153 offset:1024
	ds_read_b128 v[210:213], v152
	ds_read_b128 v[214:217], v152 offset:1024
	global_load_lds_dwordx4 v[166:167], off
	v_lshl_add_u64 v[166:167], v[240:241], 0, s[22:23]
	s_mov_b32 m0, s73
	s_nop 0
	global_load_lds_dwordx4 v[166:167], off
	s_waitcnt lgkmcnt(8)
	s_barrier
	s_waitcnt lgkmcnt(0)
	s_waitcnt lgkmcnt(0)
	v_mfma_f32_16x16x32_bf16 v[124:127], v[168:171], v[186:189], v[124:127]
	v_mfma_f32_16x16x32_bf16 v[120:123], v[178:181], v[186:189], v[120:123]
	v_mfma_f32_16x16x32_bf16 v[116:119], v[168:171], v[194:197], v[116:119]
	v_mfma_f32_16x16x32_bf16 v[112:115], v[178:181], v[194:197], v[112:115]
	v_mfma_f32_16x16x32_bf16 v[108:111], v[168:171], v[202:205], v[108:111]
	v_mfma_f32_16x16x32_bf16 v[104:107], v[178:181], v[202:205], v[104:107]
	v_mfma_f32_16x16x32_bf16 v[100:103], v[168:171], v[210:213], v[100:103]
	v_mfma_f32_16x16x32_bf16 v[96:99], v[178:181], v[210:213], v[96:99]
	v_mfma_f32_16x16x32_bf16 v[124:127], v[174:177], v[190:193], v[124:127]
	v_mfma_f32_16x16x32_bf16 v[120:123], v[182:185], v[190:193], v[120:123]
	v_mfma_f32_16x16x32_bf16 v[116:119], v[174:177], v[198:201], v[116:119]
	v_mfma_f32_16x16x32_bf16 v[112:115], v[182:185], v[198:201], v[112:115]
	v_mfma_f32_16x16x32_bf16 v[108:111], v[174:177], v[206:209], v[108:111]
	v_mfma_f32_16x16x32_bf16 v[104:107], v[182:185], v[206:209], v[104:107]
	v_mfma_f32_16x16x32_bf16 v[100:103], v[174:177], v[214:217], v[100:103]
	v_mfma_f32_16x16x32_bf16 v[96:99], v[182:185], v[214:217], v[96:99]
	s_barrier
	v_add_u32_e32 v165, s63, v156
	v_lshl_add_u64 v[242:243], v[144:145], 0, s[50:51]
	v_readfirstlane_b32 s73, v165
	v_lshl_add_u64 v[166:167], v[242:243], 0, s[24:25]
	s_mov_b32 m0, s73
	ds_read_b128 v[218:221], v163
	ds_read_b128 v[222:225], v163 offset:1024
	ds_read_b128 v[226:229], v163 offset:2048
	ds_read_b128 v[230:233], v163 offset:3072
	global_load_lds_dwordx4 v[166:167], off
	v_add_u32_e32 v166, 0x2000, v165
	v_lshl_add_u64 v[244:245], v[142:143], 0, s[50:51]
	v_readfirstlane_b32 s73, v166
	v_lshl_add_u64 v[234:235], v[244:245], 0, s[24:25]
	s_mov_b32 m0, s73
	s_nop 0
	global_load_lds_dwordx4 v[234:235], off
	s_barrier
	s_waitcnt lgkmcnt(0)
	s_waitcnt lgkmcnt(0)
	v_mfma_f32_16x16x32_bf16 v[92:95], v[218:221], v[186:189], v[92:95]
	v_mfma_f32_16x16x32_bf16 v[88:91], v[226:229], v[186:189], v[88:91]
	v_mfma_f32_16x16x32_bf16 v[84:87], v[218:221], v[194:197], v[84:87]
	v_mfma_f32_16x16x32_bf16 v[80:83], v[226:229], v[194:197], v[80:83]
	v_mfma_f32_16x16x32_bf16 v[76:79], v[218:221], v[202:205], v[76:79]
	v_mfma_f32_16x16x32_bf16 v[72:75], v[226:229], v[202:205], v[72:75]
	v_mfma_f32_16x16x32_bf16 v[68:71], v[218:221], v[210:213], v[68:71]
	v_mfma_f32_16x16x32_bf16 v[64:67], v[226:229], v[210:213], v[64:67]
	v_mfma_f32_16x16x32_bf16 v[92:95], v[222:225], v[190:193], v[92:95]
	v_mfma_f32_16x16x32_bf16 v[88:91], v[230:233], v[190:193], v[88:91]
	v_mfma_f32_16x16x32_bf16 v[84:87], v[222:225], v[198:201], v[84:87]
	v_mfma_f32_16x16x32_bf16 v[80:83], v[230:233], v[198:201], v[80:83]
	v_mfma_f32_16x16x32_bf16 v[76:79], v[222:225], v[206:209], v[76:79]
	v_mfma_f32_16x16x32_bf16 v[72:75], v[230:233], v[206:209], v[72:75]
	v_mfma_f32_16x16x32_bf16 v[68:71], v[222:225], v[214:217], v[68:71]
	v_mfma_f32_16x16x32_bf16 v[64:67], v[230:233], v[214:217], v[64:67]
	s_barrier
	v_readfirstlane_b32 s73, v147
	v_add_u32_e32 v167, 0x2000, v147
	v_lshl_add_u64 v[234:235], v[238:239], 0, s[26:27]
	s_mov_b32 m0, s73
	v_readfirstlane_b32 s73, v167
	ds_read_b128 v[186:189], v155 offset:16384
	ds_read_b128 v[190:193], v155 offset:17408
	ds_read_b128 v[194:197], v154 offset:16384
	ds_read_b128 v[198:201], v154 offset:17408
	ds_read_b128 v[202:205], v153 offset:16384
	ds_read_b128 v[206:209], v153 offset:17408
	ds_read_b128 v[210:213], v152 offset:16384
	ds_read_b128 v[214:217], v152 offset:17408
	global_load_lds_dwordx4 v[234:235], off
	v_lshl_add_u64 v[234:235], v[240:241], 0, s[26:27]
	s_mov_b32 m0, s73
	s_nop 0
	global_load_lds_dwordx4 v[234:235], off
	s_barrier
	s_waitcnt lgkmcnt(0)
	s_waitcnt lgkmcnt(0)
	v_mfma_f32_16x16x32_bf16 v[60:63], v[168:171], v[186:189], v[60:63]
	v_mfma_f32_16x16x32_bf16 v[56:59], v[178:181], v[186:189], v[56:59]
	v_mfma_f32_16x16x32_bf16 v[52:55], v[168:171], v[194:197], v[52:55]
	v_mfma_f32_16x16x32_bf16 v[48:51], v[178:181], v[194:197], v[48:51]
	v_mfma_f32_16x16x32_bf16 v[44:47], v[168:171], v[202:205], v[44:47]
	v_mfma_f32_16x16x32_bf16 v[40:43], v[178:181], v[202:205], v[40:43]
	v_mfma_f32_16x16x32_bf16 v[36:39], v[168:171], v[210:213], v[36:39]
	v_mfma_f32_16x16x32_bf16 v[32:35], v[178:181], v[210:213], v[32:35]
	v_mfma_f32_16x16x32_bf16 v[60:63], v[174:177], v[190:193], v[60:63]
	v_mfma_f32_16x16x32_bf16 v[56:59], v[182:185], v[190:193], v[56:59]
	v_mfma_f32_16x16x32_bf16 v[52:55], v[174:177], v[198:201], v[52:55]
	v_mfma_f32_16x16x32_bf16 v[48:51], v[182:185], v[198:201], v[48:51]
	v_mfma_f32_16x16x32_bf16 v[44:47], v[174:177], v[206:209], v[44:47]
	v_mfma_f32_16x16x32_bf16 v[40:43], v[182:185], v[206:209], v[40:43]
	v_mfma_f32_16x16x32_bf16 v[36:39], v[174:177], v[214:217], v[36:39]
	v_mfma_f32_16x16x32_bf16 v[32:35], v[182:185], v[214:217], v[32:35]
	s_barrier
; #define STAGE(P, BASE, LD, br, kt) do { const char* _g = (const char*)((BASE) + (size_t)(br) * (LD) + (size_t)(kt) * 64); \
;     for (int _i = 0; _i < 2; ++_i) { int _b = tidx * 16 + _i * 8192; int _r, _c; stage_rc(_b, _r, _c); \
;       __builtin_amdgcn_global_load_lds((const unsigned*)(_g + (unsigned)((_r * (LD) + _c) * 2)), (unsigned*)((char*)(P) + _b), 16, 0, 0); } } while (0)
; #define LDA(dst, b, h) for (int m = 0; m < 4; ++m) for (int k = 0; k < 2; ++k) \
;     dst[m][k] = *reinterpret_cast<const bf16x8*>((char*)SA(b, h) + lds_byte(wr * 64 + m * 16 + fr, k * 32 + fq * 8))
; #define LDB(dst, b, h) for (int n = 0; n < 2; ++n) for (int k = 0; k < 2; ++k) \
;     dst[n][k] = *reinterpret_cast<const bf16x8*>((char*)SB(b, h) + lds_byte(wc * 32 + n * 16 + fr, k * 32 + fq * 8))
; #define MMA(ai, bj, At_, Bt_) do { __builtin_amdgcn_s_setprio(1); \
;     for (int k = 0; k < 2; ++k) for (int m = 0; m < 4; ++m) for (int n = 0; n < 2; ++n) \
;       acc[ai][bj][m][n] = __builtin_amdgcn_mfma_f32_16x16x32_bf16(At_[m][k], Bt_[n][k], acc[ai][bj][m][n], 0, 0, 0); \
;     __builtin_amdgcn_s_setprio(0); } while (0)
; #define WAIT_V(n) asm volatile("s_waitcnt vmcnt(" #n ")" ::: "memory")
; #define WAIT_L(n) asm volatile("s_waitcnt lgkmcnt(" #n ")" ::: "memory")
; #define BAR __builtin_amdgcn_s_barrier()
; #define SCHED __builtin_amdgcn_sched_barrier(0)
; template <int EPI, int lda, int ldb, int N, int K>
; __device__ __forceinline__ void gemm_phase(const u16* __restrict__ A, const u16* __restrict__ Bt, const GemmEpi ep, int wv) {
;     ...
;       STAGE(SB(0, 1), Bt, ldb, bcol + HALF, t + 2);
;       WAIT_V(6); BAR; MMA(1, 1, At, B1); BAR;
;       LDB(B0, 1, 0); SCHED; LDA(At, 1, 0); STAGE(SA(0, 1), Ab, lda, brow + HALF, t + 2);
;       WAIT_L(8); BAR; WAIT_L(0); MMA(0, 0, At, B0); BAR; SCHED;
;       LDB(B1, 1, 1); STAGE(SB(1, 0), Bt, ldb, bcol, t + 3);
;       BAR; WAIT_L(0); MMA(0, 1, At, B1); BAR;
	v_add_u32_e32 v168, s64, v156
	v_lshl_add_u64 v[246:247], v[140:141], 0, s[50:51]
	v_readfirstlane_b32 s73, v168
	v_add_u32_e32 v169, 0x2000, v168
	v_lshl_add_u64 v[170:171], v[246:247], 0, s[40:41]
	s_mov_b32 m0, s73
	v_lshl_add_u64 v[248:249], v[138:139], 0, s[50:51]
	v_readfirstlane_b32 s73, v169
	global_load_lds_dwordx4 v[170:171], off
	v_lshl_add_u64 v[170:171], v[248:249], 0, s[40:41]
	s_mov_b32 m0, s73
	s_nop 0
	global_load_lds_dwordx4 v[170:171], off
	s_waitcnt vmcnt(6)
	s_barrier
	v_mfma_f32_16x16x32_bf16 v[28:31], v[218:221], v[186:189], v[28:31]
	v_mfma_f32_16x16x32_bf16 v[24:27], v[226:229], v[186:189], v[24:27]
	v_mfma_f32_16x16x32_bf16 v[20:23], v[218:221], v[194:197], v[20:23]
	v_mfma_f32_16x16x32_bf16 v[16:19], v[226:229], v[194:197], v[16:19]
	v_mfma_f32_16x16x32_bf16 v[12:15], v[218:221], v[202:205], v[12:15]
	v_mfma_f32_16x16x32_bf16 v[8:11], v[226:229], v[202:205], v[8:11]
	v_mfma_f32_16x16x32_bf16 v[4:7], v[218:221], v[210:213], v[4:7]
	v_mfma_f32_16x16x32_bf16 v[0:3], v[226:229], v[210:213], v[0:3]
	v_mfma_f32_16x16x32_bf16 v[28:31], v[222:225], v[190:193], v[28:31]
	v_mfma_f32_16x16x32_bf16 v[24:27], v[230:233], v[190:193], v[24:27]
	v_mfma_f32_16x16x32_bf16 v[20:23], v[222:225], v[198:201], v[20:23]
	v_mfma_f32_16x16x32_bf16 v[16:19], v[230:233], v[198:201], v[16:19]
	v_mfma_f32_16x16x32_bf16 v[12:15], v[222:225], v[206:209], v[12:15]
	v_mfma_f32_16x16x32_bf16 v[8:11], v[230:233], v[206:209], v[8:11]
	v_mfma_f32_16x16x32_bf16 v[4:7], v[222:225], v[214:217], v[4:7]
	v_mfma_f32_16x16x32_bf16 v[0:3], v[230:233], v[214:217], v[0:3]
	s_barrier
	ds_read_b128 v[174:177], v159
	ds_read_b128 v[178:181], v159 offset:1024
	ds_read_b128 v[182:185], v159 offset:2048
	ds_read_b128 v[186:189], v159 offset:3072
	v_add_u32_e32 v170, 0x4000, v147
	v_add_u32_e32 v171, 0x6000, v147
	v_readfirstlane_b32 s73, v170
	v_lshl_add_u64 v[222:223], v[238:239], 0, s[42:43]
	s_mov_b32 m0, s73
	v_readfirstlane_b32 s73, v171
	ds_read_b128 v[190:193], v155 offset:32768
	ds_read_b128 v[194:197], v155 offset:33792
	ds_read_b128 v[198:201], v154 offset:32768
	ds_read_b128 v[202:205], v154 offset:33792
	ds_read_b128 v[206:209], v153 offset:32768
	ds_read_b128 v[210:213], v153 offset:33792
	ds_read_b128 v[214:217], v152 offset:32768
	ds_read_b128 v[218:221], v152 offset:33792
	global_load_lds_dwordx4 v[222:223], off
	v_lshl_add_u64 v[222:223], v[240:241], 0, s[42:43]
	s_mov_b32 m0, s73
	s_nop 0
	global_load_lds_dwordx4 v[222:223], off
	s_waitcnt lgkmcnt(8)
	s_barrier
	s_waitcnt lgkmcnt(0)
	s_waitcnt lgkmcnt(0)
	v_mfma_f32_16x16x32_bf16 v[124:127], v[174:177], v[190:193], v[124:127]
	v_mfma_f32_16x16x32_bf16 v[120:123], v[182:185], v[190:193], v[120:123]
	v_mfma_f32_16x16x32_bf16 v[116:119], v[174:177], v[198:201], v[116:119]
	v_mfma_f32_16x16x32_bf16 v[112:115], v[182:185], v[198:201], v[112:115]
	v_mfma_f32_16x16x32_bf16 v[108:111], v[174:177], v[206:209], v[108:111]
	v_mfma_f32_16x16x32_bf16 v[104:107], v[182:185], v[206:209], v[104:107]
	v_mfma_f32_16x16x32_bf16 v[100:103], v[174:177], v[214:217], v[100:103]
	v_mfma_f32_16x16x32_bf16 v[96:99], v[182:185], v[214:217], v[96:99]
	v_mfma_f32_16x16x32_bf16 v[124:127], v[178:181], v[194:197], v[124:127]
	v_mfma_f32_16x16x32_bf16 v[120:123], v[186:189], v[194:197], v[120:123]
	v_mfma_f32_16x16x32_bf16 v[116:119], v[178:181], v[202:205], v[116:119]
	v_mfma_f32_16x16x32_bf16 v[112:115], v[186:189], v[202:205], v[112:115]
	v_mfma_f32_16x16x32_bf16 v[108:111], v[178:181], v[210:213], v[108:111]
	v_mfma_f32_16x16x32_bf16 v[104:107], v[186:189], v[210:213], v[104:107]
	v_mfma_f32_16x16x32_bf16 v[100:103], v[178:181], v[218:221], v[100:103]
	v_mfma_f32_16x16x32_bf16 v[96:99], v[186:189], v[218:221], v[96:99]
	s_barrier
	v_readfirstlane_b32 s73, v158
	v_lshl_add_u64 v[242:243], v[242:243], 0, s[44:45]
	s_mov_b32 m0, s73
	ds_read_b128 v[222:225], v157
	ds_read_b128 v[226:229], v157 offset:1024
	ds_read_b128 v[230:233], v157 offset:2048
	ds_read_b128 v[234:237], v157 offset:3072
	global_load_lds_dwordx4 v[242:243], off
	v_lshl_add_u64 v[242:243], v[244:245], 0, s[44:45]
	v_add_u32_e32 v244, 0x2000, v158
	s_nop 0
	v_readfirstlane_b32 s73, v244
	s_mov_b32 m0, s73
	s_nop 0
	global_load_lds_dwordx4 v[242:243], off
	s_barrier
	s_waitcnt lgkmcnt(0)
	s_waitcnt lgkmcnt(0)
	v_mfma_f32_16x16x32_bf16 v[92:95], v[222:225], v[190:193], v[92:95]
	v_mfma_f32_16x16x32_bf16 v[88:91], v[230:233], v[190:193], v[88:91]
	v_mfma_f32_16x16x32_bf16 v[84:87], v[222:225], v[198:201], v[84:87]
	v_mfma_f32_16x16x32_bf16 v[80:83], v[230:233], v[198:201], v[80:83]
	v_mfma_f32_16x16x32_bf16 v[76:79], v[222:225], v[206:209], v[76:79]
	v_mfma_f32_16x16x32_bf16 v[72:75], v[230:233], v[206:209], v[72:75]
	v_mfma_f32_16x16x32_bf16 v[68:71], v[222:225], v[214:217], v[68:71]
	v_mfma_f32_16x16x32_bf16 v[64:67], v[230:233], v[214:217], v[64:67]
	v_mfma_f32_16x16x32_bf16 v[92:95], v[226:229], v[194:197], v[92:95]
	v_mfma_f32_16x16x32_bf16 v[88:91], v[234:237], v[194:197], v[88:91]
	v_mfma_f32_16x16x32_bf16 v[84:87], v[226:229], v[202:205], v[84:87]
	v_mfma_f32_16x16x32_bf16 v[80:83], v[234:237], v[202:205], v[80:83]
	v_mfma_f32_16x16x32_bf16 v[76:79], v[226:229], v[210:213], v[76:79]
	v_mfma_f32_16x16x32_bf16 v[72:75], v[234:237], v[210:213], v[72:75]
	v_mfma_f32_16x16x32_bf16 v[68:71], v[226:229], v[218:221], v[68:71]
	v_mfma_f32_16x16x32_bf16 v[64:67], v[234:237], v[218:221], v[64:67]
	s_barrier
; #define STAGE(P, BASE, LD, br, kt) do { const char* _g = (const char*)((BASE) + (size_t)(br) * (LD) + (size_t)(kt) * 64); \
;     for (int _i = 0; _i < 2; ++_i) { int _b = tidx * 16 + _i * 8192; int _r, _c; stage_rc(_b, _r, _c); \
;       __builtin_amdgcn_global_load_lds((const unsigned*)(_g + (unsigned)((_r * (LD) + _c) * 2)), (unsigned*)((char*)(P) + _b), 16, 0, 0); } } while (0)
; #define LDA(dst, b, h) for (int m = 0; m < 4; ++m) for (int k = 0; k < 2; ++k) \
;     dst[m][k] = *reinterpret_cast<const bf16x8*>((char*)SA(b, h) + lds_byte(wr * 64 + m * 16 + fr, k * 32 + fq * 8))
; #define LDB(dst, b, h) for (int n = 0; n < 2; ++n) for (int k = 0; k < 2; ++k) \
;     dst[n][k] = *reinterpret_cast<const bf16x8*>((char*)SB(b, h) + lds_byte(wc * 32 + n * 16 + fr, k * 32 + fq * 8))
; #define MMA(ai, bj, At_, Bt_) do { __builtin_amdgcn_s_setprio(1); \
;     for (int k = 0; k < 2; ++k) for (int m = 0; m < 4; ++m) for (int n = 0; n < 2; ++n) \
;       acc[ai][bj][m][n] = __builtin_amdgcn_mfma_f32_16x16x32_bf16(At_[m][k], Bt_[n][k], acc[ai][bj][m][n], 0, 0, 0); \
;     __builtin_amdgcn_s_setprio(0); } while (0)
; #define WAIT_V(n) asm volatile("s_waitcnt vmcnt(" #n ")" ::: "memory")
; #define WAIT_L(n) asm volatile("s_waitcnt lgkmcnt(" #n ")" ::: "memory")
; #define BAR __builtin_amdgcn_s_barrier()
; #define SCHED __builtin_amdgcn_sched_barrier(0)
; template <int EPI, int lda, int ldb, int N, int K>
; __device__ __forceinline__ void gemm_phase(const u16* __restrict__ A, const u16* __restrict__ Bt, const GemmEpi ep, int wv) {
;     ...
;       LDA(At, 1, 1); STAGE(SA(1, 0), Ab, lda, brow, t + 3);
;       BAR; WAIT_L(0); MMA(1, 0, At, B0); BAR; SCHED;
;       STAGE(SB(1, 1), Bt, ldb, bcol + HALF, t + 3);
;       WAIT_V(6); BAR; MMA(1, 1, At, B1); BAR;
;     }
;     { LDB(B0, 0, 0); LDA(At, 0, 0); STAGE(SA(1, 1), Ab, lda, brow + HALF, nt - 1);
;       BAR; WAIT_L(0); MMA(0, 0, At, B0); BAR;
	v_readfirstlane_b32 s73, v160
	v_lshl_add_u64 v[238:239], v[238:239], 0, s[46:47]
	s_mov_b32 m0, s73
	v_readfirstlane_b32 s73, v161
	ds_read_b128 v[190:193], v155 offset:49152
	ds_read_b128 v[194:197], v155 offset:50176
	ds_read_b128 v[198:201], v154 offset:49152
	ds_read_b128 v[202:205], v154 offset:50176
	ds_read_b128 v[206:209], v153 offset:49152
	ds_read_b128 v[210:213], v153 offset:50176
	ds_read_b128 v[214:217], v152 offset:49152
	ds_read_b128 v[218:221], v152 offset:50176
	global_load_lds_dwordx4 v[238:239], off
	v_lshl_add_u64 v[238:239], v[240:241], 0, s[46:47]
	s_mov_b32 m0, s73
	s_nop 0
	global_load_lds_dwordx4 v[238:239], off
	s_barrier
	s_waitcnt lgkmcnt(0)
	s_waitcnt lgkmcnt(0)
	v_mfma_f32_16x16x32_bf16 v[60:63], v[174:177], v[190:193], v[60:63]
	v_mfma_f32_16x16x32_bf16 v[56:59], v[182:185], v[190:193], v[56:59]
	v_mfma_f32_16x16x32_bf16 v[52:55], v[174:177], v[198:201], v[52:55]
	v_mfma_f32_16x16x32_bf16 v[48:51], v[182:185], v[198:201], v[48:51]
	v_mfma_f32_16x16x32_bf16 v[44:47], v[174:177], v[206:209], v[44:47]
	v_mfma_f32_16x16x32_bf16 v[40:43], v[182:185], v[206:209], v[40:43]
	v_mfma_f32_16x16x32_bf16 v[36:39], v[174:177], v[214:217], v[36:39]
	v_mfma_f32_16x16x32_bf16 v[32:35], v[182:185], v[214:217], v[32:35]
	v_mfma_f32_16x16x32_bf16 v[60:63], v[178:181], v[194:197], v[60:63]
	v_mfma_f32_16x16x32_bf16 v[56:59], v[186:189], v[194:197], v[56:59]
	v_mfma_f32_16x16x32_bf16 v[52:55], v[178:181], v[202:205], v[52:55]
	v_mfma_f32_16x16x32_bf16 v[48:51], v[186:189], v[202:205], v[48:51]
	v_mfma_f32_16x16x32_bf16 v[44:47], v[178:181], v[210:213], v[44:47]
	v_mfma_f32_16x16x32_bf16 v[40:43], v[186:189], v[210:213], v[40:43]
	v_mfma_f32_16x16x32_bf16 v[36:39], v[178:181], v[218:221], v[36:39]
	v_mfma_f32_16x16x32_bf16 v[32:35], v[186:189], v[218:221], v[32:35]
	s_barrier
	v_readfirstlane_b32 s73, v162
	v_add_u32_e32 v176, 0x2000, v162
	v_lshl_add_u64 v[174:175], v[246:247], 0, s[48:49]
	s_mov_b32 m0, s73
	v_readfirstlane_b32 s73, v176
	global_load_lds_dwordx4 v[174:175], off
	v_lshl_add_u64 v[174:175], v[248:249], 0, s[48:49]
	s_mov_b32 m0, s73
	s_nop 0
	global_load_lds_dwordx4 v[174:175], off
	s_waitcnt vmcnt(6)
	s_barrier
	v_mfma_f32_16x16x32_bf16 v[28:31], v[222:225], v[190:193], v[28:31]
	v_mfma_f32_16x16x32_bf16 v[24:27], v[230:233], v[190:193], v[24:27]
	v_mfma_f32_16x16x32_bf16 v[20:23], v[222:225], v[198:201], v[20:23]
	v_mfma_f32_16x16x32_bf16 v[16:19], v[230:233], v[198:201], v[16:19]
	v_mfma_f32_16x16x32_bf16 v[12:15], v[222:225], v[206:209], v[12:15]
	v_mfma_f32_16x16x32_bf16 v[8:11], v[230:233], v[206:209], v[8:11]
	v_mfma_f32_16x16x32_bf16 v[4:7], v[222:225], v[214:217], v[4:7]
	v_mfma_f32_16x16x32_bf16 v[0:3], v[230:233], v[214:217], v[0:3]
	v_mfma_f32_16x16x32_bf16 v[28:31], v[226:229], v[194:197], v[28:31]
	v_mfma_f32_16x16x32_bf16 v[24:27], v[234:237], v[194:197], v[24:27]
	v_mfma_f32_16x16x32_bf16 v[20:23], v[226:229], v[202:205], v[20:23]
	v_mfma_f32_16x16x32_bf16 v[16:19], v[234:237], v[202:205], v[16:19]
	v_mfma_f32_16x16x32_bf16 v[12:15], v[226:229], v[210:213], v[12:15]
	v_mfma_f32_16x16x32_bf16 v[8:11], v[234:237], v[210:213], v[8:11]
	v_mfma_f32_16x16x32_bf16 v[4:7], v[226:229], v[218:221], v[4:7]
	v_mfma_f32_16x16x32_bf16 v[0:3], v[234:237], v[218:221], v[0:3]
	s_barrier
	s_add_i32 s72, s72, 2
	s_add_u32 s50, s50, 0x100
	s_addc_u32 s51, s51, 0
	s_cmpk_gt_u32 s72, 0x51
	s_cbranch_scc0 .LBB0_838
	s_add_i32 s50, s18, 0x80
	s_mul_hi_i32 s51, s50, 0x2b00
	s_mulk_i32 s50, 0x2b00
	s_add_u32 s50, s56, s50
	s_addc_u32 s51, s57, s51
	s_add_u32 s50, s50, 0x2a80
	s_addc_u32 s51, s51, 0
	v_readfirstlane_b32 s72, v172
	v_lshl_add_u64 v[160:161], s[50:51], 0, v[128:129]
	s_mov_b32 m0, s72
	ds_read_b128 v[134:137], v164
	ds_read_b128 v[138:141], v164 offset:1024
	ds_read_b128 v[142:145], v164 offset:2048
	ds_read_b128 v[174:177], v164 offset:3072
	ds_read_b128 v[178:181], v155
	ds_read_b128 v[182:185], v155 offset:1024
	ds_read_b128 v[186:189], v154
	ds_read_b128 v[190:193], v154 offset:1024
	ds_read_b128 v[194:197], v153
	ds_read_b128 v[198:201], v153 offset:1024
	ds_read_b128 v[202:205], v152
	ds_read_b128 v[206:209], v152 offset:1024
	global_load_lds_dwordx4 v[160:161], off
	v_lshl_add_u64 v[160:161], s[50:51], 0, v[132:133]
	v_readfirstlane_b32 s50, v173
	s_mov_b32 m0, s50
	s_nop 0
	global_load_lds_dwordx4 v[160:161], off
	s_barrier
	s_waitcnt lgkmcnt(0)
	s_waitcnt lgkmcnt(0)
	v_mfma_f32_16x16x32_bf16 v[124:127], v[134:137], v[178:181], v[124:127]
	v_mfma_f32_16x16x32_bf16 v[120:123], v[142:145], v[178:181], v[120:123]
	v_mfma_f32_16x16x32_bf16 v[116:119], v[134:137], v[186:189], v[116:119]
	v_mfma_f32_16x16x32_bf16 v[112:115], v[142:145], v[186:189], v[112:115]
	v_mfma_f32_16x16x32_bf16 v[108:111], v[134:137], v[194:197], v[108:111]
	v_mfma_f32_16x16x32_bf16 v[104:107], v[142:145], v[194:197], v[104:107]
	v_mfma_f32_16x16x32_bf16 v[100:103], v[134:137], v[202:205], v[100:103]
	v_mfma_f32_16x16x32_bf16 v[96:99], v[142:145], v[202:205], v[96:99]
	v_mfma_f32_16x16x32_bf16 v[124:127], v[138:141], v[182:185], v[124:127]
	v_mfma_f32_16x16x32_bf16 v[120:123], v[174:177], v[182:185], v[120:123]
	v_mfma_f32_16x16x32_bf16 v[116:119], v[138:141], v[190:193], v[116:119]
	v_mfma_f32_16x16x32_bf16 v[112:115], v[174:177], v[190:193], v[112:115]
	v_mfma_f32_16x16x32_bf16 v[108:111], v[138:141], v[198:201], v[108:111]
	v_mfma_f32_16x16x32_bf16 v[104:107], v[174:177], v[198:201], v[104:107]
	v_mfma_f32_16x16x32_bf16 v[100:103], v[138:141], v[206:209], v[100:103]
	v_mfma_f32_16x16x32_bf16 v[96:99], v[174:177], v[206:209], v[96:99]
	s_barrier
; #define LDA(dst, b, h) for (int m = 0; m < 4; ++m) for (int k = 0; k < 2; ++k) \
;     dst[m][k] = *reinterpret_cast<const bf16x8*>((char*)SA(b, h) + lds_byte(wr * 64 + m * 16 + fr, k * 32 + fq * 8))
; #define LDB(dst, b, h) for (int n = 0; n < 2; ++n) for (int k = 0; k < 2; ++k) \
;     dst[n][k] = *reinterpret_cast<const bf16x8*>((char*)SB(b, h) + lds_byte(wc * 32 + n * 16 + fr, k * 32 + fq * 8))
; #define MMA(ai, bj, At_, Bt_) do { __builtin_amdgcn_s_setprio(1); \
;     for (int k = 0; k < 2; ++k) for (int m = 0; m < 4; ++m) for (int n = 0; n < 2; ++n) \
;       acc[ai][bj][m][n] = __builtin_amdgcn_mfma_f32_16x16x32_bf16(At_[m][k], Bt_[n][k], acc[ai][bj][m][n], 0, 0, 0); \
;     __builtin_amdgcn_s_setprio(0); } while (0)
; #define WAIT_V(n) asm volatile("s_waitcnt vmcnt(" #n ")" ::: "memory")
; #define WAIT_L(n) asm volatile("s_waitcnt lgkmcnt(" #n ")" ::: "memory")
; #define BAR __builtin_amdgcn_s_barrier()
; template <int EPI, int lda, int ldb, int N, int K>
; __device__ __forceinline__ void gemm_phase(const u16* __restrict__ A, const u16* __restrict__ Bt, const GemmEpi ep, int wv) {
;     ...
;       LDB(B1, 0, 1); BAR; WAIT_L(0); MMA(0, 1, At, B1); BAR;
;       LDA(At, 0, 1); WAIT_V(4); BAR; WAIT_L(0); MMA(1, 0, At, B0); MMA(1, 1, At, B1); BAR; }
;     { LDB(B0, 1, 0); LDA(At, 1, 0); WAIT_V(2); BAR; WAIT_L(0); MMA(0, 0, At, B0); BAR;
	ds_read_b128 v[210:213], v163
	ds_read_b128 v[214:217], v163 offset:1024
	ds_read_b128 v[218:221], v163 offset:2048
	ds_read_b128 v[160:163], v163 offset:3072
	s_barrier
	s_waitcnt lgkmcnt(0)
	s_waitcnt lgkmcnt(0)
	v_mfma_f32_16x16x32_bf16 v[92:95], v[210:213], v[178:181], v[92:95]
	v_mfma_f32_16x16x32_bf16 v[88:91], v[218:221], v[178:181], v[88:91]
	v_mfma_f32_16x16x32_bf16 v[76:79], v[210:213], v[194:197], v[76:79]
	v_mfma_f32_16x16x32_bf16 v[72:75], v[218:221], v[194:197], v[72:75]
	v_mfma_f32_16x16x32_bf16 v[84:87], v[210:213], v[186:189], v[84:87]
	v_mfma_f32_16x16x32_bf16 v[80:83], v[218:221], v[186:189], v[80:83]
	v_mfma_f32_16x16x32_bf16 v[68:71], v[210:213], v[202:205], v[68:71]
	v_mfma_f32_16x16x32_bf16 v[64:67], v[218:221], v[202:205], v[64:67]
	v_mfma_f32_16x16x32_bf16 v[92:95], v[214:217], v[182:185], v[92:95]
	v_mfma_f32_16x16x32_bf16 v[88:91], v[160:163], v[182:185], v[88:91]
	v_mfma_f32_16x16x32_bf16 v[76:79], v[214:217], v[198:201], v[76:79]
	v_mfma_f32_16x16x32_bf16 v[72:75], v[160:163], v[198:201], v[72:75]
	v_mfma_f32_16x16x32_bf16 v[178:181], v[214:217], v[190:193], v[84:87]
	v_mfma_f32_16x16x32_bf16 v[182:185], v[160:163], v[190:193], v[80:83]
	v_mfma_f32_16x16x32_bf16 v[186:189], v[214:217], v[206:209], v[68:71]
	v_mfma_f32_16x16x32_bf16 v[190:193], v[160:163], v[206:209], v[64:67]
	s_barrier
	s_nop 0
	ds_read_b128 v[64:67], v155 offset:16384
	ds_read_b128 v[68:71], v155 offset:17408
	ds_read_b128 v[80:83], v154 offset:16384
	ds_read_b128 v[84:87], v154 offset:17408
	ds_read_b128 v[194:197], v153 offset:16384
	ds_read_b128 v[198:201], v153 offset:17408
	ds_read_b128 v[202:205], v152 offset:16384
	ds_read_b128 v[206:209], v152 offset:17408
	s_waitcnt vmcnt(4)
	s_barrier
	s_waitcnt lgkmcnt(0)
	s_waitcnt lgkmcnt(0)
	v_mfma_f32_16x16x32_bf16 v[60:63], v[134:137], v[64:67], v[60:63]
	v_mfma_f32_16x16x32_bf16 v[56:59], v[142:145], v[64:67], v[56:59]
	v_mfma_f32_16x16x32_bf16 v[52:55], v[134:137], v[80:83], v[52:55]
	v_mfma_f32_16x16x32_bf16 v[48:51], v[142:145], v[80:83], v[48:51]
	v_mfma_f32_16x16x32_bf16 v[44:47], v[134:137], v[194:197], v[44:47]
	v_mfma_f32_16x16x32_bf16 v[40:43], v[142:145], v[194:197], v[40:43]
	v_mfma_f32_16x16x32_bf16 v[36:39], v[134:137], v[202:205], v[36:39]
	v_mfma_f32_16x16x32_bf16 v[32:35], v[142:145], v[202:205], v[32:35]
	v_mfma_f32_16x16x32_bf16 v[60:63], v[138:141], v[68:71], v[60:63]
	v_mfma_f32_16x16x32_bf16 v[56:59], v[174:177], v[68:71], v[56:59]
	v_mfma_f32_16x16x32_bf16 v[52:55], v[138:141], v[84:87], v[52:55]
	v_mfma_f32_16x16x32_bf16 v[48:51], v[174:177], v[84:87], v[48:51]
	v_mfma_f32_16x16x32_bf16 v[44:47], v[138:141], v[198:201], v[44:47]
	v_mfma_f32_16x16x32_bf16 v[40:43], v[174:177], v[198:201], v[40:43]
	v_mfma_f32_16x16x32_bf16 v[36:39], v[138:141], v[206:209], v[36:39]
	v_mfma_f32_16x16x32_bf16 v[32:35], v[174:177], v[206:209], v[32:35]
	v_mfma_f32_16x16x32_bf16 v[28:31], v[210:213], v[64:67], v[28:31]
	v_mfma_f32_16x16x32_bf16 v[16:19], v[218:221], v[80:83], v[16:19]
	v_mfma_f32_16x16x32_bf16 v[12:15], v[210:213], v[194:197], v[12:15]
	v_mfma_f32_16x16x32_bf16 v[0:3], v[218:221], v[202:205], v[0:3]
	v_mfma_f32_16x16x32_bf16 v[24:27], v[218:221], v[64:67], v[24:27]
	v_mfma_f32_16x16x32_bf16 v[20:23], v[210:213], v[80:83], v[20:23]
	v_mfma_f32_16x16x32_bf16 v[8:11], v[218:221], v[194:197], v[8:11]
	v_mfma_f32_16x16x32_bf16 v[4:7], v[210:213], v[202:205], v[4:7]
	v_mfma_f32_16x16x32_bf16 v[28:31], v[214:217], v[68:71], v[28:31]
	v_mfma_f32_16x16x32_bf16 v[16:19], v[160:163], v[84:87], v[16:19]
	v_mfma_f32_16x16x32_bf16 v[12:15], v[214:217], v[198:201], v[12:15]
	v_mfma_f32_16x16x32_bf16 v[0:3], v[160:163], v[206:209], v[0:3]
	v_mfma_f32_16x16x32_bf16 v[134:137], v[160:163], v[68:71], v[24:27]
	v_mfma_f32_16x16x32_bf16 v[138:141], v[214:217], v[84:87], v[20:23]
	v_mfma_f32_16x16x32_bf16 v[142:145], v[160:163], v[198:201], v[8:11]
	v_mfma_f32_16x16x32_bf16 v[172:175], v[214:217], v[206:209], v[4:7]
	s_barrier
	s_nop 0
	ds_read_b128 v[4:7], v159
	ds_read_b128 v[8:11], v159 offset:1024
	ds_read_b128 v[20:23], v159 offset:2048
	ds_read_b128 v[158:161], v159 offset:3072
	ds_read_b128 v[24:27], v155 offset:32768
	ds_read_b128 v[194:197], v155 offset:33792
	ds_read_b128 v[198:201], v154 offset:32768
	ds_read_b128 v[202:205], v154 offset:33792
	ds_read_b128 v[206:209], v153 offset:32768
	ds_read_b128 v[210:213], v153 offset:33792
	ds_read_b128 v[214:217], v152 offset:32768
	ds_read_b128 v[218:221], v152 offset:33792
	s_waitcnt vmcnt(2)
	s_barrier
; #define LDA(dst, b, h) for (int m = 0; m < 4; ++m) for (int k = 0; k < 2; ++k) \
;     dst[m][k] = *reinterpret_cast<const bf16x8*>((char*)SA(b, h) + lds_byte(wr * 64 + m * 16 + fr, k * 32 + fq * 8))
; #define LDB(dst, b, h) for (int n = 0; n < 2; ++n) for (int k = 0; k < 2; ++k) \
;     dst[n][k] = *reinterpret_cast<const bf16x8*>((char*)SB(b, h) + lds_byte(wc * 32 + n * 16 + fr, k * 32 + fq * 8))
; #define MMA(ai, bj, At_, Bt_) do { __builtin_amdgcn_s_setprio(1); \
;     for (int k = 0; k < 2; ++k) for (int m = 0; m < 4; ++m) for (int n = 0; n < 2; ++n) \
;       acc[ai][bj][m][n] = __builtin_amdgcn_mfma_f32_16x16x32_bf16(At_[m][k], Bt_[n][k], acc[ai][bj][m][n], 0, 0, 0); \
;     __builtin_amdgcn_s_setprio(0); } while (0)
; #define WAIT_V(n) asm volatile("s_waitcnt vmcnt(" #n ")" ::: "memory")
; #define WAIT_L(n) asm volatile("s_waitcnt lgkmcnt(" #n ")" ::: "memory")
; #define BAR __builtin_amdgcn_s_barrier()
; template <int EPI, int lda, int ldb, int N, int K>
; __device__ __forceinline__ void gemm_phase(const u16* __restrict__ A, const u16* __restrict__ Bt, const GemmEpi ep, int wv) {
;     ...
;     { LDB(B0, 1, 0); LDA(At, 1, 0); WAIT_V(2); BAR; WAIT_L(0); MMA(0, 0, At, B0); BAR;
;       LDB(B1, 1, 1); WAIT_V(0); BAR; WAIT_L(0); MMA(0, 1, At, B1); BAR;
;       LDA(At, 1, 1); BAR; WAIT_L(0); MMA(1, 0, At, B0); MMA(1, 1, At, B1); BAR; }
;     if (wr == 0) BAR;
	s_waitcnt lgkmcnt(0)
	s_waitcnt lgkmcnt(0)
	v_mfma_f32_16x16x32_bf16 v[64:67], v[4:7], v[24:27], v[124:127]
	v_mfma_f32_16x16x32_bf16 v[68:71], v[20:23], v[24:27], v[120:123]
	v_mfma_f32_16x16x32_bf16 v[80:83], v[4:7], v[198:201], v[116:119]
	v_mfma_f32_16x16x32_bf16 v[84:87], v[20:23], v[198:201], v[112:115]
	v_mfma_f32_16x16x32_bf16 v[108:111], v[4:7], v[206:209], v[108:111]
	v_mfma_f32_16x16x32_bf16 v[104:107], v[20:23], v[206:209], v[104:107]
	v_mfma_f32_16x16x32_bf16 v[120:123], v[4:7], v[214:217], v[100:103]
	v_mfma_f32_16x16x32_bf16 v[124:127], v[20:23], v[214:217], v[96:99]
	v_mfma_f32_16x16x32_bf16 v[116:119], v[8:11], v[194:197], v[64:67]
	v_mfma_f32_16x16x32_bf16 v[112:115], v[158:161], v[194:197], v[68:71]
	v_mfma_f32_16x16x32_bf16 v[100:103], v[8:11], v[202:205], v[80:83]
	v_mfma_f32_16x16x32_bf16 v[96:99], v[158:161], v[202:205], v[84:87]
	v_mfma_f32_16x16x32_bf16 v[84:87], v[8:11], v[210:213], v[108:111]
	v_mfma_f32_16x16x32_bf16 v[80:83], v[158:161], v[210:213], v[104:107]
	v_mfma_f32_16x16x32_bf16 v[68:71], v[8:11], v[218:221], v[120:123]
	v_mfma_f32_16x16x32_bf16 v[64:67], v[158:161], v[218:221], v[124:127]
	s_barrier
	ds_read_b128 v[222:225], v157
	ds_read_b128 v[226:229], v157 offset:1024
	ds_read_b128 v[230:233], v157 offset:2048
	ds_read_b128 v[234:237], v157 offset:3072
	s_waitcnt vmcnt(0)
	s_barrier
	s_waitcnt lgkmcnt(0)
	s_waitcnt lgkmcnt(0)
	v_mfma_f32_16x16x32_bf16 v[92:95], v[222:225], v[24:27], v[92:95]
	v_mfma_f32_16x16x32_bf16 v[24:27], v[230:233], v[24:27], v[88:91]
	v_mfma_f32_16x16x32_bf16 v[88:91], v[222:225], v[198:201], v[178:181]
	v_mfma_f32_16x16x32_bf16 v[104:107], v[230:233], v[198:201], v[182:185]
	v_mfma_f32_16x16x32_bf16 v[76:79], v[222:225], v[206:209], v[76:79]
	v_mfma_f32_16x16x32_bf16 v[72:75], v[230:233], v[206:209], v[72:75]
	v_mfma_f32_16x16x32_bf16 v[176:179], v[222:225], v[214:217], v[186:189]
	v_mfma_f32_16x16x32_bf16 v[180:183], v[230:233], v[214:217], v[190:193]
	v_mfma_f32_16x16x32_bf16 v[124:127], v[226:229], v[194:197], v[92:95]
	v_mfma_f32_16x16x32_bf16 v[120:123], v[234:237], v[194:197], v[24:27]
	v_mfma_f32_16x16x32_bf16 v[108:111], v[226:229], v[202:205], v[88:91]
	v_mfma_f32_16x16x32_bf16 v[104:107], v[234:237], v[202:205], v[104:107]
	v_mfma_f32_16x16x32_bf16 v[92:95], v[226:229], v[210:213], v[76:79]
	v_mfma_f32_16x16x32_bf16 v[88:91], v[234:237], v[210:213], v[72:75]
	v_mfma_f32_16x16x32_bf16 v[76:79], v[226:229], v[218:221], v[176:179]
	v_mfma_f32_16x16x32_bf16 v[72:75], v[234:237], v[218:221], v[180:183]
	s_barrier
	ds_read_b128 v[176:179], v155 offset:49152
	ds_read_b128 v[180:183], v155 offset:50176
	ds_read_b128 v[184:187], v154 offset:49152
	ds_read_b128 v[154:157], v154 offset:50176
	ds_read_b128 v[188:191], v153 offset:49152
	ds_read_b128 v[192:195], v153 offset:50176
	ds_read_b128 v[196:199], v152 offset:49152
	ds_read_b128 v[200:203], v152 offset:50176
	s_barrier
	s_waitcnt lgkmcnt(0)
	s_waitcnt lgkmcnt(0)
	v_mfma_f32_16x16x32_bf16 v[24:27], v[4:7], v[176:179], v[60:63]
	v_mfma_f32_16x16x32_bf16 v[60:63], v[20:23], v[176:179], v[56:59]
	v_mfma_f32_16x16x32_bf16 v[204:207], v[4:7], v[184:187], v[52:55]
	v_mfma_f32_16x16x32_bf16 v[48:51], v[20:23], v[184:187], v[48:51]
	v_mfma_f32_16x16x32_bf16 v[44:47], v[4:7], v[188:191], v[44:47]
	v_mfma_f32_16x16x32_bf16 v[208:211], v[20:23], v[188:191], v[40:43]
	v_mfma_f32_16x16x32_bf16 v[4:7], v[4:7], v[196:199], v[36:39]
	v_mfma_f32_16x16x32_bf16 v[32:35], v[20:23], v[196:199], v[32:35]
	v_mfma_f32_16x16x32_bf16 v[56:59], v[8:11], v[180:183], v[24:27]
	v_mfma_f32_16x16x32_bf16 v[52:55], v[158:161], v[180:183], v[60:63]
	v_mfma_f32_16x16x32_bf16 v[40:43], v[8:11], v[154:157], v[204:207]
	v_mfma_f32_16x16x32_bf16 v[36:39], v[158:161], v[154:157], v[48:51]
	v_mfma_f32_16x16x32_bf16 v[24:27], v[8:11], v[192:195], v[44:47]
	v_mfma_f32_16x16x32_bf16 v[20:23], v[158:161], v[192:195], v[208:211]
	v_mfma_f32_16x16x32_bf16 v[8:11], v[8:11], v[200:203], v[4:7]
	v_mfma_f32_16x16x32_bf16 v[4:7], v[158:161], v[200:203], v[32:35]
	v_mfma_f32_16x16x32_bf16 v[28:31], v[222:225], v[176:179], v[28:31]
	v_mfma_f32_16x16x32_bf16 v[32:35], v[230:233], v[176:179], v[134:137]
	v_mfma_f32_16x16x32_bf16 v[44:47], v[222:225], v[184:187], v[138:141]
	v_mfma_f32_16x16x32_bf16 v[16:19], v[230:233], v[184:187], v[16:19]
	v_mfma_f32_16x16x32_bf16 v[12:15], v[222:225], v[188:191], v[12:15]
	v_mfma_f32_16x16x32_bf16 v[134:137], v[230:233], v[188:191], v[142:145]
	v_mfma_f32_16x16x32_bf16 v[138:141], v[222:225], v[196:199], v[172:175]
	v_mfma_f32_16x16x32_bf16 v[0:3], v[230:233], v[196:199], v[0:3]
	v_mfma_f32_16x16x32_bf16 v[60:63], v[226:229], v[180:183], v[28:31]
	v_mfma_f32_16x16x32_bf16 v[48:51], v[234:237], v[180:183], v[32:35]
	v_mfma_f32_16x16x32_bf16 v[44:47], v[226:229], v[154:157], v[44:47]
	v_mfma_f32_16x16x32_bf16 v[32:35], v[234:237], v[154:157], v[16:19]
	v_mfma_f32_16x16x32_bf16 v[28:31], v[226:229], v[192:195], v[12:15]
	v_mfma_f32_16x16x32_bf16 v[16:19], v[234:237], v[192:195], v[134:137]
	v_mfma_f32_16x16x32_bf16 v[12:15], v[226:229], v[200:203], v[138:141]
	v_mfma_f32_16x16x32_bf16 v[0:3], v[234:237], v[200:203], v[0:3]
	v_cmp_gt_u32_e32 vcc, s69, v130
	s_barrier
	s_and_saveexec_b64 s[50:51], vcc
	s_cbranch_execz .LBB0_841
	s_barrier

; #define STAGE(P, BASE, LD, br, kt) do { const char* _g = (const char*)((BASE) + (size_t)(br) * (LD) + (size_t)(kt) * 64); \
;     for (int _i = 0; _i < 2; ++_i) { int _b = tidx * 16 + _i * 8192; int _r, _c; stage_rc(_b, _r, _c); \
;       __builtin_amdgcn_global_load_lds((const unsigned*)(_g + (unsigned)((_r * (LD) + _c) * 2)), (unsigned*)((char*)(P) + _b), 16, 0, 0); } } while (0)
; #define LDA(dst, b, h) for (int m = 0; m < 4; ++m) for (int k = 0; k < 2; ++k) \
;     dst[m][k] = *reinterpret_cast<const bf16x8*>((char*)SA(b, h) + lds_byte(wr * 64 + m * 16 + fr, k * 32 + fq * 8))
; #define LDB(dst, b, h) for (int n = 0; n < 2; ++n) for (int k = 0; k < 2; ++k) \
;     dst[n][k] = *reinterpret_cast<const bf16x8*>((char*)SB(b, h) + lds_byte(wc * 32 + n * 16 + fr, k * 32 + fq * 8))
; #define MMA(ai, bj, At_, Bt_) do { __builtin_amdgcn_s_setprio(1); \
;     for (int k = 0; k < 2; ++k) for (int m = 0; m < 4; ++m) for (int n = 0; n < 2; ++n) \
;       acc[ai][bj][m][n] = __builtin_amdgcn_mfma_f32_16x16x32_bf16(At_[m][k], Bt_[n][k], acc[ai][bj][m][n], 0, 0, 0); \
;     __builtin_amdgcn_s_setprio(0); } while (0)
; #define WAIT_L(n) asm volatile("s_waitcnt lgkmcnt(" #n ")" ::: "memory")
; #define BAR __builtin_amdgcn_s_barrier()
; #define SCHED __builtin_amdgcn_sched_barrier(0)
; template <int EPI, int lda, int ldb, int N, int K>
; __device__ __forceinline__ void gemm_phase(const u16* __restrict__ A, const u16* __restrict__ Bt, const GemmEpi ep, int wv) {
;     ...
;       LDB(B0, 0, 0); SCHED; LDA(At, 0, 0); STAGE(SA(1, 1), Ab, lda, brow + HALF, t + 1);
;       WAIT_L(8); BAR; WAIT_L(0); MMA(0, 0, At, B0); BAR; SCHED;
;       LDB(B1, 0, 1); STAGE(SB(0, 0), Bt, ldb, bcol, t + 2);
;       BAR; WAIT_L(0); MMA(0, 1, At, B1); BAR;
;       LDA(At, 0, 1); STAGE(SA(0, 0), Ab, lda, brow, t + 2);
;       BAR; WAIT_L(0); MMA(1, 0, At, B0); BAR; SCHED;
.LBB0_1147:
	ds_read_b128 v[172:175], v161
	ds_read_b128 v[176:179], v161 offset:1024
	ds_read_b128 v[180:183], v161 offset:2048
	ds_read_b128 v[184:187], v161 offset:3072
	v_add_u32_e32 v169, 0xc000, v148
	v_lshl_add_u64 v[236:237], v[138:139], 0, s[60:61]
	v_readfirstlane_b32 s63, v169
	v_add_u32_e32 v170, 0xe000, v148
	v_lshl_add_u64 v[162:163], v[236:237], 0, s[22:23]
	s_mov_b32 m0, s63
	v_lshl_add_u64 v[238:239], v[140:141], 0, s[60:61]
	v_readfirstlane_b32 s63, v170
	ds_read_b128 v[164:167], v152
	ds_read_b128 v[188:191], v152 offset:1024
	ds_read_b128 v[192:195], v151
	ds_read_b128 v[196:199], v151 offset:1024
	ds_read_b128 v[200:203], v150
	ds_read_b128 v[204:207], v150 offset:1024
	ds_read_b128 v[208:211], v149
	ds_read_b128 v[212:215], v149 offset:1024
	global_load_lds_dwordx4 v[162:163], off
	v_lshl_add_u64 v[162:163], v[238:239], 0, s[22:23]
	s_mov_b32 m0, s63
	s_nop 0
	global_load_lds_dwordx4 v[162:163], off
	s_waitcnt lgkmcnt(8)
	s_barrier
	s_waitcnt lgkmcnt(0)
	s_waitcnt lgkmcnt(0)
	v_mfma_f32_16x16x32_bf16 v[124:127], v[164:167], v[172:175], v[124:127]
	v_mfma_f32_16x16x32_bf16 v[120:123], v[164:167], v[180:183], v[120:123]
	v_mfma_f32_16x16x32_bf16 v[116:119], v[192:195], v[172:175], v[116:119]
	v_mfma_f32_16x16x32_bf16 v[112:115], v[192:195], v[180:183], v[112:115]
	v_mfma_f32_16x16x32_bf16 v[108:111], v[200:203], v[172:175], v[108:111]
	v_mfma_f32_16x16x32_bf16 v[104:107], v[200:203], v[180:183], v[104:107]
	v_mfma_f32_16x16x32_bf16 v[100:103], v[208:211], v[172:175], v[100:103]
	v_mfma_f32_16x16x32_bf16 v[96:99], v[208:211], v[180:183], v[96:99]
	v_mfma_f32_16x16x32_bf16 v[124:127], v[188:191], v[176:179], v[124:127]
	v_mfma_f32_16x16x32_bf16 v[120:123], v[188:191], v[184:187], v[120:123]
	v_mfma_f32_16x16x32_bf16 v[116:119], v[196:199], v[176:179], v[116:119]
	v_mfma_f32_16x16x32_bf16 v[112:115], v[196:199], v[184:187], v[112:115]
	v_mfma_f32_16x16x32_bf16 v[108:111], v[204:207], v[176:179], v[108:111]
	v_mfma_f32_16x16x32_bf16 v[104:107], v[204:207], v[184:187], v[104:107]
	v_mfma_f32_16x16x32_bf16 v[100:103], v[212:215], v[176:179], v[100:103]
	v_mfma_f32_16x16x32_bf16 v[96:99], v[212:215], v[184:187], v[96:99]
	s_barrier
	v_add_u32_e32 v162, s75, v154
	v_lshl_add_u64 v[240:241], v[134:135], 0, s[60:61]
	v_readfirstlane_b32 s63, v162
	v_add_u32_e32 v163, 0x2000, v162
	v_lshl_add_u64 v[232:233], v[240:241], 0, s[24:25]
	s_mov_b32 m0, s63
	v_lshl_add_u64 v[242:243], v[136:137], 0, s[60:61]
	v_readfirstlane_b32 s63, v163
	ds_read_b128 v[216:219], v160
	ds_read_b128 v[220:223], v160 offset:1024
	ds_read_b128 v[224:227], v160 offset:2048
	ds_read_b128 v[228:231], v160 offset:3072
	global_load_lds_dwordx4 v[232:233], off
	v_lshl_add_u64 v[232:233], v[242:243], 0, s[24:25]
	s_mov_b32 m0, s63
	s_nop 0
	global_load_lds_dwordx4 v[232:233], off
	s_barrier
	s_waitcnt lgkmcnt(0)
	s_waitcnt lgkmcnt(0)
	v_mfma_f32_16x16x32_bf16 v[92:95], v[164:167], v[216:219], v[92:95]
	v_mfma_f32_16x16x32_bf16 v[88:91], v[164:167], v[224:227], v[88:91]
	v_mfma_f32_16x16x32_bf16 v[84:87], v[192:195], v[216:219], v[84:87]
	v_mfma_f32_16x16x32_bf16 v[80:83], v[192:195], v[224:227], v[80:83]
	v_mfma_f32_16x16x32_bf16 v[76:79], v[200:203], v[216:219], v[76:79]
	v_mfma_f32_16x16x32_bf16 v[72:75], v[200:203], v[224:227], v[72:75]
	v_mfma_f32_16x16x32_bf16 v[68:71], v[208:211], v[216:219], v[68:71]
	v_mfma_f32_16x16x32_bf16 v[64:67], v[208:211], v[224:227], v[64:67]
	v_mfma_f32_16x16x32_bf16 v[92:95], v[188:191], v[220:223], v[92:95]
	v_mfma_f32_16x16x32_bf16 v[88:91], v[188:191], v[228:231], v[88:91]
	v_mfma_f32_16x16x32_bf16 v[84:87], v[196:199], v[220:223], v[84:87]
	v_mfma_f32_16x16x32_bf16 v[80:83], v[196:199], v[228:231], v[80:83]
	v_mfma_f32_16x16x32_bf16 v[76:79], v[204:207], v[220:223], v[76:79]
	v_mfma_f32_16x16x32_bf16 v[72:75], v[204:207], v[228:231], v[72:75]
	v_mfma_f32_16x16x32_bf16 v[68:71], v[212:215], v[220:223], v[68:71]
	v_mfma_f32_16x16x32_bf16 v[64:67], v[212:215], v[228:231], v[64:67]
	s_barrier
	v_readfirstlane_b32 s63, v148
	v_lshl_add_u64 v[164:165], v[236:237], 0, s[26:27]
	s_mov_b32 m0, s63
	ds_read_b128 v[188:191], v152 offset:16384
	ds_read_b128 v[192:195], v152 offset:17408
	ds_read_b128 v[196:199], v151 offset:16384
	ds_read_b128 v[200:203], v151 offset:17408
	ds_read_b128 v[204:207], v150 offset:16384
	ds_read_b128 v[208:211], v150 offset:17408
	ds_read_b128 v[212:215], v149 offset:16384
	ds_read_b128 v[232:235], v149 offset:17408
	global_load_lds_dwordx4 v[164:165], off
	v_add_u32_e32 v164, 0x2000, v148
	v_lshl_add_u64 v[166:167], v[238:239], 0, s[26:27]
	v_readfirstlane_b32 s63, v164
	s_mov_b32 m0, s63
	s_nop 0
	global_load_lds_dwordx4 v[166:167], off
	s_barrier
	s_waitcnt lgkmcnt(0)
	s_waitcnt lgkmcnt(0)
	v_mfma_f32_16x16x32_bf16 v[60:63], v[188:191], v[172:175], v[60:63]
	v_mfma_f32_16x16x32_bf16 v[56:59], v[188:191], v[180:183], v[56:59]
	v_mfma_f32_16x16x32_bf16 v[52:55], v[196:199], v[172:175], v[52:55]
	v_mfma_f32_16x16x32_bf16 v[48:51], v[196:199], v[180:183], v[48:51]
	v_mfma_f32_16x16x32_bf16 v[44:47], v[204:207], v[172:175], v[44:47]
	v_mfma_f32_16x16x32_bf16 v[40:43], v[204:207], v[180:183], v[40:43]
	v_mfma_f32_16x16x32_bf16 v[36:39], v[212:215], v[172:175], v[36:39]
	v_mfma_f32_16x16x32_bf16 v[32:35], v[212:215], v[180:183], v[32:35]
	v_mfma_f32_16x16x32_bf16 v[60:63], v[192:195], v[176:179], v[60:63]
	v_mfma_f32_16x16x32_bf16 v[56:59], v[192:195], v[184:187], v[56:59]
	v_mfma_f32_16x16x32_bf16 v[52:55], v[200:203], v[176:179], v[52:55]
	v_mfma_f32_16x16x32_bf16 v[48:51], v[200:203], v[184:187], v[48:51]
	v_mfma_f32_16x16x32_bf16 v[44:47], v[208:211], v[176:179], v[44:47]
	v_mfma_f32_16x16x32_bf16 v[40:43], v[208:211], v[184:187], v[40:43]
	v_mfma_f32_16x16x32_bf16 v[36:39], v[232:235], v[176:179], v[36:39]
	v_mfma_f32_16x16x32_bf16 v[32:35], v[232:235], v[184:187], v[32:35]
	s_barrier
; #define STAGE(P, BASE, LD, br, kt) do { const char* _g = (const char*)((BASE) + (size_t)(br) * (LD) + (size_t)(kt) * 64); \
;     for (int _i = 0; _i < 2; ++_i) { int _b = tidx * 16 + _i * 8192; int _r, _c; stage_rc(_b, _r, _c); \
;       __builtin_amdgcn_global_load_lds((const unsigned*)(_g + (unsigned)((_r * (LD) + _c) * 2)), (unsigned*)((char*)(P) + _b), 16, 0, 0); } } while (0)
; #define LDA(dst, b, h) for (int m = 0; m < 4; ++m) for (int k = 0; k < 2; ++k) \
;     dst[m][k] = *reinterpret_cast<const bf16x8*>((char*)SA(b, h) + lds_byte(wr * 64 + m * 16 + fr, k * 32 + fq * 8))
; #define LDB(dst, b, h) for (int n = 0; n < 2; ++n) for (int k = 0; k < 2; ++k) \
;     dst[n][k] = *reinterpret_cast<const bf16x8*>((char*)SB(b, h) + lds_byte(wc * 32 + n * 16 + fr, k * 32 + fq * 8))
; #define MMA(ai, bj, At_, Bt_) do { __builtin_amdgcn_s_setprio(1); \
;     for (int k = 0; k < 2; ++k) for (int m = 0; m < 4; ++m) for (int n = 0; n < 2; ++n) \
;       acc[ai][bj][m][n] = __builtin_amdgcn_mfma_f32_16x16x32_bf16(At_[m][k], Bt_[n][k], acc[ai][bj][m][n], 0, 0, 0); \
;     __builtin_amdgcn_s_setprio(0); } while (0)
; #define WAIT_V(n) asm volatile("s_waitcnt vmcnt(" #n ")" ::: "memory")
; #define WAIT_L(n) asm volatile("s_waitcnt lgkmcnt(" #n ")" ::: "memory")
; #define BAR __builtin_amdgcn_s_barrier()
; #define SCHED __builtin_amdgcn_sched_barrier(0)
; template <int EPI, int lda, int ldb, int N, int K>
; __device__ __forceinline__ void gemm_phase(const u16* __restrict__ A, const u16* __restrict__ Bt, const GemmEpi ep, int wv) {
;     ...
;       STAGE(SB(0, 1), Bt, ldb, bcol + HALF, t + 2);
;       WAIT_V(6); BAR; MMA(1, 1, At, B1); BAR;
;       LDB(B0, 1, 0); SCHED; LDA(At, 1, 0); STAGE(SA(0, 1), Ab, lda, brow + HALF, t + 2);
;       WAIT_L(8); BAR; WAIT_L(0); MMA(0, 0, At, B0); BAR; SCHED;
;       LDB(B1, 1, 1); STAGE(SB(1, 0), Bt, ldb, bcol, t + 3);
;       BAR; WAIT_L(0); MMA(0, 1, At, B1); BAR;
;       LDA(At, 1, 1); STAGE(SA(1, 0), Ab, lda, brow, t + 3);
	v_add_u32_e32 v165, s76, v154
	v_lshl_add_u64 v[166:167], v[240:241], 0, s[40:41]
	v_readfirstlane_b32 s63, v165
	s_mov_b32 m0, s63
	v_lshl_add_u64 v[172:173], v[242:243], 0, s[40:41]
	global_load_lds_dwordx4 v[166:167], off
	v_add_u32_e32 v166, 0x2000, v165
	s_nop 0
	v_readfirstlane_b32 s63, v166
	s_mov_b32 m0, s63
	s_nop 0
	global_load_lds_dwordx4 v[172:173], off
	s_waitcnt vmcnt(6)
	s_barrier
	v_mfma_f32_16x16x32_bf16 v[28:31], v[188:191], v[216:219], v[28:31]
	v_mfma_f32_16x16x32_bf16 v[24:27], v[188:191], v[224:227], v[24:27]
	v_mfma_f32_16x16x32_bf16 v[20:23], v[196:199], v[216:219], v[20:23]
	v_mfma_f32_16x16x32_bf16 v[16:19], v[196:199], v[224:227], v[16:19]
	v_mfma_f32_16x16x32_bf16 v[12:15], v[204:207], v[216:219], v[12:15]
	v_mfma_f32_16x16x32_bf16 v[8:11], v[204:207], v[224:227], v[8:11]
	v_mfma_f32_16x16x32_bf16 v[4:7], v[212:215], v[216:219], v[4:7]
	v_mfma_f32_16x16x32_bf16 v[0:3], v[212:215], v[224:227], v[0:3]
	v_mfma_f32_16x16x32_bf16 v[28:31], v[192:195], v[220:223], v[28:31]
	v_mfma_f32_16x16x32_bf16 v[24:27], v[192:195], v[228:231], v[24:27]
	v_mfma_f32_16x16x32_bf16 v[20:23], v[200:203], v[220:223], v[20:23]
	v_mfma_f32_16x16x32_bf16 v[16:19], v[200:203], v[228:231], v[16:19]
	v_mfma_f32_16x16x32_bf16 v[12:15], v[208:211], v[220:223], v[12:15]
	v_mfma_f32_16x16x32_bf16 v[8:11], v[208:211], v[228:231], v[8:11]
	v_mfma_f32_16x16x32_bf16 v[4:7], v[232:235], v[220:223], v[4:7]
	v_mfma_f32_16x16x32_bf16 v[0:3], v[232:235], v[228:231], v[0:3]
	s_barrier
	ds_read_b128 v[172:175], v155
	ds_read_b128 v[176:179], v155 offset:1024
	ds_read_b128 v[180:183], v155 offset:2048
	ds_read_b128 v[184:187], v155 offset:3072
	v_add_u32_e32 v167, 0x4000, v148
	v_add_u32_e32 v168, 0x6000, v148
	v_readfirstlane_b32 s63, v167
	v_lshl_add_u64 v[220:221], v[236:237], 0, s[42:43]
	s_mov_b32 m0, s63
	v_readfirstlane_b32 s63, v168
	ds_read_b128 v[188:191], v152 offset:32768
	ds_read_b128 v[192:195], v152 offset:33792
	ds_read_b128 v[196:199], v151 offset:32768
	ds_read_b128 v[200:203], v151 offset:33792
	ds_read_b128 v[204:207], v150 offset:32768
	ds_read_b128 v[208:211], v150 offset:33792
	ds_read_b128 v[212:215], v149 offset:32768
	ds_read_b128 v[216:219], v149 offset:33792
	global_load_lds_dwordx4 v[220:221], off
	v_lshl_add_u64 v[220:221], v[238:239], 0, s[42:43]
	s_mov_b32 m0, s63
	s_nop 0
	global_load_lds_dwordx4 v[220:221], off
	s_waitcnt lgkmcnt(8)
	s_barrier
	s_waitcnt lgkmcnt(0)
	s_waitcnt lgkmcnt(0)
	v_mfma_f32_16x16x32_bf16 v[124:127], v[188:191], v[172:175], v[124:127]
	v_mfma_f32_16x16x32_bf16 v[120:123], v[188:191], v[180:183], v[120:123]
	v_mfma_f32_16x16x32_bf16 v[116:119], v[196:199], v[172:175], v[116:119]
	v_mfma_f32_16x16x32_bf16 v[112:115], v[196:199], v[180:183], v[112:115]
	v_mfma_f32_16x16x32_bf16 v[108:111], v[204:207], v[172:175], v[108:111]
	v_mfma_f32_16x16x32_bf16 v[104:107], v[204:207], v[180:183], v[104:107]
	v_mfma_f32_16x16x32_bf16 v[100:103], v[212:215], v[172:175], v[100:103]
	v_mfma_f32_16x16x32_bf16 v[96:99], v[212:215], v[180:183], v[96:99]
	v_mfma_f32_16x16x32_bf16 v[124:127], v[192:195], v[176:179], v[124:127]
	v_mfma_f32_16x16x32_bf16 v[120:123], v[192:195], v[184:187], v[120:123]
	v_mfma_f32_16x16x32_bf16 v[116:119], v[200:203], v[176:179], v[116:119]
	v_mfma_f32_16x16x32_bf16 v[112:115], v[200:203], v[184:187], v[112:115]
	v_mfma_f32_16x16x32_bf16 v[108:111], v[208:211], v[176:179], v[108:111]
	v_mfma_f32_16x16x32_bf16 v[104:107], v[208:211], v[184:187], v[104:107]
	v_mfma_f32_16x16x32_bf16 v[100:103], v[216:219], v[176:179], v[100:103]
	v_mfma_f32_16x16x32_bf16 v[96:99], v[216:219], v[184:187], v[96:99]
	s_barrier
	v_readfirstlane_b32 s63, v156
	v_add_u32_e32 v171, 0x2000, v156
	v_lshl_add_u64 v[244:245], v[240:241], 0, s[44:45]
	s_mov_b32 m0, s63
	v_readfirstlane_b32 s63, v171
	ds_read_b128 v[220:223], v153
	ds_read_b128 v[224:227], v153 offset:1024
	ds_read_b128 v[228:231], v153 offset:2048
	ds_read_b128 v[232:235], v153 offset:3072
	global_load_lds_dwordx4 v[244:245], off
	v_lshl_add_u64 v[244:245], v[242:243], 0, s[44:45]
	s_mov_b32 m0, s63
	s_nop 0
	global_load_lds_dwordx4 v[244:245], off
	s_barrier
	s_waitcnt lgkmcnt(0)
	s_waitcnt lgkmcnt(0)
	v_mfma_f32_16x16x32_bf16 v[92:95], v[188:191], v[220:223], v[92:95]
	v_mfma_f32_16x16x32_bf16 v[88:91], v[188:191], v[228:231], v[88:91]
	v_mfma_f32_16x16x32_bf16 v[84:87], v[196:199], v[220:223], v[84:87]
	v_mfma_f32_16x16x32_bf16 v[80:83], v[196:199], v[228:231], v[80:83]
	v_mfma_f32_16x16x32_bf16 v[76:79], v[204:207], v[220:223], v[76:79]
	v_mfma_f32_16x16x32_bf16 v[72:75], v[204:207], v[228:231], v[72:75]
	v_mfma_f32_16x16x32_bf16 v[68:71], v[212:215], v[220:223], v[68:71]
	v_mfma_f32_16x16x32_bf16 v[64:67], v[212:215], v[228:231], v[64:67]
	v_mfma_f32_16x16x32_bf16 v[92:95], v[192:195], v[224:227], v[92:95]
	v_mfma_f32_16x16x32_bf16 v[88:91], v[192:195], v[232:235], v[88:91]
	v_mfma_f32_16x16x32_bf16 v[84:87], v[200:203], v[224:227], v[84:87]
	v_mfma_f32_16x16x32_bf16 v[80:83], v[200:203], v[232:235], v[80:83]
	v_mfma_f32_16x16x32_bf16 v[76:79], v[208:211], v[224:227], v[76:79]
	v_mfma_f32_16x16x32_bf16 v[72:75], v[208:211], v[232:235], v[72:75]
	v_mfma_f32_16x16x32_bf16 v[68:71], v[216:219], v[224:227], v[68:71]
	v_mfma_f32_16x16x32_bf16 v[64:67], v[216:219], v[232:235], v[64:67]
	s_barrier
	v_readfirstlane_b32 s63, v157
	v_lshl_add_u64 v[236:237], v[236:237], 0, s[46:47]
	s_mov_b32 m0, s63
	v_readfirstlane_b32 s63, v158
	ds_read_b128 v[188:191], v152 offset:49152
	ds_read_b128 v[192:195], v152 offset:50176
	ds_read_b128 v[196:199], v151 offset:49152
	ds_read_b128 v[200:203], v151 offset:50176
	ds_read_b128 v[204:207], v150 offset:49152
	ds_read_b128 v[208:211], v150 offset:50176
	ds_read_b128 v[212:215], v149 offset:49152
	ds_read_b128 v[216:219], v149 offset:50176
	global_load_lds_dwordx4 v[236:237], off
	v_lshl_add_u64 v[236:237], v[238:239], 0, s[46:47]
	s_mov_b32 m0, s63
	s_nop 0
	global_load_lds_dwordx4 v[236:237], off
	s_barrier
; #define STAGE(P, BASE, LD, br, kt) do { const char* _g = (const char*)((BASE) + (size_t)(br) * (LD) + (size_t)(kt) * 64); \
;     for (int _i = 0; _i < 2; ++_i) { int _b = tidx * 16 + _i * 8192; int _r, _c; stage_rc(_b, _r, _c); \
;       __builtin_amdgcn_global_load_lds((const unsigned*)(_g + (unsigned)((_r * (LD) + _c) * 2)), (unsigned*)((char*)(P) + _b), 16, 0, 0); } } while (0)
; #define LDA(dst, b, h) for (int m = 0; m < 4; ++m) for (int k = 0; k < 2; ++k) \
;     dst[m][k] = *reinterpret_cast<const bf16x8*>((char*)SA(b, h) + lds_byte(wr * 64 + m * 16 + fr, k * 32 + fq * 8))
; #define LDB(dst, b, h) for (int n = 0; n < 2; ++n) for (int k = 0; k < 2; ++k) \
;     dst[n][k] = *reinterpret_cast<const bf16x8*>((char*)SB(b, h) + lds_byte(wc * 32 + n * 16 + fr, k * 32 + fq * 8))
; #define MMA(ai, bj, At_, Bt_) do { __builtin_amdgcn_s_setprio(1); \
;     for (int k = 0; k < 2; ++k) for (int m = 0; m < 4; ++m) for (int n = 0; n < 2; ++n) \
;       acc[ai][bj][m][n] = __builtin_amdgcn_mfma_f32_16x16x32_bf16(At_[m][k], Bt_[n][k], acc[ai][bj][m][n], 0, 0, 0); \
;     __builtin_amdgcn_s_setprio(0); } while (0)
; #define WAIT_V(n) asm volatile("s_waitcnt vmcnt(" #n ")" ::: "memory")
; #define WAIT_L(n) asm volatile("s_waitcnt lgkmcnt(" #n ")" ::: "memory")
; #define BAR __builtin_amdgcn_s_barrier()
; #define SCHED __builtin_amdgcn_sched_barrier(0)
; template <int EPI, int lda, int ldb, int N, int K>
; __device__ __forceinline__ void gemm_phase(const u16* __restrict__ A, const u16* __restrict__ Bt, const GemmEpi ep, int wv) {
;     ...
;       BAR; WAIT_L(0); MMA(1, 0, At, B0); BAR; SCHED;
;       STAGE(SB(1, 1), Bt, ldb, bcol + HALF, t + 3);
;       WAIT_V(6); BAR; MMA(1, 1, At, B1); BAR;
;     }
;     { LDB(B0, 0, 0); LDA(At, 0, 0); STAGE(SA(1, 1), Ab, lda, brow + HALF, nt - 1);
;       BAR; WAIT_L(0); MMA(0, 0, At, B0); BAR;
;       LDB(B1, 0, 1); BAR; WAIT_L(0); MMA(0, 1, At, B1); BAR;
	s_waitcnt lgkmcnt(0)
	s_waitcnt lgkmcnt(0)
	v_mfma_f32_16x16x32_bf16 v[60:63], v[188:191], v[172:175], v[60:63]
	v_mfma_f32_16x16x32_bf16 v[56:59], v[188:191], v[180:183], v[56:59]
	v_mfma_f32_16x16x32_bf16 v[52:55], v[196:199], v[172:175], v[52:55]
	v_mfma_f32_16x16x32_bf16 v[48:51], v[196:199], v[180:183], v[48:51]
	v_mfma_f32_16x16x32_bf16 v[44:47], v[204:207], v[172:175], v[44:47]
	v_mfma_f32_16x16x32_bf16 v[40:43], v[204:207], v[180:183], v[40:43]
	v_mfma_f32_16x16x32_bf16 v[36:39], v[212:215], v[172:175], v[36:39]
	v_mfma_f32_16x16x32_bf16 v[32:35], v[212:215], v[180:183], v[32:35]
	v_mfma_f32_16x16x32_bf16 v[60:63], v[192:195], v[176:179], v[60:63]
	v_mfma_f32_16x16x32_bf16 v[56:59], v[192:195], v[184:187], v[56:59]
	v_mfma_f32_16x16x32_bf16 v[52:55], v[200:203], v[176:179], v[52:55]
	v_mfma_f32_16x16x32_bf16 v[48:51], v[200:203], v[184:187], v[48:51]
	v_mfma_f32_16x16x32_bf16 v[44:47], v[208:211], v[176:179], v[44:47]
	v_mfma_f32_16x16x32_bf16 v[40:43], v[208:211], v[184:187], v[40:43]
	v_mfma_f32_16x16x32_bf16 v[36:39], v[216:219], v[176:179], v[36:39]
	v_mfma_f32_16x16x32_bf16 v[32:35], v[216:219], v[184:187], v[32:35]
	s_barrier
	v_readfirstlane_b32 s63, v159
	v_add_u32_e32 v171, 0x2000, v159
	v_lshl_add_u64 v[172:173], v[240:241], 0, s[48:49]
	s_mov_b32 m0, s63
	v_readfirstlane_b32 s63, v171
	global_load_lds_dwordx4 v[172:173], off
	v_lshl_add_u64 v[172:173], v[242:243], 0, s[48:49]
	s_mov_b32 m0, s63
	s_nop 0
	global_load_lds_dwordx4 v[172:173], off
	s_waitcnt vmcnt(6)
	s_barrier
	v_mfma_f32_16x16x32_bf16 v[28:31], v[188:191], v[220:223], v[28:31]
	v_mfma_f32_16x16x32_bf16 v[24:27], v[188:191], v[228:231], v[24:27]
	v_mfma_f32_16x16x32_bf16 v[20:23], v[196:199], v[220:223], v[20:23]
	v_mfma_f32_16x16x32_bf16 v[16:19], v[196:199], v[228:231], v[16:19]
	v_mfma_f32_16x16x32_bf16 v[12:15], v[204:207], v[220:223], v[12:15]
	v_mfma_f32_16x16x32_bf16 v[8:11], v[204:207], v[228:231], v[8:11]
	v_mfma_f32_16x16x32_bf16 v[4:7], v[212:215], v[220:223], v[4:7]
	v_mfma_f32_16x16x32_bf16 v[0:3], v[212:215], v[228:231], v[0:3]
	v_mfma_f32_16x16x32_bf16 v[28:31], v[192:195], v[224:227], v[28:31]
	v_mfma_f32_16x16x32_bf16 v[24:27], v[192:195], v[232:235], v[24:27]
	v_mfma_f32_16x16x32_bf16 v[20:23], v[200:203], v[224:227], v[20:23]
	v_mfma_f32_16x16x32_bf16 v[16:19], v[200:203], v[232:235], v[16:19]
	v_mfma_f32_16x16x32_bf16 v[12:15], v[208:211], v[224:227], v[12:15]
	v_mfma_f32_16x16x32_bf16 v[8:11], v[208:211], v[232:235], v[8:11]
	v_mfma_f32_16x16x32_bf16 v[4:7], v[216:219], v[224:227], v[4:7]
	v_mfma_f32_16x16x32_bf16 v[0:3], v[216:219], v[232:235], v[0:3]
	s_barrier
	s_add_i32 s62, s62, 2
	s_add_u32 s60, s60, 0x100
	s_addc_u32 s61, s61, 0
	s_cmp_gt_u32 s62, 27
	s_cbranch_scc0 .LBB0_1147
	s_add_i32 s60, s58, 0x80
	s_mul_hi_i32 s61, s60, 0x1080
	s_mulk_i32 s60, 0x1080
	s_add_u32 s60, s69, s60
	s_addc_u32 s61, s70, s61
	v_lshl_add_u64 v[208:209], s[60:61], 0, v[128:129]
	v_readfirstlane_b32 s62, v169
	v_lshl_add_u64 v[208:209], v[208:209], 0, s[50:51]
	s_mov_b32 m0, s62
	ds_read_b128 v[134:137], v161
	ds_read_b128 v[138:141], v161 offset:1024
	ds_read_b128 v[156:159], v161 offset:2048
	ds_read_b128 v[172:175], v161 offset:3072
	ds_read_b128 v[176:179], v152
	ds_read_b128 v[180:183], v152 offset:1024
	ds_read_b128 v[184:187], v151
	ds_read_b128 v[188:191], v151 offset:1024
	ds_read_b128 v[192:195], v150
	ds_read_b128 v[196:199], v150 offset:1024
	ds_read_b128 v[200:203], v149
	ds_read_b128 v[204:207], v149 offset:1024
	global_load_lds_dwordx4 v[208:209], off
	v_lshl_add_u64 v[208:209], s[60:61], 0, v[132:133]
	v_readfirstlane_b32 s60, v170
	v_lshl_add_u64 v[208:209], v[208:209], 0, s[50:51]
	s_mov_b32 m0, s60
	s_nop 0
	global_load_lds_dwordx4 v[208:209], off
	s_barrier
	s_waitcnt lgkmcnt(0)
	s_waitcnt lgkmcnt(0)
	v_mfma_f32_16x16x32_bf16 v[124:127], v[176:179], v[134:137], v[124:127]
	v_mfma_f32_16x16x32_bf16 v[120:123], v[176:179], v[156:159], v[120:123]
	v_mfma_f32_16x16x32_bf16 v[116:119], v[184:187], v[134:137], v[116:119]
	v_mfma_f32_16x16x32_bf16 v[112:115], v[184:187], v[156:159], v[112:115]
	v_mfma_f32_16x16x32_bf16 v[108:111], v[192:195], v[134:137], v[108:111]
	v_mfma_f32_16x16x32_bf16 v[104:107], v[192:195], v[156:159], v[104:107]
	v_mfma_f32_16x16x32_bf16 v[100:103], v[200:203], v[134:137], v[100:103]
	v_mfma_f32_16x16x32_bf16 v[96:99], v[200:203], v[156:159], v[96:99]
	v_mfma_f32_16x16x32_bf16 v[124:127], v[180:183], v[138:141], v[124:127]
	v_mfma_f32_16x16x32_bf16 v[120:123], v[180:183], v[172:175], v[120:123]
	v_mfma_f32_16x16x32_bf16 v[116:119], v[188:191], v[138:141], v[116:119]
	v_mfma_f32_16x16x32_bf16 v[112:115], v[188:191], v[172:175], v[112:115]
	v_mfma_f32_16x16x32_bf16 v[108:111], v[196:199], v[138:141], v[108:111]
	v_mfma_f32_16x16x32_bf16 v[104:107], v[196:199], v[172:175], v[104:107]
	v_mfma_f32_16x16x32_bf16 v[100:103], v[204:207], v[138:141], v[100:103]
	v_mfma_f32_16x16x32_bf16 v[96:99], v[204:207], v[172:175], v[96:99]
	s_barrier
	ds_read_b128 v[208:211], v160
	ds_read_b128 v[212:215], v160 offset:1024
	ds_read_b128 v[216:219], v160 offset:2048
	ds_read_b128 v[220:223], v160 offset:3072
	s_barrier
; #define LDA(dst, b, h) for (int m = 0; m < 4; ++m) for (int k = 0; k < 2; ++k) \
;     dst[m][k] = *reinterpret_cast<const bf16x8*>((char*)SA(b, h) + lds_byte(wr * 64 + m * 16 + fr, k * 32 + fq * 8))
; #define LDB(dst, b, h) for (int n = 0; n < 2; ++n) for (int k = 0; k < 2; ++k) \
;     dst[n][k] = *reinterpret_cast<const bf16x8*>((char*)SB(b, h) + lds_byte(wc * 32 + n * 16 + fr, k * 32 + fq * 8))
; #define MMA(ai, bj, At_, Bt_) do { __builtin_amdgcn_s_setprio(1); \
;     for (int k = 0; k < 2; ++k) for (int m = 0; m < 4; ++m) for (int n = 0; n < 2; ++n) \
;       acc[ai][bj][m][n] = __builtin_amdgcn_mfma_f32_16x16x32_bf16(At_[m][k], Bt_[n][k], acc[ai][bj][m][n], 0, 0, 0); \
;     __builtin_amdgcn_s_setprio(0); } while (0)
; #define WAIT_V(n) asm volatile("s_waitcnt vmcnt(" #n ")" ::: "memory")
; #define WAIT_L(n) asm volatile("s_waitcnt lgkmcnt(" #n ")" ::: "memory")
; #define BAR __builtin_amdgcn_s_barrier()
; template <int EPI, int lda, int ldb, int N, int K>
; __device__ __forceinline__ void gemm_phase(const u16* __restrict__ A, const u16* __restrict__ Bt, const GemmEpi ep, int wv) {
;     ...
;       LDB(B1, 0, 1); BAR; WAIT_L(0); MMA(0, 1, At, B1); BAR;
;       LDA(At, 0, 1); WAIT_V(4); BAR; WAIT_L(0); MMA(1, 0, At, B0); MMA(1, 1, At, B1); BAR; }
;     { LDB(B0, 1, 0); LDA(At, 1, 0); WAIT_V(2); BAR; WAIT_L(0); MMA(0, 0, At, B0); BAR;
	s_waitcnt lgkmcnt(0)
	s_waitcnt lgkmcnt(0)
	v_mfma_f32_16x16x32_bf16 v[92:95], v[176:179], v[208:211], v[92:95]
	v_mfma_f32_16x16x32_bf16 v[88:91], v[176:179], v[216:219], v[88:91]
	v_mfma_f32_16x16x32_bf16 v[76:79], v[192:195], v[208:211], v[76:79]
	v_mfma_f32_16x16x32_bf16 v[72:75], v[192:195], v[216:219], v[72:75]
	v_mfma_f32_16x16x32_bf16 v[84:87], v[184:187], v[208:211], v[84:87]
	v_mfma_f32_16x16x32_bf16 v[80:83], v[184:187], v[216:219], v[80:83]
	v_mfma_f32_16x16x32_bf16 v[68:71], v[200:203], v[208:211], v[68:71]
	v_mfma_f32_16x16x32_bf16 v[64:67], v[200:203], v[216:219], v[64:67]
	v_mfma_f32_16x16x32_bf16 v[92:95], v[180:183], v[212:215], v[92:95]
	v_mfma_f32_16x16x32_bf16 v[88:91], v[180:183], v[220:223], v[88:91]
	v_mfma_f32_16x16x32_bf16 v[76:79], v[196:199], v[212:215], v[76:79]
	v_mfma_f32_16x16x32_bf16 v[72:75], v[196:199], v[220:223], v[72:75]
	v_mfma_f32_16x16x32_bf16 v[176:179], v[188:191], v[212:215], v[84:87]
	v_mfma_f32_16x16x32_bf16 v[180:183], v[188:191], v[220:223], v[80:83]
	v_mfma_f32_16x16x32_bf16 v[184:187], v[204:207], v[212:215], v[68:71]
	v_mfma_f32_16x16x32_bf16 v[188:191], v[204:207], v[220:223], v[64:67]
	s_barrier
	s_nop 0
	ds_read_b128 v[64:67], v152 offset:16384
	ds_read_b128 v[68:71], v152 offset:17408
	ds_read_b128 v[80:83], v151 offset:16384
	ds_read_b128 v[84:87], v151 offset:17408
	ds_read_b128 v[192:195], v150 offset:16384
	ds_read_b128 v[196:199], v150 offset:17408
	ds_read_b128 v[200:203], v149 offset:16384
	ds_read_b128 v[204:207], v149 offset:17408
	s_waitcnt vmcnt(4)
	s_barrier
	s_waitcnt lgkmcnt(0)
	s_waitcnt lgkmcnt(0)
	v_mfma_f32_16x16x32_bf16 v[60:63], v[64:67], v[134:137], v[60:63]
	v_mfma_f32_16x16x32_bf16 v[56:59], v[64:67], v[156:159], v[56:59]
	v_mfma_f32_16x16x32_bf16 v[52:55], v[80:83], v[134:137], v[52:55]
	v_mfma_f32_16x16x32_bf16 v[48:51], v[80:83], v[156:159], v[48:51]
	v_mfma_f32_16x16x32_bf16 v[44:47], v[192:195], v[134:137], v[44:47]
	v_mfma_f32_16x16x32_bf16 v[40:43], v[192:195], v[156:159], v[40:43]
	v_mfma_f32_16x16x32_bf16 v[36:39], v[200:203], v[134:137], v[36:39]
	v_mfma_f32_16x16x32_bf16 v[32:35], v[200:203], v[156:159], v[32:35]
	v_mfma_f32_16x16x32_bf16 v[60:63], v[68:71], v[138:141], v[60:63]
	v_mfma_f32_16x16x32_bf16 v[56:59], v[68:71], v[172:175], v[56:59]
	v_mfma_f32_16x16x32_bf16 v[52:55], v[84:87], v[138:141], v[52:55]
	v_mfma_f32_16x16x32_bf16 v[48:51], v[84:87], v[172:175], v[48:51]
	v_mfma_f32_16x16x32_bf16 v[44:47], v[196:199], v[138:141], v[44:47]
	v_mfma_f32_16x16x32_bf16 v[40:43], v[196:199], v[172:175], v[40:43]
	v_mfma_f32_16x16x32_bf16 v[36:39], v[204:207], v[138:141], v[36:39]
	v_mfma_f32_16x16x32_bf16 v[32:35], v[204:207], v[172:175], v[32:35]
	v_mfma_f32_16x16x32_bf16 v[28:31], v[64:67], v[208:211], v[28:31]
	v_mfma_f32_16x16x32_bf16 v[24:27], v[64:67], v[216:219], v[24:27]
	v_mfma_f32_16x16x32_bf16 v[12:15], v[192:195], v[208:211], v[12:15]
	v_mfma_f32_16x16x32_bf16 v[8:11], v[192:195], v[216:219], v[8:11]
	v_mfma_f32_16x16x32_bf16 v[20:23], v[80:83], v[208:211], v[20:23]
	v_mfma_f32_16x16x32_bf16 v[16:19], v[80:83], v[216:219], v[16:19]
	v_mfma_f32_16x16x32_bf16 v[4:7], v[200:203], v[208:211], v[4:7]
	v_mfma_f32_16x16x32_bf16 v[0:3], v[200:203], v[216:219], v[0:3]
	v_mfma_f32_16x16x32_bf16 v[28:31], v[68:71], v[212:215], v[28:31]
	v_mfma_f32_16x16x32_bf16 v[24:27], v[68:71], v[220:223], v[24:27]
	v_mfma_f32_16x16x32_bf16 v[12:15], v[196:199], v[212:215], v[12:15]
	v_mfma_f32_16x16x32_bf16 v[8:11], v[196:199], v[220:223], v[8:11]
	v_mfma_f32_16x16x32_bf16 v[134:137], v[84:87], v[212:215], v[20:23]
	v_mfma_f32_16x16x32_bf16 v[138:141], v[84:87], v[220:223], v[16:19]
	v_mfma_f32_16x16x32_bf16 v[156:159], v[204:207], v[212:215], v[4:7]
	v_mfma_f32_16x16x32_bf16 v[170:173], v[204:207], v[220:223], v[0:3]
	s_barrier
	s_nop 0
	ds_read_b128 v[0:3], v155
	ds_read_b128 v[4:7], v155 offset:1024
	ds_read_b128 v[16:19], v155 offset:2048
	ds_read_b128 v[192:195], v155 offset:3072
	ds_read_b128 v[20:23], v152 offset:32768
	ds_read_b128 v[196:199], v152 offset:33792
	ds_read_b128 v[200:203], v151 offset:32768
	ds_read_b128 v[204:207], v151 offset:33792
	ds_read_b128 v[208:211], v150 offset:32768
	ds_read_b128 v[212:215], v150 offset:33792
	ds_read_b128 v[216:219], v149 offset:32768
	ds_read_b128 v[220:223], v149 offset:33792
	s_waitcnt vmcnt(2)
	s_barrier
; #define LDA(dst, b, h) for (int m = 0; m < 4; ++m) for (int k = 0; k < 2; ++k) \
;     dst[m][k] = *reinterpret_cast<const bf16x8*>((char*)SA(b, h) + lds_byte(wr * 64 + m * 16 + fr, k * 32 + fq * 8))
; #define LDB(dst, b, h) for (int n = 0; n < 2; ++n) for (int k = 0; k < 2; ++k) \
;     dst[n][k] = *reinterpret_cast<const bf16x8*>((char*)SB(b, h) + lds_byte(wc * 32 + n * 16 + fr, k * 32 + fq * 8))
; #define MMA(ai, bj, At_, Bt_) do { __builtin_amdgcn_s_setprio(1); \
;     for (int k = 0; k < 2; ++k) for (int m = 0; m < 4; ++m) for (int n = 0; n < 2; ++n) \
;       acc[ai][bj][m][n] = __builtin_amdgcn_mfma_f32_16x16x32_bf16(At_[m][k], Bt_[n][k], acc[ai][bj][m][n], 0, 0, 0); \
;     __builtin_amdgcn_s_setprio(0); } while (0)
; #define WAIT_V(n) asm volatile("s_waitcnt vmcnt(" #n ")" ::: "memory")
; #define WAIT_L(n) asm volatile("s_waitcnt lgkmcnt(" #n ")" ::: "memory")
; #define BAR __builtin_amdgcn_s_barrier()
; template <int EPI, int lda, int ldb, int N, int K>
; __device__ __forceinline__ void gemm_phase(const u16* __restrict__ A, const u16* __restrict__ Bt, const GemmEpi ep, int wv) {
;     ...
;     { LDB(B0, 1, 0); LDA(At, 1, 0); WAIT_V(2); BAR; WAIT_L(0); MMA(0, 0, At, B0); BAR;
;       LDB(B1, 1, 1); WAIT_V(0); BAR; WAIT_L(0); MMA(0, 1, At, B1); BAR;
;       LDA(At, 1, 1); BAR; WAIT_L(0); MMA(1, 0, At, B0); MMA(1, 1, At, B1); BAR; }
;     if (wr == 0) BAR;
	s_waitcnt lgkmcnt(0)
	s_waitcnt lgkmcnt(0)
	v_mfma_f32_16x16x32_bf16 v[64:67], v[20:23], v[0:3], v[124:127]
	v_mfma_f32_16x16x32_bf16 v[68:71], v[20:23], v[16:19], v[120:123]
	v_mfma_f32_16x16x32_bf16 v[80:83], v[200:203], v[0:3], v[116:119]
	v_mfma_f32_16x16x32_bf16 v[84:87], v[200:203], v[16:19], v[112:115]
	v_mfma_f32_16x16x32_bf16 v[108:111], v[208:211], v[0:3], v[108:111]
	v_mfma_f32_16x16x32_bf16 v[104:107], v[208:211], v[16:19], v[104:107]
	v_mfma_f32_16x16x32_bf16 v[120:123], v[216:219], v[0:3], v[100:103]
	v_mfma_f32_16x16x32_bf16 v[124:127], v[216:219], v[16:19], v[96:99]
	v_mfma_f32_16x16x32_bf16 v[116:119], v[196:199], v[4:7], v[64:67]
	v_mfma_f32_16x16x32_bf16 v[112:115], v[196:199], v[192:195], v[68:71]
	v_mfma_f32_16x16x32_bf16 v[100:103], v[204:207], v[4:7], v[80:83]
	v_mfma_f32_16x16x32_bf16 v[96:99], v[204:207], v[192:195], v[84:87]
	v_mfma_f32_16x16x32_bf16 v[84:87], v[212:215], v[4:7], v[108:111]
	v_mfma_f32_16x16x32_bf16 v[80:83], v[212:215], v[192:195], v[104:107]
	v_mfma_f32_16x16x32_bf16 v[68:71], v[220:223], v[4:7], v[120:123]
	v_mfma_f32_16x16x32_bf16 v[64:67], v[220:223], v[192:195], v[124:127]
	s_barrier
	ds_read_b128 v[224:227], v153
	ds_read_b128 v[228:231], v153 offset:1024
	ds_read_b128 v[232:235], v153 offset:2048
	ds_read_b128 v[236:239], v153 offset:3072
	s_waitcnt vmcnt(0)
	s_barrier
	s_waitcnt lgkmcnt(0)
	s_waitcnt lgkmcnt(0)
	v_mfma_f32_16x16x32_bf16 v[92:95], v[20:23], v[224:227], v[92:95]
	v_mfma_f32_16x16x32_bf16 v[20:23], v[20:23], v[232:235], v[88:91]
	v_mfma_f32_16x16x32_bf16 v[88:91], v[200:203], v[224:227], v[176:179]
	v_mfma_f32_16x16x32_bf16 v[104:107], v[200:203], v[232:235], v[180:183]
	v_mfma_f32_16x16x32_bf16 v[76:79], v[208:211], v[224:227], v[76:79]
	v_mfma_f32_16x16x32_bf16 v[72:75], v[208:211], v[232:235], v[72:75]
	v_mfma_f32_16x16x32_bf16 v[174:177], v[216:219], v[224:227], v[184:187]
	v_mfma_f32_16x16x32_bf16 v[178:181], v[216:219], v[232:235], v[188:191]
	v_mfma_f32_16x16x32_bf16 v[124:127], v[196:199], v[228:231], v[92:95]
	v_mfma_f32_16x16x32_bf16 v[120:123], v[196:199], v[236:239], v[20:23]
	v_mfma_f32_16x16x32_bf16 v[108:111], v[204:207], v[228:231], v[88:91]
	v_mfma_f32_16x16x32_bf16 v[104:107], v[204:207], v[236:239], v[104:107]
	v_mfma_f32_16x16x32_bf16 v[92:95], v[212:215], v[228:231], v[76:79]
	v_mfma_f32_16x16x32_bf16 v[88:91], v[212:215], v[236:239], v[72:75]
	v_mfma_f32_16x16x32_bf16 v[76:79], v[220:223], v[228:231], v[174:177]
	v_mfma_f32_16x16x32_bf16 v[72:75], v[220:223], v[236:239], v[178:181]
	s_barrier
	ds_read_b128 v[174:177], v152 offset:49152
	ds_read_b128 v[152:155], v152 offset:50176
	ds_read_b128 v[178:181], v151 offset:49152
	ds_read_b128 v[182:185], v151 offset:50176
	ds_read_b128 v[186:189], v150 offset:49152
	ds_read_b128 v[196:199], v150 offset:50176
	ds_read_b128 v[200:203], v149 offset:49152
	ds_read_b128 v[204:207], v149 offset:50176
	s_barrier
	s_waitcnt lgkmcnt(0)
	s_waitcnt lgkmcnt(0)
	v_mfma_f32_16x16x32_bf16 v[20:23], v[174:177], v[0:3], v[60:63]
	v_mfma_f32_16x16x32_bf16 v[56:59], v[174:177], v[16:19], v[56:59]
	v_mfma_f32_16x16x32_bf16 v[60:63], v[178:181], v[0:3], v[52:55]
	v_mfma_f32_16x16x32_bf16 v[208:211], v[178:181], v[16:19], v[48:51]
	v_mfma_f32_16x16x32_bf16 v[44:47], v[186:189], v[0:3], v[44:47]
	v_mfma_f32_16x16x32_bf16 v[40:43], v[186:189], v[16:19], v[40:43]
	v_mfma_f32_16x16x32_bf16 v[0:3], v[200:203], v[0:3], v[36:39]
	v_mfma_f32_16x16x32_bf16 v[212:215], v[200:203], v[16:19], v[32:35]
	v_mfma_f32_16x16x32_bf16 v[52:55], v[152:155], v[4:7], v[20:23]
	v_mfma_f32_16x16x32_bf16 v[48:51], v[152:155], v[192:195], v[56:59]
	v_mfma_f32_16x16x32_bf16 v[36:39], v[182:185], v[4:7], v[60:63]
	v_mfma_f32_16x16x32_bf16 v[32:35], v[182:185], v[192:195], v[208:211]
	v_mfma_f32_16x16x32_bf16 v[20:23], v[196:199], v[4:7], v[44:47]
	v_mfma_f32_16x16x32_bf16 v[16:19], v[196:199], v[192:195], v[40:43]
	v_mfma_f32_16x16x32_bf16 v[4:7], v[204:207], v[4:7], v[0:3]
	v_mfma_f32_16x16x32_bf16 v[0:3], v[204:207], v[192:195], v[212:215]
	v_mfma_f32_16x16x32_bf16 v[28:31], v[174:177], v[224:227], v[28:31]
	v_mfma_f32_16x16x32_bf16 v[24:27], v[174:177], v[232:235], v[24:27]
	v_mfma_f32_16x16x32_bf16 v[40:43], v[178:181], v[224:227], v[134:137]
	v_mfma_f32_16x16x32_bf16 v[134:137], v[178:181], v[232:235], v[138:141]
	v_mfma_f32_16x16x32_bf16 v[12:15], v[186:189], v[224:227], v[12:15]
	v_mfma_f32_16x16x32_bf16 v[8:11], v[186:189], v[232:235], v[8:11]
	v_mfma_f32_16x16x32_bf16 v[138:141], v[200:203], v[224:227], v[156:159]
	v_mfma_f32_16x16x32_bf16 v[156:159], v[200:203], v[232:235], v[170:173]
	v_mfma_f32_16x16x32_bf16 v[60:63], v[152:155], v[228:231], v[28:31]
	v_mfma_f32_16x16x32_bf16 v[56:59], v[152:155], v[236:239], v[24:27]
	v_mfma_f32_16x16x32_bf16 v[44:47], v[182:185], v[228:231], v[40:43]
	v_mfma_f32_16x16x32_bf16 v[40:43], v[182:185], v[236:239], v[134:137]
	v_mfma_f32_16x16x32_bf16 v[28:31], v[196:199], v[228:231], v[12:15]
	v_mfma_f32_16x16x32_bf16 v[24:27], v[196:199], v[236:239], v[8:11]
	v_mfma_f32_16x16x32_bf16 v[12:15], v[204:207], v[228:231], v[138:141]
	v_mfma_f32_16x16x32_bf16 v[8:11], v[204:207], v[236:239], v[156:159]
	v_cmp_gt_u32_e32 vcc, s80, v130
	s_barrier
	s_and_saveexec_b64 s[60:61], vcc
	s_cbranch_execz .LBB0_1150
	s_barrier

; #define STAGE(P, BASE, LD, br, kt) do { const char* _g = (const char*)((BASE) + (size_t)(br) * (LD) + (size_t)(kt) * 64); \
;     for (int _i = 0; _i < 2; ++_i) { int _b = tidx * 16 + _i * 8192; int _r, _c; stage_rc(_b, _r, _c); \
;       __builtin_amdgcn_global_load_lds((const unsigned*)(_g + (unsigned)((_r * (LD) + _c) * 2)), (unsigned*)((char*)(P) + _b), 16, 0, 0); } } while (0)
; #define LDA(dst, b, h) for (int m = 0; m < 4; ++m) for (int k = 0; k < 2; ++k) \
;     dst[m][k] = *reinterpret_cast<const bf16x8*>((char*)SA(b, h) + lds_byte(wr * 64 + m * 16 + fr, k * 32 + fq * 8))
; #define LDB(dst, b, h) for (int n = 0; n < 2; ++n) for (int k = 0; k < 2; ++k) \
;     dst[n][k] = *reinterpret_cast<const bf16x8*>((char*)SB(b, h) + lds_byte(wc * 32 + n * 16 + fr, k * 32 + fq * 8))
; #define MMA(ai, bj, At_, Bt_) do { __builtin_amdgcn_s_setprio(1); \
;     for (int k = 0; k < 2; ++k) for (int m = 0; m < 4; ++m) for (int n = 0; n < 2; ++n) \
;       acc[ai][bj][m][n] = __builtin_amdgcn_mfma_f32_16x16x32_bf16(At_[m][k], Bt_[n][k], acc[ai][bj][m][n], 0, 0, 0); \
;     __builtin_amdgcn_s_setprio(0); } while (0)
; #define WAIT_L(n) asm volatile("s_waitcnt lgkmcnt(" #n ")" ::: "memory")
; #define BAR __builtin_amdgcn_s_barrier()
; #define SCHED __builtin_amdgcn_sched_barrier(0)
; template <int EPI, int lda, int ldb, int N, int K>
; __device__ __forceinline__ void gemm_phase(const u16* __restrict__ A, const u16* __restrict__ Bt, const GemmEpi ep, int wv) {
;     ...
;       LDB(B0, 0, 0); SCHED; LDA(At, 0, 0); STAGE(SA(1, 1), Ab, lda, brow + HALF, t + 1);
;       WAIT_L(8); BAR; WAIT_L(0); MMA(0, 0, At, B0); BAR; SCHED;
;       LDB(B1, 0, 1); STAGE(SB(0, 0), Bt, ldb, bcol, t + 2);
;       BAR; WAIT_L(0); MMA(0, 1, At, B1); BAR;
;       LDA(At, 0, 1); STAGE(SA(0, 0), Ab, lda, brow, t + 2);
;       BAR; WAIT_L(0); MMA(1, 0, At, B0); BAR; SCHED;
.LBB0_1448:
	ds_read_b128 v[164:167], v160
	ds_read_b128 v[170:173], v160 offset:1024
	ds_read_b128 v[174:177], v160 offset:2048
	ds_read_b128 v[178:181], v160 offset:3072
	v_add_u32_e32 v168, 0xc000, v143
	v_lshl_add_u64 v[234:235], v[138:139], 0, s[44:45]
	v_readfirstlane_b32 s47, v168
	v_add_u32_e32 v169, 0xe000, v143
	v_lshl_add_u64 v[162:163], v[234:235], 0, s[20:21]
	s_mov_b32 m0, s47
	v_lshl_add_u64 v[236:237], v[140:141], 0, s[44:45]
	v_readfirstlane_b32 s47, v169
	ds_read_b128 v[182:185], v151
	ds_read_b128 v[186:189], v151 offset:1024
	ds_read_b128 v[190:193], v150
	ds_read_b128 v[194:197], v150 offset:1024
	ds_read_b128 v[198:201], v149
	ds_read_b128 v[202:205], v149 offset:1024
	ds_read_b128 v[206:209], v148
	ds_read_b128 v[210:213], v148 offset:1024
	global_load_lds_dwordx4 v[162:163], off
	v_lshl_add_u64 v[162:163], v[236:237], 0, s[20:21]
	s_mov_b32 m0, s47
	s_nop 0
	global_load_lds_dwordx4 v[162:163], off
	s_waitcnt lgkmcnt(8)
	s_barrier
	s_waitcnt lgkmcnt(0)
	s_waitcnt lgkmcnt(0)
	v_mfma_f32_16x16x32_bf16 v[124:127], v[164:167], v[182:185], v[124:127]
	v_mfma_f32_16x16x32_bf16 v[120:123], v[174:177], v[182:185], v[120:123]
	v_mfma_f32_16x16x32_bf16 v[116:119], v[164:167], v[190:193], v[116:119]
	v_mfma_f32_16x16x32_bf16 v[112:115], v[174:177], v[190:193], v[112:115]
	v_mfma_f32_16x16x32_bf16 v[108:111], v[164:167], v[198:201], v[108:111]
	v_mfma_f32_16x16x32_bf16 v[104:107], v[174:177], v[198:201], v[104:107]
	v_mfma_f32_16x16x32_bf16 v[100:103], v[164:167], v[206:209], v[100:103]
	v_mfma_f32_16x16x32_bf16 v[96:99], v[174:177], v[206:209], v[96:99]
	v_mfma_f32_16x16x32_bf16 v[124:127], v[170:173], v[186:189], v[124:127]
	v_mfma_f32_16x16x32_bf16 v[120:123], v[178:181], v[186:189], v[120:123]
	v_mfma_f32_16x16x32_bf16 v[116:119], v[170:173], v[194:197], v[116:119]
	v_mfma_f32_16x16x32_bf16 v[112:115], v[178:181], v[194:197], v[112:115]
	v_mfma_f32_16x16x32_bf16 v[108:111], v[170:173], v[202:205], v[108:111]
	v_mfma_f32_16x16x32_bf16 v[104:107], v[178:181], v[202:205], v[104:107]
	v_mfma_f32_16x16x32_bf16 v[100:103], v[170:173], v[210:213], v[100:103]
	v_mfma_f32_16x16x32_bf16 v[96:99], v[178:181], v[210:213], v[96:99]
	s_barrier
	v_add_u32_e32 v161, s55, v153
	v_lshl_add_u64 v[238:239], v[134:135], 0, s[44:45]
	v_readfirstlane_b32 s47, v161
	v_lshl_add_u64 v[162:163], v[238:239], 0, s[22:23]
	s_mov_b32 m0, s47
	ds_read_b128 v[214:217], v159
	ds_read_b128 v[218:221], v159 offset:1024
	ds_read_b128 v[222:225], v159 offset:2048
	ds_read_b128 v[226:229], v159 offset:3072
	global_load_lds_dwordx4 v[162:163], off
	v_add_u32_e32 v162, 0x2000, v161
	v_lshl_add_u64 v[240:241], v[136:137], 0, s[44:45]
	v_readfirstlane_b32 s47, v162
	v_lshl_add_u64 v[230:231], v[240:241], 0, s[22:23]
	s_mov_b32 m0, s47
	s_nop 0
	global_load_lds_dwordx4 v[230:231], off
	s_barrier
	s_waitcnt lgkmcnt(0)
	s_waitcnt lgkmcnt(0)
	v_mfma_f32_16x16x32_bf16 v[92:95], v[214:217], v[182:185], v[92:95]
	v_mfma_f32_16x16x32_bf16 v[88:91], v[222:225], v[182:185], v[88:91]
	v_mfma_f32_16x16x32_bf16 v[84:87], v[214:217], v[190:193], v[84:87]
	v_mfma_f32_16x16x32_bf16 v[80:83], v[222:225], v[190:193], v[80:83]
	v_mfma_f32_16x16x32_bf16 v[76:79], v[214:217], v[198:201], v[76:79]
	v_mfma_f32_16x16x32_bf16 v[72:75], v[222:225], v[198:201], v[72:75]
	v_mfma_f32_16x16x32_bf16 v[68:71], v[214:217], v[206:209], v[68:71]
	v_mfma_f32_16x16x32_bf16 v[64:67], v[222:225], v[206:209], v[64:67]
	v_mfma_f32_16x16x32_bf16 v[92:95], v[218:221], v[186:189], v[92:95]
	v_mfma_f32_16x16x32_bf16 v[88:91], v[226:229], v[186:189], v[88:91]
	v_mfma_f32_16x16x32_bf16 v[84:87], v[218:221], v[194:197], v[84:87]
	v_mfma_f32_16x16x32_bf16 v[80:83], v[226:229], v[194:197], v[80:83]
	v_mfma_f32_16x16x32_bf16 v[76:79], v[218:221], v[202:205], v[76:79]
	v_mfma_f32_16x16x32_bf16 v[72:75], v[226:229], v[202:205], v[72:75]
	v_mfma_f32_16x16x32_bf16 v[68:71], v[218:221], v[210:213], v[68:71]
	v_mfma_f32_16x16x32_bf16 v[64:67], v[226:229], v[210:213], v[64:67]
	s_barrier
	v_readfirstlane_b32 s47, v143
	v_add_u32_e32 v163, 0x2000, v143
	v_lshl_add_u64 v[230:231], v[234:235], 0, s[24:25]
	s_mov_b32 m0, s47
	v_readfirstlane_b32 s47, v163
	ds_read_b128 v[182:185], v151 offset:16384
	ds_read_b128 v[186:189], v151 offset:17408
	ds_read_b128 v[190:193], v150 offset:16384
	ds_read_b128 v[194:197], v150 offset:17408
	ds_read_b128 v[198:201], v149 offset:16384
	ds_read_b128 v[202:205], v149 offset:17408
	ds_read_b128 v[206:209], v148 offset:16384
	ds_read_b128 v[210:213], v148 offset:17408
	global_load_lds_dwordx4 v[230:231], off
	v_lshl_add_u64 v[230:231], v[236:237], 0, s[24:25]
	s_mov_b32 m0, s47
	s_nop 0
	global_load_lds_dwordx4 v[230:231], off
	s_barrier
	s_waitcnt lgkmcnt(0)
	s_waitcnt lgkmcnt(0)
	v_mfma_f32_16x16x32_bf16 v[60:63], v[164:167], v[182:185], v[60:63]
	v_mfma_f32_16x16x32_bf16 v[56:59], v[174:177], v[182:185], v[56:59]
	v_mfma_f32_16x16x32_bf16 v[52:55], v[164:167], v[190:193], v[52:55]
	v_mfma_f32_16x16x32_bf16 v[48:51], v[174:177], v[190:193], v[48:51]
	v_mfma_f32_16x16x32_bf16 v[44:47], v[164:167], v[198:201], v[44:47]
	v_mfma_f32_16x16x32_bf16 v[40:43], v[174:177], v[198:201], v[40:43]
	v_mfma_f32_16x16x32_bf16 v[36:39], v[164:167], v[206:209], v[36:39]
	v_mfma_f32_16x16x32_bf16 v[32:35], v[174:177], v[206:209], v[32:35]
	v_mfma_f32_16x16x32_bf16 v[60:63], v[170:173], v[186:189], v[60:63]
	v_mfma_f32_16x16x32_bf16 v[56:59], v[178:181], v[186:189], v[56:59]
	v_mfma_f32_16x16x32_bf16 v[52:55], v[170:173], v[194:197], v[52:55]
	v_mfma_f32_16x16x32_bf16 v[48:51], v[178:181], v[194:197], v[48:51]
	v_mfma_f32_16x16x32_bf16 v[44:47], v[170:173], v[202:205], v[44:47]
	v_mfma_f32_16x16x32_bf16 v[40:43], v[178:181], v[202:205], v[40:43]
	v_mfma_f32_16x16x32_bf16 v[36:39], v[170:173], v[210:213], v[36:39]
	v_mfma_f32_16x16x32_bf16 v[32:35], v[178:181], v[210:213], v[32:35]
	s_barrier
; #define STAGE(P, BASE, LD, br, kt) do { const char* _g = (const char*)((BASE) + (size_t)(br) * (LD) + (size_t)(kt) * 64); \
;     for (int _i = 0; _i < 2; ++_i) { int _b = tidx * 16 + _i * 8192; int _r, _c; stage_rc(_b, _r, _c); \
;       __builtin_amdgcn_global_load_lds((const unsigned*)(_g + (unsigned)((_r * (LD) + _c) * 2)), (unsigned*)((char*)(P) + _b), 16, 0, 0); } } while (0)
; #define LDA(dst, b, h) for (int m = 0; m < 4; ++m) for (int k = 0; k < 2; ++k) \
;     dst[m][k] = *reinterpret_cast<const bf16x8*>((char*)SA(b, h) + lds_byte(wr * 64 + m * 16 + fr, k * 32 + fq * 8))
; #define LDB(dst, b, h) for (int n = 0; n < 2; ++n) for (int k = 0; k < 2; ++k) \
;     dst[n][k] = *reinterpret_cast<const bf16x8*>((char*)SB(b, h) + lds_byte(wc * 32 + n * 16 + fr, k * 32 + fq * 8))
; #define MMA(ai, bj, At_, Bt_) do { __builtin_amdgcn_s_setprio(1); \
;     for (int k = 0; k < 2; ++k) for (int m = 0; m < 4; ++m) for (int n = 0; n < 2; ++n) \
;       acc[ai][bj][m][n] = __builtin_amdgcn_mfma_f32_16x16x32_bf16(At_[m][k], Bt_[n][k], acc[ai][bj][m][n], 0, 0, 0); \
;     __builtin_amdgcn_s_setprio(0); } while (0)
; #define WAIT_V(n) asm volatile("s_waitcnt vmcnt(" #n ")" ::: "memory")
; #define WAIT_L(n) asm volatile("s_waitcnt lgkmcnt(" #n ")" ::: "memory")
; #define BAR __builtin_amdgcn_s_barrier()
; #define SCHED __builtin_amdgcn_sched_barrier(0)
; template <int EPI, int lda, int ldb, int N, int K>
; __device__ __forceinline__ void gemm_phase(const u16* __restrict__ A, const u16* __restrict__ Bt, const GemmEpi ep, int wv) {
;     ...
;       STAGE(SB(0, 1), Bt, ldb, bcol + HALF, t + 2);
;       WAIT_V(6); BAR; MMA(1, 1, At, B1); BAR;
;       LDB(B0, 1, 0); SCHED; LDA(At, 1, 0); STAGE(SA(0, 1), Ab, lda, brow + HALF, t + 2);
;       WAIT_L(8); BAR; WAIT_L(0); MMA(0, 0, At, B0); BAR; SCHED;
;       LDB(B1, 1, 1); STAGE(SB(1, 0), Bt, ldb, bcol, t + 3);
;       BAR; WAIT_L(0); MMA(0, 1, At, B1); BAR;
;       LDA(At, 1, 1); STAGE(SA(1, 0), Ab, lda, brow, t + 3);
	v_add_u32_e32 v164, s56, v153
	v_add_u32_e32 v165, 0x2000, v164
	v_readfirstlane_b32 s47, v164
	v_lshl_add_u64 v[166:167], v[238:239], 0, s[26:27]
	s_mov_b32 m0, s47
	v_readfirstlane_b32 s47, v165
	global_load_lds_dwordx4 v[166:167], off
	v_lshl_add_u64 v[166:167], v[240:241], 0, s[26:27]
	s_mov_b32 m0, s47
	s_nop 0
	global_load_lds_dwordx4 v[166:167], off
	s_waitcnt vmcnt(6)
	s_barrier
	v_mfma_f32_16x16x32_bf16 v[28:31], v[214:217], v[182:185], v[28:31]
	v_mfma_f32_16x16x32_bf16 v[24:27], v[222:225], v[182:185], v[24:27]
	v_mfma_f32_16x16x32_bf16 v[20:23], v[214:217], v[190:193], v[20:23]
	v_mfma_f32_16x16x32_bf16 v[16:19], v[222:225], v[190:193], v[16:19]
	v_mfma_f32_16x16x32_bf16 v[12:15], v[214:217], v[198:201], v[12:15]
	v_mfma_f32_16x16x32_bf16 v[8:11], v[222:225], v[198:201], v[8:11]
	v_mfma_f32_16x16x32_bf16 v[4:7], v[214:217], v[206:209], v[4:7]
	v_mfma_f32_16x16x32_bf16 v[0:3], v[222:225], v[206:209], v[0:3]
	v_mfma_f32_16x16x32_bf16 v[28:31], v[218:221], v[186:189], v[28:31]
	v_mfma_f32_16x16x32_bf16 v[24:27], v[226:229], v[186:189], v[24:27]
	v_mfma_f32_16x16x32_bf16 v[20:23], v[218:221], v[194:197], v[20:23]
	v_mfma_f32_16x16x32_bf16 v[16:19], v[226:229], v[194:197], v[16:19]
	v_mfma_f32_16x16x32_bf16 v[12:15], v[218:221], v[202:205], v[12:15]
	v_mfma_f32_16x16x32_bf16 v[8:11], v[226:229], v[202:205], v[8:11]
	v_mfma_f32_16x16x32_bf16 v[4:7], v[218:221], v[210:213], v[4:7]
	v_mfma_f32_16x16x32_bf16 v[0:3], v[226:229], v[210:213], v[0:3]
	s_barrier
	ds_read_b128 v[170:173], v154
	ds_read_b128 v[174:177], v154 offset:1024
	ds_read_b128 v[178:181], v154 offset:2048
	ds_read_b128 v[182:185], v154 offset:3072
	v_add_u32_e32 v166, 0x4000, v143
	v_add_u32_e32 v167, 0x6000, v143
	v_readfirstlane_b32 s47, v166
	v_lshl_add_u64 v[218:219], v[234:235], 0, s[34:35]
	s_mov_b32 m0, s47
	v_readfirstlane_b32 s47, v167
	ds_read_b128 v[186:189], v151 offset:32768
	ds_read_b128 v[190:193], v151 offset:33792
	ds_read_b128 v[194:197], v150 offset:32768
	ds_read_b128 v[198:201], v150 offset:33792
	ds_read_b128 v[202:205], v149 offset:32768
	ds_read_b128 v[206:209], v149 offset:33792
	ds_read_b128 v[210:213], v148 offset:32768
	ds_read_b128 v[214:217], v148 offset:33792
	global_load_lds_dwordx4 v[218:219], off
	v_lshl_add_u64 v[218:219], v[236:237], 0, s[34:35]
	s_mov_b32 m0, s47
	s_nop 0
	global_load_lds_dwordx4 v[218:219], off
	s_waitcnt lgkmcnt(8)
	s_barrier
	s_waitcnt lgkmcnt(0)
	s_waitcnt lgkmcnt(0)
	v_mfma_f32_16x16x32_bf16 v[124:127], v[170:173], v[186:189], v[124:127]
	v_mfma_f32_16x16x32_bf16 v[120:123], v[178:181], v[186:189], v[120:123]
	v_mfma_f32_16x16x32_bf16 v[116:119], v[170:173], v[194:197], v[116:119]
	v_mfma_f32_16x16x32_bf16 v[112:115], v[178:181], v[194:197], v[112:115]
	v_mfma_f32_16x16x32_bf16 v[108:111], v[170:173], v[202:205], v[108:111]
	v_mfma_f32_16x16x32_bf16 v[104:107], v[178:181], v[202:205], v[104:107]
	v_mfma_f32_16x16x32_bf16 v[100:103], v[170:173], v[210:213], v[100:103]
	v_mfma_f32_16x16x32_bf16 v[96:99], v[178:181], v[210:213], v[96:99]
	v_mfma_f32_16x16x32_bf16 v[124:127], v[174:177], v[190:193], v[124:127]
	v_mfma_f32_16x16x32_bf16 v[120:123], v[182:185], v[190:193], v[120:123]
	v_mfma_f32_16x16x32_bf16 v[116:119], v[174:177], v[198:201], v[116:119]
	v_mfma_f32_16x16x32_bf16 v[112:115], v[182:185], v[198:201], v[112:115]
	v_mfma_f32_16x16x32_bf16 v[108:111], v[174:177], v[206:209], v[108:111]
	v_mfma_f32_16x16x32_bf16 v[104:107], v[182:185], v[206:209], v[104:107]
	v_mfma_f32_16x16x32_bf16 v[100:103], v[174:177], v[214:217], v[100:103]
	v_mfma_f32_16x16x32_bf16 v[96:99], v[182:185], v[214:217], v[96:99]
	s_barrier
	v_readfirstlane_b32 s47, v155
	v_add_u32_e32 v244, 0x2000, v155
	v_lshl_add_u64 v[242:243], v[238:239], 0, s[36:37]
	s_mov_b32 m0, s47
	v_readfirstlane_b32 s47, v244
	ds_read_b128 v[218:221], v152
	ds_read_b128 v[222:225], v152 offset:1024
	ds_read_b128 v[226:229], v152 offset:2048
	ds_read_b128 v[230:233], v152 offset:3072
	global_load_lds_dwordx4 v[242:243], off
	v_lshl_add_u64 v[242:243], v[240:241], 0, s[36:37]
	s_mov_b32 m0, s47
	s_nop 0
	global_load_lds_dwordx4 v[242:243], off
	s_barrier
	s_waitcnt lgkmcnt(0)
	s_waitcnt lgkmcnt(0)
	v_mfma_f32_16x16x32_bf16 v[92:95], v[218:221], v[186:189], v[92:95]
	v_mfma_f32_16x16x32_bf16 v[88:91], v[226:229], v[186:189], v[88:91]
	v_mfma_f32_16x16x32_bf16 v[84:87], v[218:221], v[194:197], v[84:87]
	v_mfma_f32_16x16x32_bf16 v[80:83], v[226:229], v[194:197], v[80:83]
	v_mfma_f32_16x16x32_bf16 v[76:79], v[218:221], v[202:205], v[76:79]
	v_mfma_f32_16x16x32_bf16 v[72:75], v[226:229], v[202:205], v[72:75]
	v_mfma_f32_16x16x32_bf16 v[68:71], v[218:221], v[210:213], v[68:71]
	v_mfma_f32_16x16x32_bf16 v[64:67], v[226:229], v[210:213], v[64:67]
	v_mfma_f32_16x16x32_bf16 v[92:95], v[222:225], v[190:193], v[92:95]
	v_mfma_f32_16x16x32_bf16 v[88:91], v[230:233], v[190:193], v[88:91]
	v_mfma_f32_16x16x32_bf16 v[84:87], v[222:225], v[198:201], v[84:87]
	v_mfma_f32_16x16x32_bf16 v[80:83], v[230:233], v[198:201], v[80:83]
	v_mfma_f32_16x16x32_bf16 v[76:79], v[222:225], v[206:209], v[76:79]
	v_mfma_f32_16x16x32_bf16 v[72:75], v[230:233], v[206:209], v[72:75]
	v_mfma_f32_16x16x32_bf16 v[68:71], v[222:225], v[214:217], v[68:71]
	v_mfma_f32_16x16x32_bf16 v[64:67], v[230:233], v[214:217], v[64:67]
	s_barrier
	v_readfirstlane_b32 s47, v156
	v_lshl_add_u64 v[234:235], v[234:235], 0, s[38:39]
	s_mov_b32 m0, s47
	v_readfirstlane_b32 s47, v157
	ds_read_b128 v[186:189], v151 offset:49152
	ds_read_b128 v[190:193], v151 offset:50176
	ds_read_b128 v[194:197], v150 offset:49152
	ds_read_b128 v[198:201], v150 offset:50176
	ds_read_b128 v[202:205], v149 offset:49152
	ds_read_b128 v[206:209], v149 offset:50176
	ds_read_b128 v[210:213], v148 offset:49152
	ds_read_b128 v[214:217], v148 offset:50176
	global_load_lds_dwordx4 v[234:235], off
	v_lshl_add_u64 v[234:235], v[236:237], 0, s[38:39]
	s_mov_b32 m0, s47
	s_nop 0
	global_load_lds_dwordx4 v[234:235], off
	s_barrier
; #define STAGE(P, BASE, LD, br, kt) do { const char* _g = (const char*)((BASE) + (size_t)(br) * (LD) + (size_t)(kt) * 64); \
;     for (int _i = 0; _i < 2; ++_i) { int _b = tidx * 16 + _i * 8192; int _r, _c; stage_rc(_b, _r, _c); \
;       __builtin_amdgcn_global_load_lds((const unsigned*)(_g + (unsigned)((_r * (LD) + _c) * 2)), (unsigned*)((char*)(P) + _b), 16, 0, 0); } } while (0)
; #define LDA(dst, b, h) for (int m = 0; m < 4; ++m) for (int k = 0; k < 2; ++k) \
;     dst[m][k] = *reinterpret_cast<const bf16x8*>((char*)SA(b, h) + lds_byte(wr * 64 + m * 16 + fr, k * 32 + fq * 8))
; #define LDB(dst, b, h) for (int n = 0; n < 2; ++n) for (int k = 0; k < 2; ++k) \
;     dst[n][k] = *reinterpret_cast<const bf16x8*>((char*)SB(b, h) + lds_byte(wc * 32 + n * 16 + fr, k * 32 + fq * 8))
; #define MMA(ai, bj, At_, Bt_) do { __builtin_amdgcn_s_setprio(1); \
;     for (int k = 0; k < 2; ++k) for (int m = 0; m < 4; ++m) for (int n = 0; n < 2; ++n) \
;       acc[ai][bj][m][n] = __builtin_amdgcn_mfma_f32_16x16x32_bf16(At_[m][k], Bt_[n][k], acc[ai][bj][m][n], 0, 0, 0); \
;     __builtin_amdgcn_s_setprio(0); } while (0)
; #define WAIT_V(n) asm volatile("s_waitcnt vmcnt(" #n ")" ::: "memory")
; #define WAIT_L(n) asm volatile("s_waitcnt lgkmcnt(" #n ")" ::: "memory")
; #define BAR __builtin_amdgcn_s_barrier()
; #define SCHED __builtin_amdgcn_sched_barrier(0)
; template <int EPI, int lda, int ldb, int N, int K>
; __device__ __forceinline__ void gemm_phase(const u16* __restrict__ A, const u16* __restrict__ Bt, const GemmEpi ep, int wv) {
;     ...
;       BAR; WAIT_L(0); MMA(1, 0, At, B0); BAR; SCHED;
;       STAGE(SB(1, 1), Bt, ldb, bcol + HALF, t + 3);
;       WAIT_V(6); BAR; MMA(1, 1, At, B1); BAR;
;     }
;     { LDB(B0, 0, 0); LDA(At, 0, 0); STAGE(SA(1, 1), Ab, lda, brow + HALF, nt - 1);
;       BAR; WAIT_L(0); MMA(0, 0, At, B0); BAR;
;       LDB(B1, 0, 1); BAR; WAIT_L(0); MMA(0, 1, At, B1); BAR;
	s_waitcnt lgkmcnt(0)
	s_waitcnt lgkmcnt(0)
	v_mfma_f32_16x16x32_bf16 v[60:63], v[170:173], v[186:189], v[60:63]
	v_mfma_f32_16x16x32_bf16 v[56:59], v[178:181], v[186:189], v[56:59]
	v_mfma_f32_16x16x32_bf16 v[52:55], v[170:173], v[194:197], v[52:55]
	v_mfma_f32_16x16x32_bf16 v[48:51], v[178:181], v[194:197], v[48:51]
	v_mfma_f32_16x16x32_bf16 v[44:47], v[170:173], v[202:205], v[44:47]
	v_mfma_f32_16x16x32_bf16 v[40:43], v[178:181], v[202:205], v[40:43]
	v_mfma_f32_16x16x32_bf16 v[36:39], v[170:173], v[210:213], v[36:39]
	v_mfma_f32_16x16x32_bf16 v[32:35], v[178:181], v[210:213], v[32:35]
	v_mfma_f32_16x16x32_bf16 v[60:63], v[174:177], v[190:193], v[60:63]
	v_mfma_f32_16x16x32_bf16 v[56:59], v[182:185], v[190:193], v[56:59]
	v_mfma_f32_16x16x32_bf16 v[52:55], v[174:177], v[198:201], v[52:55]
	v_mfma_f32_16x16x32_bf16 v[48:51], v[182:185], v[198:201], v[48:51]
	v_mfma_f32_16x16x32_bf16 v[44:47], v[174:177], v[206:209], v[44:47]
	v_mfma_f32_16x16x32_bf16 v[40:43], v[182:185], v[206:209], v[40:43]
	v_mfma_f32_16x16x32_bf16 v[36:39], v[174:177], v[214:217], v[36:39]
	v_mfma_f32_16x16x32_bf16 v[32:35], v[182:185], v[214:217], v[32:35]
	s_barrier
	v_readfirstlane_b32 s47, v158
	v_add_u32_e32 v172, 0x2000, v158
	v_lshl_add_u64 v[170:171], v[238:239], 0, s[40:41]
	s_mov_b32 m0, s47
	v_readfirstlane_b32 s47, v172
	global_load_lds_dwordx4 v[170:171], off
	v_lshl_add_u64 v[170:171], v[240:241], 0, s[40:41]
	s_mov_b32 m0, s47
	s_nop 0
	global_load_lds_dwordx4 v[170:171], off
	s_waitcnt vmcnt(6)
	s_barrier
	v_mfma_f32_16x16x32_bf16 v[28:31], v[218:221], v[186:189], v[28:31]
	v_mfma_f32_16x16x32_bf16 v[24:27], v[226:229], v[186:189], v[24:27]
	v_mfma_f32_16x16x32_bf16 v[20:23], v[218:221], v[194:197], v[20:23]
	v_mfma_f32_16x16x32_bf16 v[16:19], v[226:229], v[194:197], v[16:19]
	v_mfma_f32_16x16x32_bf16 v[12:15], v[218:221], v[202:205], v[12:15]
	v_mfma_f32_16x16x32_bf16 v[8:11], v[226:229], v[202:205], v[8:11]
	v_mfma_f32_16x16x32_bf16 v[4:7], v[218:221], v[210:213], v[4:7]
	v_mfma_f32_16x16x32_bf16 v[0:3], v[226:229], v[210:213], v[0:3]
	v_mfma_f32_16x16x32_bf16 v[28:31], v[222:225], v[190:193], v[28:31]
	v_mfma_f32_16x16x32_bf16 v[24:27], v[230:233], v[190:193], v[24:27]
	v_mfma_f32_16x16x32_bf16 v[20:23], v[222:225], v[198:201], v[20:23]
	v_mfma_f32_16x16x32_bf16 v[16:19], v[230:233], v[198:201], v[16:19]
	v_mfma_f32_16x16x32_bf16 v[12:15], v[222:225], v[206:209], v[12:15]
	v_mfma_f32_16x16x32_bf16 v[8:11], v[230:233], v[206:209], v[8:11]
	v_mfma_f32_16x16x32_bf16 v[4:7], v[222:225], v[214:217], v[4:7]
	v_mfma_f32_16x16x32_bf16 v[0:3], v[230:233], v[214:217], v[0:3]
	s_barrier
	s_add_i32 s46, s46, 2
	s_add_u32 s44, s44, 0x100
	s_addc_u32 s45, s45, 0
	s_cmp_gt_u32 s46, 27
	s_cbranch_scc0 .LBB0_1448
	s_lshl_b64 s[44:45], s[16:17], 12
	s_add_u32 s44, s14, s44
	s_addc_u32 s45, s15, s45
	s_add_u32 s44, s44, 0x80000
	s_addc_u32 s45, s45, 0
	v_lshl_add_u64 v[156:157], s[44:45], 0, v[128:129]
	v_readfirstlane_b32 s46, v168
	v_lshl_add_u64 v[156:157], v[156:157], 0, s[42:43]
	s_mov_b32 m0, s46
	ds_read_b128 v[134:137], v160
	ds_read_b128 v[138:141], v160 offset:1024
	ds_read_b128 v[170:173], v160 offset:2048
	ds_read_b128 v[174:177], v160 offset:3072
	ds_read_b128 v[178:181], v151
	ds_read_b128 v[182:185], v151 offset:1024
	ds_read_b128 v[186:189], v150
	ds_read_b128 v[190:193], v150 offset:1024
	ds_read_b128 v[194:197], v149
	ds_read_b128 v[198:201], v149 offset:1024
	ds_read_b128 v[202:205], v148
	ds_read_b128 v[206:209], v148 offset:1024
	global_load_lds_dwordx4 v[156:157], off
	v_lshl_add_u64 v[156:157], s[44:45], 0, v[132:133]
	v_readfirstlane_b32 s44, v169
	v_lshl_add_u64 v[156:157], v[156:157], 0, s[42:43]
	s_mov_b32 m0, s44
	s_nop 0
	global_load_lds_dwordx4 v[156:157], off
	s_barrier
	s_waitcnt lgkmcnt(0)
	s_waitcnt lgkmcnt(0)
	v_mfma_f32_16x16x32_bf16 v[124:127], v[134:137], v[178:181], v[124:127]
	v_mfma_f32_16x16x32_bf16 v[120:123], v[170:173], v[178:181], v[120:123]
	v_mfma_f32_16x16x32_bf16 v[116:119], v[134:137], v[186:189], v[116:119]
	v_mfma_f32_16x16x32_bf16 v[112:115], v[170:173], v[186:189], v[112:115]
	v_mfma_f32_16x16x32_bf16 v[108:111], v[134:137], v[194:197], v[108:111]
	v_mfma_f32_16x16x32_bf16 v[104:107], v[170:173], v[194:197], v[104:107]
	v_mfma_f32_16x16x32_bf16 v[100:103], v[134:137], v[202:205], v[100:103]
	v_mfma_f32_16x16x32_bf16 v[96:99], v[170:173], v[202:205], v[96:99]
	v_mfma_f32_16x16x32_bf16 v[124:127], v[138:141], v[182:185], v[124:127]
	v_mfma_f32_16x16x32_bf16 v[120:123], v[174:177], v[182:185], v[120:123]
	v_mfma_f32_16x16x32_bf16 v[116:119], v[138:141], v[190:193], v[116:119]
	v_mfma_f32_16x16x32_bf16 v[112:115], v[174:177], v[190:193], v[112:115]
	v_mfma_f32_16x16x32_bf16 v[108:111], v[138:141], v[198:201], v[108:111]
	v_mfma_f32_16x16x32_bf16 v[104:107], v[174:177], v[198:201], v[104:107]
	v_mfma_f32_16x16x32_bf16 v[100:103], v[138:141], v[206:209], v[100:103]
	v_mfma_f32_16x16x32_bf16 v[96:99], v[174:177], v[206:209], v[96:99]
	s_barrier
	ds_read_b128 v[210:213], v159
	ds_read_b128 v[214:217], v159 offset:1024
	ds_read_b128 v[218:221], v159 offset:2048
	ds_read_b128 v[156:159], v159 offset:3072
	s_barrier
; #define LDA(dst, b, h) for (int m = 0; m < 4; ++m) for (int k = 0; k < 2; ++k) \
;     dst[m][k] = *reinterpret_cast<const bf16x8*>((char*)SA(b, h) + lds_byte(wr * 64 + m * 16 + fr, k * 32 + fq * 8))
; #define LDB(dst, b, h) for (int n = 0; n < 2; ++n) for (int k = 0; k < 2; ++k) \
;     dst[n][k] = *reinterpret_cast<const bf16x8*>((char*)SB(b, h) + lds_byte(wc * 32 + n * 16 + fr, k * 32 + fq * 8))
; #define MMA(ai, bj, At_, Bt_) do { __builtin_amdgcn_s_setprio(1); \
;     for (int k = 0; k < 2; ++k) for (int m = 0; m < 4; ++m) for (int n = 0; n < 2; ++n) \
;       acc[ai][bj][m][n] = __builtin_amdgcn_mfma_f32_16x16x32_bf16(At_[m][k], Bt_[n][k], acc[ai][bj][m][n], 0, 0, 0); \
;     __builtin_amdgcn_s_setprio(0); } while (0)
; #define WAIT_V(n) asm volatile("s_waitcnt vmcnt(" #n ")" ::: "memory")
; #define WAIT_L(n) asm volatile("s_waitcnt lgkmcnt(" #n ")" ::: "memory")
; #define BAR __builtin_amdgcn_s_barrier()
; template <int EPI, int lda, int ldb, int N, int K>
; __device__ __forceinline__ void gemm_phase(const u16* __restrict__ A, const u16* __restrict__ Bt, const GemmEpi ep, int wv) {
;     ...
;       LDB(B1, 0, 1); BAR; WAIT_L(0); MMA(0, 1, At, B1); BAR;
;       LDA(At, 0, 1); WAIT_V(4); BAR; WAIT_L(0); MMA(1, 0, At, B0); MMA(1, 1, At, B1); BAR; }
;     { LDB(B0, 1, 0); LDA(At, 1, 0); WAIT_V(2); BAR; WAIT_L(0); MMA(0, 0, At, B0); BAR;
	s_waitcnt lgkmcnt(0)
	s_waitcnt lgkmcnt(0)
	v_mfma_f32_16x16x32_bf16 v[92:95], v[210:213], v[178:181], v[92:95]
	v_mfma_f32_16x16x32_bf16 v[88:91], v[218:221], v[178:181], v[88:91]
	v_mfma_f32_16x16x32_bf16 v[76:79], v[210:213], v[194:197], v[76:79]
	v_mfma_f32_16x16x32_bf16 v[72:75], v[218:221], v[194:197], v[72:75]
	v_mfma_f32_16x16x32_bf16 v[84:87], v[210:213], v[186:189], v[84:87]
	v_mfma_f32_16x16x32_bf16 v[80:83], v[218:221], v[186:189], v[80:83]
	v_mfma_f32_16x16x32_bf16 v[68:71], v[210:213], v[202:205], v[68:71]
	v_mfma_f32_16x16x32_bf16 v[64:67], v[218:221], v[202:205], v[64:67]
	v_mfma_f32_16x16x32_bf16 v[92:95], v[214:217], v[182:185], v[92:95]
	v_mfma_f32_16x16x32_bf16 v[88:91], v[156:159], v[182:185], v[88:91]
	v_mfma_f32_16x16x32_bf16 v[76:79], v[214:217], v[198:201], v[76:79]
	v_mfma_f32_16x16x32_bf16 v[72:75], v[156:159], v[198:201], v[72:75]
	v_mfma_f32_16x16x32_bf16 v[178:181], v[214:217], v[190:193], v[84:87]
	v_mfma_f32_16x16x32_bf16 v[182:185], v[156:159], v[190:193], v[80:83]
	v_mfma_f32_16x16x32_bf16 v[186:189], v[214:217], v[206:209], v[68:71]
	v_mfma_f32_16x16x32_bf16 v[190:193], v[156:159], v[206:209], v[64:67]
	s_barrier
	s_nop 0
	ds_read_b128 v[64:67], v151 offset:16384
	ds_read_b128 v[68:71], v151 offset:17408
	ds_read_b128 v[80:83], v150 offset:16384
	ds_read_b128 v[84:87], v150 offset:17408
	ds_read_b128 v[194:197], v149 offset:16384
	ds_read_b128 v[198:201], v149 offset:17408
	ds_read_b128 v[202:205], v148 offset:16384
	ds_read_b128 v[206:209], v148 offset:17408
	s_waitcnt vmcnt(4)
	s_barrier
	s_waitcnt lgkmcnt(0)
	s_waitcnt lgkmcnt(0)
	v_mfma_f32_16x16x32_bf16 v[60:63], v[134:137], v[64:67], v[60:63]
	v_mfma_f32_16x16x32_bf16 v[56:59], v[170:173], v[64:67], v[56:59]
	v_mfma_f32_16x16x32_bf16 v[52:55], v[134:137], v[80:83], v[52:55]
	v_mfma_f32_16x16x32_bf16 v[48:51], v[170:173], v[80:83], v[48:51]
	v_mfma_f32_16x16x32_bf16 v[44:47], v[134:137], v[194:197], v[44:47]
	v_mfma_f32_16x16x32_bf16 v[40:43], v[170:173], v[194:197], v[40:43]
	v_mfma_f32_16x16x32_bf16 v[36:39], v[134:137], v[202:205], v[36:39]
	v_mfma_f32_16x16x32_bf16 v[32:35], v[170:173], v[202:205], v[32:35]
	v_mfma_f32_16x16x32_bf16 v[60:63], v[138:141], v[68:71], v[60:63]
	v_mfma_f32_16x16x32_bf16 v[56:59], v[174:177], v[68:71], v[56:59]
	v_mfma_f32_16x16x32_bf16 v[52:55], v[138:141], v[84:87], v[52:55]
	v_mfma_f32_16x16x32_bf16 v[48:51], v[174:177], v[84:87], v[48:51]
	v_mfma_f32_16x16x32_bf16 v[44:47], v[138:141], v[198:201], v[44:47]
	v_mfma_f32_16x16x32_bf16 v[40:43], v[174:177], v[198:201], v[40:43]
	v_mfma_f32_16x16x32_bf16 v[36:39], v[138:141], v[206:209], v[36:39]
	v_mfma_f32_16x16x32_bf16 v[32:35], v[174:177], v[206:209], v[32:35]
	v_mfma_f32_16x16x32_bf16 v[28:31], v[210:213], v[64:67], v[28:31]
	v_mfma_f32_16x16x32_bf16 v[20:23], v[210:213], v[80:83], v[20:23]
	v_mfma_f32_16x16x32_bf16 v[12:15], v[210:213], v[194:197], v[12:15]
	v_mfma_f32_16x16x32_bf16 v[4:7], v[210:213], v[202:205], v[4:7]
	v_mfma_f32_16x16x32_bf16 v[24:27], v[218:221], v[64:67], v[24:27]
	v_mfma_f32_16x16x32_bf16 v[16:19], v[218:221], v[80:83], v[16:19]
	v_mfma_f32_16x16x32_bf16 v[8:11], v[218:221], v[194:197], v[8:11]
	v_mfma_f32_16x16x32_bf16 v[0:3], v[218:221], v[202:205], v[0:3]
	v_mfma_f32_16x16x32_bf16 v[28:31], v[214:217], v[68:71], v[28:31]
	v_mfma_f32_16x16x32_bf16 v[20:23], v[214:217], v[84:87], v[20:23]
	v_mfma_f32_16x16x32_bf16 v[12:15], v[214:217], v[198:201], v[12:15]
	v_mfma_f32_16x16x32_bf16 v[4:7], v[214:217], v[206:209], v[4:7]
	v_mfma_f32_16x16x32_bf16 v[134:137], v[156:159], v[68:71], v[24:27]
	v_mfma_f32_16x16x32_bf16 v[138:141], v[156:159], v[84:87], v[16:19]
	v_mfma_f32_16x16x32_bf16 v[168:171], v[156:159], v[198:201], v[8:11]
	v_mfma_f32_16x16x32_bf16 v[156:159], v[156:159], v[206:209], v[0:3]
	s_barrier
	s_nop 0
	ds_read_b128 v[0:3], v154
	ds_read_b128 v[8:11], v154 offset:1024
	ds_read_b128 v[16:19], v154 offset:2048
	ds_read_b128 v[172:175], v154 offset:3072
	ds_read_b128 v[24:27], v151 offset:32768
	ds_read_b128 v[194:197], v151 offset:33792
	ds_read_b128 v[198:201], v150 offset:32768
	ds_read_b128 v[202:205], v150 offset:33792
	ds_read_b128 v[206:209], v149 offset:32768
	ds_read_b128 v[210:213], v149 offset:33792
	ds_read_b128 v[214:217], v148 offset:32768
	ds_read_b128 v[218:221], v148 offset:33792
	s_waitcnt vmcnt(2)
	s_barrier
; #define LDA(dst, b, h) for (int m = 0; m < 4; ++m) for (int k = 0; k < 2; ++k) \
;     dst[m][k] = *reinterpret_cast<const bf16x8*>((char*)SA(b, h) + lds_byte(wr * 64 + m * 16 + fr, k * 32 + fq * 8))
; #define LDB(dst, b, h) for (int n = 0; n < 2; ++n) for (int k = 0; k < 2; ++k) \
;     dst[n][k] = *reinterpret_cast<const bf16x8*>((char*)SB(b, h) + lds_byte(wc * 32 + n * 16 + fr, k * 32 + fq * 8))
; #define MMA(ai, bj, At_, Bt_) do { __builtin_amdgcn_s_setprio(1); \
;     for (int k = 0; k < 2; ++k) for (int m = 0; m < 4; ++m) for (int n = 0; n < 2; ++n) \
;       acc[ai][bj][m][n] = __builtin_amdgcn_mfma_f32_16x16x32_bf16(At_[m][k], Bt_[n][k], acc[ai][bj][m][n], 0, 0, 0); \
;     __builtin_amdgcn_s_setprio(0); } while (0)
; #define WAIT_V(n) asm volatile("s_waitcnt vmcnt(" #n ")" ::: "memory")
; #define WAIT_L(n) asm volatile("s_waitcnt lgkmcnt(" #n ")" ::: "memory")
; #define BAR __builtin_amdgcn_s_barrier()
; template <int EPI, int lda, int ldb, int N, int K>
; __device__ __forceinline__ void gemm_phase(const u16* __restrict__ A, const u16* __restrict__ Bt, const GemmEpi ep, int wv) {
;     ...
;     { LDB(B0, 1, 0); LDA(At, 1, 0); WAIT_V(2); BAR; WAIT_L(0); MMA(0, 0, At, B0); BAR;
;       LDB(B1, 1, 1); WAIT_V(0); BAR; WAIT_L(0); MMA(0, 1, At, B1); BAR;
;       LDA(At, 1, 1); BAR; WAIT_L(0); MMA(1, 0, At, B0); MMA(1, 1, At, B1); BAR; }
;     if (wr == 0) BAR;
	s_waitcnt lgkmcnt(0)
	s_waitcnt lgkmcnt(0)
	v_mfma_f32_16x16x32_bf16 v[64:67], v[0:3], v[24:27], v[124:127]
	v_mfma_f32_16x16x32_bf16 v[68:71], v[16:19], v[24:27], v[120:123]
	v_mfma_f32_16x16x32_bf16 v[80:83], v[0:3], v[198:201], v[116:119]
	v_mfma_f32_16x16x32_bf16 v[84:87], v[16:19], v[198:201], v[112:115]
	v_mfma_f32_16x16x32_bf16 v[108:111], v[0:3], v[206:209], v[108:111]
	v_mfma_f32_16x16x32_bf16 v[104:107], v[16:19], v[206:209], v[104:107]
	v_mfma_f32_16x16x32_bf16 v[120:123], v[0:3], v[214:217], v[100:103]
	v_mfma_f32_16x16x32_bf16 v[124:127], v[16:19], v[214:217], v[96:99]
	v_mfma_f32_16x16x32_bf16 v[116:119], v[8:11], v[194:197], v[64:67]
	v_mfma_f32_16x16x32_bf16 v[112:115], v[172:175], v[194:197], v[68:71]
	v_mfma_f32_16x16x32_bf16 v[100:103], v[8:11], v[202:205], v[80:83]
	v_mfma_f32_16x16x32_bf16 v[96:99], v[172:175], v[202:205], v[84:87]
	v_mfma_f32_16x16x32_bf16 v[84:87], v[8:11], v[210:213], v[108:111]
	v_mfma_f32_16x16x32_bf16 v[80:83], v[172:175], v[210:213], v[104:107]
	v_mfma_f32_16x16x32_bf16 v[68:71], v[8:11], v[218:221], v[120:123]
	v_mfma_f32_16x16x32_bf16 v[64:67], v[172:175], v[218:221], v[124:127]
	s_barrier
	ds_read_b128 v[222:225], v152
	ds_read_b128 v[226:229], v152 offset:1024
	ds_read_b128 v[230:233], v152 offset:2048
	ds_read_b128 v[152:155], v152 offset:3072
	s_waitcnt vmcnt(0)
	s_barrier
	s_waitcnt lgkmcnt(0)
	s_waitcnt lgkmcnt(0)
	v_mfma_f32_16x16x32_bf16 v[92:95], v[222:225], v[24:27], v[92:95]
	v_mfma_f32_16x16x32_bf16 v[24:27], v[230:233], v[24:27], v[88:91]
	v_mfma_f32_16x16x32_bf16 v[88:91], v[222:225], v[198:201], v[178:181]
	v_mfma_f32_16x16x32_bf16 v[104:107], v[230:233], v[198:201], v[182:185]
	v_mfma_f32_16x16x32_bf16 v[76:79], v[222:225], v[206:209], v[76:79]
	v_mfma_f32_16x16x32_bf16 v[72:75], v[230:233], v[206:209], v[72:75]
	v_mfma_f32_16x16x32_bf16 v[176:179], v[222:225], v[214:217], v[186:189]
	v_mfma_f32_16x16x32_bf16 v[180:183], v[230:233], v[214:217], v[190:193]
	v_mfma_f32_16x16x32_bf16 v[124:127], v[226:229], v[194:197], v[92:95]
	v_mfma_f32_16x16x32_bf16 v[120:123], v[152:155], v[194:197], v[24:27]
	v_mfma_f32_16x16x32_bf16 v[108:111], v[226:229], v[202:205], v[88:91]
	v_mfma_f32_16x16x32_bf16 v[104:107], v[152:155], v[202:205], v[104:107]
	v_mfma_f32_16x16x32_bf16 v[92:95], v[226:229], v[210:213], v[76:79]
	v_mfma_f32_16x16x32_bf16 v[88:91], v[152:155], v[210:213], v[72:75]
	v_mfma_f32_16x16x32_bf16 v[76:79], v[226:229], v[218:221], v[176:179]
	v_mfma_f32_16x16x32_bf16 v[72:75], v[152:155], v[218:221], v[180:183]
	s_barrier
	ds_read_b128 v[176:179], v151 offset:49152
	ds_read_b128 v[180:183], v151 offset:50176
	ds_read_b128 v[184:187], v150 offset:49152
	ds_read_b128 v[188:191], v150 offset:50176
	ds_read_b128 v[192:195], v149 offset:49152
	ds_read_b128 v[196:199], v149 offset:50176
	ds_read_b128 v[200:203], v148 offset:49152
	ds_read_b128 v[148:151], v148 offset:50176
	s_barrier
	s_waitcnt lgkmcnt(0)
	s_waitcnt lgkmcnt(0)
	v_mfma_f32_16x16x32_bf16 v[24:27], v[0:3], v[176:179], v[60:63]
	v_mfma_f32_16x16x32_bf16 v[60:63], v[16:19], v[176:179], v[56:59]
	v_mfma_f32_16x16x32_bf16 v[52:55], v[0:3], v[184:187], v[52:55]
	v_mfma_f32_16x16x32_bf16 v[204:207], v[16:19], v[184:187], v[48:51]
	v_mfma_f32_16x16x32_bf16 v[44:47], v[0:3], v[192:195], v[44:47]
	v_mfma_f32_16x16x32_bf16 v[208:211], v[16:19], v[192:195], v[40:43]
	v_mfma_f32_16x16x32_bf16 v[0:3], v[0:3], v[200:203], v[36:39]
	v_mfma_f32_16x16x32_bf16 v[36:39], v[16:19], v[200:203], v[32:35]
	v_mfma_f32_16x16x32_bf16 v[56:59], v[8:11], v[180:183], v[24:27]
	v_mfma_f32_16x16x32_bf16 v[48:51], v[172:175], v[180:183], v[60:63]
	v_mfma_f32_16x16x32_bf16 v[40:43], v[8:11], v[188:191], v[52:55]
	v_mfma_f32_16x16x32_bf16 v[32:35], v[172:175], v[188:191], v[204:207]
	v_mfma_f32_16x16x32_bf16 v[24:27], v[8:11], v[196:199], v[44:47]
	v_mfma_f32_16x16x32_bf16 v[16:19], v[172:175], v[196:199], v[208:211]
	v_mfma_f32_16x16x32_bf16 v[8:11], v[8:11], v[148:151], v[0:3]
	v_mfma_f32_16x16x32_bf16 v[0:3], v[172:175], v[148:151], v[36:39]
	v_mfma_f32_16x16x32_bf16 v[28:31], v[222:225], v[176:179], v[28:31]
	v_mfma_f32_16x16x32_bf16 v[36:39], v[230:233], v[176:179], v[134:137]
	v_mfma_f32_16x16x32_bf16 v[20:23], v[222:225], v[184:187], v[20:23]
	v_mfma_f32_16x16x32_bf16 v[134:137], v[230:233], v[184:187], v[138:141]
	v_mfma_f32_16x16x32_bf16 v[12:15], v[222:225], v[192:195], v[12:15]
	v_mfma_f32_16x16x32_bf16 v[138:141], v[230:233], v[192:195], v[168:171]
	v_mfma_f32_16x16x32_bf16 v[4:7], v[222:225], v[200:203], v[4:7]
	v_mfma_f32_16x16x32_bf16 v[156:159], v[230:233], v[200:203], v[156:159]
	v_mfma_f32_16x16x32_bf16 v[60:63], v[226:229], v[180:183], v[28:31]
	v_mfma_f32_16x16x32_bf16 v[52:55], v[152:155], v[180:183], v[36:39]
	v_mfma_f32_16x16x32_bf16 v[44:47], v[226:229], v[188:191], v[20:23]
	v_mfma_f32_16x16x32_bf16 v[36:39], v[152:155], v[188:191], v[134:137]
	v_mfma_f32_16x16x32_bf16 v[28:31], v[226:229], v[196:199], v[12:15]
	v_mfma_f32_16x16x32_bf16 v[20:23], v[152:155], v[196:199], v[138:141]
	v_mfma_f32_16x16x32_bf16 v[12:15], v[226:229], v[148:151], v[4:7]
	v_mfma_f32_16x16x32_bf16 v[4:7], v[152:155], v[148:151], v[156:159]
	v_cmp_gt_u32_e32 vcc, s60, v130
	s_barrier
	s_and_saveexec_b64 s[44:45], vcc
	s_cbranch_execz .LBB0_1451
	s_barrier

; #define STAGE(P, BASE, LD, br, kt) do { const char* _g = (const char*)((BASE) + (size_t)(br) * (LD) + (size_t)(kt) * 64); \
;     for (int _i = 0; _i < 2; ++_i) { int _b = tidx * 16 + _i * 8192; int _r, _c; stage_rc(_b, _r, _c); \
;       __builtin_amdgcn_global_load_lds((const unsigned*)(_g + (unsigned)((_r * (LD) + _c) * 2)), (unsigned*)((char*)(P) + _b), 16, 0, 0); } } while (0)
; #define LDA(dst, b, h) for (int m = 0; m < 4; ++m) for (int k = 0; k < 2; ++k) \
;     dst[m][k] = *reinterpret_cast<const bf16x8*>((char*)SA(b, h) + lds_byte(wr * 64 + m * 16 + fr, k * 32 + fq * 8))
; #define LDB(dst, b, h) for (int n = 0; n < 2; ++n) for (int k = 0; k < 2; ++k) \
;     dst[n][k] = *reinterpret_cast<const bf16x8*>((char*)SB(b, h) + lds_byte(wc * 32 + n * 16 + fr, k * 32 + fq * 8))
; #define MMA(ai, bj, At_, Bt_) do { __builtin_amdgcn_s_setprio(1); \
;     for (int k = 0; k < 2; ++k) for (int m = 0; m < 4; ++m) for (int n = 0; n < 2; ++n) \
;       acc[ai][bj][m][n] = __builtin_amdgcn_mfma_f32_16x16x32_bf16(At_[m][k], Bt_[n][k], acc[ai][bj][m][n], 0, 0, 0); \
;     __builtin_amdgcn_s_setprio(0); } while (0)
; #define WAIT_L(n) asm volatile("s_waitcnt lgkmcnt(" #n ")" ::: "memory")
; #define BAR __builtin_amdgcn_s_barrier()
; #define SCHED __builtin_amdgcn_sched_barrier(0)
; template <int EPI, int lda, int ldb, int N, int K>
; __device__ __forceinline__ void gemm_phase(const u16* __restrict__ A, const u16* __restrict__ Bt, const GemmEpi ep, int wv) {
;     ...
;       LDB(B0, 0, 0); SCHED; LDA(At, 0, 0); STAGE(SA(1, 1), Ab, lda, brow + HALF, t + 1);
;       WAIT_L(8); BAR; WAIT_L(0); MMA(0, 0, At, B0); BAR; SCHED;
;       LDB(B1, 0, 1); STAGE(SB(0, 0), Bt, ldb, bcol, t + 2);
;       BAR; WAIT_L(0); MMA(0, 1, At, B1); BAR;
;       LDA(At, 0, 1); STAGE(SA(0, 0), Ab, lda, brow, t + 2);
;       BAR; WAIT_L(0); MMA(1, 0, At, B0); BAR; SCHED;
.LBB0_1564:
	ds_read_b128 v[172:175], v161
	ds_read_b128 v[176:179], v161 offset:1024
	ds_read_b128 v[180:183], v161 offset:2048
	ds_read_b128 v[184:187], v161 offset:3072
	v_add_u32_e32 v169, 0xc000, v148
	v_lshl_add_u64 v[236:237], v[136:137], 0, s[40:41]
	v_readfirstlane_b32 s43, v169
	v_add_u32_e32 v170, 0xe000, v148
	v_lshl_add_u64 v[162:163], v[236:237], 0, s[14:15]
	s_mov_b32 m0, s43
	v_lshl_add_u64 v[238:239], v[134:135], 0, s[40:41]
	v_readfirstlane_b32 s43, v170
	ds_read_b128 v[164:167], v152
	ds_read_b128 v[188:191], v152 offset:1024
	ds_read_b128 v[192:195], v151
	ds_read_b128 v[196:199], v151 offset:1024
	ds_read_b128 v[200:203], v150
	ds_read_b128 v[204:207], v150 offset:1024
	ds_read_b128 v[208:211], v149
	ds_read_b128 v[212:215], v149 offset:1024
	global_load_lds_dwordx4 v[162:163], off
	v_lshl_add_u64 v[162:163], v[238:239], 0, s[14:15]
	s_mov_b32 m0, s43
	s_nop 0
	global_load_lds_dwordx4 v[162:163], off
	s_waitcnt lgkmcnt(8)
	s_barrier
	s_waitcnt lgkmcnt(0)
	s_waitcnt lgkmcnt(0)
	v_mfma_f32_16x16x32_bf16 v[124:127], v[172:175], v[164:167], v[124:127]
	v_mfma_f32_16x16x32_bf16 v[120:123], v[180:183], v[164:167], v[120:123]
	v_mfma_f32_16x16x32_bf16 v[116:119], v[172:175], v[192:195], v[116:119]
	v_mfma_f32_16x16x32_bf16 v[112:115], v[180:183], v[192:195], v[112:115]
	v_mfma_f32_16x16x32_bf16 v[108:111], v[172:175], v[200:203], v[108:111]
	v_mfma_f32_16x16x32_bf16 v[104:107], v[180:183], v[200:203], v[104:107]
	v_mfma_f32_16x16x32_bf16 v[100:103], v[172:175], v[208:211], v[100:103]
	v_mfma_f32_16x16x32_bf16 v[96:99], v[180:183], v[208:211], v[96:99]
	v_mfma_f32_16x16x32_bf16 v[124:127], v[176:179], v[188:191], v[124:127]
	v_mfma_f32_16x16x32_bf16 v[120:123], v[184:187], v[188:191], v[120:123]
	v_mfma_f32_16x16x32_bf16 v[116:119], v[176:179], v[196:199], v[116:119]
	v_mfma_f32_16x16x32_bf16 v[112:115], v[184:187], v[196:199], v[112:115]
	v_mfma_f32_16x16x32_bf16 v[108:111], v[176:179], v[204:207], v[108:111]
	v_mfma_f32_16x16x32_bf16 v[104:107], v[184:187], v[204:207], v[104:107]
	v_mfma_f32_16x16x32_bf16 v[100:103], v[176:179], v[212:215], v[100:103]
	v_mfma_f32_16x16x32_bf16 v[96:99], v[184:187], v[212:215], v[96:99]
	s_barrier
	v_add_u32_e32 v162, s52, v153
	v_lshl_add_u64 v[240:241], v[140:141], 0, s[40:41]
	v_readfirstlane_b32 s43, v162
	v_add_u32_e32 v163, 0x2000, v162
	v_lshl_add_u64 v[232:233], v[240:241], 0, s[16:17]
	s_mov_b32 m0, s43
	v_lshl_add_u64 v[242:243], v[138:139], 0, s[40:41]
	v_readfirstlane_b32 s43, v163
	ds_read_b128 v[216:219], v160
	ds_read_b128 v[220:223], v160 offset:1024
	ds_read_b128 v[224:227], v160 offset:2048
	ds_read_b128 v[228:231], v160 offset:3072
	global_load_lds_dwordx4 v[232:233], off
	v_lshl_add_u64 v[232:233], v[242:243], 0, s[16:17]
	s_mov_b32 m0, s43
	s_nop 0
	global_load_lds_dwordx4 v[232:233], off
	s_barrier
	s_waitcnt lgkmcnt(0)
	s_waitcnt lgkmcnt(0)
	v_mfma_f32_16x16x32_bf16 v[92:95], v[216:219], v[164:167], v[92:95]
	v_mfma_f32_16x16x32_bf16 v[88:91], v[224:227], v[164:167], v[88:91]
	v_mfma_f32_16x16x32_bf16 v[84:87], v[216:219], v[192:195], v[84:87]
	v_mfma_f32_16x16x32_bf16 v[80:83], v[224:227], v[192:195], v[80:83]
	v_mfma_f32_16x16x32_bf16 v[76:79], v[216:219], v[200:203], v[76:79]
	v_mfma_f32_16x16x32_bf16 v[72:75], v[224:227], v[200:203], v[72:75]
	v_mfma_f32_16x16x32_bf16 v[68:71], v[216:219], v[208:211], v[68:71]
	v_mfma_f32_16x16x32_bf16 v[64:67], v[224:227], v[208:211], v[64:67]
	v_mfma_f32_16x16x32_bf16 v[92:95], v[220:223], v[188:191], v[92:95]
	v_mfma_f32_16x16x32_bf16 v[88:91], v[228:231], v[188:191], v[88:91]
	v_mfma_f32_16x16x32_bf16 v[84:87], v[220:223], v[196:199], v[84:87]
	v_mfma_f32_16x16x32_bf16 v[80:83], v[228:231], v[196:199], v[80:83]
	v_mfma_f32_16x16x32_bf16 v[76:79], v[220:223], v[204:207], v[76:79]
	v_mfma_f32_16x16x32_bf16 v[72:75], v[228:231], v[204:207], v[72:75]
	v_mfma_f32_16x16x32_bf16 v[68:71], v[220:223], v[212:215], v[68:71]
	v_mfma_f32_16x16x32_bf16 v[64:67], v[228:231], v[212:215], v[64:67]
	s_barrier
	v_readfirstlane_b32 s43, v148
	v_lshl_add_u64 v[164:165], v[236:237], 0, s[18:19]
	s_mov_b32 m0, s43
	ds_read_b128 v[188:191], v152 offset:16384
	ds_read_b128 v[192:195], v152 offset:17408
	ds_read_b128 v[196:199], v151 offset:16384
	ds_read_b128 v[200:203], v151 offset:17408
	ds_read_b128 v[204:207], v150 offset:16384
	ds_read_b128 v[208:211], v150 offset:17408
	ds_read_b128 v[212:215], v149 offset:16384
	ds_read_b128 v[232:235], v149 offset:17408
	global_load_lds_dwordx4 v[164:165], off
	v_add_u32_e32 v164, 0x2000, v148
	v_lshl_add_u64 v[166:167], v[238:239], 0, s[18:19]
	v_readfirstlane_b32 s43, v164
	s_mov_b32 m0, s43
	s_nop 0
	global_load_lds_dwordx4 v[166:167], off
	s_barrier
	s_waitcnt lgkmcnt(0)
	s_waitcnt lgkmcnt(0)
	v_mfma_f32_16x16x32_bf16 v[60:63], v[172:175], v[188:191], v[60:63]
	v_mfma_f32_16x16x32_bf16 v[56:59], v[180:183], v[188:191], v[56:59]
	v_mfma_f32_16x16x32_bf16 v[52:55], v[172:175], v[196:199], v[52:55]
	v_mfma_f32_16x16x32_bf16 v[48:51], v[180:183], v[196:199], v[48:51]
	v_mfma_f32_16x16x32_bf16 v[44:47], v[172:175], v[204:207], v[44:47]
	v_mfma_f32_16x16x32_bf16 v[40:43], v[180:183], v[204:207], v[40:43]
	v_mfma_f32_16x16x32_bf16 v[36:39], v[172:175], v[212:215], v[36:39]
	v_mfma_f32_16x16x32_bf16 v[32:35], v[180:183], v[212:215], v[32:35]
	v_mfma_f32_16x16x32_bf16 v[60:63], v[176:179], v[192:195], v[60:63]
	v_mfma_f32_16x16x32_bf16 v[56:59], v[184:187], v[192:195], v[56:59]
	v_mfma_f32_16x16x32_bf16 v[52:55], v[176:179], v[200:203], v[52:55]
	v_mfma_f32_16x16x32_bf16 v[48:51], v[184:187], v[200:203], v[48:51]
	v_mfma_f32_16x16x32_bf16 v[44:47], v[176:179], v[208:211], v[44:47]
	v_mfma_f32_16x16x32_bf16 v[40:43], v[184:187], v[208:211], v[40:43]
	v_mfma_f32_16x16x32_bf16 v[36:39], v[176:179], v[232:235], v[36:39]
	v_mfma_f32_16x16x32_bf16 v[32:35], v[184:187], v[232:235], v[32:35]
	s_barrier
; #define STAGE(P, BASE, LD, br, kt) do { const char* _g = (const char*)((BASE) + (size_t)(br) * (LD) + (size_t)(kt) * 64); \
;     for (int _i = 0; _i < 2; ++_i) { int _b = tidx * 16 + _i * 8192; int _r, _c; stage_rc(_b, _r, _c); \
;       __builtin_amdgcn_global_load_lds((const unsigned*)(_g + (unsigned)((_r * (LD) + _c) * 2)), (unsigned*)((char*)(P) + _b), 16, 0, 0); } } while (0)
; #define LDA(dst, b, h) for (int m = 0; m < 4; ++m) for (int k = 0; k < 2; ++k) \
;     dst[m][k] = *reinterpret_cast<const bf16x8*>((char*)SA(b, h) + lds_byte(wr * 64 + m * 16 + fr, k * 32 + fq * 8))
; #define LDB(dst, b, h) for (int n = 0; n < 2; ++n) for (int k = 0; k < 2; ++k) \
;     dst[n][k] = *reinterpret_cast<const bf16x8*>((char*)SB(b, h) + lds_byte(wc * 32 + n * 16 + fr, k * 32 + fq * 8))
; #define MMA(ai, bj, At_, Bt_) do { __builtin_amdgcn_s_setprio(1); \
;     for (int k = 0; k < 2; ++k) for (int m = 0; m < 4; ++m) for (int n = 0; n < 2; ++n) \
;       acc[ai][bj][m][n] = __builtin_amdgcn_mfma_f32_16x16x32_bf16(At_[m][k], Bt_[n][k], acc[ai][bj][m][n], 0, 0, 0); \
;     __builtin_amdgcn_s_setprio(0); } while (0)
; #define WAIT_V(n) asm volatile("s_waitcnt vmcnt(" #n ")" ::: "memory")
; #define WAIT_L(n) asm volatile("s_waitcnt lgkmcnt(" #n ")" ::: "memory")
; #define BAR __builtin_amdgcn_s_barrier()
; #define SCHED __builtin_amdgcn_sched_barrier(0)
; template <int EPI, int lda, int ldb, int N, int K>
; __device__ __forceinline__ void gemm_phase(const u16* __restrict__ A, const u16* __restrict__ Bt, const GemmEpi ep, int wv) {
;     ...
;       STAGE(SB(0, 1), Bt, ldb, bcol + HALF, t + 2);
;       WAIT_V(6); BAR; MMA(1, 1, At, B1); BAR;
;       LDB(B0, 1, 0); SCHED; LDA(At, 1, 0); STAGE(SA(0, 1), Ab, lda, brow + HALF, t + 2);
;       WAIT_L(8); BAR; WAIT_L(0); MMA(0, 0, At, B0); BAR; SCHED;
;       LDB(B1, 1, 1); STAGE(SB(1, 0), Bt, ldb, bcol, t + 3);
;       BAR; WAIT_L(0); MMA(0, 1, At, B1); BAR;
;       LDA(At, 1, 1); STAGE(SA(1, 0), Ab, lda, brow, t + 3);
	v_add_u32_e32 v165, s53, v153
	v_lshl_add_u64 v[166:167], v[240:241], 0, s[20:21]
	v_readfirstlane_b32 s43, v165
	s_mov_b32 m0, s43
	v_lshl_add_u64 v[172:173], v[242:243], 0, s[20:21]
	global_load_lds_dwordx4 v[166:167], off
	v_add_u32_e32 v166, 0x2000, v165
	s_nop 0
	v_readfirstlane_b32 s43, v166
	s_mov_b32 m0, s43
	s_nop 0
	global_load_lds_dwordx4 v[172:173], off
	s_waitcnt vmcnt(6)
	s_barrier
	v_mfma_f32_16x16x32_bf16 v[28:31], v[216:219], v[188:191], v[28:31]
	v_mfma_f32_16x16x32_bf16 v[24:27], v[224:227], v[188:191], v[24:27]
	v_mfma_f32_16x16x32_bf16 v[20:23], v[216:219], v[196:199], v[20:23]
	v_mfma_f32_16x16x32_bf16 v[16:19], v[224:227], v[196:199], v[16:19]
	v_mfma_f32_16x16x32_bf16 v[12:15], v[216:219], v[204:207], v[12:15]
	v_mfma_f32_16x16x32_bf16 v[8:11], v[224:227], v[204:207], v[8:11]
	v_mfma_f32_16x16x32_bf16 v[4:7], v[216:219], v[212:215], v[4:7]
	v_mfma_f32_16x16x32_bf16 v[0:3], v[224:227], v[212:215], v[0:3]
	v_mfma_f32_16x16x32_bf16 v[28:31], v[220:223], v[192:195], v[28:31]
	v_mfma_f32_16x16x32_bf16 v[24:27], v[228:231], v[192:195], v[24:27]
	v_mfma_f32_16x16x32_bf16 v[20:23], v[220:223], v[200:203], v[20:23]
	v_mfma_f32_16x16x32_bf16 v[16:19], v[228:231], v[200:203], v[16:19]
	v_mfma_f32_16x16x32_bf16 v[12:15], v[220:223], v[208:211], v[12:15]
	v_mfma_f32_16x16x32_bf16 v[8:11], v[228:231], v[208:211], v[8:11]
	v_mfma_f32_16x16x32_bf16 v[4:7], v[220:223], v[232:235], v[4:7]
	v_mfma_f32_16x16x32_bf16 v[0:3], v[228:231], v[232:235], v[0:3]
	s_barrier
	ds_read_b128 v[172:175], v156
	ds_read_b128 v[176:179], v156 offset:1024
	ds_read_b128 v[180:183], v156 offset:2048
	ds_read_b128 v[184:187], v156 offset:3072
	v_add_u32_e32 v167, 0x4000, v148
	v_add_u32_e32 v168, 0x6000, v148
	v_readfirstlane_b32 s43, v167
	v_lshl_add_u64 v[220:221], v[236:237], 0, s[22:23]
	s_mov_b32 m0, s43
	v_readfirstlane_b32 s43, v168
	ds_read_b128 v[188:191], v152 offset:32768
	ds_read_b128 v[192:195], v152 offset:33792
	ds_read_b128 v[196:199], v151 offset:32768
	ds_read_b128 v[200:203], v151 offset:33792
	ds_read_b128 v[204:207], v150 offset:32768
	ds_read_b128 v[208:211], v150 offset:33792
	ds_read_b128 v[212:215], v149 offset:32768
	ds_read_b128 v[216:219], v149 offset:33792
	global_load_lds_dwordx4 v[220:221], off
	v_lshl_add_u64 v[220:221], v[238:239], 0, s[22:23]
	s_mov_b32 m0, s43
	s_nop 0
	global_load_lds_dwordx4 v[220:221], off
	s_waitcnt lgkmcnt(8)
	s_barrier
	s_waitcnt lgkmcnt(0)
	s_waitcnt lgkmcnt(0)
	v_mfma_f32_16x16x32_bf16 v[124:127], v[172:175], v[188:191], v[124:127]
	v_mfma_f32_16x16x32_bf16 v[120:123], v[180:183], v[188:191], v[120:123]
	v_mfma_f32_16x16x32_bf16 v[116:119], v[172:175], v[196:199], v[116:119]
	v_mfma_f32_16x16x32_bf16 v[112:115], v[180:183], v[196:199], v[112:115]
	v_mfma_f32_16x16x32_bf16 v[108:111], v[172:175], v[204:207], v[108:111]
	v_mfma_f32_16x16x32_bf16 v[104:107], v[180:183], v[204:207], v[104:107]
	v_mfma_f32_16x16x32_bf16 v[100:103], v[172:175], v[212:215], v[100:103]
	v_mfma_f32_16x16x32_bf16 v[96:99], v[180:183], v[212:215], v[96:99]
	v_mfma_f32_16x16x32_bf16 v[124:127], v[176:179], v[192:195], v[124:127]
	v_mfma_f32_16x16x32_bf16 v[120:123], v[184:187], v[192:195], v[120:123]
	v_mfma_f32_16x16x32_bf16 v[116:119], v[176:179], v[200:203], v[116:119]
	v_mfma_f32_16x16x32_bf16 v[112:115], v[184:187], v[200:203], v[112:115]
	v_mfma_f32_16x16x32_bf16 v[108:111], v[176:179], v[208:211], v[108:111]
	v_mfma_f32_16x16x32_bf16 v[104:107], v[184:187], v[208:211], v[104:107]
	v_mfma_f32_16x16x32_bf16 v[100:103], v[176:179], v[216:219], v[100:103]
	v_mfma_f32_16x16x32_bf16 v[96:99], v[184:187], v[216:219], v[96:99]
	s_barrier
	v_readfirstlane_b32 s43, v155
	v_add_u32_e32 v171, 0x2000, v155
	v_lshl_add_u64 v[244:245], v[240:241], 0, s[24:25]
	s_mov_b32 m0, s43
	v_readfirstlane_b32 s43, v171
	ds_read_b128 v[220:223], v154
	ds_read_b128 v[224:227], v154 offset:1024
	ds_read_b128 v[228:231], v154 offset:2048
	ds_read_b128 v[232:235], v154 offset:3072
	global_load_lds_dwordx4 v[244:245], off
	v_lshl_add_u64 v[244:245], v[242:243], 0, s[24:25]
	s_mov_b32 m0, s43
	s_nop 0
	global_load_lds_dwordx4 v[244:245], off
	s_barrier
	s_waitcnt lgkmcnt(0)
	s_waitcnt lgkmcnt(0)
	v_mfma_f32_16x16x32_bf16 v[92:95], v[220:223], v[188:191], v[92:95]
	v_mfma_f32_16x16x32_bf16 v[88:91], v[228:231], v[188:191], v[88:91]
	v_mfma_f32_16x16x32_bf16 v[84:87], v[220:223], v[196:199], v[84:87]
	v_mfma_f32_16x16x32_bf16 v[80:83], v[228:231], v[196:199], v[80:83]
	v_mfma_f32_16x16x32_bf16 v[76:79], v[220:223], v[204:207], v[76:79]
	v_mfma_f32_16x16x32_bf16 v[72:75], v[228:231], v[204:207], v[72:75]
	v_mfma_f32_16x16x32_bf16 v[68:71], v[220:223], v[212:215], v[68:71]
	v_mfma_f32_16x16x32_bf16 v[64:67], v[228:231], v[212:215], v[64:67]
	v_mfma_f32_16x16x32_bf16 v[92:95], v[224:227], v[192:195], v[92:95]
	v_mfma_f32_16x16x32_bf16 v[88:91], v[232:235], v[192:195], v[88:91]
	v_mfma_f32_16x16x32_bf16 v[84:87], v[224:227], v[200:203], v[84:87]
	v_mfma_f32_16x16x32_bf16 v[80:83], v[232:235], v[200:203], v[80:83]
	v_mfma_f32_16x16x32_bf16 v[76:79], v[224:227], v[208:211], v[76:79]
	v_mfma_f32_16x16x32_bf16 v[72:75], v[232:235], v[208:211], v[72:75]
	v_mfma_f32_16x16x32_bf16 v[68:71], v[224:227], v[216:219], v[68:71]
	v_mfma_f32_16x16x32_bf16 v[64:67], v[232:235], v[216:219], v[64:67]
	s_barrier
	v_readfirstlane_b32 s43, v157
	v_lshl_add_u64 v[236:237], v[236:237], 0, s[26:27]
	s_mov_b32 m0, s43
	v_readfirstlane_b32 s43, v158
	ds_read_b128 v[188:191], v152 offset:49152
	ds_read_b128 v[192:195], v152 offset:50176
	ds_read_b128 v[196:199], v151 offset:49152
	ds_read_b128 v[200:203], v151 offset:50176
	ds_read_b128 v[204:207], v150 offset:49152
	ds_read_b128 v[208:211], v150 offset:50176
	ds_read_b128 v[212:215], v149 offset:49152
	ds_read_b128 v[216:219], v149 offset:50176
	global_load_lds_dwordx4 v[236:237], off
	v_lshl_add_u64 v[236:237], v[238:239], 0, s[26:27]
	s_mov_b32 m0, s43
	s_nop 0
	global_load_lds_dwordx4 v[236:237], off
	s_barrier
; #define STAGE(P, BASE, LD, br, kt) do { const char* _g = (const char*)((BASE) + (size_t)(br) * (LD) + (size_t)(kt) * 64); \
;     for (int _i = 0; _i < 2; ++_i) { int _b = tidx * 16 + _i * 8192; int _r, _c; stage_rc(_b, _r, _c); \
;       __builtin_amdgcn_global_load_lds((const unsigned*)(_g + (unsigned)((_r * (LD) + _c) * 2)), (unsigned*)((char*)(P) + _b), 16, 0, 0); } } while (0)
; #define LDA(dst, b, h) for (int m = 0; m < 4; ++m) for (int k = 0; k < 2; ++k) \
;     dst[m][k] = *reinterpret_cast<const bf16x8*>((char*)SA(b, h) + lds_byte(wr * 64 + m * 16 + fr, k * 32 + fq * 8))
; #define LDB(dst, b, h) for (int n = 0; n < 2; ++n) for (int k = 0; k < 2; ++k) \
;     dst[n][k] = *reinterpret_cast<const bf16x8*>((char*)SB(b, h) + lds_byte(wc * 32 + n * 16 + fr, k * 32 + fq * 8))
; #define MMA(ai, bj, At_, Bt_) do { __builtin_amdgcn_s_setprio(1); \
;     for (int k = 0; k < 2; ++k) for (int m = 0; m < 4; ++m) for (int n = 0; n < 2; ++n) \
;       acc[ai][bj][m][n] = __builtin_amdgcn_mfma_f32_16x16x32_bf16(At_[m][k], Bt_[n][k], acc[ai][bj][m][n], 0, 0, 0); \
;     __builtin_amdgcn_s_setprio(0); } while (0)
; #define WAIT_V(n) asm volatile("s_waitcnt vmcnt(" #n ")" ::: "memory")
; #define WAIT_L(n) asm volatile("s_waitcnt lgkmcnt(" #n ")" ::: "memory")
; #define BAR __builtin_amdgcn_s_barrier()
; #define SCHED __builtin_amdgcn_sched_barrier(0)
; template <int EPI, int lda, int ldb, int N, int K>
; __device__ __forceinline__ void gemm_phase(const u16* __restrict__ A, const u16* __restrict__ Bt, const GemmEpi ep, int wv) {
;     ...
;       BAR; WAIT_L(0); MMA(1, 0, At, B0); BAR; SCHED;
;       STAGE(SB(1, 1), Bt, ldb, bcol + HALF, t + 3);
;       WAIT_V(6); BAR; MMA(1, 1, At, B1); BAR;
;     }
;     { LDB(B0, 0, 0); LDA(At, 0, 0); STAGE(SA(1, 1), Ab, lda, brow + HALF, nt - 1);
;       BAR; WAIT_L(0); MMA(0, 0, At, B0); BAR;
;       LDB(B1, 0, 1); BAR; WAIT_L(0); MMA(0, 1, At, B1); BAR;
	s_waitcnt lgkmcnt(0)
	s_waitcnt lgkmcnt(0)
	v_mfma_f32_16x16x32_bf16 v[60:63], v[172:175], v[188:191], v[60:63]
	v_mfma_f32_16x16x32_bf16 v[56:59], v[180:183], v[188:191], v[56:59]
	v_mfma_f32_16x16x32_bf16 v[52:55], v[172:175], v[196:199], v[52:55]
	v_mfma_f32_16x16x32_bf16 v[48:51], v[180:183], v[196:199], v[48:51]
	v_mfma_f32_16x16x32_bf16 v[44:47], v[172:175], v[204:207], v[44:47]
	v_mfma_f32_16x16x32_bf16 v[40:43], v[180:183], v[204:207], v[40:43]
	v_mfma_f32_16x16x32_bf16 v[36:39], v[172:175], v[212:215], v[36:39]
	v_mfma_f32_16x16x32_bf16 v[32:35], v[180:183], v[212:215], v[32:35]
	v_mfma_f32_16x16x32_bf16 v[60:63], v[176:179], v[192:195], v[60:63]
	v_mfma_f32_16x16x32_bf16 v[56:59], v[184:187], v[192:195], v[56:59]
	v_mfma_f32_16x16x32_bf16 v[52:55], v[176:179], v[200:203], v[52:55]
	v_mfma_f32_16x16x32_bf16 v[48:51], v[184:187], v[200:203], v[48:51]
	v_mfma_f32_16x16x32_bf16 v[44:47], v[176:179], v[208:211], v[44:47]
	v_mfma_f32_16x16x32_bf16 v[40:43], v[184:187], v[208:211], v[40:43]
	v_mfma_f32_16x16x32_bf16 v[36:39], v[176:179], v[216:219], v[36:39]
	v_mfma_f32_16x16x32_bf16 v[32:35], v[184:187], v[216:219], v[32:35]
	s_barrier
	v_readfirstlane_b32 s43, v159
	v_add_u32_e32 v171, 0x2000, v159
	v_lshl_add_u64 v[172:173], v[240:241], 0, s[34:35]
	s_mov_b32 m0, s43
	v_readfirstlane_b32 s43, v171
	global_load_lds_dwordx4 v[172:173], off
	v_lshl_add_u64 v[172:173], v[242:243], 0, s[34:35]
	s_mov_b32 m0, s43
	s_nop 0
	global_load_lds_dwordx4 v[172:173], off
	s_waitcnt vmcnt(6)
	s_barrier
	v_mfma_f32_16x16x32_bf16 v[28:31], v[220:223], v[188:191], v[28:31]
	v_mfma_f32_16x16x32_bf16 v[24:27], v[228:231], v[188:191], v[24:27]
	v_mfma_f32_16x16x32_bf16 v[20:23], v[220:223], v[196:199], v[20:23]
	v_mfma_f32_16x16x32_bf16 v[16:19], v[228:231], v[196:199], v[16:19]
	v_mfma_f32_16x16x32_bf16 v[12:15], v[220:223], v[204:207], v[12:15]
	v_mfma_f32_16x16x32_bf16 v[8:11], v[228:231], v[204:207], v[8:11]
	v_mfma_f32_16x16x32_bf16 v[4:7], v[220:223], v[212:215], v[4:7]
	v_mfma_f32_16x16x32_bf16 v[0:3], v[228:231], v[212:215], v[0:3]
	v_mfma_f32_16x16x32_bf16 v[28:31], v[224:227], v[192:195], v[28:31]
	v_mfma_f32_16x16x32_bf16 v[24:27], v[232:235], v[192:195], v[24:27]
	v_mfma_f32_16x16x32_bf16 v[20:23], v[224:227], v[200:203], v[20:23]
	v_mfma_f32_16x16x32_bf16 v[16:19], v[232:235], v[200:203], v[16:19]
	v_mfma_f32_16x16x32_bf16 v[12:15], v[224:227], v[208:211], v[12:15]
	v_mfma_f32_16x16x32_bf16 v[8:11], v[232:235], v[208:211], v[8:11]
	v_mfma_f32_16x16x32_bf16 v[4:7], v[224:227], v[216:219], v[4:7]
	v_mfma_f32_16x16x32_bf16 v[0:3], v[232:235], v[216:219], v[0:3]
	s_barrier
	s_add_i32 s42, s42, 2
	s_add_u32 s40, s40, 0x100
	s_addc_u32 s41, s41, 0
	s_cmp_gt_u32 s42, 27
	s_cbranch_scc0 .LBB0_1564
	s_add_i32 s40, s38, 0x80
	s_mul_hi_i32 s41, s40, 0x1080
	s_mulk_i32 s40, 0x1080
	s_add_u32 s40, s49, s40
	s_addc_u32 s41, s50, s41
	v_lshl_add_u64 v[158:159], s[40:41], 0, v[128:129]
	v_readfirstlane_b32 s42, v169
	v_lshl_add_u64 v[158:159], v[158:159], 0, s[36:37]
	s_mov_b32 m0, s42
	ds_read_b128 v[134:137], v161
	ds_read_b128 v[138:141], v161 offset:1024
	ds_read_b128 v[172:175], v161 offset:2048
	ds_read_b128 v[176:179], v161 offset:3072
	ds_read_b128 v[180:183], v152
	ds_read_b128 v[184:187], v152 offset:1024
	ds_read_b128 v[188:191], v151
	ds_read_b128 v[192:195], v151 offset:1024
	ds_read_b128 v[196:199], v150
	ds_read_b128 v[200:203], v150 offset:1024
	ds_read_b128 v[204:207], v149
	ds_read_b128 v[208:211], v149 offset:1024
	global_load_lds_dwordx4 v[158:159], off
	v_lshl_add_u64 v[158:159], s[40:41], 0, v[132:133]
	v_readfirstlane_b32 s40, v170
	v_lshl_add_u64 v[158:159], v[158:159], 0, s[36:37]
	s_mov_b32 m0, s40
	s_nop 0
	global_load_lds_dwordx4 v[158:159], off
	s_barrier
	s_waitcnt lgkmcnt(0)
	s_waitcnt lgkmcnt(0)
	v_mfma_f32_16x16x32_bf16 v[124:127], v[134:137], v[180:183], v[124:127]
	v_mfma_f32_16x16x32_bf16 v[120:123], v[172:175], v[180:183], v[120:123]
	v_mfma_f32_16x16x32_bf16 v[116:119], v[134:137], v[188:191], v[116:119]
	v_mfma_f32_16x16x32_bf16 v[112:115], v[172:175], v[188:191], v[112:115]
	v_mfma_f32_16x16x32_bf16 v[108:111], v[134:137], v[196:199], v[108:111]
	v_mfma_f32_16x16x32_bf16 v[104:107], v[172:175], v[196:199], v[104:107]
	v_mfma_f32_16x16x32_bf16 v[100:103], v[134:137], v[204:207], v[100:103]
	v_mfma_f32_16x16x32_bf16 v[96:99], v[172:175], v[204:207], v[96:99]
	v_mfma_f32_16x16x32_bf16 v[124:127], v[138:141], v[184:187], v[124:127]
	v_mfma_f32_16x16x32_bf16 v[120:123], v[176:179], v[184:187], v[120:123]
	v_mfma_f32_16x16x32_bf16 v[116:119], v[138:141], v[192:195], v[116:119]
	v_mfma_f32_16x16x32_bf16 v[112:115], v[176:179], v[192:195], v[112:115]
	v_mfma_f32_16x16x32_bf16 v[108:111], v[138:141], v[200:203], v[108:111]
	v_mfma_f32_16x16x32_bf16 v[104:107], v[176:179], v[200:203], v[104:107]
	v_mfma_f32_16x16x32_bf16 v[100:103], v[138:141], v[208:211], v[100:103]
	v_mfma_f32_16x16x32_bf16 v[96:99], v[176:179], v[208:211], v[96:99]
	s_barrier
	ds_read_b128 v[212:215], v160
	ds_read_b128 v[216:219], v160 offset:1024
	ds_read_b128 v[220:223], v160 offset:2048
	ds_read_b128 v[158:161], v160 offset:3072
	s_barrier
; #define LDA(dst, b, h) for (int m = 0; m < 4; ++m) for (int k = 0; k < 2; ++k) \
;     dst[m][k] = *reinterpret_cast<const bf16x8*>((char*)SA(b, h) + lds_byte(wr * 64 + m * 16 + fr, k * 32 + fq * 8))
; #define LDB(dst, b, h) for (int n = 0; n < 2; ++n) for (int k = 0; k < 2; ++k) \
;     dst[n][k] = *reinterpret_cast<const bf16x8*>((char*)SB(b, h) + lds_byte(wc * 32 + n * 16 + fr, k * 32 + fq * 8))
; #define MMA(ai, bj, At_, Bt_) do { __builtin_amdgcn_s_setprio(1); \
;     for (int k = 0; k < 2; ++k) for (int m = 0; m < 4; ++m) for (int n = 0; n < 2; ++n) \
;       acc[ai][bj][m][n] = __builtin_amdgcn_mfma_f32_16x16x32_bf16(At_[m][k], Bt_[n][k], acc[ai][bj][m][n], 0, 0, 0); \
;     __builtin_amdgcn_s_setprio(0); } while (0)
; #define WAIT_V(n) asm volatile("s_waitcnt vmcnt(" #n ")" ::: "memory")
; #define WAIT_L(n) asm volatile("s_waitcnt lgkmcnt(" #n ")" ::: "memory")
; #define BAR __builtin_amdgcn_s_barrier()
; template <int EPI, int lda, int ldb, int N, int K>
; __device__ __forceinline__ void gemm_phase(const u16* __restrict__ A, const u16* __restrict__ Bt, const GemmEpi ep, int wv) {
;     ...
;       LDB(B1, 0, 1); BAR; WAIT_L(0); MMA(0, 1, At, B1); BAR;
;       LDA(At, 0, 1); WAIT_V(4); BAR; WAIT_L(0); MMA(1, 0, At, B0); MMA(1, 1, At, B1); BAR; }
;     { LDB(B0, 1, 0); LDA(At, 1, 0); WAIT_V(2); BAR; WAIT_L(0); MMA(0, 0, At, B0); BAR;
	s_waitcnt lgkmcnt(0)
	s_waitcnt lgkmcnt(0)
	v_mfma_f32_16x16x32_bf16 v[92:95], v[212:215], v[180:183], v[92:95]
	v_mfma_f32_16x16x32_bf16 v[88:91], v[220:223], v[180:183], v[88:91]
	v_mfma_f32_16x16x32_bf16 v[76:79], v[212:215], v[196:199], v[76:79]
	v_mfma_f32_16x16x32_bf16 v[72:75], v[220:223], v[196:199], v[72:75]
	v_mfma_f32_16x16x32_bf16 v[84:87], v[212:215], v[188:191], v[84:87]
	v_mfma_f32_16x16x32_bf16 v[80:83], v[220:223], v[188:191], v[80:83]
	v_mfma_f32_16x16x32_bf16 v[68:71], v[212:215], v[204:207], v[68:71]
	v_mfma_f32_16x16x32_bf16 v[64:67], v[220:223], v[204:207], v[64:67]
	v_mfma_f32_16x16x32_bf16 v[92:95], v[216:219], v[184:187], v[92:95]
	v_mfma_f32_16x16x32_bf16 v[88:91], v[158:161], v[184:187], v[88:91]
	v_mfma_f32_16x16x32_bf16 v[76:79], v[216:219], v[200:203], v[76:79]
	v_mfma_f32_16x16x32_bf16 v[72:75], v[158:161], v[200:203], v[72:75]
	v_mfma_f32_16x16x32_bf16 v[180:183], v[216:219], v[192:195], v[84:87]
	v_mfma_f32_16x16x32_bf16 v[184:187], v[158:161], v[192:195], v[80:83]
	v_mfma_f32_16x16x32_bf16 v[188:191], v[216:219], v[208:211], v[68:71]
	v_mfma_f32_16x16x32_bf16 v[192:195], v[158:161], v[208:211], v[64:67]
	s_barrier
	s_nop 0
	ds_read_b128 v[64:67], v152 offset:16384
	ds_read_b128 v[68:71], v152 offset:17408
	ds_read_b128 v[80:83], v151 offset:16384
	ds_read_b128 v[84:87], v151 offset:17408
	ds_read_b128 v[196:199], v150 offset:16384
	ds_read_b128 v[200:203], v150 offset:17408
	ds_read_b128 v[204:207], v149 offset:16384
	ds_read_b128 v[208:211], v149 offset:17408
	s_waitcnt vmcnt(4)
	s_barrier
	s_waitcnt lgkmcnt(0)
	s_waitcnt lgkmcnt(0)
	v_mfma_f32_16x16x32_bf16 v[60:63], v[134:137], v[64:67], v[60:63]
	v_mfma_f32_16x16x32_bf16 v[56:59], v[172:175], v[64:67], v[56:59]
	v_mfma_f32_16x16x32_bf16 v[52:55], v[134:137], v[80:83], v[52:55]
	v_mfma_f32_16x16x32_bf16 v[48:51], v[172:175], v[80:83], v[48:51]
	v_mfma_f32_16x16x32_bf16 v[44:47], v[134:137], v[196:199], v[44:47]
	v_mfma_f32_16x16x32_bf16 v[40:43], v[172:175], v[196:199], v[40:43]
	v_mfma_f32_16x16x32_bf16 v[36:39], v[134:137], v[204:207], v[36:39]
	v_mfma_f32_16x16x32_bf16 v[32:35], v[172:175], v[204:207], v[32:35]
	v_mfma_f32_16x16x32_bf16 v[60:63], v[138:141], v[68:71], v[60:63]
	v_mfma_f32_16x16x32_bf16 v[56:59], v[176:179], v[68:71], v[56:59]
	v_mfma_f32_16x16x32_bf16 v[52:55], v[138:141], v[84:87], v[52:55]
	v_mfma_f32_16x16x32_bf16 v[48:51], v[176:179], v[84:87], v[48:51]
	v_mfma_f32_16x16x32_bf16 v[44:47], v[138:141], v[200:203], v[44:47]
	v_mfma_f32_16x16x32_bf16 v[40:43], v[176:179], v[200:203], v[40:43]
	v_mfma_f32_16x16x32_bf16 v[36:39], v[138:141], v[208:211], v[36:39]
	v_mfma_f32_16x16x32_bf16 v[32:35], v[176:179], v[208:211], v[32:35]
	v_mfma_f32_16x16x32_bf16 v[28:31], v[212:215], v[64:67], v[28:31]
	v_mfma_f32_16x16x32_bf16 v[24:27], v[220:223], v[64:67], v[24:27]
	v_mfma_f32_16x16x32_bf16 v[12:15], v[212:215], v[196:199], v[12:15]
	v_mfma_f32_16x16x32_bf16 v[8:11], v[220:223], v[196:199], v[8:11]
	v_mfma_f32_16x16x32_bf16 v[20:23], v[212:215], v[80:83], v[20:23]
	v_mfma_f32_16x16x32_bf16 v[16:19], v[220:223], v[80:83], v[16:19]
	v_mfma_f32_16x16x32_bf16 v[4:7], v[212:215], v[204:207], v[4:7]
	v_mfma_f32_16x16x32_bf16 v[0:3], v[220:223], v[204:207], v[0:3]
	v_mfma_f32_16x16x32_bf16 v[28:31], v[216:219], v[68:71], v[28:31]
	v_mfma_f32_16x16x32_bf16 v[24:27], v[158:161], v[68:71], v[24:27]
	v_mfma_f32_16x16x32_bf16 v[12:15], v[216:219], v[200:203], v[12:15]
	v_mfma_f32_16x16x32_bf16 v[8:11], v[158:161], v[200:203], v[8:11]
	v_mfma_f32_16x16x32_bf16 v[134:137], v[216:219], v[84:87], v[20:23]
	v_mfma_f32_16x16x32_bf16 v[138:141], v[158:161], v[84:87], v[16:19]
	v_mfma_f32_16x16x32_bf16 v[170:173], v[216:219], v[208:211], v[4:7]
	v_mfma_f32_16x16x32_bf16 v[158:161], v[158:161], v[208:211], v[0:3]
	s_barrier
	s_nop 0
	ds_read_b128 v[0:3], v156
	ds_read_b128 v[4:7], v156 offset:1024
	ds_read_b128 v[16:19], v156 offset:2048
	ds_read_b128 v[174:177], v156 offset:3072
	ds_read_b128 v[20:23], v152 offset:32768
	ds_read_b128 v[196:199], v152 offset:33792
	ds_read_b128 v[200:203], v151 offset:32768
	ds_read_b128 v[204:207], v151 offset:33792
	ds_read_b128 v[208:211], v150 offset:32768
	ds_read_b128 v[212:215], v150 offset:33792
	ds_read_b128 v[216:219], v149 offset:32768
	ds_read_b128 v[220:223], v149 offset:33792
	s_waitcnt vmcnt(2)
	s_barrier
; #define LDA(dst, b, h) for (int m = 0; m < 4; ++m) for (int k = 0; k < 2; ++k) \
;     dst[m][k] = *reinterpret_cast<const bf16x8*>((char*)SA(b, h) + lds_byte(wr * 64 + m * 16 + fr, k * 32 + fq * 8))
; #define LDB(dst, b, h) for (int n = 0; n < 2; ++n) for (int k = 0; k < 2; ++k) \
;     dst[n][k] = *reinterpret_cast<const bf16x8*>((char*)SB(b, h) + lds_byte(wc * 32 + n * 16 + fr, k * 32 + fq * 8))
; #define MMA(ai, bj, At_, Bt_) do { __builtin_amdgcn_s_setprio(1); \
;     for (int k = 0; k < 2; ++k) for (int m = 0; m < 4; ++m) for (int n = 0; n < 2; ++n) \
;       acc[ai][bj][m][n] = __builtin_amdgcn_mfma_f32_16x16x32_bf16(At_[m][k], Bt_[n][k], acc[ai][bj][m][n], 0, 0, 0); \
;     __builtin_amdgcn_s_setprio(0); } while (0)
; #define WAIT_V(n) asm volatile("s_waitcnt vmcnt(" #n ")" ::: "memory")
; #define WAIT_L(n) asm volatile("s_waitcnt lgkmcnt(" #n ")" ::: "memory")
; #define BAR __builtin_amdgcn_s_barrier()
; template <int EPI, int lda, int ldb, int N, int K>
; __device__ __forceinline__ void gemm_phase(const u16* __restrict__ A, const u16* __restrict__ Bt, const GemmEpi ep, int wv) {
;     ...
;     { LDB(B0, 1, 0); LDA(At, 1, 0); WAIT_V(2); BAR; WAIT_L(0); MMA(0, 0, At, B0); BAR;
;       LDB(B1, 1, 1); WAIT_V(0); BAR; WAIT_L(0); MMA(0, 1, At, B1); BAR;
;       LDA(At, 1, 1); BAR; WAIT_L(0); MMA(1, 0, At, B0); MMA(1, 1, At, B1); BAR; }
;     if (wr == 0) BAR;
	s_waitcnt lgkmcnt(0)
	s_waitcnt lgkmcnt(0)
	v_mfma_f32_16x16x32_bf16 v[64:67], v[0:3], v[20:23], v[124:127]
	v_mfma_f32_16x16x32_bf16 v[68:71], v[16:19], v[20:23], v[120:123]
	v_mfma_f32_16x16x32_bf16 v[80:83], v[0:3], v[200:203], v[116:119]
	v_mfma_f32_16x16x32_bf16 v[84:87], v[16:19], v[200:203], v[112:115]
	v_mfma_f32_16x16x32_bf16 v[108:111], v[0:3], v[208:211], v[108:111]
	v_mfma_f32_16x16x32_bf16 v[104:107], v[16:19], v[208:211], v[104:107]
	v_mfma_f32_16x16x32_bf16 v[120:123], v[0:3], v[216:219], v[100:103]
	v_mfma_f32_16x16x32_bf16 v[124:127], v[16:19], v[216:219], v[96:99]
	v_mfma_f32_16x16x32_bf16 v[116:119], v[4:7], v[196:199], v[64:67]
	v_mfma_f32_16x16x32_bf16 v[112:115], v[174:177], v[196:199], v[68:71]
	v_mfma_f32_16x16x32_bf16 v[100:103], v[4:7], v[204:207], v[80:83]
	v_mfma_f32_16x16x32_bf16 v[96:99], v[174:177], v[204:207], v[84:87]
	v_mfma_f32_16x16x32_bf16 v[84:87], v[4:7], v[212:215], v[108:111]
	v_mfma_f32_16x16x32_bf16 v[80:83], v[174:177], v[212:215], v[104:107]
	v_mfma_f32_16x16x32_bf16 v[68:71], v[4:7], v[220:223], v[120:123]
	v_mfma_f32_16x16x32_bf16 v[64:67], v[174:177], v[220:223], v[124:127]
	s_barrier
	ds_read_b128 v[224:227], v154
	ds_read_b128 v[228:231], v154 offset:1024
	ds_read_b128 v[232:235], v154 offset:2048
	ds_read_b128 v[154:157], v154 offset:3072
	s_waitcnt vmcnt(0)
	s_barrier
	s_waitcnt lgkmcnt(0)
	s_waitcnt lgkmcnt(0)
	v_mfma_f32_16x16x32_bf16 v[92:95], v[224:227], v[20:23], v[92:95]
	v_mfma_f32_16x16x32_bf16 v[20:23], v[232:235], v[20:23], v[88:91]
	v_mfma_f32_16x16x32_bf16 v[88:91], v[224:227], v[200:203], v[180:183]
	v_mfma_f32_16x16x32_bf16 v[104:107], v[232:235], v[200:203], v[184:187]
	v_mfma_f32_16x16x32_bf16 v[76:79], v[224:227], v[208:211], v[76:79]
	v_mfma_f32_16x16x32_bf16 v[72:75], v[232:235], v[208:211], v[72:75]
	v_mfma_f32_16x16x32_bf16 v[178:181], v[224:227], v[216:219], v[188:191]
	v_mfma_f32_16x16x32_bf16 v[182:185], v[232:235], v[216:219], v[192:195]
	v_mfma_f32_16x16x32_bf16 v[124:127], v[228:231], v[196:199], v[92:95]
	v_mfma_f32_16x16x32_bf16 v[120:123], v[154:157], v[196:199], v[20:23]
	v_mfma_f32_16x16x32_bf16 v[108:111], v[228:231], v[204:207], v[88:91]
	v_mfma_f32_16x16x32_bf16 v[104:107], v[154:157], v[204:207], v[104:107]
	v_mfma_f32_16x16x32_bf16 v[92:95], v[228:231], v[212:215], v[76:79]
	v_mfma_f32_16x16x32_bf16 v[88:91], v[154:157], v[212:215], v[72:75]
	v_mfma_f32_16x16x32_bf16 v[76:79], v[228:231], v[220:223], v[178:181]
	v_mfma_f32_16x16x32_bf16 v[72:75], v[154:157], v[220:223], v[182:185]
	s_barrier
	ds_read_b128 v[178:181], v152 offset:49152
	ds_read_b128 v[182:185], v152 offset:50176
	ds_read_b128 v[186:189], v151 offset:49152
	ds_read_b128 v[190:193], v151 offset:50176
	ds_read_b128 v[194:197], v150 offset:49152
	ds_read_b128 v[150:153], v150 offset:50176
	ds_read_b128 v[198:201], v149 offset:49152
	ds_read_b128 v[202:205], v149 offset:50176
	s_barrier
	s_waitcnt lgkmcnt(0)
	s_waitcnt lgkmcnt(0)
	v_mfma_f32_16x16x32_bf16 v[20:23], v[0:3], v[178:181], v[60:63]
	v_mfma_f32_16x16x32_bf16 v[56:59], v[16:19], v[178:181], v[56:59]
	v_mfma_f32_16x16x32_bf16 v[60:63], v[0:3], v[186:189], v[52:55]
	v_mfma_f32_16x16x32_bf16 v[206:209], v[16:19], v[186:189], v[48:51]
	v_mfma_f32_16x16x32_bf16 v[44:47], v[0:3], v[194:197], v[44:47]
	v_mfma_f32_16x16x32_bf16 v[40:43], v[16:19], v[194:197], v[40:43]
	v_mfma_f32_16x16x32_bf16 v[0:3], v[0:3], v[198:201], v[36:39]
	v_mfma_f32_16x16x32_bf16 v[210:213], v[16:19], v[198:201], v[32:35]
	v_mfma_f32_16x16x32_bf16 v[52:55], v[4:7], v[182:185], v[20:23]
	v_mfma_f32_16x16x32_bf16 v[48:51], v[174:177], v[182:185], v[56:59]
	v_mfma_f32_16x16x32_bf16 v[36:39], v[4:7], v[190:193], v[60:63]
	v_mfma_f32_16x16x32_bf16 v[32:35], v[174:177], v[190:193], v[206:209]
	v_mfma_f32_16x16x32_bf16 v[20:23], v[4:7], v[150:153], v[44:47]
	v_mfma_f32_16x16x32_bf16 v[16:19], v[174:177], v[150:153], v[40:43]
	v_mfma_f32_16x16x32_bf16 v[4:7], v[4:7], v[202:205], v[0:3]
	v_mfma_f32_16x16x32_bf16 v[0:3], v[174:177], v[202:205], v[210:213]
	v_mfma_f32_16x16x32_bf16 v[28:31], v[224:227], v[178:181], v[28:31]
	v_mfma_f32_16x16x32_bf16 v[24:27], v[232:235], v[178:181], v[24:27]
	v_mfma_f32_16x16x32_bf16 v[40:43], v[224:227], v[186:189], v[134:137]
	v_mfma_f32_16x16x32_bf16 v[134:137], v[232:235], v[186:189], v[138:141]
	v_mfma_f32_16x16x32_bf16 v[12:15], v[224:227], v[194:197], v[12:15]
	v_mfma_f32_16x16x32_bf16 v[8:11], v[232:235], v[194:197], v[8:11]
	v_mfma_f32_16x16x32_bf16 v[138:141], v[224:227], v[198:201], v[170:173]
	v_mfma_f32_16x16x32_bf16 v[158:161], v[232:235], v[198:201], v[158:161]
	v_mfma_f32_16x16x32_bf16 v[60:63], v[228:231], v[182:185], v[28:31]
	v_mfma_f32_16x16x32_bf16 v[56:59], v[154:157], v[182:185], v[24:27]
	v_mfma_f32_16x16x32_bf16 v[44:47], v[228:231], v[190:193], v[40:43]
	v_mfma_f32_16x16x32_bf16 v[40:43], v[154:157], v[190:193], v[134:137]
	v_mfma_f32_16x16x32_bf16 v[28:31], v[228:231], v[150:153], v[12:15]
	v_mfma_f32_16x16x32_bf16 v[24:27], v[154:157], v[150:153], v[8:11]
	v_mfma_f32_16x16x32_bf16 v[12:15], v[228:231], v[202:205], v[138:141]
	v_mfma_f32_16x16x32_bf16 v[8:11], v[154:157], v[202:205], v[158:161]
	v_cmp_gt_u32_e32 vcc, s54, v130
	s_barrier
	s_and_saveexec_b64 s[40:41], vcc
	s_cbranch_execz .LBB0_1567
	s_barrier

; #define STAGE(P, BASE, LD, br, kt) do { const char* _g = (const char*)((BASE) + (size_t)(br) * (LD) + (size_t)(kt) * 64); \
;     for (int _i = 0; _i < 2; ++_i) { int _b = tidx * 16 + _i * 8192; int _r, _c; stage_rc(_b, _r, _c); \
;       __builtin_amdgcn_global_load_lds((const unsigned*)(_g + (unsigned)((_r * (LD) + _c) * 2)), (unsigned*)((char*)(P) + _b), 16, 0, 0); } } while (0)
; #define LDA(dst, b, h) for (int m = 0; m < 4; ++m) for (int k = 0; k < 2; ++k) \
;     dst[m][k] = *reinterpret_cast<const bf16x8*>((char*)SA(b, h) + lds_byte(wr * 64 + m * 16 + fr, k * 32 + fq * 8))
; #define LDB(dst, b, h) for (int n = 0; n < 2; ++n) for (int k = 0; k < 2; ++k) \
;     dst[n][k] = *reinterpret_cast<const bf16x8*>((char*)SB(b, h) + lds_byte(wc * 32 + n * 16 + fr, k * 32 + fq * 8))
; #define MMA(ai, bj, At_, Bt_) do { __builtin_amdgcn_s_setprio(1); \
;     for (int k = 0; k < 2; ++k) for (int m = 0; m < 4; ++m) for (int n = 0; n < 2; ++n) \
;       acc[ai][bj][m][n] = __builtin_amdgcn_mfma_f32_16x16x32_bf16(At_[m][k], Bt_[n][k], acc[ai][bj][m][n], 0, 0, 0); \
;     __builtin_amdgcn_s_setprio(0); } while (0)
; #define WAIT_L(n) asm volatile("s_waitcnt lgkmcnt(" #n ")" ::: "memory")
; #define BAR __builtin_amdgcn_s_barrier()
; #define SCHED __builtin_amdgcn_sched_barrier(0)
; template <int EPI, int lda, int ldb, int N, int K>
; __device__ __forceinline__ void gemm_phase(const u16* __restrict__ A, const u16* __restrict__ Bt, const GemmEpi ep, int wv) {
;     ...
;       LDB(B0, 0, 0); SCHED; LDA(At, 0, 0); STAGE(SA(1, 1), Ab, lda, brow + HALF, t + 1);
;       WAIT_L(8); BAR; WAIT_L(0); MMA(0, 0, At, B0); BAR; SCHED;
;       LDB(B1, 0, 1); STAGE(SB(0, 0), Bt, ldb, bcol, t + 2);
;       BAR; WAIT_L(0); MMA(0, 1, At, B1); BAR;
;       LDA(At, 0, 1); STAGE(SA(0, 0), Ab, lda, brow, t + 2);
;       BAR; WAIT_L(0); MMA(1, 0, At, B0); BAR; SCHED;
.LBB0_1624:
	ds_read_b128 v[174:177], v163
	ds_read_b128 v[178:181], v163 offset:1024
	ds_read_b128 v[182:185], v163 offset:2048
	ds_read_b128 v[186:189], v163 offset:3072
	v_add_u32_e32 v171, 0xc000, v149
	v_lshl_add_u64 v[238:239], v[134:135], 0, s[28:29]
	v_readfirstlane_b32 s50, v171
	v_add_u32_e32 v172, 0xe000, v149
	v_lshl_add_u64 v[164:165], v[238:239], 0, s[10:11]
	s_mov_b32 m0, s50
	v_lshl_add_u64 v[240:241], v[132:133], 0, s[28:29]
	v_readfirstlane_b32 s50, v172
	ds_read_b128 v[166:169], v154
	ds_read_b128 v[190:193], v154 offset:1024
	ds_read_b128 v[194:197], v153
	ds_read_b128 v[198:201], v153 offset:1024
	ds_read_b128 v[202:205], v151
	ds_read_b128 v[206:209], v151 offset:1024
	ds_read_b128 v[210:213], v150
	ds_read_b128 v[214:217], v150 offset:1024
	global_load_lds_dwordx4 v[164:165], off
	v_lshl_add_u64 v[164:165], v[240:241], 0, s[10:11]
	s_mov_b32 m0, s50
	s_nop 0
	global_load_lds_dwordx4 v[164:165], off
	s_waitcnt lgkmcnt(8)
	s_barrier
	s_waitcnt lgkmcnt(0)
	s_waitcnt lgkmcnt(0)
	v_mfma_f32_16x16x32_bf16 v[124:127], v[166:169], v[174:177], v[124:127]
	v_mfma_f32_16x16x32_bf16 v[120:123], v[166:169], v[182:185], v[120:123]
	v_mfma_f32_16x16x32_bf16 v[116:119], v[194:197], v[174:177], v[116:119]
	v_mfma_f32_16x16x32_bf16 v[112:115], v[194:197], v[182:185], v[112:115]
	v_mfma_f32_16x16x32_bf16 v[108:111], v[202:205], v[174:177], v[108:111]
	v_mfma_f32_16x16x32_bf16 v[104:107], v[202:205], v[182:185], v[104:107]
	v_mfma_f32_16x16x32_bf16 v[100:103], v[210:213], v[174:177], v[100:103]
	v_mfma_f32_16x16x32_bf16 v[96:99], v[210:213], v[182:185], v[96:99]
	v_mfma_f32_16x16x32_bf16 v[124:127], v[190:193], v[178:181], v[124:127]
	v_mfma_f32_16x16x32_bf16 v[120:123], v[190:193], v[186:189], v[120:123]
	v_mfma_f32_16x16x32_bf16 v[116:119], v[198:201], v[178:181], v[116:119]
	v_mfma_f32_16x16x32_bf16 v[112:115], v[198:201], v[186:189], v[112:115]
	v_mfma_f32_16x16x32_bf16 v[108:111], v[206:209], v[178:181], v[108:111]
	v_mfma_f32_16x16x32_bf16 v[104:107], v[206:209], v[186:189], v[104:107]
	v_mfma_f32_16x16x32_bf16 v[100:103], v[214:217], v[178:181], v[100:103]
	v_mfma_f32_16x16x32_bf16 v[96:99], v[214:217], v[186:189], v[96:99]
	s_barrier
	v_add_u32_e32 v164, s40, v155
	v_lshl_add_u64 v[242:243], v[142:143], 0, s[28:29]
	v_readfirstlane_b32 s50, v164
	v_add_u32_e32 v165, 0x2000, v164
	v_lshl_add_u64 v[234:235], v[242:243], 0, s[12:13]
	s_mov_b32 m0, s50
	v_lshl_add_u64 v[244:245], v[140:141], 0, s[28:29]
	v_readfirstlane_b32 s50, v165
	ds_read_b128 v[218:221], v162
	ds_read_b128 v[222:225], v162 offset:1024
	ds_read_b128 v[226:229], v162 offset:2048
	ds_read_b128 v[230:233], v162 offset:3072
	global_load_lds_dwordx4 v[234:235], off
	v_lshl_add_u64 v[234:235], v[244:245], 0, s[12:13]
	s_mov_b32 m0, s50
	s_nop 0
	global_load_lds_dwordx4 v[234:235], off
	s_barrier
	s_waitcnt lgkmcnt(0)
	s_waitcnt lgkmcnt(0)
	v_mfma_f32_16x16x32_bf16 v[92:95], v[166:169], v[218:221], v[92:95]
	v_mfma_f32_16x16x32_bf16 v[88:91], v[166:169], v[226:229], v[88:91]
	v_mfma_f32_16x16x32_bf16 v[84:87], v[194:197], v[218:221], v[84:87]
	v_mfma_f32_16x16x32_bf16 v[80:83], v[194:197], v[226:229], v[80:83]
	v_mfma_f32_16x16x32_bf16 v[76:79], v[202:205], v[218:221], v[76:79]
	v_mfma_f32_16x16x32_bf16 v[72:75], v[202:205], v[226:229], v[72:75]
	v_mfma_f32_16x16x32_bf16 v[68:71], v[210:213], v[218:221], v[68:71]
	v_mfma_f32_16x16x32_bf16 v[64:67], v[210:213], v[226:229], v[64:67]
	v_mfma_f32_16x16x32_bf16 v[92:95], v[190:193], v[222:225], v[92:95]
	v_mfma_f32_16x16x32_bf16 v[88:91], v[190:193], v[230:233], v[88:91]
	v_mfma_f32_16x16x32_bf16 v[84:87], v[198:201], v[222:225], v[84:87]
	v_mfma_f32_16x16x32_bf16 v[80:83], v[198:201], v[230:233], v[80:83]
	v_mfma_f32_16x16x32_bf16 v[76:79], v[206:209], v[222:225], v[76:79]
	v_mfma_f32_16x16x32_bf16 v[72:75], v[206:209], v[230:233], v[72:75]
	v_mfma_f32_16x16x32_bf16 v[68:71], v[214:217], v[222:225], v[68:71]
	v_mfma_f32_16x16x32_bf16 v[64:67], v[214:217], v[230:233], v[64:67]
	s_barrier
	v_readfirstlane_b32 s50, v149
	v_lshl_add_u64 v[166:167], v[238:239], 0, s[14:15]
	s_mov_b32 m0, s50
	ds_read_b128 v[190:193], v154 offset:16384
	ds_read_b128 v[194:197], v154 offset:17408
	ds_read_b128 v[198:201], v153 offset:16384
	ds_read_b128 v[202:205], v153 offset:17408
	ds_read_b128 v[206:209], v151 offset:16384
	ds_read_b128 v[210:213], v151 offset:17408
	ds_read_b128 v[214:217], v150 offset:16384
	ds_read_b128 v[234:237], v150 offset:17408
	global_load_lds_dwordx4 v[166:167], off
	v_add_u32_e32 v166, 0x2000, v149
	v_lshl_add_u64 v[168:169], v[240:241], 0, s[14:15]
	v_readfirstlane_b32 s50, v166
	s_mov_b32 m0, s50
	s_nop 0
	global_load_lds_dwordx4 v[168:169], off
	s_barrier
	s_waitcnt lgkmcnt(0)
	s_waitcnt lgkmcnt(0)
	v_mfma_f32_16x16x32_bf16 v[60:63], v[190:193], v[174:177], v[60:63]
	v_mfma_f32_16x16x32_bf16 v[56:59], v[190:193], v[182:185], v[56:59]
	v_mfma_f32_16x16x32_bf16 v[52:55], v[198:201], v[174:177], v[52:55]
	v_mfma_f32_16x16x32_bf16 v[48:51], v[198:201], v[182:185], v[48:51]
	v_mfma_f32_16x16x32_bf16 v[44:47], v[206:209], v[174:177], v[44:47]
	v_mfma_f32_16x16x32_bf16 v[40:43], v[206:209], v[182:185], v[40:43]
	v_mfma_f32_16x16x32_bf16 v[36:39], v[214:217], v[174:177], v[36:39]
	v_mfma_f32_16x16x32_bf16 v[32:35], v[214:217], v[182:185], v[32:35]
	v_mfma_f32_16x16x32_bf16 v[60:63], v[194:197], v[178:181], v[60:63]
	v_mfma_f32_16x16x32_bf16 v[56:59], v[194:197], v[186:189], v[56:59]
	v_mfma_f32_16x16x32_bf16 v[52:55], v[202:205], v[178:181], v[52:55]
	v_mfma_f32_16x16x32_bf16 v[48:51], v[202:205], v[186:189], v[48:51]
	v_mfma_f32_16x16x32_bf16 v[44:47], v[210:213], v[178:181], v[44:47]
	v_mfma_f32_16x16x32_bf16 v[40:43], v[210:213], v[186:189], v[40:43]
	v_mfma_f32_16x16x32_bf16 v[36:39], v[234:237], v[178:181], v[36:39]
	v_mfma_f32_16x16x32_bf16 v[32:35], v[234:237], v[186:189], v[32:35]
	s_barrier
; #define STAGE(P, BASE, LD, br, kt) do { const char* _g = (const char*)((BASE) + (size_t)(br) * (LD) + (size_t)(kt) * 64); \
;     for (int _i = 0; _i < 2; ++_i) { int _b = tidx * 16 + _i * 8192; int _r, _c; stage_rc(_b, _r, _c); \
;       __builtin_amdgcn_global_load_lds((const unsigned*)(_g + (unsigned)((_r * (LD) + _c) * 2)), (unsigned*)((char*)(P) + _b), 16, 0, 0); } } while (0)
; #define LDA(dst, b, h) for (int m = 0; m < 4; ++m) for (int k = 0; k < 2; ++k) \
;     dst[m][k] = *reinterpret_cast<const bf16x8*>((char*)SA(b, h) + lds_byte(wr * 64 + m * 16 + fr, k * 32 + fq * 8))
; #define LDB(dst, b, h) for (int n = 0; n < 2; ++n) for (int k = 0; k < 2; ++k) \
;     dst[n][k] = *reinterpret_cast<const bf16x8*>((char*)SB(b, h) + lds_byte(wc * 32 + n * 16 + fr, k * 32 + fq * 8))
; #define MMA(ai, bj, At_, Bt_) do { __builtin_amdgcn_s_setprio(1); \
;     for (int k = 0; k < 2; ++k) for (int m = 0; m < 4; ++m) for (int n = 0; n < 2; ++n) \
;       acc[ai][bj][m][n] = __builtin_amdgcn_mfma_f32_16x16x32_bf16(At_[m][k], Bt_[n][k], acc[ai][bj][m][n], 0, 0, 0); \
;     __builtin_amdgcn_s_setprio(0); } while (0)
; #define WAIT_V(n) asm volatile("s_waitcnt vmcnt(" #n ")" ::: "memory")
; #define WAIT_L(n) asm volatile("s_waitcnt lgkmcnt(" #n ")" ::: "memory")
; #define BAR __builtin_amdgcn_s_barrier()
; #define SCHED __builtin_amdgcn_sched_barrier(0)
; template <int EPI, int lda, int ldb, int N, int K>
; __device__ __forceinline__ void gemm_phase(const u16* __restrict__ A, const u16* __restrict__ Bt, const GemmEpi ep, int wv) {
;     ...
;       STAGE(SB(0, 1), Bt, ldb, bcol + HALF, t + 2);
;       WAIT_V(6); BAR; MMA(1, 1, At, B1); BAR;
;       LDB(B0, 1, 0); SCHED; LDA(At, 1, 0); STAGE(SA(0, 1), Ab, lda, brow + HALF, t + 2);
;       WAIT_L(8); BAR; WAIT_L(0); MMA(0, 0, At, B0); BAR; SCHED;
;       LDB(B1, 1, 1); STAGE(SB(1, 0), Bt, ldb, bcol, t + 3);
;       BAR; WAIT_L(0); MMA(0, 1, At, B1); BAR;
	v_add_u32_e32 v167, s41, v155
	v_lshl_add_u64 v[246:247], v[138:139], 0, s[28:29]
	v_readfirstlane_b32 s50, v167
	v_lshl_add_u64 v[168:169], v[246:247], 0, s[16:17]
	s_mov_b32 m0, s50
	v_lshl_add_u64 v[248:249], v[136:137], 0, s[28:29]
	global_load_lds_dwordx4 v[168:169], off
	v_add_u32_e32 v168, 0x2000, v167
	v_lshl_add_u64 v[174:175], v[248:249], 0, s[16:17]
	v_readfirstlane_b32 s50, v168
	s_mov_b32 m0, s50
	s_nop 0
	global_load_lds_dwordx4 v[174:175], off
	s_waitcnt vmcnt(6)
	s_barrier
	v_mfma_f32_16x16x32_bf16 v[28:31], v[190:193], v[218:221], v[28:31]
	v_mfma_f32_16x16x32_bf16 v[24:27], v[190:193], v[226:229], v[24:27]
	v_mfma_f32_16x16x32_bf16 v[20:23], v[198:201], v[218:221], v[20:23]
	v_mfma_f32_16x16x32_bf16 v[16:19], v[198:201], v[226:229], v[16:19]
	v_mfma_f32_16x16x32_bf16 v[12:15], v[206:209], v[218:221], v[12:15]
	v_mfma_f32_16x16x32_bf16 v[8:11], v[206:209], v[226:229], v[8:11]
	v_mfma_f32_16x16x32_bf16 v[4:7], v[214:217], v[218:221], v[4:7]
	v_mfma_f32_16x16x32_bf16 v[0:3], v[214:217], v[226:229], v[0:3]
	v_mfma_f32_16x16x32_bf16 v[28:31], v[194:197], v[222:225], v[28:31]
	v_mfma_f32_16x16x32_bf16 v[24:27], v[194:197], v[230:233], v[24:27]
	v_mfma_f32_16x16x32_bf16 v[20:23], v[202:205], v[222:225], v[20:23]
	v_mfma_f32_16x16x32_bf16 v[16:19], v[202:205], v[230:233], v[16:19]
	v_mfma_f32_16x16x32_bf16 v[12:15], v[210:213], v[222:225], v[12:15]
	v_mfma_f32_16x16x32_bf16 v[8:11], v[210:213], v[230:233], v[8:11]
	v_mfma_f32_16x16x32_bf16 v[4:7], v[234:237], v[222:225], v[4:7]
	v_mfma_f32_16x16x32_bf16 v[0:3], v[234:237], v[230:233], v[0:3]
	s_barrier
	ds_read_b128 v[174:177], v158
	ds_read_b128 v[178:181], v158 offset:1024
	ds_read_b128 v[182:185], v158 offset:2048
	ds_read_b128 v[186:189], v158 offset:3072
	v_add_u32_e32 v169, 0x4000, v149
	v_add_u32_e32 v170, 0x6000, v149
	v_readfirstlane_b32 s50, v169
	v_lshl_add_u64 v[222:223], v[238:239], 0, s[18:19]
	s_mov_b32 m0, s50
	v_readfirstlane_b32 s50, v170
	ds_read_b128 v[190:193], v154 offset:32768
	ds_read_b128 v[194:197], v154 offset:33792
	ds_read_b128 v[198:201], v153 offset:32768
	ds_read_b128 v[202:205], v153 offset:33792
	ds_read_b128 v[206:209], v151 offset:32768
	ds_read_b128 v[210:213], v151 offset:33792
	ds_read_b128 v[214:217], v150 offset:32768
	ds_read_b128 v[218:221], v150 offset:33792
	global_load_lds_dwordx4 v[222:223], off
	v_lshl_add_u64 v[222:223], v[240:241], 0, s[18:19]
	s_mov_b32 m0, s50
	s_nop 0
	global_load_lds_dwordx4 v[222:223], off
	s_waitcnt lgkmcnt(8)
	s_barrier
	s_waitcnt lgkmcnt(0)
	s_waitcnt lgkmcnt(0)
	v_mfma_f32_16x16x32_bf16 v[124:127], v[190:193], v[174:177], v[124:127]
	v_mfma_f32_16x16x32_bf16 v[120:123], v[190:193], v[182:185], v[120:123]
	v_mfma_f32_16x16x32_bf16 v[116:119], v[198:201], v[174:177], v[116:119]
	v_mfma_f32_16x16x32_bf16 v[112:115], v[198:201], v[182:185], v[112:115]
	v_mfma_f32_16x16x32_bf16 v[108:111], v[206:209], v[174:177], v[108:111]
	v_mfma_f32_16x16x32_bf16 v[104:107], v[206:209], v[182:185], v[104:107]
	v_mfma_f32_16x16x32_bf16 v[100:103], v[214:217], v[174:177], v[100:103]
	v_mfma_f32_16x16x32_bf16 v[96:99], v[214:217], v[182:185], v[96:99]
	v_mfma_f32_16x16x32_bf16 v[124:127], v[194:197], v[178:181], v[124:127]
	v_mfma_f32_16x16x32_bf16 v[120:123], v[194:197], v[186:189], v[120:123]
	v_mfma_f32_16x16x32_bf16 v[116:119], v[202:205], v[178:181], v[116:119]
	v_mfma_f32_16x16x32_bf16 v[112:115], v[202:205], v[186:189], v[112:115]
	v_mfma_f32_16x16x32_bf16 v[108:111], v[210:213], v[178:181], v[108:111]
	v_mfma_f32_16x16x32_bf16 v[104:107], v[210:213], v[186:189], v[104:107]
	v_mfma_f32_16x16x32_bf16 v[100:103], v[218:221], v[178:181], v[100:103]
	v_mfma_f32_16x16x32_bf16 v[96:99], v[218:221], v[186:189], v[96:99]
	s_barrier
	v_readfirstlane_b32 s50, v157
	v_add_u32_e32 v173, 0x2000, v157
	v_lshl_add_u64 v[242:243], v[242:243], 0, s[20:21]
	s_mov_b32 m0, s50
	v_readfirstlane_b32 s50, v173
	ds_read_b128 v[222:225], v156
	ds_read_b128 v[226:229], v156 offset:1024
	ds_read_b128 v[230:233], v156 offset:2048
	ds_read_b128 v[234:237], v156 offset:3072
	global_load_lds_dwordx4 v[242:243], off
	v_lshl_add_u64 v[242:243], v[244:245], 0, s[20:21]
	s_mov_b32 m0, s50
	s_nop 0
	global_load_lds_dwordx4 v[242:243], off
	s_barrier
	s_waitcnt lgkmcnt(0)
	s_waitcnt lgkmcnt(0)
	v_mfma_f32_16x16x32_bf16 v[92:95], v[190:193], v[222:225], v[92:95]
	v_mfma_f32_16x16x32_bf16 v[88:91], v[190:193], v[230:233], v[88:91]
	v_mfma_f32_16x16x32_bf16 v[84:87], v[198:201], v[222:225], v[84:87]
	v_mfma_f32_16x16x32_bf16 v[80:83], v[198:201], v[230:233], v[80:83]
	v_mfma_f32_16x16x32_bf16 v[76:79], v[206:209], v[222:225], v[76:79]
	v_mfma_f32_16x16x32_bf16 v[72:75], v[206:209], v[230:233], v[72:75]
	v_mfma_f32_16x16x32_bf16 v[68:71], v[214:217], v[222:225], v[68:71]
	v_mfma_f32_16x16x32_bf16 v[64:67], v[214:217], v[230:233], v[64:67]
	v_mfma_f32_16x16x32_bf16 v[92:95], v[194:197], v[226:229], v[92:95]
	v_mfma_f32_16x16x32_bf16 v[88:91], v[194:197], v[234:237], v[88:91]
	v_mfma_f32_16x16x32_bf16 v[84:87], v[202:205], v[226:229], v[84:87]
	v_mfma_f32_16x16x32_bf16 v[80:83], v[202:205], v[234:237], v[80:83]
	v_mfma_f32_16x16x32_bf16 v[76:79], v[210:213], v[226:229], v[76:79]
	v_mfma_f32_16x16x32_bf16 v[72:75], v[210:213], v[234:237], v[72:75]
	v_mfma_f32_16x16x32_bf16 v[68:71], v[218:221], v[226:229], v[68:71]
	v_mfma_f32_16x16x32_bf16 v[64:67], v[218:221], v[234:237], v[64:67]
	s_barrier
; #define STAGE(P, BASE, LD, br, kt) do { const char* _g = (const char*)((BASE) + (size_t)(br) * (LD) + (size_t)(kt) * 64); \
;     for (int _i = 0; _i < 2; ++_i) { int _b = tidx * 16 + _i * 8192; int _r, _c; stage_rc(_b, _r, _c); \
;       __builtin_amdgcn_global_load_lds((const unsigned*)(_g + (unsigned)((_r * (LD) + _c) * 2)), (unsigned*)((char*)(P) + _b), 16, 0, 0); } } while (0)
; #define LDA(dst, b, h) for (int m = 0; m < 4; ++m) for (int k = 0; k < 2; ++k) \
;     dst[m][k] = *reinterpret_cast<const bf16x8*>((char*)SA(b, h) + lds_byte(wr * 64 + m * 16 + fr, k * 32 + fq * 8))
; #define LDB(dst, b, h) for (int n = 0; n < 2; ++n) for (int k = 0; k < 2; ++k) \
;     dst[n][k] = *reinterpret_cast<const bf16x8*>((char*)SB(b, h) + lds_byte(wc * 32 + n * 16 + fr, k * 32 + fq * 8))
; #define MMA(ai, bj, At_, Bt_) do { __builtin_amdgcn_s_setprio(1); \
;     for (int k = 0; k < 2; ++k) for (int m = 0; m < 4; ++m) for (int n = 0; n < 2; ++n) \
;       acc[ai][bj][m][n] = __builtin_amdgcn_mfma_f32_16x16x32_bf16(At_[m][k], Bt_[n][k], acc[ai][bj][m][n], 0, 0, 0); \
;     __builtin_amdgcn_s_setprio(0); } while (0)
; #define WAIT_V(n) asm volatile("s_waitcnt vmcnt(" #n ")" ::: "memory")
; #define WAIT_L(n) asm volatile("s_waitcnt lgkmcnt(" #n ")" ::: "memory")
; #define BAR __builtin_amdgcn_s_barrier()
; #define SCHED __builtin_amdgcn_sched_barrier(0)
; template <int EPI, int lda, int ldb, int N, int K>
; __device__ __forceinline__ void gemm_phase(const u16* __restrict__ A, const u16* __restrict__ Bt, const GemmEpi ep, int wv) {
;     ...
;       LDA(At, 1, 1); STAGE(SA(1, 0), Ab, lda, brow, t + 3);
;       BAR; WAIT_L(0); MMA(1, 0, At, B0); BAR; SCHED;
;       STAGE(SB(1, 1), Bt, ldb, bcol + HALF, t + 3);
;       WAIT_V(6); BAR; MMA(1, 1, At, B1); BAR;
;     }
;     { LDB(B0, 0, 0); LDA(At, 0, 0); STAGE(SA(1, 1), Ab, lda, brow + HALF, nt - 1);
;       BAR; WAIT_L(0); MMA(0, 0, At, B0); BAR;
	v_readfirstlane_b32 s50, v159
	v_lshl_add_u64 v[238:239], v[238:239], 0, s[22:23]
	s_mov_b32 m0, s50
	v_readfirstlane_b32 s50, v160
	ds_read_b128 v[190:193], v154 offset:49152
	ds_read_b128 v[194:197], v154 offset:50176
	ds_read_b128 v[198:201], v153 offset:49152
	ds_read_b128 v[202:205], v153 offset:50176
	ds_read_b128 v[206:209], v151 offset:49152
	ds_read_b128 v[210:213], v151 offset:50176
	ds_read_b128 v[214:217], v150 offset:49152
	ds_read_b128 v[218:221], v150 offset:50176
	global_load_lds_dwordx4 v[238:239], off
	v_lshl_add_u64 v[238:239], v[240:241], 0, s[22:23]
	s_mov_b32 m0, s50
	s_nop 0
	global_load_lds_dwordx4 v[238:239], off
	s_barrier
	s_waitcnt lgkmcnt(0)
	s_waitcnt lgkmcnt(0)
	v_mfma_f32_16x16x32_bf16 v[60:63], v[190:193], v[174:177], v[60:63]
	v_mfma_f32_16x16x32_bf16 v[56:59], v[190:193], v[182:185], v[56:59]
	v_mfma_f32_16x16x32_bf16 v[52:55], v[198:201], v[174:177], v[52:55]
	v_mfma_f32_16x16x32_bf16 v[48:51], v[198:201], v[182:185], v[48:51]
	v_mfma_f32_16x16x32_bf16 v[44:47], v[206:209], v[174:177], v[44:47]
	v_mfma_f32_16x16x32_bf16 v[40:43], v[206:209], v[182:185], v[40:43]
	v_mfma_f32_16x16x32_bf16 v[36:39], v[214:217], v[174:177], v[36:39]
	v_mfma_f32_16x16x32_bf16 v[32:35], v[214:217], v[182:185], v[32:35]
	v_mfma_f32_16x16x32_bf16 v[60:63], v[194:197], v[178:181], v[60:63]
	v_mfma_f32_16x16x32_bf16 v[56:59], v[194:197], v[186:189], v[56:59]
	v_mfma_f32_16x16x32_bf16 v[52:55], v[202:205], v[178:181], v[52:55]
	v_mfma_f32_16x16x32_bf16 v[48:51], v[202:205], v[186:189], v[48:51]
	v_mfma_f32_16x16x32_bf16 v[44:47], v[210:213], v[178:181], v[44:47]
	v_mfma_f32_16x16x32_bf16 v[40:43], v[210:213], v[186:189], v[40:43]
	v_mfma_f32_16x16x32_bf16 v[36:39], v[218:221], v[178:181], v[36:39]
	v_mfma_f32_16x16x32_bf16 v[32:35], v[218:221], v[186:189], v[32:35]
	s_barrier
	v_readfirstlane_b32 s50, v161
	v_add_u32_e32 v173, 0x2000, v161
	v_lshl_add_u64 v[174:175], v[246:247], 0, s[24:25]
	s_mov_b32 m0, s50
	v_readfirstlane_b32 s50, v173
	global_load_lds_dwordx4 v[174:175], off
	v_lshl_add_u64 v[174:175], v[248:249], 0, s[24:25]
	s_mov_b32 m0, s50
	s_nop 0
	global_load_lds_dwordx4 v[174:175], off
	s_waitcnt vmcnt(6)
	s_barrier
	v_mfma_f32_16x16x32_bf16 v[28:31], v[190:193], v[222:225], v[28:31]
	v_mfma_f32_16x16x32_bf16 v[24:27], v[190:193], v[230:233], v[24:27]
	v_mfma_f32_16x16x32_bf16 v[20:23], v[198:201], v[222:225], v[20:23]
	v_mfma_f32_16x16x32_bf16 v[16:19], v[198:201], v[230:233], v[16:19]
	v_mfma_f32_16x16x32_bf16 v[12:15], v[206:209], v[222:225], v[12:15]
	v_mfma_f32_16x16x32_bf16 v[8:11], v[206:209], v[230:233], v[8:11]
	v_mfma_f32_16x16x32_bf16 v[4:7], v[214:217], v[222:225], v[4:7]
	v_mfma_f32_16x16x32_bf16 v[0:3], v[214:217], v[230:233], v[0:3]
	v_mfma_f32_16x16x32_bf16 v[28:31], v[194:197], v[226:229], v[28:31]
	v_mfma_f32_16x16x32_bf16 v[24:27], v[194:197], v[234:237], v[24:27]
	v_mfma_f32_16x16x32_bf16 v[20:23], v[202:205], v[226:229], v[20:23]
	v_mfma_f32_16x16x32_bf16 v[16:19], v[202:205], v[234:237], v[16:19]
	v_mfma_f32_16x16x32_bf16 v[12:15], v[210:213], v[226:229], v[12:15]
	v_mfma_f32_16x16x32_bf16 v[8:11], v[210:213], v[234:237], v[8:11]
	v_mfma_f32_16x16x32_bf16 v[4:7], v[218:221], v[226:229], v[4:7]
	v_mfma_f32_16x16x32_bf16 v[0:3], v[218:221], v[234:237], v[0:3]
	s_barrier
	s_add_i32 s49, s49, 2
	s_add_u32 s28, s28, 0x100
	s_addc_u32 s29, s29, 0
	s_cmpk_gt_u32 s49, 0x51
	s_cbranch_scc0 .LBB0_1624
	s_add_i32 s28, s48, 0x80
	s_mul_hi_i32 s29, s28, 0x2b00
	s_mulk_i32 s28, 0x2b00
	s_add_u32 s28, s34, s28
	s_addc_u32 s29, s35, s29
	s_add_u32 s28, s28, 0x2a80
	s_addc_u32 s29, s29, 0
	v_readfirstlane_b32 s49, v171
	v_lshl_add_u64 v[160:161], s[28:29], 0, v[128:129]
	s_mov_b32 m0, s49
	ds_read_b128 v[132:135], v163
	ds_read_b128 v[136:139], v163 offset:1024
	ds_read_b128 v[140:143], v163 offset:2048
	ds_read_b128 v[174:177], v163 offset:3072
	ds_read_b128 v[178:181], v154
	ds_read_b128 v[182:185], v154 offset:1024
	ds_read_b128 v[186:189], v153
	ds_read_b128 v[190:193], v153 offset:1024
	ds_read_b128 v[194:197], v151
	ds_read_b128 v[198:201], v151 offset:1024
	ds_read_b128 v[202:205], v150
	ds_read_b128 v[206:209], v150 offset:1024
	global_load_lds_dwordx4 v[160:161], off
	v_lshl_add_u64 v[160:161], s[28:29], 0, v[130:131]
	v_readfirstlane_b32 s28, v172
	s_mov_b32 m0, s28
	s_nop 0
	global_load_lds_dwordx4 v[160:161], off
	s_barrier
	s_waitcnt lgkmcnt(0)
	s_waitcnt lgkmcnt(0)
	v_mfma_f32_16x16x32_bf16 v[124:127], v[178:181], v[132:135], v[124:127]
	v_mfma_f32_16x16x32_bf16 v[120:123], v[178:181], v[140:143], v[120:123]
	v_mfma_f32_16x16x32_bf16 v[116:119], v[186:189], v[132:135], v[116:119]
	v_mfma_f32_16x16x32_bf16 v[112:115], v[186:189], v[140:143], v[112:115]
	v_mfma_f32_16x16x32_bf16 v[108:111], v[194:197], v[132:135], v[108:111]
	v_mfma_f32_16x16x32_bf16 v[104:107], v[194:197], v[140:143], v[104:107]
	v_mfma_f32_16x16x32_bf16 v[100:103], v[202:205], v[132:135], v[100:103]
	v_mfma_f32_16x16x32_bf16 v[96:99], v[202:205], v[140:143], v[96:99]
	v_mfma_f32_16x16x32_bf16 v[124:127], v[182:185], v[136:139], v[124:127]
	v_mfma_f32_16x16x32_bf16 v[120:123], v[182:185], v[174:177], v[120:123]
	v_mfma_f32_16x16x32_bf16 v[116:119], v[190:193], v[136:139], v[116:119]
	v_mfma_f32_16x16x32_bf16 v[112:115], v[190:193], v[174:177], v[112:115]
	v_mfma_f32_16x16x32_bf16 v[108:111], v[198:201], v[136:139], v[108:111]
	v_mfma_f32_16x16x32_bf16 v[104:107], v[198:201], v[174:177], v[104:107]
	v_mfma_f32_16x16x32_bf16 v[100:103], v[206:209], v[136:139], v[100:103]
	v_mfma_f32_16x16x32_bf16 v[96:99], v[206:209], v[174:177], v[96:99]
	s_barrier
; #define LDA(dst, b, h) for (int m = 0; m < 4; ++m) for (int k = 0; k < 2; ++k) \
;     dst[m][k] = *reinterpret_cast<const bf16x8*>((char*)SA(b, h) + lds_byte(wr * 64 + m * 16 + fr, k * 32 + fq * 8))
; #define LDB(dst, b, h) for (int n = 0; n < 2; ++n) for (int k = 0; k < 2; ++k) \
;     dst[n][k] = *reinterpret_cast<const bf16x8*>((char*)SB(b, h) + lds_byte(wc * 32 + n * 16 + fr, k * 32 + fq * 8))
; #define MMA(ai, bj, At_, Bt_) do { __builtin_amdgcn_s_setprio(1); \
;     for (int k = 0; k < 2; ++k) for (int m = 0; m < 4; ++m) for (int n = 0; n < 2; ++n) \
;       acc[ai][bj][m][n] = __builtin_amdgcn_mfma_f32_16x16x32_bf16(At_[m][k], Bt_[n][k], acc[ai][bj][m][n], 0, 0, 0); \
;     __builtin_amdgcn_s_setprio(0); } while (0)
; #define WAIT_V(n) asm volatile("s_waitcnt vmcnt(" #n ")" ::: "memory")
; #define WAIT_L(n) asm volatile("s_waitcnt lgkmcnt(" #n ")" ::: "memory")
; #define BAR __builtin_amdgcn_s_barrier()
; template <int EPI, int lda, int ldb, int N, int K>
; __device__ __forceinline__ void gemm_phase(const u16* __restrict__ A, const u16* __restrict__ Bt, const GemmEpi ep, int wv) {
;     ...
;       LDB(B1, 0, 1); BAR; WAIT_L(0); MMA(0, 1, At, B1); BAR;
;       LDA(At, 0, 1); WAIT_V(4); BAR; WAIT_L(0); MMA(1, 0, At, B0); MMA(1, 1, At, B1); BAR; }
;     { LDB(B0, 1, 0); LDA(At, 1, 0); WAIT_V(2); BAR; WAIT_L(0); MMA(0, 0, At, B0); BAR;
	ds_read_b128 v[210:213], v162
	ds_read_b128 v[214:217], v162 offset:1024
	ds_read_b128 v[218:221], v162 offset:2048
	ds_read_b128 v[160:163], v162 offset:3072
	s_barrier
	s_waitcnt lgkmcnt(0)
	s_waitcnt lgkmcnt(0)
	v_mfma_f32_16x16x32_bf16 v[92:95], v[178:181], v[210:213], v[92:95]
	v_mfma_f32_16x16x32_bf16 v[88:91], v[178:181], v[218:221], v[88:91]
	v_mfma_f32_16x16x32_bf16 v[72:75], v[194:197], v[218:221], v[72:75]
	v_mfma_f32_16x16x32_bf16 v[68:71], v[202:205], v[210:213], v[68:71]
	v_mfma_f32_16x16x32_bf16 v[84:87], v[186:189], v[210:213], v[84:87]
	v_mfma_f32_16x16x32_bf16 v[80:83], v[186:189], v[218:221], v[80:83]
	v_mfma_f32_16x16x32_bf16 v[76:79], v[194:197], v[210:213], v[76:79]
	v_mfma_f32_16x16x32_bf16 v[64:67], v[202:205], v[218:221], v[64:67]
	v_mfma_f32_16x16x32_bf16 v[92:95], v[182:185], v[214:217], v[92:95]
	v_mfma_f32_16x16x32_bf16 v[88:91], v[182:185], v[160:163], v[88:91]
	v_mfma_f32_16x16x32_bf16 v[72:75], v[198:201], v[160:163], v[72:75]
	v_mfma_f32_16x16x32_bf16 v[68:71], v[206:209], v[214:217], v[68:71]
	v_mfma_f32_16x16x32_bf16 v[178:181], v[190:193], v[214:217], v[84:87]
	v_mfma_f32_16x16x32_bf16 v[182:185], v[190:193], v[160:163], v[80:83]
	v_mfma_f32_16x16x32_bf16 v[186:189], v[198:201], v[214:217], v[76:79]
	v_mfma_f32_16x16x32_bf16 v[190:193], v[206:209], v[160:163], v[64:67]
	s_barrier
	s_nop 0
	ds_read_b128 v[64:67], v154 offset:16384
	ds_read_b128 v[76:79], v154 offset:17408
	ds_read_b128 v[80:83], v153 offset:16384
	ds_read_b128 v[84:87], v153 offset:17408
	ds_read_b128 v[194:197], v151 offset:16384
	ds_read_b128 v[198:201], v151 offset:17408
	ds_read_b128 v[202:205], v150 offset:16384
	ds_read_b128 v[206:209], v150 offset:17408
	s_waitcnt vmcnt(4)
	s_barrier
	s_waitcnt lgkmcnt(0)
	s_waitcnt lgkmcnt(0)
	v_mfma_f32_16x16x32_bf16 v[60:63], v[64:67], v[132:135], v[60:63]
	v_mfma_f32_16x16x32_bf16 v[56:59], v[64:67], v[140:143], v[56:59]
	v_mfma_f32_16x16x32_bf16 v[52:55], v[80:83], v[132:135], v[52:55]
	v_mfma_f32_16x16x32_bf16 v[48:51], v[80:83], v[140:143], v[48:51]
	v_mfma_f32_16x16x32_bf16 v[44:47], v[194:197], v[132:135], v[44:47]
	v_mfma_f32_16x16x32_bf16 v[40:43], v[194:197], v[140:143], v[40:43]
	v_mfma_f32_16x16x32_bf16 v[36:39], v[202:205], v[132:135], v[36:39]
	v_mfma_f32_16x16x32_bf16 v[32:35], v[202:205], v[140:143], v[32:35]
	v_mfma_f32_16x16x32_bf16 v[60:63], v[76:79], v[136:139], v[60:63]
	v_mfma_f32_16x16x32_bf16 v[56:59], v[76:79], v[174:177], v[56:59]
	v_mfma_f32_16x16x32_bf16 v[52:55], v[84:87], v[136:139], v[52:55]
	v_mfma_f32_16x16x32_bf16 v[48:51], v[84:87], v[174:177], v[48:51]
	v_mfma_f32_16x16x32_bf16 v[44:47], v[198:201], v[136:139], v[44:47]
	v_mfma_f32_16x16x32_bf16 v[40:43], v[198:201], v[174:177], v[40:43]
	v_mfma_f32_16x16x32_bf16 v[36:39], v[206:209], v[136:139], v[36:39]
	v_mfma_f32_16x16x32_bf16 v[32:35], v[206:209], v[174:177], v[32:35]
	v_mfma_f32_16x16x32_bf16 v[28:31], v[64:67], v[210:213], v[28:31]
	v_mfma_f32_16x16x32_bf16 v[24:27], v[64:67], v[218:221], v[24:27]
	v_mfma_f32_16x16x32_bf16 v[12:15], v[194:197], v[210:213], v[12:15]
	v_mfma_f32_16x16x32_bf16 v[8:11], v[194:197], v[218:221], v[8:11]
	v_mfma_f32_16x16x32_bf16 v[20:23], v[80:83], v[210:213], v[20:23]
	v_mfma_f32_16x16x32_bf16 v[16:19], v[80:83], v[218:221], v[16:19]
	v_mfma_f32_16x16x32_bf16 v[4:7], v[202:205], v[210:213], v[4:7]
	v_mfma_f32_16x16x32_bf16 v[0:3], v[202:205], v[218:221], v[0:3]
	v_mfma_f32_16x16x32_bf16 v[28:31], v[76:79], v[214:217], v[28:31]
	v_mfma_f32_16x16x32_bf16 v[24:27], v[76:79], v[160:163], v[24:27]
	v_mfma_f32_16x16x32_bf16 v[12:15], v[198:201], v[214:217], v[12:15]
	v_mfma_f32_16x16x32_bf16 v[8:11], v[198:201], v[160:163], v[8:11]
	v_mfma_f32_16x16x32_bf16 v[132:135], v[84:87], v[214:217], v[20:23]
	v_mfma_f32_16x16x32_bf16 v[136:139], v[84:87], v[160:163], v[16:19]
	v_mfma_f32_16x16x32_bf16 v[140:143], v[206:209], v[214:217], v[4:7]
	v_mfma_f32_16x16x32_bf16 v[160:163], v[206:209], v[160:163], v[0:3]
	s_barrier
	s_nop 0
	ds_read_b128 v[0:3], v158
	ds_read_b128 v[4:7], v158 offset:1024
	ds_read_b128 v[16:19], v158 offset:2048
	ds_read_b128 v[172:175], v158 offset:3072
	ds_read_b128 v[20:23], v154 offset:32768
	ds_read_b128 v[194:197], v154 offset:33792
	ds_read_b128 v[198:201], v153 offset:32768
	ds_read_b128 v[202:205], v153 offset:33792
	ds_read_b128 v[206:209], v151 offset:32768
	ds_read_b128 v[210:213], v151 offset:33792
	ds_read_b128 v[214:217], v150 offset:32768
	ds_read_b128 v[218:221], v150 offset:33792
	s_waitcnt vmcnt(2)
	s_barrier
; #define LDA(dst, b, h) for (int m = 0; m < 4; ++m) for (int k = 0; k < 2; ++k) \
;     dst[m][k] = *reinterpret_cast<const bf16x8*>((char*)SA(b, h) + lds_byte(wr * 64 + m * 16 + fr, k * 32 + fq * 8))
; #define LDB(dst, b, h) for (int n = 0; n < 2; ++n) for (int k = 0; k < 2; ++k) \
;     dst[n][k] = *reinterpret_cast<const bf16x8*>((char*)SB(b, h) + lds_byte(wc * 32 + n * 16 + fr, k * 32 + fq * 8))
; #define MMA(ai, bj, At_, Bt_) do { __builtin_amdgcn_s_setprio(1); \
;     for (int k = 0; k < 2; ++k) for (int m = 0; m < 4; ++m) for (int n = 0; n < 2; ++n) \
;       acc[ai][bj][m][n] = __builtin_amdgcn_mfma_f32_16x16x32_bf16(At_[m][k], Bt_[n][k], acc[ai][bj][m][n], 0, 0, 0); \
;     __builtin_amdgcn_s_setprio(0); } while (0)
; #define WAIT_V(n) asm volatile("s_waitcnt vmcnt(" #n ")" ::: "memory")
; #define WAIT_L(n) asm volatile("s_waitcnt lgkmcnt(" #n ")" ::: "memory")
; #define BAR __builtin_amdgcn_s_barrier()
; template <int EPI, int lda, int ldb, int N, int K>
; __device__ __forceinline__ void gemm_phase(const u16* __restrict__ A, const u16* __restrict__ Bt, const GemmEpi ep, int wv) {
;     ...
;     { LDB(B0, 1, 0); LDA(At, 1, 0); WAIT_V(2); BAR; WAIT_L(0); MMA(0, 0, At, B0); BAR;
;       LDB(B1, 1, 1); WAIT_V(0); BAR; WAIT_L(0); MMA(0, 1, At, B1); BAR;
;       LDA(At, 1, 1); BAR; WAIT_L(0); MMA(1, 0, At, B0); MMA(1, 1, At, B1); BAR; }
;     if (wr == 0) BAR;
	s_waitcnt lgkmcnt(0)
	s_waitcnt lgkmcnt(0)
	v_mfma_f32_16x16x32_bf16 v[64:67], v[20:23], v[0:3], v[124:127]
	v_mfma_f32_16x16x32_bf16 v[76:79], v[20:23], v[16:19], v[120:123]
	v_mfma_f32_16x16x32_bf16 v[80:83], v[198:201], v[0:3], v[116:119]
	v_mfma_f32_16x16x32_bf16 v[84:87], v[198:201], v[16:19], v[112:115]
	v_mfma_f32_16x16x32_bf16 v[108:111], v[206:209], v[0:3], v[108:111]
	v_mfma_f32_16x16x32_bf16 v[104:107], v[206:209], v[16:19], v[104:107]
	v_mfma_f32_16x16x32_bf16 v[120:123], v[214:217], v[0:3], v[100:103]
	v_mfma_f32_16x16x32_bf16 v[124:127], v[214:217], v[16:19], v[96:99]
	v_mfma_f32_16x16x32_bf16 v[116:119], v[194:197], v[4:7], v[64:67]
	v_mfma_f32_16x16x32_bf16 v[112:115], v[194:197], v[172:175], v[76:79]
	v_mfma_f32_16x16x32_bf16 v[100:103], v[202:205], v[4:7], v[80:83]
	v_mfma_f32_16x16x32_bf16 v[96:99], v[202:205], v[172:175], v[84:87]
	v_mfma_f32_16x16x32_bf16 v[84:87], v[210:213], v[4:7], v[108:111]
	v_mfma_f32_16x16x32_bf16 v[80:83], v[210:213], v[172:175], v[104:107]
	v_mfma_f32_16x16x32_bf16 v[76:79], v[218:221], v[4:7], v[120:123]
	v_mfma_f32_16x16x32_bf16 v[64:67], v[218:221], v[172:175], v[124:127]
	s_barrier
	ds_read_b128 v[222:225], v156
	ds_read_b128 v[226:229], v156 offset:1024
	ds_read_b128 v[230:233], v156 offset:2048
	ds_read_b128 v[156:159], v156 offset:3072
	s_waitcnt vmcnt(0)
	s_barrier
	s_waitcnt lgkmcnt(0)
	s_waitcnt lgkmcnt(0)
	v_mfma_f32_16x16x32_bf16 v[92:95], v[20:23], v[222:225], v[92:95]
	v_mfma_f32_16x16x32_bf16 v[20:23], v[20:23], v[230:233], v[88:91]
	v_mfma_f32_16x16x32_bf16 v[88:91], v[198:201], v[222:225], v[178:181]
	v_mfma_f32_16x16x32_bf16 v[104:107], v[198:201], v[230:233], v[182:185]
	v_mfma_f32_16x16x32_bf16 v[176:179], v[206:209], v[222:225], v[186:189]
	v_mfma_f32_16x16x32_bf16 v[72:75], v[206:209], v[230:233], v[72:75]
	v_mfma_f32_16x16x32_bf16 v[68:71], v[214:217], v[222:225], v[68:71]
	v_mfma_f32_16x16x32_bf16 v[180:183], v[214:217], v[230:233], v[190:193]
	v_mfma_f32_16x16x32_bf16 v[124:127], v[194:197], v[226:229], v[92:95]
	v_mfma_f32_16x16x32_bf16 v[120:123], v[194:197], v[156:159], v[20:23]
	v_mfma_f32_16x16x32_bf16 v[108:111], v[202:205], v[226:229], v[88:91]
	v_mfma_f32_16x16x32_bf16 v[104:107], v[202:205], v[156:159], v[104:107]
	v_mfma_f32_16x16x32_bf16 v[92:95], v[210:213], v[226:229], v[176:179]
	v_mfma_f32_16x16x32_bf16 v[88:91], v[210:213], v[156:159], v[72:75]
	v_mfma_f32_16x16x32_bf16 v[72:75], v[218:221], v[226:229], v[68:71]
	v_mfma_f32_16x16x32_bf16 v[68:71], v[218:221], v[156:159], v[180:183]
	s_barrier
	ds_read_b128 v[176:179], v154 offset:49152
	ds_read_b128 v[180:183], v154 offset:50176
	ds_read_b128 v[184:187], v153 offset:49152
	ds_read_b128 v[188:191], v153 offset:50176
	ds_read_b128 v[192:195], v151 offset:49152
	ds_read_b128 v[196:199], v151 offset:50176
	ds_read_b128 v[200:203], v150 offset:49152
	ds_read_b128 v[204:207], v150 offset:50176
	s_barrier
	s_waitcnt lgkmcnt(0)
	s_waitcnt lgkmcnt(0)
	v_mfma_f32_16x16x32_bf16 v[20:23], v[176:179], v[0:3], v[60:63]
	v_mfma_f32_16x16x32_bf16 v[56:59], v[176:179], v[16:19], v[56:59]
	v_mfma_f32_16x16x32_bf16 v[60:63], v[184:187], v[0:3], v[52:55]
	v_mfma_f32_16x16x32_bf16 v[208:211], v[184:187], v[16:19], v[48:51]
	v_mfma_f32_16x16x32_bf16 v[44:47], v[192:195], v[0:3], v[44:47]
	v_mfma_f32_16x16x32_bf16 v[40:43], v[192:195], v[16:19], v[40:43]
	v_mfma_f32_16x16x32_bf16 v[0:3], v[200:203], v[0:3], v[36:39]
	v_mfma_f32_16x16x32_bf16 v[212:215], v[200:203], v[16:19], v[32:35]
	v_mfma_f32_16x16x32_bf16 v[52:55], v[180:183], v[4:7], v[20:23]
	v_mfma_f32_16x16x32_bf16 v[48:51], v[180:183], v[172:175], v[56:59]
	v_mfma_f32_16x16x32_bf16 v[36:39], v[188:191], v[4:7], v[60:63]
	v_mfma_f32_16x16x32_bf16 v[32:35], v[188:191], v[172:175], v[208:211]
	v_mfma_f32_16x16x32_bf16 v[20:23], v[196:199], v[4:7], v[44:47]
	v_mfma_f32_16x16x32_bf16 v[16:19], v[196:199], v[172:175], v[40:43]
	v_mfma_f32_16x16x32_bf16 v[4:7], v[204:207], v[4:7], v[0:3]
	v_mfma_f32_16x16x32_bf16 v[0:3], v[204:207], v[172:175], v[212:215]
	v_mfma_f32_16x16x32_bf16 v[28:31], v[176:179], v[222:225], v[28:31]
	v_mfma_f32_16x16x32_bf16 v[24:27], v[176:179], v[230:233], v[24:27]
	v_mfma_f32_16x16x32_bf16 v[40:43], v[184:187], v[222:225], v[132:135]
	v_mfma_f32_16x16x32_bf16 v[132:135], v[184:187], v[230:233], v[136:139]
	v_mfma_f32_16x16x32_bf16 v[12:15], v[192:195], v[222:225], v[12:15]
	v_mfma_f32_16x16x32_bf16 v[8:11], v[192:195], v[230:233], v[8:11]
	v_mfma_f32_16x16x32_bf16 v[136:139], v[200:203], v[222:225], v[140:143]
	v_mfma_f32_16x16x32_bf16 v[140:143], v[200:203], v[230:233], v[160:163]
	v_mfma_f32_16x16x32_bf16 v[60:63], v[180:183], v[226:229], v[28:31]
	v_mfma_f32_16x16x32_bf16 v[56:59], v[180:183], v[156:159], v[24:27]
	v_mfma_f32_16x16x32_bf16 v[44:47], v[188:191], v[226:229], v[40:43]
	v_mfma_f32_16x16x32_bf16 v[40:43], v[188:191], v[156:159], v[132:135]
	v_mfma_f32_16x16x32_bf16 v[28:31], v[196:199], v[226:229], v[12:15]
	v_mfma_f32_16x16x32_bf16 v[24:27], v[196:199], v[156:159], v[8:11]
	v_mfma_f32_16x16x32_bf16 v[12:15], v[204:207], v[226:229], v[136:139]
	v_mfma_f32_16x16x32_bf16 v[8:11], v[204:207], v[156:159], v[140:143]
	v_cmp_gt_u32_e32 vcc, s46, v147
	s_barrier
	s_and_saveexec_b64 s[28:29], vcc
	s_cbranch_execz .LBB0_1627
	s_barrier
